# EpiConv prompt path made fall-through: sample-row context blocks and sample-only context stores moved out of line (on top of the VALU trim)
# speedup vs baseline: 1.0121x; 1.0115x over previous
; __device__ __forceinline__ unsigned pk2(float lo, float hi) { const f32x2 v = {lo, hi}; const bf16x2_t b = __builtin_convertvector(v, bf16x2_t); return __builtin_bit_cast(unsigned, b); }
;     __device__ __forceinline__ void operator()(const f32x4 (&acc)[2][2][4][2], const pg8::Unit& u, int wr, int wc, int fr, int fq, PG8_LAS unsigned char* xl) const {
;     ...
;                         const f32x4 cur = acc[ai][bj][m][n]; f32x4 p1, p2;
;                         if (!sample) { const f32x4 prv = (m == 0) ? hb[bj] : acc[ai][bj][m == 0 ? 0 : m - 1][n];
; #pragma unroll
;                             for (int j = 0; j < 4; ++j) { const float s1 = fr == 15 ? prv[j] : cur[j], s2 = fr >= 14 ? prv[j] : cur[j]; p1[j] = dpp_ror<1>(s1); p2[j] = dpp_ror<2>(s2); }
;                         } else { const int t = fr & 3, b = (row - MP) >> 2;
; #pragma unroll
;                             for (int j = 0; j < 4; ++j) { p1[j] = dpp_ror<1>(cur[j]); p2[j] = dpp_ror<2>(cur[j]); }
;                             const f32x4 c1 = *(const f32x4*)(ctx_s + (size_t)(b * 2 + 1) * FF2 + bj * FF + jc0 + 4 * n), c0 = *(const f32x4*)(ctx_s + (size_t)(b * 2) * FF2 + bj * FF + jc0 + 4 * n);
; #pragma unroll
;                             for (int j = 0; j < 4; ++j) { p2[j] = t == 0 ? c0[j] : (t == 1 ? c1[j] : p2[j]); p1[j] = t == 0 ? c1[j] : p1[j]; }
;                         }
;                         cc[bj] = bb[bj] + w0[bj] * p2 + w1[bj] * p1 + w2[bj] * cur;
;                     }
;                     const f32x4 gv = gelu_mul4(cc[0], cc[1]);
;                     u32x2 w; w.x = pk2(gv[0], gv[1]); w.y = pk2(gv[2], gv[3]);
;                     *(u32x2*)(G + (size_t)row * FF + jc0 + 4 * n) = w;
;                     if (!sample && ai == 0 && wr == 0 && m == 0 && fr < 2 && (pm & 7) != 0) {
; #pragma unroll
;                         for (int bj = 0; bj < 2; ++bj) *(f32x4*)(PH + (size_t)(pm * 2 + fr) * FF2 + bj * FF + jc0 + 4 * n) = cc[bj];
;                     }
;                     if (sample && (fr & 3) >= 2) { const int b = (row - MP) >> 2, t = fr & 3;
; #pragma unroll
;                         for (int bj = 0; bj < 2; ++bj) *(f32x4*)(nf_s + (size_t)(b * 2 + t - 2) * FF2 + bj * FF + jc0 + 4 * n) = acc[ai][bj][m][n];
;                     }
.LBB0_567:
	s_or_b64 exec, exec, s[34:35]
	s_nor_b64 s[34:35], s[96:97], s[20:21]
	v_add_u32_e32 v224, v224, v215
	s_and_saveexec_b64 s[78:79], s[34:35]
	s_cbranch_execnz .Lnfs_0_0
.LBB0_569:
	s_or_b64 exec, exec, s[78:79]
	v_add_u32_e32 v160, 0xffffc010, v225
	v_ashrrev_i32_e32 v160, 1, v160
	v_and_b32_e32 v226, 0xffffffee, v160
	s_and_b64 vcc, exec, s[22:23]
	s_mov_b64 s[78:79], -1
	s_cbranch_vccz .Lsmp_0_0
.LBB0_571:
.LBB0_572:
	v_cndmask_b32_e64 v160, v148, v156, s[16:17]
	v_cndmask_b32_e64 v164, v148, v156, s[8:9]
	v_cndmask_b32_e64 v161, v149, v157, s[16:17]
	v_cndmask_b32_e64 v165, v149, v157, s[8:9]
	v_cndmask_b32_e64 v162, v150, v158, s[16:17]
	v_cndmask_b32_e64 v166, v150, v158, s[8:9]
	v_cndmask_b32_e64 v163, v151, v159, s[16:17]
	v_cndmask_b32_e64 v167, v151, v159, s[8:9]
	v_mov_b32_dpp v160, v160 row_ror:1 row_mask:0xf bank_mask:0xf
	v_mov_b32_dpp v164, v164 row_ror:2 row_mask:0xf bank_mask:0xf
	v_mov_b32_dpp v161, v161 row_ror:1 row_mask:0xf bank_mask:0xf
	v_mov_b32_dpp v165, v165 row_ror:2 row_mask:0xf bank_mask:0xf
	v_mov_b32_dpp v162, v162 row_ror:1 row_mask:0xf bank_mask:0xf
	v_mov_b32_dpp v166, v166 row_ror:2 row_mask:0xf bank_mask:0xf
	v_mov_b32_dpp v163, v163 row_ror:1 row_mask:0xf bank_mask:0xf
	v_mov_b32_dpp v167, v167 row_ror:2 row_mask:0xf bank_mask:0xf
.LBB0_573:
	s_and_b64 vcc, exec, s[22:23]
	s_mov_b64 s[78:79], -1
	s_cbranch_vccz .Lsmp_0_1
.LBB0_575:
.LBB0_576:
	v_cndmask_b32_e64 v156, v144, v152, s[16:17]
	v_cndmask_b32_e64 v168, v144, v152, s[8:9]
	v_cndmask_b32_e64 v157, v145, v153, s[16:17]
	v_cndmask_b32_e64 v169, v145, v153, s[8:9]
	v_cndmask_b32_e64 v158, v146, v154, s[16:17]
	v_cndmask_b32_e64 v170, v146, v154, s[8:9]
	v_cndmask_b32_e64 v159, v147, v155, s[16:17]
	v_cndmask_b32_e64 v171, v147, v155, s[8:9]
	v_mov_b32_dpp v156, v156 row_ror:1 row_mask:0xf bank_mask:0xf
	v_mov_b32_dpp v168, v168 row_ror:2 row_mask:0xf bank_mask:0xf
	v_mov_b32_dpp v157, v157 row_ror:1 row_mask:0xf bank_mask:0xf
	v_mov_b32_dpp v169, v169 row_ror:2 row_mask:0xf bank_mask:0xf
	v_mov_b32_dpp v158, v158 row_ror:1 row_mask:0xf bank_mask:0xf
	v_mov_b32_dpp v170, v170 row_ror:2 row_mask:0xf bank_mask:0xf
	v_mov_b32_dpp v159, v159 row_ror:1 row_mask:0xf bank_mask:0xf
	v_mov_b32_dpp v171, v171 row_ror:2 row_mask:0xf bank_mask:0xf
.LBB0_577:
	v_pk_fma_f32 v[152:153], v[114:115], v[166:167], v[118:119]
	v_pk_fma_f32 v[154:155], v[112:113], v[164:165], v[116:117]
	v_pk_fma_f32 v[152:153], v[110:111], v[162:163], v[152:153]
	v_pk_fma_f32 v[154:155], v[108:109], v[160:161], v[154:155]
	v_pk_fma_f32 v[152:153], v[150:151], v[98:99], v[152:153]
	v_pk_fma_f32 v[154:155], v[148:149], v[96:97], v[154:155]
	v_pk_fma_f32 v[160:161], v[106:107], v[170:171], v[122:123]
	v_pk_fma_f32 v[162:163], v[104:105], v[168:169], v[120:121]
	v_pk_fma_f32 v[158:159], v[102:103], v[158:159], v[160:161]
	v_pk_fma_f32 v[156:157], v[100:101], v[156:157], v[162:163]
	v_pk_mul_f32 v[160:161], v[152:153], v[152:153]
	v_pk_mul_f32 v[162:163], v[154:155], v[154:155]
	v_pk_fma_f32 v[160:161], v[160:161], s[84:85], v[246:247] op_sel_hi:[1,0,0]
	v_pk_fma_f32 v[162:163], v[162:163], s[84:85], v[246:247] op_sel_hi:[1,0,0]
	v_pk_mul_f32 v[160:161], v[152:153], v[160:161]
	v_pk_mul_f32 v[162:163], v[154:155], v[162:163]
	v_exp_f32_e32 v160, v160
	v_exp_f32_e32 v162, v162
	v_exp_f32_e32 v161, v161
	v_exp_f32_e32 v163, v163
	v_pk_fma_f32 v[158:159], v[146:147], v[94:95], v[158:159]
	v_pk_fma_f32 v[156:157], v[144:145], v[92:93], v[156:157]
	v_pk_add_f32 v[160:161], v[160:161], 1.0 op_sel_hi:[1,0]
	v_pk_add_f32 v[162:163], v[162:163], 1.0 op_sel_hi:[1,0]
	v_rcp_f32_e32 v160, v160
	v_rcp_f32_e32 v162, v162
	v_rcp_f32_e32 v161, v161
	v_rcp_f32_e32 v163, v163
	v_pk_mul_f32 v[152:153], v[152:153], v[158:159]
	v_pk_mul_f32 v[154:155], v[154:155], v[156:157]
	v_pk_mul_f32 v[152:153], v[152:153], v[160:161]
	v_pk_mul_f32 v[154:155], v[154:155], v[162:163]
	v_cvt_pk_bf16_f32 v154, v154, v155
	v_cvt_pk_bf16_f32 v155, v152, v153
	s_mul_i32 s100, s37, 16
	v_lshl_add_u64 v[168:169], v[178:179], 0, s[100:101]
	v_add_u32_e32 v170, v226, v215
	ds_bpermute_b32 v236, v244, v168
	ds_bpermute_b32 v237, v244, v169
	ds_bpermute_b32 v238, v244, v154
	ds_bpermute_b32 v239, v244, v155
	s_waitcnt lgkmcnt(0)
	global_store_dwordx2 v[236:237], v[238:239], off
	s_and_saveexec_b64 s[78:79], s[34:35]
	s_cbranch_execnz .Lnfs_0_1
.LBB0_579:
	s_or_b64 exec, exec, s[78:79]
	v_add_u32_e32 v152, 0xffffc020, v225
	v_ashrrev_i32_e32 v152, 1, v152
	v_and_b32_e32 v171, -10, v152
	s_and_b64 vcc, exec, s[22:23]
	s_mov_b64 s[78:79], -1
	s_cbranch_vccz .Lsmp_0_2
.LBB0_581:
.LBB0_582:
	v_cndmask_b32_e64 v152, v140, v148, s[16:17]
	v_cndmask_b32_e64 v156, v140, v148, s[8:9]
	v_cndmask_b32_e64 v153, v141, v149, s[16:17]
	v_cndmask_b32_e64 v157, v141, v149, s[8:9]
	v_cndmask_b32_e64 v154, v142, v150, s[16:17]
	v_cndmask_b32_e64 v158, v142, v150, s[8:9]
	v_cndmask_b32_e64 v155, v143, v151, s[16:17]
	v_cndmask_b32_e64 v159, v143, v151, s[8:9]
	v_mov_b32_dpp v152, v152 row_ror:1 row_mask:0xf bank_mask:0xf
	v_mov_b32_dpp v156, v156 row_ror:2 row_mask:0xf bank_mask:0xf
	v_mov_b32_dpp v153, v153 row_ror:1 row_mask:0xf bank_mask:0xf
	v_mov_b32_dpp v157, v157 row_ror:2 row_mask:0xf bank_mask:0xf
	v_mov_b32_dpp v154, v154 row_ror:1 row_mask:0xf bank_mask:0xf
	v_mov_b32_dpp v158, v158 row_ror:2 row_mask:0xf bank_mask:0xf
	v_mov_b32_dpp v155, v155 row_ror:1 row_mask:0xf bank_mask:0xf
	v_mov_b32_dpp v159, v159 row_ror:2 row_mask:0xf bank_mask:0xf

; __device__ __forceinline__ unsigned pk2(float lo, float hi) { const f32x2 v = {lo, hi}; const bf16x2_t b = __builtin_convertvector(v, bf16x2_t); return __builtin_bit_cast(unsigned, b); }
;     __device__ __forceinline__ void operator()(const f32x4 (&acc)[2][2][4][2], const pg8::Unit& u, int wr, int wc, int fr, int fq, PG8_LAS unsigned char* xl) const {
;     ...
;                         const f32x4 cur = acc[ai][bj][m][n]; f32x4 p1, p2;
;                         if (!sample) { const f32x4 prv = (m == 0) ? hb[bj] : acc[ai][bj][m == 0 ? 0 : m - 1][n];
; #pragma unroll
;                             for (int j = 0; j < 4; ++j) { const float s1 = fr == 15 ? prv[j] : cur[j], s2 = fr >= 14 ? prv[j] : cur[j]; p1[j] = dpp_ror<1>(s1); p2[j] = dpp_ror<2>(s2); }
;                         } else { const int t = fr & 3, b = (row - MP) >> 2;
; #pragma unroll
;                             for (int j = 0; j < 4; ++j) { p1[j] = dpp_ror<1>(cur[j]); p2[j] = dpp_ror<2>(cur[j]); }
;                             const f32x4 c1 = *(const f32x4*)(ctx_s + (size_t)(b * 2 + 1) * FF2 + bj * FF + jc0 + 4 * n), c0 = *(const f32x4*)(ctx_s + (size_t)(b * 2) * FF2 + bj * FF + jc0 + 4 * n);
; #pragma unroll
;                             for (int j = 0; j < 4; ++j) { p2[j] = t == 0 ? c0[j] : (t == 1 ? c1[j] : p2[j]); p1[j] = t == 0 ? c1[j] : p1[j]; }
;                         }
;                         cc[bj] = bb[bj] + w0[bj] * p2 + w1[bj] * p1 + w2[bj] * cur;
;                     }
;                     const f32x4 gv = gelu_mul4(cc[0], cc[1]);
;                     u32x2 w; w.x = pk2(gv[0], gv[1]); w.y = pk2(gv[2], gv[3]);
;                     *(u32x2*)(G + (size_t)row * FF + jc0 + 4 * n) = w;
;                     if (!sample && ai == 0 && wr == 0 && m == 0 && fr < 2 && (pm & 7) != 0) {
; #pragma unroll
;                         for (int bj = 0; bj < 2; ++bj) *(f32x4*)(PH + (size_t)(pm * 2 + fr) * FF2 + bj * FF + jc0 + 4 * n) = cc[bj];
;                     }
;                     if (sample && (fr & 3) >= 2) { const int b = (row - MP) >> 2, t = fr & 3;
; #pragma unroll
;                         for (int bj = 0; bj < 2; ++bj) *(f32x4*)(nf_s + (size_t)(b * 2 + t - 2) * FF2 + bj * FF + jc0 + 4 * n) = acc[ai][bj][m][n];
;                     }
.LBB0_585:
.LBB0_586:
	v_cndmask_b32_e64 v148, v136, v144, s[16:17]
	v_cndmask_b32_e64 v160, v136, v144, s[8:9]
	v_cndmask_b32_e64 v149, v137, v145, s[16:17]
	v_cndmask_b32_e64 v161, v137, v145, s[8:9]
	v_cndmask_b32_e64 v150, v138, v146, s[16:17]
	v_cndmask_b32_e64 v162, v138, v146, s[8:9]
	v_cndmask_b32_e64 v151, v139, v147, s[16:17]
	v_cndmask_b32_e64 v163, v139, v147, s[8:9]
	v_mov_b32_dpp v148, v148 row_ror:1 row_mask:0xf bank_mask:0xf
	v_mov_b32_dpp v160, v160 row_ror:2 row_mask:0xf bank_mask:0xf
	v_mov_b32_dpp v149, v149 row_ror:1 row_mask:0xf bank_mask:0xf
	v_mov_b32_dpp v161, v161 row_ror:2 row_mask:0xf bank_mask:0xf
	v_mov_b32_dpp v150, v150 row_ror:1 row_mask:0xf bank_mask:0xf
	v_mov_b32_dpp v162, v162 row_ror:2 row_mask:0xf bank_mask:0xf
	v_mov_b32_dpp v151, v151 row_ror:1 row_mask:0xf bank_mask:0xf
	v_mov_b32_dpp v163, v163 row_ror:2 row_mask:0xf bank_mask:0xf
.LBB0_587:
	v_pk_fma_f32 v[144:145], v[114:115], v[158:159], v[118:119]
	v_pk_fma_f32 v[146:147], v[112:113], v[156:157], v[116:117]
	v_pk_fma_f32 v[144:145], v[110:111], v[154:155], v[144:145]
	v_pk_fma_f32 v[146:147], v[108:109], v[152:153], v[146:147]
	v_pk_fma_f32 v[144:145], v[142:143], v[98:99], v[144:145]
	v_pk_fma_f32 v[146:147], v[140:141], v[96:97], v[146:147]
	v_pk_fma_f32 v[152:153], v[106:107], v[162:163], v[122:123]
	v_pk_fma_f32 v[154:155], v[104:105], v[160:161], v[120:121]
	v_pk_fma_f32 v[150:151], v[102:103], v[150:151], v[152:153]
	v_pk_fma_f32 v[148:149], v[100:101], v[148:149], v[154:155]
	v_pk_mul_f32 v[152:153], v[144:145], v[144:145]
	v_pk_mul_f32 v[154:155], v[146:147], v[146:147]
	v_pk_fma_f32 v[152:153], v[152:153], s[84:85], v[246:247] op_sel_hi:[1,0,0]
	v_pk_fma_f32 v[154:155], v[154:155], s[84:85], v[246:247] op_sel_hi:[1,0,0]
	v_pk_mul_f32 v[152:153], v[144:145], v[152:153]
	v_pk_mul_f32 v[154:155], v[146:147], v[154:155]
	v_exp_f32_e32 v152, v152
	v_exp_f32_e32 v154, v154
	v_exp_f32_e32 v153, v153
	v_exp_f32_e32 v155, v155
	v_pk_fma_f32 v[150:151], v[138:139], v[94:95], v[150:151]
	v_pk_fma_f32 v[148:149], v[136:137], v[92:93], v[148:149]
	v_pk_add_f32 v[152:153], v[152:153], 1.0 op_sel_hi:[1,0]
	v_pk_add_f32 v[154:155], v[154:155], 1.0 op_sel_hi:[1,0]
	v_rcp_f32_e32 v152, v152
	v_rcp_f32_e32 v154, v154
	v_rcp_f32_e32 v153, v153
	v_rcp_f32_e32 v155, v155
	v_pk_mul_f32 v[144:145], v[144:145], v[150:151]
	v_pk_mul_f32 v[146:147], v[146:147], v[148:149]
	v_pk_mul_f32 v[144:145], v[144:145], v[152:153]
	v_pk_mul_f32 v[146:147], v[146:147], v[154:155]
	v_cvt_pk_bf16_f32 v146, v146, v147
	v_cvt_pk_bf16_f32 v147, v144, v145
	s_mul_i32 s100, s37, 32
	v_lshl_add_u64 v[160:161], v[178:179], 0, s[100:101]
	v_add_u32_e32 v162, v171, v215
	ds_bpermute_b32 v236, v244, v160
	ds_bpermute_b32 v237, v244, v161
	ds_bpermute_b32 v238, v244, v146
	ds_bpermute_b32 v239, v244, v147
	s_waitcnt lgkmcnt(0)
	global_store_dwordx2 v[236:237], v[238:239], off
	s_and_saveexec_b64 s[78:79], s[34:35]
	s_cbranch_execnz .Lnfs_0_2
.LBB0_589:
	s_or_b64 exec, exec, s[78:79]
	v_add_u32_e32 v144, 0xffffc030, v225
	v_ashrrev_i32_e32 v144, 1, v144
	v_and_b32_e32 v163, -2, v144
	s_and_b64 vcc, exec, s[22:23]
	s_mov_b64 s[78:79], -1
	s_cbranch_vccz .Lsmp_0_4
.LBB0_591:
.LBB0_592:
	v_cndmask_b32_e64 v144, v132, v140, s[16:17]
	v_cndmask_b32_e64 v148, v132, v140, s[8:9]
	v_cndmask_b32_e64 v145, v133, v141, s[16:17]
	v_cndmask_b32_e64 v149, v133, v141, s[8:9]
	v_cndmask_b32_e64 v146, v134, v142, s[16:17]
	v_cndmask_b32_e64 v150, v134, v142, s[8:9]
	v_cndmask_b32_e64 v147, v135, v143, s[16:17]
	v_cndmask_b32_e64 v151, v135, v143, s[8:9]
	v_mov_b32_dpp v144, v144 row_ror:1 row_mask:0xf bank_mask:0xf
	v_mov_b32_dpp v148, v148 row_ror:2 row_mask:0xf bank_mask:0xf
	v_mov_b32_dpp v145, v145 row_ror:1 row_mask:0xf bank_mask:0xf
	v_mov_b32_dpp v149, v149 row_ror:2 row_mask:0xf bank_mask:0xf
	v_mov_b32_dpp v146, v146 row_ror:1 row_mask:0xf bank_mask:0xf
	v_mov_b32_dpp v150, v150 row_ror:2 row_mask:0xf bank_mask:0xf
	v_mov_b32_dpp v147, v147 row_ror:1 row_mask:0xf bank_mask:0xf
	v_mov_b32_dpp v151, v151 row_ror:2 row_mask:0xf bank_mask:0xf

; __device__ __forceinline__ unsigned pk2(float lo, float hi) { const f32x2 v = {lo, hi}; const bf16x2_t b = __builtin_convertvector(v, bf16x2_t); return __builtin_bit_cast(unsigned, b); }
;     __device__ __forceinline__ void operator()(const f32x4 (&acc)[2][2][4][2], const pg8::Unit& u, int wr, int wc, int fr, int fq, PG8_LAS unsigned char* xl) const {
;     ...
;                         const f32x4 cur = acc[ai][bj][m][n]; f32x4 p1, p2;
;                         if (!sample) { const f32x4 prv = (m == 0) ? hb[bj] : acc[ai][bj][m == 0 ? 0 : m - 1][n];
; #pragma unroll
;                             for (int j = 0; j < 4; ++j) { const float s1 = fr == 15 ? prv[j] : cur[j], s2 = fr >= 14 ? prv[j] : cur[j]; p1[j] = dpp_ror<1>(s1); p2[j] = dpp_ror<2>(s2); }
;                         } else { const int t = fr & 3, b = (row - MP) >> 2;
; #pragma unroll
;                             for (int j = 0; j < 4; ++j) { p1[j] = dpp_ror<1>(cur[j]); p2[j] = dpp_ror<2>(cur[j]); }
;                             const f32x4 c1 = *(const f32x4*)(ctx_s + (size_t)(b * 2 + 1) * FF2 + bj * FF + jc0 + 4 * n), c0 = *(const f32x4*)(ctx_s + (size_t)(b * 2) * FF2 + bj * FF + jc0 + 4 * n);
; #pragma unroll
;                             for (int j = 0; j < 4; ++j) { p2[j] = t == 0 ? c0[j] : (t == 1 ? c1[j] : p2[j]); p1[j] = t == 0 ? c1[j] : p1[j]; }
;                         }
;                         cc[bj] = bb[bj] + w0[bj] * p2 + w1[bj] * p1 + w2[bj] * cur;
;                     }
;                     const f32x4 gv = gelu_mul4(cc[0], cc[1]);
;                     u32x2 w; w.x = pk2(gv[0], gv[1]); w.y = pk2(gv[2], gv[3]);
;                     *(u32x2*)(G + (size_t)row * FF + jc0 + 4 * n) = w;
;                     if (!sample && ai == 0 && wr == 0 && m == 0 && fr < 2 && (pm & 7) != 0) {
; #pragma unroll
;                         for (int bj = 0; bj < 2; ++bj) *(f32x4*)(PH + (size_t)(pm * 2 + fr) * FF2 + bj * FF + jc0 + 4 * n) = cc[bj];
;                     }
;                     if (sample && (fr & 3) >= 2) { const int b = (row - MP) >> 2, t = fr & 3;
; #pragma unroll
;                         for (int bj = 0; bj < 2; ++bj) *(f32x4*)(nf_s + (size_t)(b * 2 + t - 2) * FF2 + bj * FF + jc0 + 4 * n) = acc[ai][bj][m][n];
;                     }
.LBB0_595:
.LBB0_596:
	v_cndmask_b32_e64 v140, v128, v136, s[16:17]
	v_cndmask_b32_e64 v152, v128, v136, s[8:9]
	v_cndmask_b32_e64 v141, v129, v137, s[16:17]
	v_cndmask_b32_e64 v153, v129, v137, s[8:9]
	v_cndmask_b32_e64 v142, v130, v138, s[16:17]
	v_cndmask_b32_e64 v154, v130, v138, s[8:9]
	v_cndmask_b32_e64 v143, v131, v139, s[16:17]
	v_cndmask_b32_e64 v155, v131, v139, s[8:9]
	v_mov_b32_dpp v140, v140 row_ror:1 row_mask:0xf bank_mask:0xf
	v_mov_b32_dpp v152, v152 row_ror:2 row_mask:0xf bank_mask:0xf
	v_mov_b32_dpp v141, v141 row_ror:1 row_mask:0xf bank_mask:0xf
	v_mov_b32_dpp v153, v153 row_ror:2 row_mask:0xf bank_mask:0xf
	v_mov_b32_dpp v142, v142 row_ror:1 row_mask:0xf bank_mask:0xf
	v_mov_b32_dpp v154, v154 row_ror:2 row_mask:0xf bank_mask:0xf
	v_mov_b32_dpp v143, v143 row_ror:1 row_mask:0xf bank_mask:0xf
	v_mov_b32_dpp v155, v155 row_ror:2 row_mask:0xf bank_mask:0xf
.LBB0_597:
	v_pk_fma_f32 v[136:137], v[114:115], v[150:151], v[118:119]
	v_pk_fma_f32 v[138:139], v[112:113], v[148:149], v[116:117]
	v_pk_fma_f32 v[136:137], v[110:111], v[146:147], v[136:137]
	v_pk_fma_f32 v[138:139], v[108:109], v[144:145], v[138:139]
	v_pk_fma_f32 v[136:137], v[134:135], v[98:99], v[136:137]
	v_pk_fma_f32 v[138:139], v[132:133], v[96:97], v[138:139]
	v_pk_fma_f32 v[144:145], v[106:107], v[154:155], v[122:123]
	v_pk_fma_f32 v[146:147], v[104:105], v[152:153], v[120:121]
	v_pk_fma_f32 v[142:143], v[102:103], v[142:143], v[144:145]
	v_pk_fma_f32 v[140:141], v[100:101], v[140:141], v[146:147]
	v_pk_mul_f32 v[144:145], v[136:137], v[136:137]
	v_pk_mul_f32 v[146:147], v[138:139], v[138:139]
	v_pk_fma_f32 v[144:145], v[144:145], s[84:85], v[246:247] op_sel_hi:[1,0,0]
	v_pk_fma_f32 v[146:147], v[146:147], s[84:85], v[246:247] op_sel_hi:[1,0,0]
	v_pk_mul_f32 v[144:145], v[136:137], v[144:145]
	v_pk_mul_f32 v[146:147], v[138:139], v[146:147]
	v_exp_f32_e32 v144, v144
	v_exp_f32_e32 v146, v146
	v_exp_f32_e32 v145, v145
	v_exp_f32_e32 v147, v147
	v_pk_fma_f32 v[142:143], v[130:131], v[94:95], v[142:143]
	v_pk_fma_f32 v[140:141], v[128:129], v[92:93], v[140:141]
	v_pk_add_f32 v[144:145], v[144:145], 1.0 op_sel_hi:[1,0]
	v_pk_add_f32 v[146:147], v[146:147], 1.0 op_sel_hi:[1,0]
	v_rcp_f32_e32 v144, v144
	v_rcp_f32_e32 v146, v146
	v_rcp_f32_e32 v145, v145
	v_rcp_f32_e32 v147, v147
	v_pk_mul_f32 v[136:137], v[136:137], v[142:143]
	v_pk_mul_f32 v[138:139], v[138:139], v[140:141]
	v_pk_mul_f32 v[136:137], v[136:137], v[144:145]
	v_pk_mul_f32 v[138:139], v[138:139], v[146:147]
	v_cvt_pk_bf16_f32 v138, v138, v139
	v_cvt_pk_bf16_f32 v139, v136, v137
	s_mul_i32 s100, s37, 48
	v_lshl_add_u64 v[152:153], v[178:179], 0, s[100:101]
	v_add_u32_e32 v154, v163, v215
	ds_bpermute_b32 v236, v244, v152
	ds_bpermute_b32 v237, v244, v153
	ds_bpermute_b32 v238, v244, v138
	ds_bpermute_b32 v239, v244, v139
	s_waitcnt lgkmcnt(0)
	global_store_dwordx2 v[236:237], v[238:239], off
	s_and_saveexec_b64 s[78:79], s[34:35]
	s_cbranch_execnz .Lnfs_0_3

; template <int N> __device__ __forceinline__ float dpp_ror(float v) { const int i = __builtin_bit_cast(int, v); return __builtin_bit_cast(float, __builtin_amdgcn_update_dpp(i, i, 0x120 + N, 0xF, 0xF, false)); }
;     __device__ __forceinline__ void operator()(const f32x4 (&acc)[2][2][4][2], const pg8::Unit& u, int wr, int wc, int fr, int fq, PG8_LAS unsigned char* xl) const {
;     ...
;                         const f32x4 cur = acc[ai][bj][m][n]; f32x4 p1, p2;
;                         if (!sample) { const f32x4 prv = (m == 0) ? hb[bj] : acc[ai][bj][m == 0 ? 0 : m - 1][n];
; #pragma unroll
;                             for (int j = 0; j < 4; ++j) { const float s1 = fr == 15 ? prv[j] : cur[j], s2 = fr >= 14 ? prv[j] : cur[j]; p1[j] = dpp_ror<1>(s1); p2[j] = dpp_ror<2>(s2); }
;                         } else { const int t = fr & 3, b = (row - MP) >> 2;
; #pragma unroll
;                             for (int j = 0; j < 4; ++j) { p1[j] = dpp_ror<1>(cur[j]); p2[j] = dpp_ror<2>(cur[j]); }
;                             const f32x4 c1 = *(const f32x4*)(ctx_s + (size_t)(b * 2 + 1) * FF2 + bj * FF + jc0 + 4 * n), c0 = *(const f32x4*)(ctx_s + (size_t)(b * 2) * FF2 + bj * FF + jc0 + 4 * n);
; #pragma unroll
;                             for (int j = 0; j < 4; ++j) { p2[j] = t == 0 ? c0[j] : (t == 1 ? c1[j] : p2[j]); p1[j] = t == 0 ? c1[j] : p1[j]; }
;                         }
.LBB0_601:
	s_or_b64 exec, exec, vcc
	v_add_u32_e32 v132, 0xffffc080, v225
	v_ashrrev_i32_e32 v132, 1, v132
	v_and_b32_e32 v155, 0xffffffe6, v132
	s_and_b64 vcc, exec, s[22:23]
	s_mov_b64 s[78:79], -1
	s_cbranch_vccz .Lsmp_0_6
.LBB0_603:
.LBB0_604:
	s_waitcnt lgkmcnt(1)
	v_cndmask_b32_e64 v132, v124, v140, s[16:17]
	v_cndmask_b32_e64 v136, v124, v140, s[8:9]
	v_cndmask_b32_e64 v133, v125, v141, s[16:17]
	v_cndmask_b32_e64 v137, v125, v141, s[8:9]
	v_cndmask_b32_e64 v134, v126, v142, s[16:17]
	v_cndmask_b32_e64 v138, v126, v142, s[8:9]
	v_cndmask_b32_e64 v135, v127, v143, s[16:17]
	v_cndmask_b32_e64 v139, v127, v143, s[8:9]
	v_mov_b32_dpp v132, v132 row_ror:1 row_mask:0xf bank_mask:0xf
	v_mov_b32_dpp v136, v136 row_ror:2 row_mask:0xf bank_mask:0xf
	v_mov_b32_dpp v133, v133 row_ror:1 row_mask:0xf bank_mask:0xf
	v_mov_b32_dpp v137, v137 row_ror:2 row_mask:0xf bank_mask:0xf
	v_mov_b32_dpp v134, v134 row_ror:1 row_mask:0xf bank_mask:0xf
	v_mov_b32_dpp v138, v138 row_ror:2 row_mask:0xf bank_mask:0xf
	v_mov_b32_dpp v135, v135 row_ror:1 row_mask:0xf bank_mask:0xf
	v_mov_b32_dpp v139, v139 row_ror:2 row_mask:0xf bank_mask:0xf

; __device__ __forceinline__ unsigned pk2(float lo, float hi) { const f32x2 v = {lo, hi}; const bf16x2_t b = __builtin_convertvector(v, bf16x2_t); return __builtin_bit_cast(unsigned, b); }
;     __device__ __forceinline__ void operator()(const f32x4 (&acc)[2][2][4][2], const pg8::Unit& u, int wr, int wc, int fr, int fq, PG8_LAS unsigned char* xl) const {
;     ...
;                         const f32x4 cur = acc[ai][bj][m][n]; f32x4 p1, p2;
;                         if (!sample) { const f32x4 prv = (m == 0) ? hb[bj] : acc[ai][bj][m == 0 ? 0 : m - 1][n];
; #pragma unroll
;                             for (int j = 0; j < 4; ++j) { const float s1 = fr == 15 ? prv[j] : cur[j], s2 = fr >= 14 ? prv[j] : cur[j]; p1[j] = dpp_ror<1>(s1); p2[j] = dpp_ror<2>(s2); }
;                         } else { const int t = fr & 3, b = (row - MP) >> 2;
; #pragma unroll
;                             for (int j = 0; j < 4; ++j) { p1[j] = dpp_ror<1>(cur[j]); p2[j] = dpp_ror<2>(cur[j]); }
;                             const f32x4 c1 = *(const f32x4*)(ctx_s + (size_t)(b * 2 + 1) * FF2 + bj * FF + jc0 + 4 * n), c0 = *(const f32x4*)(ctx_s + (size_t)(b * 2) * FF2 + bj * FF + jc0 + 4 * n);
; #pragma unroll
;                             for (int j = 0; j < 4; ++j) { p2[j] = t == 0 ? c0[j] : (t == 1 ? c1[j] : p2[j]); p1[j] = t == 0 ? c1[j] : p1[j]; }
;                         }
;                         cc[bj] = bb[bj] + w0[bj] * p2 + w1[bj] * p1 + w2[bj] * cur;
;                     }
;                     const f32x4 gv = gelu_mul4(cc[0], cc[1]);
;                     u32x2 w; w.x = pk2(gv[0], gv[1]); w.y = pk2(gv[2], gv[3]);
;                     *(u32x2*)(G + (size_t)row * FF + jc0 + 4 * n) = w;
;                     if (!sample && ai == 0 && wr == 0 && m == 0 && fr < 2 && (pm & 7) != 0) {
; #pragma unroll
;                         for (int bj = 0; bj < 2; ++bj) *(f32x4*)(PH + (size_t)(pm * 2 + fr) * FF2 + bj * FF + jc0 + 4 * n) = cc[bj];
;                     }
;                     if (sample && (fr & 3) >= 2) { const int b = (row - MP) >> 2, t = fr & 3;
; #pragma unroll
;                         for (int bj = 0; bj < 2; ++bj) *(f32x4*)(nf_s + (size_t)(b * 2 + t - 2) * FF2 + bj * FF + jc0 + 4 * n) = acc[ai][bj][m][n];
;                     }
.LBB0_607:
.LBB0_608:
	s_waitcnt lgkmcnt(0)
	v_cndmask_b32_e64 v140, v88, v128, s[16:17]
	v_cndmask_b32_e64 v144, v88, v128, s[8:9]
	v_cndmask_b32_e64 v141, v89, v129, s[16:17]
	v_cndmask_b32_e64 v145, v89, v129, s[8:9]
	v_cndmask_b32_e64 v142, v90, v130, s[16:17]
	v_cndmask_b32_e64 v146, v90, v130, s[8:9]
	v_cndmask_b32_e64 v143, v91, v131, s[16:17]
	v_cndmask_b32_e64 v147, v91, v131, s[8:9]
	v_mov_b32_dpp v140, v140 row_ror:1 row_mask:0xf bank_mask:0xf
	v_mov_b32_dpp v144, v144 row_ror:2 row_mask:0xf bank_mask:0xf
	v_mov_b32_dpp v141, v141 row_ror:1 row_mask:0xf bank_mask:0xf
	v_mov_b32_dpp v145, v145 row_ror:2 row_mask:0xf bank_mask:0xf
	v_mov_b32_dpp v142, v142 row_ror:1 row_mask:0xf bank_mask:0xf
	v_mov_b32_dpp v146, v146 row_ror:2 row_mask:0xf bank_mask:0xf
	v_mov_b32_dpp v143, v143 row_ror:1 row_mask:0xf bank_mask:0xf
	v_mov_b32_dpp v147, v147 row_ror:2 row_mask:0xf bank_mask:0xf
.LBB0_609:
	s_waitcnt lgkmcnt(0)
	v_pk_fma_f32 v[128:129], v[114:115], v[138:139], v[118:119]
	v_pk_fma_f32 v[130:131], v[112:113], v[136:137], v[116:117]
	v_pk_fma_f32 v[128:129], v[110:111], v[134:135], v[128:129]
	v_pk_fma_f32 v[130:131], v[108:109], v[132:133], v[130:131]
	v_pk_fma_f32 v[128:129], v[126:127], v[98:99], v[128:129]
	v_pk_fma_f32 v[130:131], v[124:125], v[96:97], v[130:131]
	v_pk_fma_f32 v[134:135], v[104:105], v[144:145], v[120:121]
	v_pk_mul_f32 v[136:137], v[128:129], v[128:129]
	v_pk_fma_f32 v[134:135], v[100:101], v[140:141], v[134:135]
	v_pk_mul_f32 v[138:139], v[130:131], v[130:131]
	v_pk_fma_f32 v[136:137], v[136:137], s[84:85], v[246:247] op_sel_hi:[1,0,0]
	v_pk_fma_f32 v[138:139], v[138:139], s[84:85], v[246:247] op_sel_hi:[1,0,0]
	v_pk_mul_f32 v[136:137], v[128:129], v[136:137]
	v_pk_mul_f32 v[138:139], v[130:131], v[138:139]
	v_exp_f32_e32 v136, v136
	v_exp_f32_e32 v138, v138
	v_exp_f32_e32 v137, v137
	v_exp_f32_e32 v139, v139
	v_pk_fma_f32 v[132:133], v[106:107], v[146:147], v[122:123]
	v_pk_fma_f32 v[134:135], v[88:89], v[92:93], v[134:135]
	v_pk_add_f32 v[136:137], v[136:137], 1.0 op_sel_hi:[1,0]
	v_pk_add_f32 v[138:139], v[138:139], 1.0 op_sel_hi:[1,0]
	v_rcp_f32_e32 v136, v136
	v_rcp_f32_e32 v138, v138
	v_rcp_f32_e32 v137, v137
	v_rcp_f32_e32 v139, v139
	v_pk_fma_f32 v[132:133], v[102:103], v[142:143], v[132:133]
	v_pk_mul_f32 v[130:131], v[130:131], v[134:135]
	v_pk_fma_f32 v[132:133], v[90:91], v[94:95], v[132:133]
	v_pk_mul_f32 v[130:131], v[130:131], v[138:139]
	v_pk_mul_f32 v[128:129], v[128:129], v[132:133]
	v_pk_mul_f32 v[128:129], v[128:129], v[136:137]
	v_cvt_pk_bf16_f32 v130, v130, v131
	v_cvt_pk_bf16_f32 v131, v128, v129
	s_mul_i32 s100, s37, 0x80
	v_lshl_add_u64 v[144:145], v[178:179], 0, s[100:101]
	v_add_u32_e32 v146, v155, v215
	ds_bpermute_b32 v236, v244, v144
	ds_bpermute_b32 v237, v244, v145
	ds_bpermute_b32 v238, v244, v130
	ds_bpermute_b32 v239, v244, v131
	s_waitcnt lgkmcnt(0)
	global_store_dwordx2 v[236:237], v[238:239], off
	s_and_saveexec_b64 s[78:79], s[34:35]
	s_cbranch_execnz .Lnfs_0_4
.LBB0_611:
	s_or_b64 exec, exec, s[78:79]
	v_add_u32_e32 v128, 0xffffc090, v225
	v_ashrrev_i32_e32 v128, 1, v128
	v_and_b32_e32 v147, 0xffffffee, v128
	s_and_b64 vcc, exec, s[22:23]
	s_mov_b64 s[78:79], -1
	s_cbranch_vccz .Lsmp_0_8
.LBB0_613:
.LBB0_614:
	v_cndmask_b32_e64 v128, v84, v124, s[16:17]
	v_cndmask_b32_e64 v132, v84, v124, s[8:9]
	v_cndmask_b32_e64 v129, v85, v125, s[16:17]
	v_cndmask_b32_e64 v133, v85, v125, s[8:9]
	v_cndmask_b32_e64 v130, v86, v126, s[16:17]
	v_cndmask_b32_e64 v134, v86, v126, s[8:9]
	v_cndmask_b32_e64 v131, v87, v127, s[16:17]
	v_cndmask_b32_e64 v135, v87, v127, s[8:9]
	v_mov_b32_dpp v128, v128 row_ror:1 row_mask:0xf bank_mask:0xf
	v_mov_b32_dpp v132, v132 row_ror:2 row_mask:0xf bank_mask:0xf
	v_mov_b32_dpp v129, v129 row_ror:1 row_mask:0xf bank_mask:0xf
	v_mov_b32_dpp v133, v133 row_ror:2 row_mask:0xf bank_mask:0xf
	v_mov_b32_dpp v130, v130 row_ror:1 row_mask:0xf bank_mask:0xf
	v_mov_b32_dpp v134, v134 row_ror:2 row_mask:0xf bank_mask:0xf
	v_mov_b32_dpp v131, v131 row_ror:1 row_mask:0xf bank_mask:0xf
	v_mov_b32_dpp v135, v135 row_ror:2 row_mask:0xf bank_mask:0xf

; __device__ __forceinline__ unsigned pk2(float lo, float hi) { const f32x2 v = {lo, hi}; const bf16x2_t b = __builtin_convertvector(v, bf16x2_t); return __builtin_bit_cast(unsigned, b); }
;     __device__ __forceinline__ void operator()(const f32x4 (&acc)[2][2][4][2], const pg8::Unit& u, int wr, int wc, int fr, int fq, PG8_LAS unsigned char* xl) const {
;     ...
;                         const f32x4 cur = acc[ai][bj][m][n]; f32x4 p1, p2;
;                         if (!sample) { const f32x4 prv = (m == 0) ? hb[bj] : acc[ai][bj][m == 0 ? 0 : m - 1][n];
; #pragma unroll
;                             for (int j = 0; j < 4; ++j) { const float s1 = fr == 15 ? prv[j] : cur[j], s2 = fr >= 14 ? prv[j] : cur[j]; p1[j] = dpp_ror<1>(s1); p2[j] = dpp_ror<2>(s2); }
;                         } else { const int t = fr & 3, b = (row - MP) >> 2;
; #pragma unroll
;                             for (int j = 0; j < 4; ++j) { p1[j] = dpp_ror<1>(cur[j]); p2[j] = dpp_ror<2>(cur[j]); }
;                             const f32x4 c1 = *(const f32x4*)(ctx_s + (size_t)(b * 2 + 1) * FF2 + bj * FF + jc0 + 4 * n), c0 = *(const f32x4*)(ctx_s + (size_t)(b * 2) * FF2 + bj * FF + jc0 + 4 * n);
; #pragma unroll
;                             for (int j = 0; j < 4; ++j) { p2[j] = t == 0 ? c0[j] : (t == 1 ? c1[j] : p2[j]); p1[j] = t == 0 ? c1[j] : p1[j]; }
;                         }
;                         cc[bj] = bb[bj] + w0[bj] * p2 + w1[bj] * p1 + w2[bj] * cur;
;                     }
;                     const f32x4 gv = gelu_mul4(cc[0], cc[1]);
;                     u32x2 w; w.x = pk2(gv[0], gv[1]); w.y = pk2(gv[2], gv[3]);
;                     *(u32x2*)(G + (size_t)row * FF + jc0 + 4 * n) = w;
;                     if (!sample && ai == 0 && wr == 0 && m == 0 && fr < 2 && (pm & 7) != 0) {
; #pragma unroll
;                         for (int bj = 0; bj < 2; ++bj) *(f32x4*)(PH + (size_t)(pm * 2 + fr) * FF2 + bj * FF + jc0 + 4 * n) = cc[bj];
;                     }
;                     if (sample && (fr & 3) >= 2) { const int b = (row - MP) >> 2, t = fr & 3;
; #pragma unroll
;                         for (int bj = 0; bj < 2; ++bj) *(f32x4*)(nf_s + (size_t)(b * 2 + t - 2) * FF2 + bj * FF + jc0 + 4 * n) = acc[ai][bj][m][n];
;                     }
.LBB0_617:
.LBB0_618:
	v_cndmask_b32_e64 v124, v80, v88, s[16:17]
	v_cndmask_b32_e64 v136, v80, v88, s[8:9]
	v_cndmask_b32_e64 v125, v81, v89, s[16:17]
	v_cndmask_b32_e64 v137, v81, v89, s[8:9]
	v_cndmask_b32_e64 v126, v82, v90, s[16:17]
	v_cndmask_b32_e64 v138, v82, v90, s[8:9]
	v_cndmask_b32_e64 v127, v83, v91, s[16:17]
	v_cndmask_b32_e64 v139, v83, v91, s[8:9]
	v_mov_b32_dpp v124, v124 row_ror:1 row_mask:0xf bank_mask:0xf
	v_mov_b32_dpp v136, v136 row_ror:2 row_mask:0xf bank_mask:0xf
	v_mov_b32_dpp v125, v125 row_ror:1 row_mask:0xf bank_mask:0xf
	v_mov_b32_dpp v137, v137 row_ror:2 row_mask:0xf bank_mask:0xf
	v_mov_b32_dpp v126, v126 row_ror:1 row_mask:0xf bank_mask:0xf
	v_mov_b32_dpp v138, v138 row_ror:2 row_mask:0xf bank_mask:0xf
	v_mov_b32_dpp v127, v127 row_ror:1 row_mask:0xf bank_mask:0xf
	v_mov_b32_dpp v139, v139 row_ror:2 row_mask:0xf bank_mask:0xf
.LBB0_619:
	v_pk_fma_f32 v[88:89], v[114:115], v[134:135], v[118:119]
	v_pk_fma_f32 v[90:91], v[112:113], v[132:133], v[116:117]
	v_pk_fma_f32 v[88:89], v[110:111], v[130:131], v[88:89]
	v_pk_fma_f32 v[90:91], v[108:109], v[128:129], v[90:91]
	v_pk_fma_f32 v[88:89], v[86:87], v[98:99], v[88:89]
	v_pk_fma_f32 v[90:91], v[84:85], v[96:97], v[90:91]
	v_pk_fma_f32 v[128:129], v[106:107], v[138:139], v[122:123]
	v_pk_fma_f32 v[130:131], v[104:105], v[136:137], v[120:121]
	v_pk_fma_f32 v[126:127], v[102:103], v[126:127], v[128:129]
	v_pk_fma_f32 v[124:125], v[100:101], v[124:125], v[130:131]
	v_pk_mul_f32 v[128:129], v[88:89], v[88:89]
	v_pk_mul_f32 v[130:131], v[90:91], v[90:91]
	v_pk_fma_f32 v[128:129], v[128:129], s[84:85], v[246:247] op_sel_hi:[1,0,0]
	v_pk_fma_f32 v[130:131], v[130:131], s[84:85], v[246:247] op_sel_hi:[1,0,0]
	v_pk_mul_f32 v[128:129], v[88:89], v[128:129]
	v_pk_mul_f32 v[130:131], v[90:91], v[130:131]
	v_exp_f32_e32 v128, v128
	v_exp_f32_e32 v130, v130
	v_exp_f32_e32 v129, v129
	v_exp_f32_e32 v131, v131
	v_pk_fma_f32 v[126:127], v[82:83], v[94:95], v[126:127]
	v_pk_fma_f32 v[124:125], v[80:81], v[92:93], v[124:125]
	v_pk_add_f32 v[128:129], v[128:129], 1.0 op_sel_hi:[1,0]
	v_pk_add_f32 v[130:131], v[130:131], 1.0 op_sel_hi:[1,0]
	v_rcp_f32_e32 v128, v128
	v_rcp_f32_e32 v130, v130
	v_rcp_f32_e32 v129, v129
	v_rcp_f32_e32 v131, v131
	v_pk_mul_f32 v[88:89], v[88:89], v[126:127]
	v_pk_mul_f32 v[90:91], v[90:91], v[124:125]
	v_pk_mul_f32 v[88:89], v[88:89], v[128:129]
	v_pk_mul_f32 v[90:91], v[90:91], v[130:131]
	v_cvt_pk_bf16_f32 v90, v90, v91
	v_cvt_pk_bf16_f32 v91, v88, v89
	s_mul_i32 s100, s37, 0x90
	v_lshl_add_u64 v[136:137], v[178:179], 0, s[100:101]
	v_add_u32_e32 v138, v147, v215
	ds_bpermute_b32 v236, v244, v136
	ds_bpermute_b32 v237, v244, v137
	ds_bpermute_b32 v238, v244, v90
	ds_bpermute_b32 v239, v244, v91
	s_waitcnt lgkmcnt(0)
	global_store_dwordx2 v[236:237], v[238:239], off
	s_and_saveexec_b64 s[78:79], s[34:35]
	s_cbranch_execnz .Lnfs_0_5
.LBB0_621:
	s_or_b64 exec, exec, s[78:79]
	v_add_u32_e32 v88, 0xffffc0a0, v225
	v_ashrrev_i32_e32 v88, 1, v88
	v_and_b32_e32 v139, -10, v88
	s_and_b64 vcc, exec, s[22:23]
	s_mov_b64 s[78:79], -1
	s_cbranch_vccz .Lsmp_0_10
.LBB0_623:
.LBB0_624:
	v_cndmask_b32_e64 v88, v76, v84, s[16:17]
	v_cndmask_b32_e64 v124, v76, v84, s[8:9]
	v_cndmask_b32_e64 v89, v77, v85, s[16:17]
	v_cndmask_b32_e64 v125, v77, v85, s[8:9]
	v_cndmask_b32_e64 v90, v78, v86, s[16:17]
	v_cndmask_b32_e64 v126, v78, v86, s[8:9]
	v_cndmask_b32_e64 v91, v79, v87, s[16:17]
	v_cndmask_b32_e64 v127, v79, v87, s[8:9]
	v_mov_b32_dpp v88, v88 row_ror:1 row_mask:0xf bank_mask:0xf
	v_mov_b32_dpp v124, v124 row_ror:2 row_mask:0xf bank_mask:0xf
	v_mov_b32_dpp v89, v89 row_ror:1 row_mask:0xf bank_mask:0xf
	v_mov_b32_dpp v125, v125 row_ror:2 row_mask:0xf bank_mask:0xf
	v_mov_b32_dpp v90, v90 row_ror:1 row_mask:0xf bank_mask:0xf
	v_mov_b32_dpp v126, v126 row_ror:2 row_mask:0xf bank_mask:0xf
	v_mov_b32_dpp v91, v91 row_ror:1 row_mask:0xf bank_mask:0xf
	v_mov_b32_dpp v127, v127 row_ror:2 row_mask:0xf bank_mask:0xf

; __device__ __forceinline__ unsigned pk2(float lo, float hi) { const f32x2 v = {lo, hi}; const bf16x2_t b = __builtin_convertvector(v, bf16x2_t); return __builtin_bit_cast(unsigned, b); }
;     __device__ __forceinline__ void operator()(const f32x4 (&acc)[2][2][4][2], const pg8::Unit& u, int wr, int wc, int fr, int fq, PG8_LAS unsigned char* xl) const {
;     ...
;                         const f32x4 cur = acc[ai][bj][m][n]; f32x4 p1, p2;
;                         if (!sample) { const f32x4 prv = (m == 0) ? hb[bj] : acc[ai][bj][m == 0 ? 0 : m - 1][n];
; #pragma unroll
;                             for (int j = 0; j < 4; ++j) { const float s1 = fr == 15 ? prv[j] : cur[j], s2 = fr >= 14 ? prv[j] : cur[j]; p1[j] = dpp_ror<1>(s1); p2[j] = dpp_ror<2>(s2); }
;                         } else { const int t = fr & 3, b = (row - MP) >> 2;
; #pragma unroll
;                             for (int j = 0; j < 4; ++j) { p1[j] = dpp_ror<1>(cur[j]); p2[j] = dpp_ror<2>(cur[j]); }
;                             const f32x4 c1 = *(const f32x4*)(ctx_s + (size_t)(b * 2 + 1) * FF2 + bj * FF + jc0 + 4 * n), c0 = *(const f32x4*)(ctx_s + (size_t)(b * 2) * FF2 + bj * FF + jc0 + 4 * n);
; #pragma unroll
;                             for (int j = 0; j < 4; ++j) { p2[j] = t == 0 ? c0[j] : (t == 1 ? c1[j] : p2[j]); p1[j] = t == 0 ? c1[j] : p1[j]; }
;                         }
;                         cc[bj] = bb[bj] + w0[bj] * p2 + w1[bj] * p1 + w2[bj] * cur;
;                     }
;                     const f32x4 gv = gelu_mul4(cc[0], cc[1]);
;                     u32x2 w; w.x = pk2(gv[0], gv[1]); w.y = pk2(gv[2], gv[3]);
;                     *(u32x2*)(G + (size_t)row * FF + jc0 + 4 * n) = w;
;                     if (!sample && ai == 0 && wr == 0 && m == 0 && fr < 2 && (pm & 7) != 0) {
; #pragma unroll
;                         for (int bj = 0; bj < 2; ++bj) *(f32x4*)(PH + (size_t)(pm * 2 + fr) * FF2 + bj * FF + jc0 + 4 * n) = cc[bj];
;                     }
;                     if (sample && (fr & 3) >= 2) { const int b = (row - MP) >> 2, t = fr & 3;
; #pragma unroll
;                         for (int bj = 0; bj < 2; ++bj) *(f32x4*)(nf_s + (size_t)(b * 2 + t - 2) * FF2 + bj * FF + jc0 + 4 * n) = acc[ai][bj][m][n];
;                     }
.LBB0_627:
.LBB0_628:
	v_cndmask_b32_e64 v84, v72, v80, s[16:17]
	v_cndmask_b32_e64 v128, v72, v80, s[8:9]
	v_cndmask_b32_e64 v85, v73, v81, s[16:17]
	v_cndmask_b32_e64 v129, v73, v81, s[8:9]
	v_cndmask_b32_e64 v86, v74, v82, s[16:17]
	v_cndmask_b32_e64 v130, v74, v82, s[8:9]
	v_cndmask_b32_e64 v87, v75, v83, s[16:17]
	v_cndmask_b32_e64 v131, v75, v83, s[8:9]
	v_mov_b32_dpp v84, v84 row_ror:1 row_mask:0xf bank_mask:0xf
	v_mov_b32_dpp v128, v128 row_ror:2 row_mask:0xf bank_mask:0xf
	v_mov_b32_dpp v85, v85 row_ror:1 row_mask:0xf bank_mask:0xf
	v_mov_b32_dpp v129, v129 row_ror:2 row_mask:0xf bank_mask:0xf
	v_mov_b32_dpp v86, v86 row_ror:1 row_mask:0xf bank_mask:0xf
	v_mov_b32_dpp v130, v130 row_ror:2 row_mask:0xf bank_mask:0xf
	v_mov_b32_dpp v87, v87 row_ror:1 row_mask:0xf bank_mask:0xf
	v_mov_b32_dpp v131, v131 row_ror:2 row_mask:0xf bank_mask:0xf
.LBB0_629:
	v_pk_fma_f32 v[80:81], v[114:115], v[126:127], v[118:119]
	v_pk_fma_f32 v[82:83], v[112:113], v[124:125], v[116:117]
	v_pk_fma_f32 v[80:81], v[110:111], v[90:91], v[80:81]
	v_pk_fma_f32 v[82:83], v[108:109], v[88:89], v[82:83]
	v_pk_fma_f32 v[80:81], v[78:79], v[98:99], v[80:81]
	v_pk_fma_f32 v[82:83], v[76:77], v[96:97], v[82:83]
	v_pk_fma_f32 v[88:89], v[106:107], v[130:131], v[122:123]
	v_pk_fma_f32 v[90:91], v[104:105], v[128:129], v[120:121]
	v_pk_fma_f32 v[86:87], v[102:103], v[86:87], v[88:89]
	v_pk_fma_f32 v[84:85], v[100:101], v[84:85], v[90:91]
	v_pk_mul_f32 v[88:89], v[80:81], v[80:81]
	v_pk_mul_f32 v[90:91], v[82:83], v[82:83]
	v_pk_fma_f32 v[88:89], v[88:89], s[84:85], v[246:247] op_sel_hi:[1,0,0]
	v_pk_fma_f32 v[90:91], v[90:91], s[84:85], v[246:247] op_sel_hi:[1,0,0]
	v_pk_mul_f32 v[88:89], v[80:81], v[88:89]
	v_pk_mul_f32 v[90:91], v[82:83], v[90:91]
	v_exp_f32_e32 v88, v88
	v_exp_f32_e32 v90, v90
	v_exp_f32_e32 v89, v89
	v_exp_f32_e32 v91, v91
	v_pk_fma_f32 v[86:87], v[74:75], v[94:95], v[86:87]
	v_pk_fma_f32 v[84:85], v[72:73], v[92:93], v[84:85]
	v_pk_add_f32 v[88:89], v[88:89], 1.0 op_sel_hi:[1,0]
	v_pk_add_f32 v[90:91], v[90:91], 1.0 op_sel_hi:[1,0]
	v_rcp_f32_e32 v88, v88
	v_rcp_f32_e32 v90, v90
	v_rcp_f32_e32 v89, v89
	v_rcp_f32_e32 v91, v91
	v_pk_mul_f32 v[80:81], v[80:81], v[86:87]
	v_pk_mul_f32 v[82:83], v[82:83], v[84:85]
	v_pk_mul_f32 v[80:81], v[80:81], v[88:89]
	v_pk_mul_f32 v[82:83], v[82:83], v[90:91]
	v_cvt_pk_bf16_f32 v82, v82, v83
	v_cvt_pk_bf16_f32 v83, v80, v81
	s_mul_i32 s100, s37, 0xa0
	v_lshl_add_u64 v[128:129], v[178:179], 0, s[100:101]
	v_add_u32_e32 v139, v139, v215
	ds_bpermute_b32 v236, v244, v128
	ds_bpermute_b32 v237, v244, v129
	ds_bpermute_b32 v238, v244, v82
	ds_bpermute_b32 v239, v244, v83
	s_waitcnt lgkmcnt(0)
	global_store_dwordx2 v[236:237], v[238:239], off
	s_and_saveexec_b64 s[78:79], s[34:35]
	s_cbranch_execnz .Lnfs_0_6
.LBB0_631:
	s_or_b64 exec, exec, s[78:79]
	v_add_u32_e32 v80, 0xffffc0b0, v225
	v_ashrrev_i32_e32 v80, 1, v80
	v_and_b32_e32 v147, -2, v80
	s_and_b64 vcc, exec, s[22:23]
	s_mov_b64 s[78:79], -1
	s_cbranch_vccz .Lsmp_0_12
.LBB0_633:
.LBB0_634:
	v_cndmask_b32_e64 v80, v12, v76, s[16:17]
	v_cndmask_b32_e64 v84, v12, v76, s[8:9]
	v_cndmask_b32_e64 v81, v13, v77, s[16:17]
	v_cndmask_b32_e64 v85, v13, v77, s[8:9]
	v_cndmask_b32_e64 v82, v14, v78, s[16:17]
	v_cndmask_b32_e64 v86, v14, v78, s[8:9]
	v_cndmask_b32_e64 v83, v15, v79, s[16:17]
	v_cndmask_b32_e64 v87, v15, v79, s[8:9]
	v_mov_b32_dpp v80, v80 row_ror:1 row_mask:0xf bank_mask:0xf
	v_mov_b32_dpp v84, v84 row_ror:2 row_mask:0xf bank_mask:0xf
	v_mov_b32_dpp v81, v81 row_ror:1 row_mask:0xf bank_mask:0xf
	v_mov_b32_dpp v85, v85 row_ror:2 row_mask:0xf bank_mask:0xf
	v_mov_b32_dpp v82, v82 row_ror:1 row_mask:0xf bank_mask:0xf
	v_mov_b32_dpp v86, v86 row_ror:2 row_mask:0xf bank_mask:0xf
	v_mov_b32_dpp v83, v83 row_ror:1 row_mask:0xf bank_mask:0xf
	v_mov_b32_dpp v87, v87 row_ror:2 row_mask:0xf bank_mask:0xf

; __device__ __forceinline__ unsigned pk2(float lo, float hi) { const f32x2 v = {lo, hi}; const bf16x2_t b = __builtin_convertvector(v, bf16x2_t); return __builtin_bit_cast(unsigned, b); }
;     __device__ __forceinline__ void operator()(const f32x4 (&acc)[2][2][4][2], const pg8::Unit& u, int wr, int wc, int fr, int fq, PG8_LAS unsigned char* xl) const {
;     ...
;                         const f32x4 cur = acc[ai][bj][m][n]; f32x4 p1, p2;
;                         if (!sample) { const f32x4 prv = (m == 0) ? hb[bj] : acc[ai][bj][m == 0 ? 0 : m - 1][n];
; #pragma unroll
;                             for (int j = 0; j < 4; ++j) { const float s1 = fr == 15 ? prv[j] : cur[j], s2 = fr >= 14 ? prv[j] : cur[j]; p1[j] = dpp_ror<1>(s1); p2[j] = dpp_ror<2>(s2); }
;                         } else { const int t = fr & 3, b = (row - MP) >> 2;
; #pragma unroll
;                             for (int j = 0; j < 4; ++j) { p1[j] = dpp_ror<1>(cur[j]); p2[j] = dpp_ror<2>(cur[j]); }
;                             const f32x4 c1 = *(const f32x4*)(ctx_s + (size_t)(b * 2 + 1) * FF2 + bj * FF + jc0 + 4 * n), c0 = *(const f32x4*)(ctx_s + (size_t)(b * 2) * FF2 + bj * FF + jc0 + 4 * n);
; #pragma unroll
;                             for (int j = 0; j < 4; ++j) { p2[j] = t == 0 ? c0[j] : (t == 1 ? c1[j] : p2[j]); p1[j] = t == 0 ? c1[j] : p1[j]; }
;                         }
;                         cc[bj] = bb[bj] + w0[bj] * p2 + w1[bj] * p1 + w2[bj] * cur;
;                     }
;                     const f32x4 gv = gelu_mul4(cc[0], cc[1]);
;                     u32x2 w; w.x = pk2(gv[0], gv[1]); w.y = pk2(gv[2], gv[3]);
;                     *(u32x2*)(G + (size_t)row * FF + jc0 + 4 * n) = w;
;                     if (!sample && ai == 0 && wr == 0 && m == 0 && fr < 2 && (pm & 7) != 0) {
; #pragma unroll
;                         for (int bj = 0; bj < 2; ++bj) *(f32x4*)(PH + (size_t)(pm * 2 + fr) * FF2 + bj * FF + jc0 + 4 * n) = cc[bj];
;                     }
;                     if (sample && (fr & 3) >= 2) { const int b = (row - MP) >> 2, t = fr & 3;
; #pragma unroll
;                         for (int bj = 0; bj < 2; ++bj) *(f32x4*)(nf_s + (size_t)(b * 2 + t - 2) * FF2 + bj * FF + jc0 + 4 * n) = acc[ai][bj][m][n];
;                     }
.LBB0_637:
.LBB0_638:
	v_cndmask_b32_e64 v76, v4, v72, s[16:17]
	v_cndmask_b32_e64 v88, v4, v72, s[8:9]
	v_cndmask_b32_e64 v77, v5, v73, s[16:17]
	v_cndmask_b32_e64 v89, v5, v73, s[8:9]
	v_cndmask_b32_e64 v78, v6, v74, s[16:17]
	v_cndmask_b32_e64 v90, v6, v74, s[8:9]
	v_cndmask_b32_e64 v79, v7, v75, s[16:17]
	v_cndmask_b32_e64 v91, v7, v75, s[8:9]
	v_mov_b32_dpp v76, v76 row_ror:1 row_mask:0xf bank_mask:0xf
	v_mov_b32_dpp v88, v88 row_ror:2 row_mask:0xf bank_mask:0xf
	v_mov_b32_dpp v77, v77 row_ror:1 row_mask:0xf bank_mask:0xf
	v_mov_b32_dpp v89, v89 row_ror:2 row_mask:0xf bank_mask:0xf
	v_mov_b32_dpp v78, v78 row_ror:1 row_mask:0xf bank_mask:0xf
	v_mov_b32_dpp v90, v90 row_ror:2 row_mask:0xf bank_mask:0xf
	v_mov_b32_dpp v79, v79 row_ror:1 row_mask:0xf bank_mask:0xf
	v_mov_b32_dpp v91, v91 row_ror:2 row_mask:0xf bank_mask:0xf
.LBB0_639:
	v_pk_fma_f32 v[72:73], v[114:115], v[86:87], v[118:119]
	v_pk_fma_f32 v[74:75], v[112:113], v[84:85], v[116:117]
	v_pk_fma_f32 v[72:73], v[110:111], v[82:83], v[72:73]
	v_pk_fma_f32 v[74:75], v[108:109], v[80:81], v[74:75]
	v_pk_fma_f32 v[72:73], v[14:15], v[98:99], v[72:73]
	v_pk_fma_f32 v[74:75], v[12:13], v[96:97], v[74:75]
	v_pk_fma_f32 v[80:81], v[106:107], v[90:91], v[122:123]
	v_pk_fma_f32 v[82:83], v[104:105], v[88:89], v[120:121]
	v_pk_fma_f32 v[78:79], v[102:103], v[78:79], v[80:81]
	v_pk_fma_f32 v[76:77], v[100:101], v[76:77], v[82:83]
	v_pk_mul_f32 v[80:81], v[72:73], v[72:73]
	v_pk_mul_f32 v[82:83], v[74:75], v[74:75]
	v_pk_fma_f32 v[80:81], v[80:81], s[84:85], v[246:247] op_sel_hi:[1,0,0]
	v_pk_fma_f32 v[82:83], v[82:83], s[84:85], v[246:247] op_sel_hi:[1,0,0]
	v_pk_mul_f32 v[80:81], v[72:73], v[80:81]
	v_pk_mul_f32 v[82:83], v[74:75], v[82:83]
	v_exp_f32_e32 v80, v80
	v_exp_f32_e32 v82, v82
	v_exp_f32_e32 v81, v81
	v_exp_f32_e32 v83, v83
	v_pk_fma_f32 v[78:79], v[6:7], v[94:95], v[78:79]
	v_pk_fma_f32 v[76:77], v[4:5], v[92:93], v[76:77]
	v_pk_add_f32 v[80:81], v[80:81], 1.0 op_sel_hi:[1,0]
	v_pk_add_f32 v[82:83], v[82:83], 1.0 op_sel_hi:[1,0]
	v_rcp_f32_e32 v80, v80
	v_rcp_f32_e32 v82, v82
	v_rcp_f32_e32 v81, v81
	v_rcp_f32_e32 v83, v83
	v_pk_mul_f32 v[72:73], v[72:73], v[78:79]
	v_pk_mul_f32 v[74:75], v[74:75], v[76:77]
	v_pk_mul_f32 v[72:73], v[72:73], v[80:81]
	v_pk_mul_f32 v[74:75], v[74:75], v[82:83]
	v_cvt_pk_bf16_f32 v74, v74, v75
	v_cvt_pk_bf16_f32 v75, v72, v73
	s_mul_i32 s100, s37, 0xb0
	v_lshl_add_u64 v[130:131], v[178:179], 0, s[100:101]
	v_add_u32_e32 v147, v147, v215
	ds_bpermute_b32 v236, v244, v130
	ds_bpermute_b32 v237, v244, v131
	ds_bpermute_b32 v238, v244, v74
	ds_bpermute_b32 v239, v244, v75
	s_waitcnt lgkmcnt(0)
	global_store_dwordx2 v[236:237], v[238:239], off
	s_and_saveexec_b64 s[78:79], s[34:35]
	s_cbranch_execnz .Lnfs_0_7

; template <int N> __device__ __forceinline__ float dpp_ror(float v) { const int i = __builtin_bit_cast(int, v); return __builtin_bit_cast(float, __builtin_amdgcn_update_dpp(i, i, 0x120 + N, 0xF, 0xF, false)); }
;     __device__ __forceinline__ void operator()(const f32x4 (&acc)[2][2][4][2], const pg8::Unit& u, int wr, int wc, int fr, int fq, PG8_LAS unsigned char* xl) const {
;     ...
;                         const f32x4 cur = acc[ai][bj][m][n]; f32x4 p1, p2;
;                         if (!sample) { const f32x4 prv = (m == 0) ? hb[bj] : acc[ai][bj][m == 0 ? 0 : m - 1][n];
; #pragma unroll
;                             for (int j = 0; j < 4; ++j) { const float s1 = fr == 15 ? prv[j] : cur[j], s2 = fr >= 14 ? prv[j] : cur[j]; p1[j] = dpp_ror<1>(s1); p2[j] = dpp_ror<2>(s2); }
;                         } else { const int t = fr & 3, b = (row - MP) >> 2;
; #pragma unroll
;                             for (int j = 0; j < 4; ++j) { p1[j] = dpp_ror<1>(cur[j]); p2[j] = dpp_ror<2>(cur[j]); }
;                             const f32x4 c1 = *(const f32x4*)(ctx_s + (size_t)(b * 2 + 1) * FF2 + bj * FF + jc0 + 4 * n), c0 = *(const f32x4*)(ctx_s + (size_t)(b * 2) * FF2 + bj * FF + jc0 + 4 * n);
; #pragma unroll
;                             for (int j = 0; j < 4; ++j) { p2[j] = t == 0 ? c0[j] : (t == 1 ? c1[j] : p2[j]); p1[j] = t == 0 ? c1[j] : p1[j]; }
;                         }
.LBB0_643:
	s_or_b64 exec, exec, vcc
	s_and_b64 vcc, exec, s[22:23]
	s_mov_b64 s[58:59], -1
	s_cbranch_vccz .Lsmp_0_14
.LBB0_645:
.LBB0_646:
	s_waitcnt lgkmcnt(1)
	v_cndmask_b32_e64 v108, v68, v116, s[16:17]
	v_cndmask_b32_e64 v112, v68, v116, s[8:9]
	v_cndmask_b32_e64 v109, v69, v117, s[16:17]
	v_cndmask_b32_e64 v113, v69, v117, s[8:9]
	v_cndmask_b32_e64 v110, v70, v118, s[16:17]
	v_cndmask_b32_e64 v114, v70, v118, s[8:9]
	v_cndmask_b32_e64 v111, v71, v119, s[16:17]
	v_cndmask_b32_e64 v115, v71, v119, s[8:9]
	v_mov_b32_dpp v108, v108 row_ror:1 row_mask:0xf bank_mask:0xf
	v_mov_b32_dpp v112, v112 row_ror:2 row_mask:0xf bank_mask:0xf
	v_mov_b32_dpp v109, v109 row_ror:1 row_mask:0xf bank_mask:0xf
	v_mov_b32_dpp v113, v113 row_ror:2 row_mask:0xf bank_mask:0xf
	v_mov_b32_dpp v110, v110 row_ror:1 row_mask:0xf bank_mask:0xf
	v_mov_b32_dpp v114, v114 row_ror:2 row_mask:0xf bank_mask:0xf
	v_mov_b32_dpp v111, v111 row_ror:1 row_mask:0xf bank_mask:0xf
	v_mov_b32_dpp v115, v115 row_ror:2 row_mask:0xf bank_mask:0xf
.LBB0_647:
	s_and_b64 vcc, exec, s[22:23]
	s_mov_b64 s[58:59], -1
	s_cbranch_vccz .Lsmp_0_15
.LBB0_649:
.LBB0_650:
	s_waitcnt lgkmcnt(0)
	v_cndmask_b32_e64 v116, v64, v104, s[16:17]
	v_cndmask_b32_e64 v120, v64, v104, s[8:9]
	v_cndmask_b32_e64 v117, v65, v105, s[16:17]
	v_cndmask_b32_e64 v121, v65, v105, s[8:9]
	v_cndmask_b32_e64 v118, v66, v106, s[16:17]
	v_cndmask_b32_e64 v122, v66, v106, s[8:9]
	v_cndmask_b32_e64 v119, v67, v107, s[16:17]
	v_cndmask_b32_e64 v123, v67, v107, s[8:9]
	v_mov_b32_dpp v116, v116 row_ror:1 row_mask:0xf bank_mask:0xf
	v_mov_b32_dpp v120, v120 row_ror:2 row_mask:0xf bank_mask:0xf
	v_mov_b32_dpp v117, v117 row_ror:1 row_mask:0xf bank_mask:0xf
	v_mov_b32_dpp v121, v121 row_ror:2 row_mask:0xf bank_mask:0xf
	v_mov_b32_dpp v118, v118 row_ror:1 row_mask:0xf bank_mask:0xf
	v_mov_b32_dpp v122, v122 row_ror:2 row_mask:0xf bank_mask:0xf
	v_mov_b32_dpp v119, v119 row_ror:1 row_mask:0xf bank_mask:0xf
	v_mov_b32_dpp v123, v123 row_ror:2 row_mask:0xf bank_mask:0xf

; __device__ __forceinline__ unsigned pk2(float lo, float hi) { const f32x2 v = {lo, hi}; const bf16x2_t b = __builtin_convertvector(v, bf16x2_t); return __builtin_bit_cast(unsigned, b); }
;     __device__ __forceinline__ void operator()(const f32x4 (&acc)[2][2][4][2], const pg8::Unit& u, int wr, int wc, int fr, int fq, PG8_LAS unsigned char* xl) const {
;     ...
;                         const f32x4 cur = acc[ai][bj][m][n]; f32x4 p1, p2;
;                         if (!sample) { const f32x4 prv = (m == 0) ? hb[bj] : acc[ai][bj][m == 0 ? 0 : m - 1][n];
; #pragma unroll
;                             for (int j = 0; j < 4; ++j) { const float s1 = fr == 15 ? prv[j] : cur[j], s2 = fr >= 14 ? prv[j] : cur[j]; p1[j] = dpp_ror<1>(s1); p2[j] = dpp_ror<2>(s2); }
;                         } else { const int t = fr & 3, b = (row - MP) >> 2;
; #pragma unroll
;                             for (int j = 0; j < 4; ++j) { p1[j] = dpp_ror<1>(cur[j]); p2[j] = dpp_ror<2>(cur[j]); }
;                             const f32x4 c1 = *(const f32x4*)(ctx_s + (size_t)(b * 2 + 1) * FF2 + bj * FF + jc0 + 4 * n), c0 = *(const f32x4*)(ctx_s + (size_t)(b * 2) * FF2 + bj * FF + jc0 + 4 * n);
; #pragma unroll
;                             for (int j = 0; j < 4; ++j) { p2[j] = t == 0 ? c0[j] : (t == 1 ? c1[j] : p2[j]); p1[j] = t == 0 ? c1[j] : p1[j]; }
;                         }
;                         cc[bj] = bb[bj] + w0[bj] * p2 + w1[bj] * p1 + w2[bj] * cur;
;                     }
;                     const f32x4 gv = gelu_mul4(cc[0], cc[1]);
;                     u32x2 w; w.x = pk2(gv[0], gv[1]); w.y = pk2(gv[2], gv[3]);
;                     *(u32x2*)(G + (size_t)row * FF + jc0 + 4 * n) = w;
;                     if (!sample && ai == 0 && wr == 0 && m == 0 && fr < 2 && (pm & 7) != 0) {
; #pragma unroll
;                         for (int bj = 0; bj < 2; ++bj) *(f32x4*)(PH + (size_t)(pm * 2 + fr) * FF2 + bj * FF + jc0 + 4 * n) = cc[bj];
;                     }
;                     if (sample && (fr & 3) >= 2) { const int b = (row - MP) >> 2, t = fr & 3;
; #pragma unroll
;                         for (int bj = 0; bj < 2; ++bj) *(f32x4*)(nf_s + (size_t)(b * 2 + t - 2) * FF2 + bj * FF + jc0 + 4 * n) = acc[ai][bj][m][n];
;                     }
.LBB0_655:
	s_or_b64 exec, exec, s[6:7]
	s_and_b64 vcc, exec, s[22:23]
	s_mov_b64 s[6:7], -1
	s_cbranch_vccz .Lsmp_0_16
.LBB0_657:
.LBB0_658:
	v_cndmask_b32_e64 v104, v60, v68, s[16:17]
	v_cndmask_b32_e64 v108, v60, v68, s[8:9]
	v_cndmask_b32_e64 v105, v61, v69, s[16:17]
	v_cndmask_b32_e64 v109, v61, v69, s[8:9]
	v_cndmask_b32_e64 v106, v62, v70, s[16:17]
	v_cndmask_b32_e64 v110, v62, v70, s[8:9]
	v_cndmask_b32_e64 v107, v63, v71, s[16:17]
	v_cndmask_b32_e64 v111, v63, v71, s[8:9]
	v_mov_b32_dpp v104, v104 row_ror:1 row_mask:0xf bank_mask:0xf
	v_mov_b32_dpp v108, v108 row_ror:2 row_mask:0xf bank_mask:0xf
	v_mov_b32_dpp v105, v105 row_ror:1 row_mask:0xf bank_mask:0xf
	v_mov_b32_dpp v109, v109 row_ror:2 row_mask:0xf bank_mask:0xf
	v_mov_b32_dpp v106, v106 row_ror:1 row_mask:0xf bank_mask:0xf
	v_mov_b32_dpp v110, v110 row_ror:2 row_mask:0xf bank_mask:0xf
	v_mov_b32_dpp v107, v107 row_ror:1 row_mask:0xf bank_mask:0xf
	v_mov_b32_dpp v111, v111 row_ror:2 row_mask:0xf bank_mask:0xf
.LBB0_659:
	s_and_b64 vcc, exec, s[22:23]
	s_mov_b64 s[6:7], -1
	s_cbranch_vccz .Lsmp_0_17
.LBB0_661:
.LBB0_662:
	v_cndmask_b32_e64 v68, v56, v64, s[16:17]
	v_cndmask_b32_e64 v112, v56, v64, s[8:9]
	v_cndmask_b32_e64 v69, v57, v65, s[16:17]
	v_cndmask_b32_e64 v113, v57, v65, s[8:9]
	v_cndmask_b32_e64 v70, v58, v66, s[16:17]
	v_cndmask_b32_e64 v114, v58, v66, s[8:9]
	v_cndmask_b32_e64 v71, v59, v67, s[16:17]
	v_cndmask_b32_e64 v115, v59, v67, s[8:9]
	v_mov_b32_dpp v68, v68 row_ror:1 row_mask:0xf bank_mask:0xf
	v_mov_b32_dpp v112, v112 row_ror:2 row_mask:0xf bank_mask:0xf
	v_mov_b32_dpp v69, v69 row_ror:1 row_mask:0xf bank_mask:0xf
	v_mov_b32_dpp v113, v113 row_ror:2 row_mask:0xf bank_mask:0xf
	v_mov_b32_dpp v70, v70 row_ror:1 row_mask:0xf bank_mask:0xf
	v_mov_b32_dpp v114, v114 row_ror:2 row_mask:0xf bank_mask:0xf
	v_mov_b32_dpp v71, v71 row_ror:1 row_mask:0xf bank_mask:0xf
	v_mov_b32_dpp v115, v115 row_ror:2 row_mask:0xf bank_mask:0xf
.LBB0_663:
	v_pk_fma_f32 v[64:65], v[94:95], v[110:111], v[102:103]
	v_pk_fma_f32 v[66:67], v[92:93], v[108:109], v[100:101]
	v_pk_fma_f32 v[64:65], v[90:91], v[106:107], v[64:65]
	v_pk_fma_f32 v[66:67], v[88:89], v[104:105], v[66:67]
	v_pk_fma_f32 v[64:65], v[62:63], v[82:83], v[64:65]
	v_pk_fma_f32 v[66:67], v[60:61], v[80:81], v[66:67]
	v_pk_fma_f32 v[104:105], v[86:87], v[114:115], v[98:99]
	v_pk_fma_f32 v[106:107], v[84:85], v[112:113], v[96:97]
	v_pk_fma_f32 v[70:71], v[78:79], v[70:71], v[104:105]
	v_pk_fma_f32 v[68:69], v[76:77], v[68:69], v[106:107]
	v_pk_mul_f32 v[104:105], v[64:65], v[64:65]
	v_pk_mul_f32 v[106:107], v[66:67], v[66:67]
	v_pk_fma_f32 v[104:105], v[104:105], s[84:85], v[246:247] op_sel_hi:[1,0,0]
	v_pk_fma_f32 v[106:107], v[106:107], s[84:85], v[246:247] op_sel_hi:[1,0,0]
	v_pk_mul_f32 v[104:105], v[64:65], v[104:105]
	v_pk_mul_f32 v[106:107], v[66:67], v[106:107]
	v_exp_f32_e32 v104, v104
	v_exp_f32_e32 v106, v106
	v_exp_f32_e32 v105, v105
	v_exp_f32_e32 v107, v107
	v_pk_fma_f32 v[70:71], v[58:59], v[74:75], v[70:71]
	v_pk_fma_f32 v[68:69], v[56:57], v[72:73], v[68:69]
	v_pk_add_f32 v[104:105], v[104:105], 1.0 op_sel_hi:[1,0]
	v_pk_add_f32 v[106:107], v[106:107], 1.0 op_sel_hi:[1,0]
	v_rcp_f32_e32 v104, v104
	v_rcp_f32_e32 v106, v106
	v_rcp_f32_e32 v105, v105
	v_rcp_f32_e32 v107, v107
	v_pk_mul_f32 v[64:65], v[64:65], v[70:71]
	v_pk_mul_f32 v[66:67], v[66:67], v[68:69]
	v_pk_mul_f32 v[64:65], v[64:65], v[104:105]
	v_pk_mul_f32 v[66:67], v[66:67], v[106:107]
	s_nop 0
	v_cvt_pk_bf16_f32 v66, v66, v67
	v_cvt_pk_bf16_f32 v67, v64, v65
	ds_bpermute_b32 v236, v244, v168
	ds_bpermute_b32 v237, v244, v169
	ds_bpermute_b32 v238, v244, v66
	ds_bpermute_b32 v239, v244, v67
	s_waitcnt lgkmcnt(0)
	global_store_dwordx2 v[236:237], v[238:239], off offset:8
	s_and_saveexec_b64 s[6:7], s[34:35]
	s_cbranch_execnz .Lnfs_0_8

; template <int N> __device__ __forceinline__ float dpp_ror(float v) { const int i = __builtin_bit_cast(int, v); return __builtin_bit_cast(float, __builtin_amdgcn_update_dpp(i, i, 0x120 + N, 0xF, 0xF, false)); }
;     __device__ __forceinline__ void operator()(const f32x4 (&acc)[2][2][4][2], const pg8::Unit& u, int wr, int wc, int fr, int fq, PG8_LAS unsigned char* xl) const {
;     ...
;                         if (!sample) { const f32x4 prv = (m == 0) ? hb[bj] : acc[ai][bj][m == 0 ? 0 : m - 1][n];
; #pragma unroll
;                             for (int j = 0; j < 4; ++j) { const float s1 = fr == 15 ? prv[j] : cur[j], s2 = fr >= 14 ? prv[j] : cur[j]; p1[j] = dpp_ror<1>(s1); p2[j] = dpp_ror<2>(s2); }
.LBB0_667:
.LBB0_668:
	v_cndmask_b32_e64 v64, v52, v60, s[16:17]
	v_cndmask_b32_e64 v68, v52, v60, s[8:9]
	v_cndmask_b32_e64 v65, v53, v61, s[16:17]
	v_cndmask_b32_e64 v69, v53, v61, s[8:9]
	v_cndmask_b32_e64 v66, v54, v62, s[16:17]
	v_cndmask_b32_e64 v70, v54, v62, s[8:9]
	v_cndmask_b32_e64 v67, v55, v63, s[16:17]
	v_cndmask_b32_e64 v71, v55, v63, s[8:9]
	v_mov_b32_dpp v64, v64 row_ror:1 row_mask:0xf bank_mask:0xf
	v_mov_b32_dpp v68, v68 row_ror:2 row_mask:0xf bank_mask:0xf
	v_mov_b32_dpp v65, v65 row_ror:1 row_mask:0xf bank_mask:0xf
	v_mov_b32_dpp v69, v69 row_ror:2 row_mask:0xf bank_mask:0xf
	v_mov_b32_dpp v66, v66 row_ror:1 row_mask:0xf bank_mask:0xf
	v_mov_b32_dpp v70, v70 row_ror:2 row_mask:0xf bank_mask:0xf
	v_mov_b32_dpp v67, v67 row_ror:1 row_mask:0xf bank_mask:0xf
	v_mov_b32_dpp v71, v71 row_ror:2 row_mask:0xf bank_mask:0xf

; __device__ __forceinline__ unsigned pk2(float lo, float hi) { const f32x2 v = {lo, hi}; const bf16x2_t b = __builtin_convertvector(v, bf16x2_t); return __builtin_bit_cast(unsigned, b); }
;     __device__ __forceinline__ void operator()(const f32x4 (&acc)[2][2][4][2], const pg8::Unit& u, int wr, int wc, int fr, int fq, PG8_LAS unsigned char* xl) const {
;     ...
;                         const f32x4 cur = acc[ai][bj][m][n]; f32x4 p1, p2;
;                         if (!sample) { const f32x4 prv = (m == 0) ? hb[bj] : acc[ai][bj][m == 0 ? 0 : m - 1][n];
; #pragma unroll
;                             for (int j = 0; j < 4; ++j) { const float s1 = fr == 15 ? prv[j] : cur[j], s2 = fr >= 14 ? prv[j] : cur[j]; p1[j] = dpp_ror<1>(s1); p2[j] = dpp_ror<2>(s2); }
;                         } else { const int t = fr & 3, b = (row - MP) >> 2;
; #pragma unroll
;                             for (int j = 0; j < 4; ++j) { p1[j] = dpp_ror<1>(cur[j]); p2[j] = dpp_ror<2>(cur[j]); }
;                             const f32x4 c1 = *(const f32x4*)(ctx_s + (size_t)(b * 2 + 1) * FF2 + bj * FF + jc0 + 4 * n), c0 = *(const f32x4*)(ctx_s + (size_t)(b * 2) * FF2 + bj * FF + jc0 + 4 * n);
; #pragma unroll
;                             for (int j = 0; j < 4; ++j) { p2[j] = t == 0 ? c0[j] : (t == 1 ? c1[j] : p2[j]); p1[j] = t == 0 ? c1[j] : p1[j]; }
;                         }
;                         cc[bj] = bb[bj] + w0[bj] * p2 + w1[bj] * p1 + w2[bj] * cur;
;                     }
;                     const f32x4 gv = gelu_mul4(cc[0], cc[1]);
;                     u32x2 w; w.x = pk2(gv[0], gv[1]); w.y = pk2(gv[2], gv[3]);
;                     *(u32x2*)(G + (size_t)row * FF + jc0 + 4 * n) = w;
;                     if (!sample && ai == 0 && wr == 0 && m == 0 && fr < 2 && (pm & 7) != 0) {
; #pragma unroll
;                         for (int bj = 0; bj < 2; ++bj) *(f32x4*)(PH + (size_t)(pm * 2 + fr) * FF2 + bj * FF + jc0 + 4 * n) = cc[bj];
;                     }
;                     if (sample && (fr & 3) >= 2) { const int b = (row - MP) >> 2, t = fr & 3;
; #pragma unroll
;                         for (int bj = 0; bj < 2; ++bj) *(f32x4*)(nf_s + (size_t)(b * 2 + t - 2) * FF2 + bj * FF + jc0 + 4 * n) = acc[ai][bj][m][n];
;                     }
.LBB0_671:
.LBB0_672:
	v_cndmask_b32_e64 v60, v48, v56, s[16:17]
	v_cndmask_b32_e64 v104, v48, v56, s[8:9]
	v_cndmask_b32_e64 v61, v49, v57, s[16:17]
	v_cndmask_b32_e64 v105, v49, v57, s[8:9]
	v_cndmask_b32_e64 v62, v50, v58, s[16:17]
	v_cndmask_b32_e64 v106, v50, v58, s[8:9]
	v_cndmask_b32_e64 v63, v51, v59, s[16:17]
	v_cndmask_b32_e64 v107, v51, v59, s[8:9]
	v_mov_b32_dpp v60, v60 row_ror:1 row_mask:0xf bank_mask:0xf
	v_mov_b32_dpp v104, v104 row_ror:2 row_mask:0xf bank_mask:0xf
	v_mov_b32_dpp v61, v61 row_ror:1 row_mask:0xf bank_mask:0xf
	v_mov_b32_dpp v105, v105 row_ror:2 row_mask:0xf bank_mask:0xf
	v_mov_b32_dpp v62, v62 row_ror:1 row_mask:0xf bank_mask:0xf
	v_mov_b32_dpp v106, v106 row_ror:2 row_mask:0xf bank_mask:0xf
	v_mov_b32_dpp v63, v63 row_ror:1 row_mask:0xf bank_mask:0xf
	v_mov_b32_dpp v107, v107 row_ror:2 row_mask:0xf bank_mask:0xf
.LBB0_673:
	v_pk_fma_f32 v[56:57], v[94:95], v[70:71], v[102:103]
	v_pk_fma_f32 v[58:59], v[92:93], v[68:69], v[100:101]
	v_pk_fma_f32 v[56:57], v[90:91], v[66:67], v[56:57]
	v_pk_fma_f32 v[58:59], v[88:89], v[64:65], v[58:59]
	v_pk_fma_f32 v[56:57], v[54:55], v[82:83], v[56:57]
	v_pk_fma_f32 v[58:59], v[52:53], v[80:81], v[58:59]
	v_pk_fma_f32 v[64:65], v[86:87], v[106:107], v[98:99]
	v_pk_fma_f32 v[66:67], v[84:85], v[104:105], v[96:97]
	v_pk_fma_f32 v[62:63], v[78:79], v[62:63], v[64:65]
	v_pk_fma_f32 v[60:61], v[76:77], v[60:61], v[66:67]
	v_pk_mul_f32 v[64:65], v[56:57], v[56:57]
	v_pk_mul_f32 v[66:67], v[58:59], v[58:59]
	v_pk_fma_f32 v[64:65], v[64:65], s[84:85], v[246:247] op_sel_hi:[1,0,0]
	v_pk_fma_f32 v[66:67], v[66:67], s[84:85], v[246:247] op_sel_hi:[1,0,0]
	v_pk_mul_f32 v[64:65], v[56:57], v[64:65]
	v_pk_mul_f32 v[66:67], v[58:59], v[66:67]
	v_exp_f32_e32 v64, v64
	v_exp_f32_e32 v66, v66
	v_exp_f32_e32 v65, v65
	v_exp_f32_e32 v67, v67
	v_pk_fma_f32 v[62:63], v[50:51], v[74:75], v[62:63]
	v_pk_fma_f32 v[60:61], v[48:49], v[72:73], v[60:61]
	v_pk_add_f32 v[64:65], v[64:65], 1.0 op_sel_hi:[1,0]
	v_pk_add_f32 v[66:67], v[66:67], 1.0 op_sel_hi:[1,0]
	v_rcp_f32_e32 v64, v64
	v_rcp_f32_e32 v66, v66
	v_rcp_f32_e32 v65, v65
	v_rcp_f32_e32 v67, v67
	v_pk_mul_f32 v[56:57], v[56:57], v[62:63]
	v_pk_mul_f32 v[58:59], v[58:59], v[60:61]
	v_pk_mul_f32 v[56:57], v[56:57], v[64:65]
	v_pk_mul_f32 v[58:59], v[58:59], v[66:67]
	s_nop 0
	v_cvt_pk_bf16_f32 v58, v58, v59
	v_cvt_pk_bf16_f32 v59, v56, v57
	ds_bpermute_b32 v236, v244, v160
	ds_bpermute_b32 v237, v244, v161
	ds_bpermute_b32 v238, v244, v58
	ds_bpermute_b32 v239, v244, v59
	s_waitcnt lgkmcnt(0)
	global_store_dwordx2 v[236:237], v[238:239], off offset:8
	s_and_saveexec_b64 s[6:7], s[34:35]
	s_cbranch_execnz .Lnfs_0_9

; template <int N> __device__ __forceinline__ float dpp_ror(float v) { const int i = __builtin_bit_cast(int, v); return __builtin_bit_cast(float, __builtin_amdgcn_update_dpp(i, i, 0x120 + N, 0xF, 0xF, false)); }
;     __device__ __forceinline__ void operator()(const f32x4 (&acc)[2][2][4][2], const pg8::Unit& u, int wr, int wc, int fr, int fq, PG8_LAS unsigned char* xl) const {
;     ...
;                         if (!sample) { const f32x4 prv = (m == 0) ? hb[bj] : acc[ai][bj][m == 0 ? 0 : m - 1][n];
; #pragma unroll
;                             for (int j = 0; j < 4; ++j) { const float s1 = fr == 15 ? prv[j] : cur[j], s2 = fr >= 14 ? prv[j] : cur[j]; p1[j] = dpp_ror<1>(s1); p2[j] = dpp_ror<2>(s2); }
.LBB0_677:
.LBB0_678:
	v_cndmask_b32_e64 v56, v44, v52, s[16:17]
	v_cndmask_b32_e64 v60, v44, v52, s[8:9]
	v_cndmask_b32_e64 v57, v45, v53, s[16:17]
	v_cndmask_b32_e64 v61, v45, v53, s[8:9]
	v_cndmask_b32_e64 v58, v46, v54, s[16:17]
	v_cndmask_b32_e64 v62, v46, v54, s[8:9]
	v_cndmask_b32_e64 v59, v47, v55, s[16:17]
	v_cndmask_b32_e64 v63, v47, v55, s[8:9]
	v_mov_b32_dpp v56, v56 row_ror:1 row_mask:0xf bank_mask:0xf
	v_mov_b32_dpp v60, v60 row_ror:2 row_mask:0xf bank_mask:0xf
	v_mov_b32_dpp v57, v57 row_ror:1 row_mask:0xf bank_mask:0xf
	v_mov_b32_dpp v61, v61 row_ror:2 row_mask:0xf bank_mask:0xf
	v_mov_b32_dpp v58, v58 row_ror:1 row_mask:0xf bank_mask:0xf
	v_mov_b32_dpp v62, v62 row_ror:2 row_mask:0xf bank_mask:0xf
	v_mov_b32_dpp v59, v59 row_ror:1 row_mask:0xf bank_mask:0xf
	v_mov_b32_dpp v63, v63 row_ror:2 row_mask:0xf bank_mask:0xf

; __device__ __forceinline__ unsigned pk2(float lo, float hi) { const f32x2 v = {lo, hi}; const bf16x2_t b = __builtin_convertvector(v, bf16x2_t); return __builtin_bit_cast(unsigned, b); }
;     __device__ __forceinline__ void operator()(const f32x4 (&acc)[2][2][4][2], const pg8::Unit& u, int wr, int wc, int fr, int fq, PG8_LAS unsigned char* xl) const {
;     ...
;                         const f32x4 cur = acc[ai][bj][m][n]; f32x4 p1, p2;
;                         if (!sample) { const f32x4 prv = (m == 0) ? hb[bj] : acc[ai][bj][m == 0 ? 0 : m - 1][n];
; #pragma unroll
;                             for (int j = 0; j < 4; ++j) { const float s1 = fr == 15 ? prv[j] : cur[j], s2 = fr >= 14 ? prv[j] : cur[j]; p1[j] = dpp_ror<1>(s1); p2[j] = dpp_ror<2>(s2); }
;                         } else { const int t = fr & 3, b = (row - MP) >> 2;
; #pragma unroll
;                             for (int j = 0; j < 4; ++j) { p1[j] = dpp_ror<1>(cur[j]); p2[j] = dpp_ror<2>(cur[j]); }
;                             const f32x4 c1 = *(const f32x4*)(ctx_s + (size_t)(b * 2 + 1) * FF2 + bj * FF + jc0 + 4 * n), c0 = *(const f32x4*)(ctx_s + (size_t)(b * 2) * FF2 + bj * FF + jc0 + 4 * n);
; #pragma unroll
;                             for (int j = 0; j < 4; ++j) { p2[j] = t == 0 ? c0[j] : (t == 1 ? c1[j] : p2[j]); p1[j] = t == 0 ? c1[j] : p1[j]; }
;                         }
;                         cc[bj] = bb[bj] + w0[bj] * p2 + w1[bj] * p1 + w2[bj] * cur;
;                     }
;                     const f32x4 gv = gelu_mul4(cc[0], cc[1]);
;                     u32x2 w; w.x = pk2(gv[0], gv[1]); w.y = pk2(gv[2], gv[3]);
;                     *(u32x2*)(G + (size_t)row * FF + jc0 + 4 * n) = w;
;                     if (!sample && ai == 0 && wr == 0 && m == 0 && fr < 2 && (pm & 7) != 0) {
; #pragma unroll
;                         for (int bj = 0; bj < 2; ++bj) *(f32x4*)(PH + (size_t)(pm * 2 + fr) * FF2 + bj * FF + jc0 + 4 * n) = cc[bj];
;                     }
;                     if (sample && (fr & 3) >= 2) { const int b = (row - MP) >> 2, t = fr & 3;
; #pragma unroll
;                         for (int bj = 0; bj < 2; ++bj) *(f32x4*)(nf_s + (size_t)(b * 2 + t - 2) * FF2 + bj * FF + jc0 + 4 * n) = acc[ai][bj][m][n];
;                     }
.LBB0_681:
.LBB0_682:
	v_cndmask_b32_e64 v52, v40, v48, s[16:17]
	v_cndmask_b32_e64 v64, v40, v48, s[8:9]
	v_cndmask_b32_e64 v53, v41, v49, s[16:17]
	v_cndmask_b32_e64 v65, v41, v49, s[8:9]
	v_cndmask_b32_e64 v54, v42, v50, s[16:17]
	v_cndmask_b32_e64 v66, v42, v50, s[8:9]
	v_cndmask_b32_e64 v55, v43, v51, s[16:17]
	v_cndmask_b32_e64 v67, v43, v51, s[8:9]
	v_mov_b32_dpp v52, v52 row_ror:1 row_mask:0xf bank_mask:0xf
	v_mov_b32_dpp v64, v64 row_ror:2 row_mask:0xf bank_mask:0xf
	v_mov_b32_dpp v53, v53 row_ror:1 row_mask:0xf bank_mask:0xf
	v_mov_b32_dpp v65, v65 row_ror:2 row_mask:0xf bank_mask:0xf
	v_mov_b32_dpp v54, v54 row_ror:1 row_mask:0xf bank_mask:0xf
	v_mov_b32_dpp v66, v66 row_ror:2 row_mask:0xf bank_mask:0xf
	v_mov_b32_dpp v55, v55 row_ror:1 row_mask:0xf bank_mask:0xf
	v_mov_b32_dpp v67, v67 row_ror:2 row_mask:0xf bank_mask:0xf
.LBB0_683:
	v_pk_fma_f32 v[48:49], v[94:95], v[62:63], v[102:103]
	v_pk_fma_f32 v[50:51], v[92:93], v[60:61], v[100:101]
	v_pk_fma_f32 v[48:49], v[90:91], v[58:59], v[48:49]
	v_pk_fma_f32 v[50:51], v[88:89], v[56:57], v[50:51]
	v_pk_fma_f32 v[48:49], v[46:47], v[82:83], v[48:49]
	v_pk_fma_f32 v[50:51], v[44:45], v[80:81], v[50:51]
	v_pk_fma_f32 v[56:57], v[86:87], v[66:67], v[98:99]
	v_pk_fma_f32 v[58:59], v[84:85], v[64:65], v[96:97]
	v_pk_fma_f32 v[54:55], v[78:79], v[54:55], v[56:57]
	v_pk_fma_f32 v[52:53], v[76:77], v[52:53], v[58:59]
	v_pk_mul_f32 v[56:57], v[48:49], v[48:49]
	v_pk_mul_f32 v[58:59], v[50:51], v[50:51]
	v_pk_fma_f32 v[56:57], v[56:57], s[84:85], v[246:247] op_sel_hi:[1,0,0]
	v_pk_fma_f32 v[58:59], v[58:59], s[84:85], v[246:247] op_sel_hi:[1,0,0]
	v_pk_mul_f32 v[56:57], v[48:49], v[56:57]
	v_pk_mul_f32 v[58:59], v[50:51], v[58:59]
	v_exp_f32_e32 v56, v56
	v_exp_f32_e32 v58, v58
	v_exp_f32_e32 v57, v57
	v_exp_f32_e32 v59, v59
	v_pk_fma_f32 v[54:55], v[42:43], v[74:75], v[54:55]
	v_pk_fma_f32 v[52:53], v[40:41], v[72:73], v[52:53]
	v_pk_add_f32 v[56:57], v[56:57], 1.0 op_sel_hi:[1,0]
	v_pk_add_f32 v[58:59], v[58:59], 1.0 op_sel_hi:[1,0]
	v_rcp_f32_e32 v56, v56
	v_rcp_f32_e32 v58, v58
	v_rcp_f32_e32 v57, v57
	v_rcp_f32_e32 v59, v59
	v_pk_mul_f32 v[48:49], v[48:49], v[54:55]
	v_pk_mul_f32 v[50:51], v[50:51], v[52:53]
	v_pk_mul_f32 v[48:49], v[48:49], v[56:57]
	v_pk_mul_f32 v[50:51], v[50:51], v[58:59]
	s_nop 0
	v_cvt_pk_bf16_f32 v50, v50, v51
	v_cvt_pk_bf16_f32 v51, v48, v49
	ds_bpermute_b32 v236, v244, v152
	ds_bpermute_b32 v237, v244, v153
	ds_bpermute_b32 v238, v244, v50
	ds_bpermute_b32 v239, v244, v51
	s_waitcnt lgkmcnt(0)
	global_store_dwordx2 v[236:237], v[238:239], off offset:8
	s_and_saveexec_b64 s[6:7], s[34:35]
	s_cbranch_execnz .Lnfs_0_10

; template <int N> __device__ __forceinline__ float dpp_ror(float v) { const int i = __builtin_bit_cast(int, v); return __builtin_bit_cast(float, __builtin_amdgcn_update_dpp(i, i, 0x120 + N, 0xF, 0xF, false)); }
;     __device__ __forceinline__ void operator()(const f32x4 (&acc)[2][2][4][2], const pg8::Unit& u, int wr, int wc, int fr, int fq, PG8_LAS unsigned char* xl) const {
;     ...
;                         if (!sample) { const f32x4 prv = (m == 0) ? hb[bj] : acc[ai][bj][m == 0 ? 0 : m - 1][n];
; #pragma unroll
;                             for (int j = 0; j < 4; ++j) { const float s1 = fr == 15 ? prv[j] : cur[j], s2 = fr >= 14 ? prv[j] : cur[j]; p1[j] = dpp_ror<1>(s1); p2[j] = dpp_ror<2>(s2); }
.LBB0_689:
.LBB0_690:
	s_waitcnt lgkmcnt(1)
	v_cndmask_b32_e64 v44, v36, v52, s[16:17]
	v_cndmask_b32_e64 v48, v36, v52, s[8:9]
	v_cndmask_b32_e64 v45, v37, v53, s[16:17]
	v_cndmask_b32_e64 v49, v37, v53, s[8:9]
	v_cndmask_b32_e64 v46, v38, v54, s[16:17]
	v_cndmask_b32_e64 v50, v38, v54, s[8:9]
	v_cndmask_b32_e64 v47, v39, v55, s[16:17]
	v_cndmask_b32_e64 v51, v39, v55, s[8:9]
	v_mov_b32_dpp v44, v44 row_ror:1 row_mask:0xf bank_mask:0xf
	v_mov_b32_dpp v48, v48 row_ror:2 row_mask:0xf bank_mask:0xf
	v_mov_b32_dpp v45, v45 row_ror:1 row_mask:0xf bank_mask:0xf
	v_mov_b32_dpp v49, v49 row_ror:2 row_mask:0xf bank_mask:0xf
	v_mov_b32_dpp v46, v46 row_ror:1 row_mask:0xf bank_mask:0xf
	v_mov_b32_dpp v50, v50 row_ror:2 row_mask:0xf bank_mask:0xf
	v_mov_b32_dpp v47, v47 row_ror:1 row_mask:0xf bank_mask:0xf
	v_mov_b32_dpp v51, v51 row_ror:2 row_mask:0xf bank_mask:0xf

; __device__ __forceinline__ unsigned pk2(float lo, float hi) { const f32x2 v = {lo, hi}; const bf16x2_t b = __builtin_convertvector(v, bf16x2_t); return __builtin_bit_cast(unsigned, b); }
;     __device__ __forceinline__ void operator()(const f32x4 (&acc)[2][2][4][2], const pg8::Unit& u, int wr, int wc, int fr, int fq, PG8_LAS unsigned char* xl) const {
;     ...
;                         const f32x4 cur = acc[ai][bj][m][n]; f32x4 p1, p2;
;                         if (!sample) { const f32x4 prv = (m == 0) ? hb[bj] : acc[ai][bj][m == 0 ? 0 : m - 1][n];
; #pragma unroll
;                             for (int j = 0; j < 4; ++j) { const float s1 = fr == 15 ? prv[j] : cur[j], s2 = fr >= 14 ? prv[j] : cur[j]; p1[j] = dpp_ror<1>(s1); p2[j] = dpp_ror<2>(s2); }
;                         } else { const int t = fr & 3, b = (row - MP) >> 2;
; #pragma unroll
;                             for (int j = 0; j < 4; ++j) { p1[j] = dpp_ror<1>(cur[j]); p2[j] = dpp_ror<2>(cur[j]); }
;                             const f32x4 c1 = *(const f32x4*)(ctx_s + (size_t)(b * 2 + 1) * FF2 + bj * FF + jc0 + 4 * n), c0 = *(const f32x4*)(ctx_s + (size_t)(b * 2) * FF2 + bj * FF + jc0 + 4 * n);
; #pragma unroll
;                             for (int j = 0; j < 4; ++j) { p2[j] = t == 0 ? c0[j] : (t == 1 ? c1[j] : p2[j]); p1[j] = t == 0 ? c1[j] : p1[j]; }
;                         }
;                         cc[bj] = bb[bj] + w0[bj] * p2 + w1[bj] * p1 + w2[bj] * cur;
;                     }
;                     const f32x4 gv = gelu_mul4(cc[0], cc[1]);
;                     u32x2 w; w.x = pk2(gv[0], gv[1]); w.y = pk2(gv[2], gv[3]);
;                     *(u32x2*)(G + (size_t)row * FF + jc0 + 4 * n) = w;
;                     if (!sample && ai == 0 && wr == 0 && m == 0 && fr < 2 && (pm & 7) != 0) {
; #pragma unroll
;                         for (int bj = 0; bj < 2; ++bj) *(f32x4*)(PH + (size_t)(pm * 2 + fr) * FF2 + bj * FF + jc0 + 4 * n) = cc[bj];
;                     }
;                     if (sample && (fr & 3) >= 2) { const int b = (row - MP) >> 2, t = fr & 3;
; #pragma unroll
;                         for (int bj = 0; bj < 2; ++bj) *(f32x4*)(nf_s + (size_t)(b * 2 + t - 2) * FF2 + bj * FF + jc0 + 4 * n) = acc[ai][bj][m][n];
;                     }
.LBB0_693:
.LBB0_694:
	s_waitcnt lgkmcnt(0)
	v_cndmask_b32_e64 v52, v32, v40, s[16:17]
	v_cndmask_b32_e64 v56, v32, v40, s[8:9]
	v_cndmask_b32_e64 v53, v33, v41, s[16:17]
	v_cndmask_b32_e64 v57, v33, v41, s[8:9]
	v_cndmask_b32_e64 v54, v34, v42, s[16:17]
	v_cndmask_b32_e64 v58, v34, v42, s[8:9]
	v_cndmask_b32_e64 v55, v35, v43, s[16:17]
	v_cndmask_b32_e64 v59, v35, v43, s[8:9]
	v_mov_b32_dpp v52, v52 row_ror:1 row_mask:0xf bank_mask:0xf
	v_mov_b32_dpp v56, v56 row_ror:2 row_mask:0xf bank_mask:0xf
	v_mov_b32_dpp v53, v53 row_ror:1 row_mask:0xf bank_mask:0xf
	v_mov_b32_dpp v57, v57 row_ror:2 row_mask:0xf bank_mask:0xf
	v_mov_b32_dpp v54, v54 row_ror:1 row_mask:0xf bank_mask:0xf
	v_mov_b32_dpp v58, v58 row_ror:2 row_mask:0xf bank_mask:0xf
	v_mov_b32_dpp v55, v55 row_ror:1 row_mask:0xf bank_mask:0xf
	v_mov_b32_dpp v59, v59 row_ror:2 row_mask:0xf bank_mask:0xf
.LBB0_695:
	s_waitcnt lgkmcnt(0)
	v_pk_fma_f32 v[40:41], v[94:95], v[50:51], v[102:103]
	v_pk_fma_f32 v[42:43], v[92:93], v[48:49], v[100:101]
	v_pk_fma_f32 v[40:41], v[90:91], v[46:47], v[40:41]
	v_pk_fma_f32 v[42:43], v[88:89], v[44:45], v[42:43]
	v_pk_fma_f32 v[40:41], v[38:39], v[82:83], v[40:41]
	v_pk_fma_f32 v[42:43], v[36:37], v[80:81], v[42:43]
	v_pk_fma_f32 v[46:47], v[84:85], v[56:57], v[96:97]
	v_pk_mul_f32 v[48:49], v[40:41], v[40:41]
	v_pk_fma_f32 v[46:47], v[76:77], v[52:53], v[46:47]
	v_pk_mul_f32 v[50:51], v[42:43], v[42:43]
	v_pk_fma_f32 v[48:49], v[48:49], s[84:85], v[246:247] op_sel_hi:[1,0,0]
	v_pk_fma_f32 v[50:51], v[50:51], s[84:85], v[246:247] op_sel_hi:[1,0,0]
	v_pk_mul_f32 v[48:49], v[40:41], v[48:49]
	v_pk_mul_f32 v[50:51], v[42:43], v[50:51]
	v_exp_f32_e32 v48, v48
	v_exp_f32_e32 v50, v50
	v_exp_f32_e32 v49, v49
	v_exp_f32_e32 v51, v51
	v_pk_fma_f32 v[44:45], v[86:87], v[58:59], v[98:99]
	v_pk_fma_f32 v[46:47], v[32:33], v[72:73], v[46:47]
	v_pk_add_f32 v[48:49], v[48:49], 1.0 op_sel_hi:[1,0]
	v_pk_add_f32 v[50:51], v[50:51], 1.0 op_sel_hi:[1,0]
	v_rcp_f32_e32 v48, v48
	v_rcp_f32_e32 v50, v50
	v_rcp_f32_e32 v49, v49
	v_rcp_f32_e32 v51, v51
	v_pk_fma_f32 v[44:45], v[78:79], v[54:55], v[44:45]
	v_pk_mul_f32 v[42:43], v[42:43], v[46:47]
	v_pk_fma_f32 v[44:45], v[34:35], v[74:75], v[44:45]
	v_pk_mul_f32 v[42:43], v[42:43], v[50:51]
	v_pk_mul_f32 v[40:41], v[40:41], v[44:45]
	v_cvt_pk_bf16_f32 v42, v42, v43
	v_pk_mul_f32 v[40:41], v[40:41], v[48:49]
	s_nop 0
	v_cvt_pk_bf16_f32 v43, v40, v41
	ds_bpermute_b32 v236, v244, v144
	ds_bpermute_b32 v237, v244, v145
	ds_bpermute_b32 v238, v244, v42
	ds_bpermute_b32 v239, v244, v43
	s_waitcnt lgkmcnt(0)
	global_store_dwordx2 v[236:237], v[238:239], off offset:8
	s_and_saveexec_b64 s[6:7], s[34:35]
	s_cbranch_execnz .Lnfs_0_11

; template <int N> __device__ __forceinline__ float dpp_ror(float v) { const int i = __builtin_bit_cast(int, v); return __builtin_bit_cast(float, __builtin_amdgcn_update_dpp(i, i, 0x120 + N, 0xF, 0xF, false)); }
;     __device__ __forceinline__ void operator()(const f32x4 (&acc)[2][2][4][2], const pg8::Unit& u, int wr, int wc, int fr, int fq, PG8_LAS unsigned char* xl) const {
;     ...
;                         if (!sample) { const f32x4 prv = (m == 0) ? hb[bj] : acc[ai][bj][m == 0 ? 0 : m - 1][n];
; #pragma unroll
;                             for (int j = 0; j < 4; ++j) { const float s1 = fr == 15 ? prv[j] : cur[j], s2 = fr >= 14 ? prv[j] : cur[j]; p1[j] = dpp_ror<1>(s1); p2[j] = dpp_ror<2>(s2); }
.LBB0_699:
.LBB0_700:
	v_cndmask_b32_e64 v40, v28, v36, s[16:17]
	v_cndmask_b32_e64 v44, v28, v36, s[8:9]
	v_cndmask_b32_e64 v41, v29, v37, s[16:17]
	v_cndmask_b32_e64 v45, v29, v37, s[8:9]
	v_cndmask_b32_e64 v42, v30, v38, s[16:17]
	v_cndmask_b32_e64 v46, v30, v38, s[8:9]
	v_cndmask_b32_e64 v43, v31, v39, s[16:17]
	v_cndmask_b32_e64 v47, v31, v39, s[8:9]
	v_mov_b32_dpp v40, v40 row_ror:1 row_mask:0xf bank_mask:0xf
	v_mov_b32_dpp v44, v44 row_ror:2 row_mask:0xf bank_mask:0xf
	v_mov_b32_dpp v41, v41 row_ror:1 row_mask:0xf bank_mask:0xf
	v_mov_b32_dpp v45, v45 row_ror:2 row_mask:0xf bank_mask:0xf
	v_mov_b32_dpp v42, v42 row_ror:1 row_mask:0xf bank_mask:0xf
	v_mov_b32_dpp v46, v46 row_ror:2 row_mask:0xf bank_mask:0xf
	v_mov_b32_dpp v43, v43 row_ror:1 row_mask:0xf bank_mask:0xf
	v_mov_b32_dpp v47, v47 row_ror:2 row_mask:0xf bank_mask:0xf

; __device__ __forceinline__ unsigned pk2(float lo, float hi) { const f32x2 v = {lo, hi}; const bf16x2_t b = __builtin_convertvector(v, bf16x2_t); return __builtin_bit_cast(unsigned, b); }
;     __device__ __forceinline__ void operator()(const f32x4 (&acc)[2][2][4][2], const pg8::Unit& u, int wr, int wc, int fr, int fq, PG8_LAS unsigned char* xl) const {
;     ...
;                         const f32x4 cur = acc[ai][bj][m][n]; f32x4 p1, p2;
;                         if (!sample) { const f32x4 prv = (m == 0) ? hb[bj] : acc[ai][bj][m == 0 ? 0 : m - 1][n];
; #pragma unroll
;                             for (int j = 0; j < 4; ++j) { const float s1 = fr == 15 ? prv[j] : cur[j], s2 = fr >= 14 ? prv[j] : cur[j]; p1[j] = dpp_ror<1>(s1); p2[j] = dpp_ror<2>(s2); }
;                         } else { const int t = fr & 3, b = (row - MP) >> 2;
; #pragma unroll
;                             for (int j = 0; j < 4; ++j) { p1[j] = dpp_ror<1>(cur[j]); p2[j] = dpp_ror<2>(cur[j]); }
;                             const f32x4 c1 = *(const f32x4*)(ctx_s + (size_t)(b * 2 + 1) * FF2 + bj * FF + jc0 + 4 * n), c0 = *(const f32x4*)(ctx_s + (size_t)(b * 2) * FF2 + bj * FF + jc0 + 4 * n);
; #pragma unroll
;                             for (int j = 0; j < 4; ++j) { p2[j] = t == 0 ? c0[j] : (t == 1 ? c1[j] : p2[j]); p1[j] = t == 0 ? c1[j] : p1[j]; }
;                         }
;                         cc[bj] = bb[bj] + w0[bj] * p2 + w1[bj] * p1 + w2[bj] * cur;
;                     }
;                     const f32x4 gv = gelu_mul4(cc[0], cc[1]);
;                     u32x2 w; w.x = pk2(gv[0], gv[1]); w.y = pk2(gv[2], gv[3]);
;                     *(u32x2*)(G + (size_t)row * FF + jc0 + 4 * n) = w;
;                     if (!sample && ai == 0 && wr == 0 && m == 0 && fr < 2 && (pm & 7) != 0) {
; #pragma unroll
;                         for (int bj = 0; bj < 2; ++bj) *(f32x4*)(PH + (size_t)(pm * 2 + fr) * FF2 + bj * FF + jc0 + 4 * n) = cc[bj];
;                     }
;                     if (sample && (fr & 3) >= 2) { const int b = (row - MP) >> 2, t = fr & 3;
; #pragma unroll
;                         for (int bj = 0; bj < 2; ++bj) *(f32x4*)(nf_s + (size_t)(b * 2 + t - 2) * FF2 + bj * FF + jc0 + 4 * n) = acc[ai][bj][m][n];
;                     }
.LBB0_703:
.LBB0_704:
	v_cndmask_b32_e64 v36, v24, v32, s[16:17]
	v_cndmask_b32_e64 v48, v24, v32, s[8:9]
	v_cndmask_b32_e64 v37, v25, v33, s[16:17]
	v_cndmask_b32_e64 v49, v25, v33, s[8:9]
	v_cndmask_b32_e64 v38, v26, v34, s[16:17]
	v_cndmask_b32_e64 v50, v26, v34, s[8:9]
	v_cndmask_b32_e64 v39, v27, v35, s[16:17]
	v_cndmask_b32_e64 v51, v27, v35, s[8:9]
	v_mov_b32_dpp v36, v36 row_ror:1 row_mask:0xf bank_mask:0xf
	v_mov_b32_dpp v48, v48 row_ror:2 row_mask:0xf bank_mask:0xf
	v_mov_b32_dpp v37, v37 row_ror:1 row_mask:0xf bank_mask:0xf
	v_mov_b32_dpp v49, v49 row_ror:2 row_mask:0xf bank_mask:0xf
	v_mov_b32_dpp v38, v38 row_ror:1 row_mask:0xf bank_mask:0xf
	v_mov_b32_dpp v50, v50 row_ror:2 row_mask:0xf bank_mask:0xf
	v_mov_b32_dpp v39, v39 row_ror:1 row_mask:0xf bank_mask:0xf
	v_mov_b32_dpp v51, v51 row_ror:2 row_mask:0xf bank_mask:0xf
.LBB0_705:
	v_pk_fma_f32 v[32:33], v[94:95], v[46:47], v[102:103]
	v_pk_fma_f32 v[34:35], v[92:93], v[44:45], v[100:101]
	v_pk_fma_f32 v[32:33], v[90:91], v[42:43], v[32:33]
	v_pk_fma_f32 v[34:35], v[88:89], v[40:41], v[34:35]
	v_pk_fma_f32 v[32:33], v[30:31], v[82:83], v[32:33]
	v_pk_fma_f32 v[34:35], v[28:29], v[80:81], v[34:35]
	v_pk_fma_f32 v[40:41], v[86:87], v[50:51], v[98:99]
	v_pk_fma_f32 v[42:43], v[84:85], v[48:49], v[96:97]
	v_pk_fma_f32 v[38:39], v[78:79], v[38:39], v[40:41]
	v_pk_fma_f32 v[36:37], v[76:77], v[36:37], v[42:43]
	v_pk_mul_f32 v[40:41], v[32:33], v[32:33]
	v_pk_mul_f32 v[42:43], v[34:35], v[34:35]
	v_pk_fma_f32 v[40:41], v[40:41], s[84:85], v[246:247] op_sel_hi:[1,0,0]
	v_pk_fma_f32 v[42:43], v[42:43], s[84:85], v[246:247] op_sel_hi:[1,0,0]
	v_pk_mul_f32 v[40:41], v[32:33], v[40:41]
	v_pk_mul_f32 v[42:43], v[34:35], v[42:43]
	v_exp_f32_e32 v40, v40
	v_exp_f32_e32 v42, v42
	v_exp_f32_e32 v41, v41
	v_exp_f32_e32 v43, v43
	v_pk_fma_f32 v[38:39], v[26:27], v[74:75], v[38:39]
	v_pk_fma_f32 v[36:37], v[24:25], v[72:73], v[36:37]
	v_pk_add_f32 v[40:41], v[40:41], 1.0 op_sel_hi:[1,0]
	v_pk_add_f32 v[42:43], v[42:43], 1.0 op_sel_hi:[1,0]
	v_rcp_f32_e32 v40, v40
	v_rcp_f32_e32 v42, v42
	v_rcp_f32_e32 v41, v41
	v_rcp_f32_e32 v43, v43
	v_pk_mul_f32 v[32:33], v[32:33], v[38:39]
	v_pk_mul_f32 v[34:35], v[34:35], v[36:37]
	v_pk_mul_f32 v[32:33], v[32:33], v[40:41]
	v_pk_mul_f32 v[34:35], v[34:35], v[42:43]
	s_nop 0
	v_cvt_pk_bf16_f32 v34, v34, v35
	v_cvt_pk_bf16_f32 v35, v32, v33
	ds_bpermute_b32 v236, v244, v136
	ds_bpermute_b32 v237, v244, v137
	ds_bpermute_b32 v238, v244, v34
	ds_bpermute_b32 v239, v244, v35
	s_waitcnt lgkmcnt(0)
	global_store_dwordx2 v[236:237], v[238:239], off offset:8
	s_and_saveexec_b64 s[6:7], s[34:35]
	s_cbranch_execnz .Lnfs_0_12

; template <int N> __device__ __forceinline__ float dpp_ror(float v) { const int i = __builtin_bit_cast(int, v); return __builtin_bit_cast(float, __builtin_amdgcn_update_dpp(i, i, 0x120 + N, 0xF, 0xF, false)); }
;     __device__ __forceinline__ void operator()(const f32x4 (&acc)[2][2][4][2], const pg8::Unit& u, int wr, int wc, int fr, int fq, PG8_LAS unsigned char* xl) const {
;     ...
;                         if (!sample) { const f32x4 prv = (m == 0) ? hb[bj] : acc[ai][bj][m == 0 ? 0 : m - 1][n];
; #pragma unroll
;                             for (int j = 0; j < 4; ++j) { const float s1 = fr == 15 ? prv[j] : cur[j], s2 = fr >= 14 ? prv[j] : cur[j]; p1[j] = dpp_ror<1>(s1); p2[j] = dpp_ror<2>(s2); }
.LBB0_709:
.LBB0_710:
	v_cndmask_b32_e64 v32, v20, v28, s[16:17]
	v_cndmask_b32_e64 v36, v20, v28, s[8:9]
	v_cndmask_b32_e64 v33, v21, v29, s[16:17]
	v_cndmask_b32_e64 v37, v21, v29, s[8:9]
	v_cndmask_b32_e64 v34, v22, v30, s[16:17]
	v_cndmask_b32_e64 v38, v22, v30, s[8:9]
	v_cndmask_b32_e64 v35, v23, v31, s[16:17]
	v_cndmask_b32_e64 v39, v23, v31, s[8:9]
	v_mov_b32_dpp v32, v32 row_ror:1 row_mask:0xf bank_mask:0xf
	v_mov_b32_dpp v36, v36 row_ror:2 row_mask:0xf bank_mask:0xf
	v_mov_b32_dpp v33, v33 row_ror:1 row_mask:0xf bank_mask:0xf
	v_mov_b32_dpp v37, v37 row_ror:2 row_mask:0xf bank_mask:0xf
	v_mov_b32_dpp v34, v34 row_ror:1 row_mask:0xf bank_mask:0xf
	v_mov_b32_dpp v38, v38 row_ror:2 row_mask:0xf bank_mask:0xf
	v_mov_b32_dpp v35, v35 row_ror:1 row_mask:0xf bank_mask:0xf
	v_mov_b32_dpp v39, v39 row_ror:2 row_mask:0xf bank_mask:0xf

; __device__ __forceinline__ unsigned pk2(float lo, float hi) { const f32x2 v = {lo, hi}; const bf16x2_t b = __builtin_convertvector(v, bf16x2_t); return __builtin_bit_cast(unsigned, b); }
;     __device__ __forceinline__ void operator()(const f32x4 (&acc)[2][2][4][2], const pg8::Unit& u, int wr, int wc, int fr, int fq, PG8_LAS unsigned char* xl) const {
;     ...
;                         const f32x4 cur = acc[ai][bj][m][n]; f32x4 p1, p2;
;                         if (!sample) { const f32x4 prv = (m == 0) ? hb[bj] : acc[ai][bj][m == 0 ? 0 : m - 1][n];
; #pragma unroll
;                             for (int j = 0; j < 4; ++j) { const float s1 = fr == 15 ? prv[j] : cur[j], s2 = fr >= 14 ? prv[j] : cur[j]; p1[j] = dpp_ror<1>(s1); p2[j] = dpp_ror<2>(s2); }
;                         } else { const int t = fr & 3, b = (row - MP) >> 2;
; #pragma unroll
;                             for (int j = 0; j < 4; ++j) { p1[j] = dpp_ror<1>(cur[j]); p2[j] = dpp_ror<2>(cur[j]); }
;                             const f32x4 c1 = *(const f32x4*)(ctx_s + (size_t)(b * 2 + 1) * FF2 + bj * FF + jc0 + 4 * n), c0 = *(const f32x4*)(ctx_s + (size_t)(b * 2) * FF2 + bj * FF + jc0 + 4 * n);
; #pragma unroll
;                             for (int j = 0; j < 4; ++j) { p2[j] = t == 0 ? c0[j] : (t == 1 ? c1[j] : p2[j]); p1[j] = t == 0 ? c1[j] : p1[j]; }
;                         }
;                         cc[bj] = bb[bj] + w0[bj] * p2 + w1[bj] * p1 + w2[bj] * cur;
;                     }
;                     const f32x4 gv = gelu_mul4(cc[0], cc[1]);
;                     u32x2 w; w.x = pk2(gv[0], gv[1]); w.y = pk2(gv[2], gv[3]);
;                     *(u32x2*)(G + (size_t)row * FF + jc0 + 4 * n) = w;
;                     if (!sample && ai == 0 && wr == 0 && m == 0 && fr < 2 && (pm & 7) != 0) {
; #pragma unroll
;                         for (int bj = 0; bj < 2; ++bj) *(f32x4*)(PH + (size_t)(pm * 2 + fr) * FF2 + bj * FF + jc0 + 4 * n) = cc[bj];
;                     }
;                     if (sample && (fr & 3) >= 2) { const int b = (row - MP) >> 2, t = fr & 3;
; #pragma unroll
;                         for (int bj = 0; bj < 2; ++bj) *(f32x4*)(nf_s + (size_t)(b * 2 + t - 2) * FF2 + bj * FF + jc0 + 4 * n) = acc[ai][bj][m][n];
;                     }
.LBB0_713:
.LBB0_714:
	v_cndmask_b32_e64 v28, v16, v24, s[16:17]
	v_cndmask_b32_e64 v40, v16, v24, s[8:9]
	v_cndmask_b32_e64 v29, v17, v25, s[16:17]
	v_cndmask_b32_e64 v41, v17, v25, s[8:9]
	v_cndmask_b32_e64 v30, v18, v26, s[16:17]
	v_cndmask_b32_e64 v42, v18, v26, s[8:9]
	v_cndmask_b32_e64 v31, v19, v27, s[16:17]
	v_cndmask_b32_e64 v43, v19, v27, s[8:9]
	v_mov_b32_dpp v28, v28 row_ror:1 row_mask:0xf bank_mask:0xf
	v_mov_b32_dpp v40, v40 row_ror:2 row_mask:0xf bank_mask:0xf
	v_mov_b32_dpp v29, v29 row_ror:1 row_mask:0xf bank_mask:0xf
	v_mov_b32_dpp v41, v41 row_ror:2 row_mask:0xf bank_mask:0xf
	v_mov_b32_dpp v30, v30 row_ror:1 row_mask:0xf bank_mask:0xf
	v_mov_b32_dpp v42, v42 row_ror:2 row_mask:0xf bank_mask:0xf
	v_mov_b32_dpp v31, v31 row_ror:1 row_mask:0xf bank_mask:0xf
	v_mov_b32_dpp v43, v43 row_ror:2 row_mask:0xf bank_mask:0xf
.LBB0_715:
	v_pk_fma_f32 v[24:25], v[94:95], v[38:39], v[102:103]
	v_pk_fma_f32 v[26:27], v[92:93], v[36:37], v[100:101]
	v_pk_fma_f32 v[24:25], v[90:91], v[34:35], v[24:25]
	v_pk_fma_f32 v[26:27], v[88:89], v[32:33], v[26:27]
	v_pk_fma_f32 v[24:25], v[22:23], v[82:83], v[24:25]
	v_pk_fma_f32 v[26:27], v[20:21], v[80:81], v[26:27]
	v_pk_fma_f32 v[32:33], v[86:87], v[42:43], v[98:99]
	v_pk_fma_f32 v[34:35], v[84:85], v[40:41], v[96:97]
	v_pk_fma_f32 v[30:31], v[78:79], v[30:31], v[32:33]
	v_pk_fma_f32 v[28:29], v[76:77], v[28:29], v[34:35]
	v_pk_mul_f32 v[32:33], v[24:25], v[24:25]
	v_pk_mul_f32 v[34:35], v[26:27], v[26:27]
	v_pk_fma_f32 v[32:33], v[32:33], s[84:85], v[246:247] op_sel_hi:[1,0,0]
	v_pk_fma_f32 v[34:35], v[34:35], s[84:85], v[246:247] op_sel_hi:[1,0,0]
	v_pk_mul_f32 v[32:33], v[24:25], v[32:33]
	v_pk_mul_f32 v[34:35], v[26:27], v[34:35]
	v_exp_f32_e32 v32, v32
	v_exp_f32_e32 v34, v34
	v_exp_f32_e32 v33, v33
	v_exp_f32_e32 v35, v35
	v_pk_fma_f32 v[30:31], v[18:19], v[74:75], v[30:31]
	v_pk_fma_f32 v[28:29], v[16:17], v[72:73], v[28:29]
	v_pk_add_f32 v[32:33], v[32:33], 1.0 op_sel_hi:[1,0]
	v_pk_add_f32 v[34:35], v[34:35], 1.0 op_sel_hi:[1,0]
	v_rcp_f32_e32 v32, v32
	v_rcp_f32_e32 v34, v34
	v_rcp_f32_e32 v33, v33
	v_rcp_f32_e32 v35, v35
	v_pk_mul_f32 v[24:25], v[24:25], v[30:31]
	v_pk_mul_f32 v[26:27], v[26:27], v[28:29]
	v_pk_mul_f32 v[24:25], v[24:25], v[32:33]
	v_pk_mul_f32 v[26:27], v[26:27], v[34:35]
	s_nop 0
	v_cvt_pk_bf16_f32 v26, v26, v27
	v_cvt_pk_bf16_f32 v27, v24, v25
	ds_bpermute_b32 v236, v244, v128
	ds_bpermute_b32 v237, v244, v129
	ds_bpermute_b32 v238, v244, v26
	ds_bpermute_b32 v239, v244, v27
	s_waitcnt lgkmcnt(0)
	global_store_dwordx2 v[236:237], v[238:239], off offset:8
	s_and_saveexec_b64 s[6:7], s[34:35]
	s_cbranch_execnz .Lnfs_0_13

; template <int N> __device__ __forceinline__ float dpp_ror(float v) { const int i = __builtin_bit_cast(int, v); return __builtin_bit_cast(float, __builtin_amdgcn_update_dpp(i, i, 0x120 + N, 0xF, 0xF, false)); }
;     __device__ __forceinline__ void operator()(const f32x4 (&acc)[2][2][4][2], const pg8::Unit& u, int wr, int wc, int fr, int fq, PG8_LAS unsigned char* xl) const {
;     ...
;                         if (!sample) { const f32x4 prv = (m == 0) ? hb[bj] : acc[ai][bj][m == 0 ? 0 : m - 1][n];
; #pragma unroll
;                             for (int j = 0; j < 4; ++j) { const float s1 = fr == 15 ? prv[j] : cur[j], s2 = fr >= 14 ? prv[j] : cur[j]; p1[j] = dpp_ror<1>(s1); p2[j] = dpp_ror<2>(s2); }
.LBB0_719:
.LBB0_720:
	v_cndmask_b32_e64 v24, v8, v20, s[16:17]
	v_cndmask_b32_e64 v28, v8, v20, s[8:9]
	v_cndmask_b32_e64 v25, v9, v21, s[16:17]
	v_cndmask_b32_e64 v29, v9, v21, s[8:9]
	v_cndmask_b32_e64 v26, v10, v22, s[16:17]
	v_cndmask_b32_e64 v30, v10, v22, s[8:9]
	v_cndmask_b32_e64 v27, v11, v23, s[16:17]
	v_cndmask_b32_e64 v31, v11, v23, s[8:9]
	v_mov_b32_dpp v24, v24 row_ror:1 row_mask:0xf bank_mask:0xf
	v_mov_b32_dpp v28, v28 row_ror:2 row_mask:0xf bank_mask:0xf
	v_mov_b32_dpp v25, v25 row_ror:1 row_mask:0xf bank_mask:0xf
	v_mov_b32_dpp v29, v29 row_ror:2 row_mask:0xf bank_mask:0xf
	v_mov_b32_dpp v26, v26 row_ror:1 row_mask:0xf bank_mask:0xf
	v_mov_b32_dpp v30, v30 row_ror:2 row_mask:0xf bank_mask:0xf
	v_mov_b32_dpp v27, v27 row_ror:1 row_mask:0xf bank_mask:0xf
	v_mov_b32_dpp v31, v31 row_ror:2 row_mask:0xf bank_mask:0xf

; __device__ __forceinline__ unsigned pk2(float lo, float hi) { const f32x2 v = {lo, hi}; const bf16x2_t b = __builtin_convertvector(v, bf16x2_t); return __builtin_bit_cast(unsigned, b); }
;     __device__ __forceinline__ void operator()(const f32x4 (&acc)[2][2][4][2], const pg8::Unit& u, int wr, int wc, int fr, int fq, PG8_LAS unsigned char* xl) const {
;     ...
;                         const f32x4 cur = acc[ai][bj][m][n]; f32x4 p1, p2;
;                         if (!sample) { const f32x4 prv = (m == 0) ? hb[bj] : acc[ai][bj][m == 0 ? 0 : m - 1][n];
; #pragma unroll
;                             for (int j = 0; j < 4; ++j) { const float s1 = fr == 15 ? prv[j] : cur[j], s2 = fr >= 14 ? prv[j] : cur[j]; p1[j] = dpp_ror<1>(s1); p2[j] = dpp_ror<2>(s2); }
;                         } else { const int t = fr & 3, b = (row - MP) >> 2;
; #pragma unroll
;                             for (int j = 0; j < 4; ++j) { p1[j] = dpp_ror<1>(cur[j]); p2[j] = dpp_ror<2>(cur[j]); }
;                             const f32x4 c1 = *(const f32x4*)(ctx_s + (size_t)(b * 2 + 1) * FF2 + bj * FF + jc0 + 4 * n), c0 = *(const f32x4*)(ctx_s + (size_t)(b * 2) * FF2 + bj * FF + jc0 + 4 * n);
; #pragma unroll
;                             for (int j = 0; j < 4; ++j) { p2[j] = t == 0 ? c0[j] : (t == 1 ? c1[j] : p2[j]); p1[j] = t == 0 ? c1[j] : p1[j]; }
;                         }
;                         cc[bj] = bb[bj] + w0[bj] * p2 + w1[bj] * p1 + w2[bj] * cur;
;                     }
;                     const f32x4 gv = gelu_mul4(cc[0], cc[1]);
;                     u32x2 w; w.x = pk2(gv[0], gv[1]); w.y = pk2(gv[2], gv[3]);
;                     *(u32x2*)(G + (size_t)row * FF + jc0 + 4 * n) = w;
;                     if (!sample && ai == 0 && wr == 0 && m == 0 && fr < 2 && (pm & 7) != 0) {
; #pragma unroll
;                         for (int bj = 0; bj < 2; ++bj) *(f32x4*)(PH + (size_t)(pm * 2 + fr) * FF2 + bj * FF + jc0 + 4 * n) = cc[bj];
;                     }
;                     if (sample && (fr & 3) >= 2) { const int b = (row - MP) >> 2, t = fr & 3;
; #pragma unroll
;                         for (int bj = 0; bj < 2; ++bj) *(f32x4*)(nf_s + (size_t)(b * 2 + t - 2) * FF2 + bj * FF + jc0 + 4 * n) = acc[ai][bj][m][n];
;                     }
.LBB0_723:
.LBB0_724:
	v_cndmask_b32_e64 v20, v0, v16, s[16:17]
	v_cndmask_b32_e64 v32, v0, v16, s[8:9]
	v_cndmask_b32_e64 v21, v1, v17, s[16:17]
	v_cndmask_b32_e64 v33, v1, v17, s[8:9]
	v_cndmask_b32_e64 v22, v2, v18, s[16:17]
	v_cndmask_b32_e64 v34, v2, v18, s[8:9]
	v_cndmask_b32_e64 v23, v3, v19, s[16:17]
	v_cndmask_b32_e64 v35, v3, v19, s[8:9]
	v_mov_b32_dpp v20, v20 row_ror:1 row_mask:0xf bank_mask:0xf
	v_mov_b32_dpp v32, v32 row_ror:2 row_mask:0xf bank_mask:0xf
	v_mov_b32_dpp v21, v21 row_ror:1 row_mask:0xf bank_mask:0xf
	v_mov_b32_dpp v33, v33 row_ror:2 row_mask:0xf bank_mask:0xf
	v_mov_b32_dpp v22, v22 row_ror:1 row_mask:0xf bank_mask:0xf
	v_mov_b32_dpp v34, v34 row_ror:2 row_mask:0xf bank_mask:0xf
	v_mov_b32_dpp v23, v23 row_ror:1 row_mask:0xf bank_mask:0xf
	v_mov_b32_dpp v35, v35 row_ror:2 row_mask:0xf bank_mask:0xf
.LBB0_725:
	v_pk_fma_f32 v[16:17], v[94:95], v[30:31], v[102:103]
	v_pk_fma_f32 v[18:19], v[92:93], v[28:29], v[100:101]
	v_pk_fma_f32 v[16:17], v[90:91], v[26:27], v[16:17]
	v_pk_fma_f32 v[18:19], v[88:89], v[24:25], v[18:19]
	v_pk_fma_f32 v[16:17], v[10:11], v[82:83], v[16:17]
	v_pk_fma_f32 v[18:19], v[8:9], v[80:81], v[18:19]
	v_pk_fma_f32 v[24:25], v[86:87], v[34:35], v[98:99]
	v_pk_fma_f32 v[26:27], v[84:85], v[32:33], v[96:97]
	v_pk_fma_f32 v[22:23], v[78:79], v[22:23], v[24:25]
	v_pk_fma_f32 v[20:21], v[76:77], v[20:21], v[26:27]
	v_pk_mul_f32 v[24:25], v[16:17], v[16:17]
	v_pk_mul_f32 v[26:27], v[18:19], v[18:19]
	v_pk_fma_f32 v[24:25], v[24:25], s[84:85], v[246:247] op_sel_hi:[1,0,0]
	v_pk_fma_f32 v[26:27], v[26:27], s[84:85], v[246:247] op_sel_hi:[1,0,0]
	v_pk_mul_f32 v[24:25], v[16:17], v[24:25]
	v_pk_mul_f32 v[26:27], v[18:19], v[26:27]
	v_exp_f32_e32 v24, v24
	v_exp_f32_e32 v26, v26
	v_exp_f32_e32 v25, v25
	v_exp_f32_e32 v27, v27
	v_pk_fma_f32 v[22:23], v[2:3], v[74:75], v[22:23]
	v_pk_fma_f32 v[20:21], v[0:1], v[72:73], v[20:21]
	v_pk_add_f32 v[24:25], v[24:25], 1.0 op_sel_hi:[1,0]
	v_pk_add_f32 v[26:27], v[26:27], 1.0 op_sel_hi:[1,0]
	v_rcp_f32_e32 v24, v24
	v_rcp_f32_e32 v26, v26
	v_rcp_f32_e32 v25, v25
	v_rcp_f32_e32 v27, v27
	v_pk_mul_f32 v[16:17], v[16:17], v[22:23]
	v_pk_mul_f32 v[18:19], v[18:19], v[20:21]
	v_pk_mul_f32 v[16:17], v[16:17], v[24:25]
	v_pk_mul_f32 v[18:19], v[18:19], v[26:27]
	s_nop 0
	v_cvt_pk_bf16_f32 v18, v18, v19
	v_cvt_pk_bf16_f32 v19, v16, v17
	ds_bpermute_b32 v236, v244, v130
	ds_bpermute_b32 v237, v244, v131
	ds_bpermute_b32 v238, v244, v18
	ds_bpermute_b32 v239, v244, v19
	s_waitcnt lgkmcnt(0)
	global_store_dwordx2 v[236:237], v[238:239], off offset:8
	s_branch .Lisl_end_0
.Lnfs_0_0:
	v_mov_b64_e32 v[160:161], s[24:25]
	v_mad_i64_i32 v[160:161], vcc, v224, s36, v[160:161]
	v_lshl_add_u64 v[160:161], v[196:197], 2, v[160:161]
	global_store_dwordx4 v[160:161], v[156:159], off
	v_add_co_u32_e32 v160, vcc, 0x2000, v160
	s_nop 1
	v_addc_co_u32_e32 v161, vcc, 0, v161, vcc
	global_store_dwordx4 v[160:161], v[152:155], off offset:3072
	s_branch .LBB0_569
.Lsmp_0_0:
	v_or_b32_e32 v162, 1, v160
	v_mov_b64_e32 v[160:161], s[40:41]
	v_mad_i64_i32 v[162:163], vcc, v162, s36, v[160:161]
	v_mad_i64_i32 v[160:161], vcc, v226, s36, v[160:161]
	v_lshl_add_u64 v[174:175], v[162:163], 0, v[198:199]
	v_lshl_add_u64 v[172:173], v[160:161], 0, v[198:199]
	global_load_dwordx4 v[160:163], v[174:175], off
	global_load_dwordx4 v[164:167], v[172:173], off
	v_mov_b32_e32 v168, v148
	v_mov_b32_e32 v169, v148
	v_mov_b32_e32 v170, v149
	v_mov_b32_e32 v171, v149
	v_mov_b32_e32 v228, v150
	v_mov_b32_e32 v230, v151
	v_mov_b32_e32 v227, v150
	v_mov_b32_e32 v229, v151
	v_mov_b32_dpp v168, v168 row_ror:1 row_mask:0xf bank_mask:0xf
	v_mov_b32_dpp v169, v169 row_ror:2 row_mask:0xf bank_mask:0xf
	v_mov_b32_dpp v170, v170 row_ror:1 row_mask:0xf bank_mask:0xf
	v_mov_b32_dpp v171, v171 row_ror:2 row_mask:0xf bank_mask:0xf
	v_mov_b32_dpp v228, v228 row_ror:2 row_mask:0xf bank_mask:0xf
	v_mov_b32_dpp v230, v230 row_ror:2 row_mask:0xf bank_mask:0xf
	v_mov_b32_dpp v227, v227 row_ror:1 row_mask:0xf bank_mask:0xf
	v_mov_b32_dpp v229, v229 row_ror:1 row_mask:0xf bank_mask:0xf
	s_waitcnt vmcnt(1)
	v_cndmask_b32_e64 v169, v169, v160, s[14:15]
	v_cndmask_b32_e64 v160, v168, v160, s[12:13]
	v_cndmask_b32_e64 v168, v171, v161, s[14:15]
	v_cndmask_b32_e64 v161, v170, v161, s[12:13]
	v_cndmask_b32_e64 v170, v228, v162, s[14:15]
	v_cndmask_b32_e64 v171, v230, v163, s[14:15]
	v_cndmask_b32_e64 v162, v227, v162, s[12:13]
	v_cndmask_b32_e64 v163, v229, v163, s[12:13]
	s_waitcnt vmcnt(0)
	v_cndmask_b32_e64 v164, v169, v164, s[12:13]
	v_cndmask_b32_e64 v165, v168, v165, s[12:13]
	v_cndmask_b32_e64 v166, v170, v166, s[12:13]
	v_cndmask_b32_e64 v167, v171, v167, s[12:13]
	s_branch .LBB0_573
.Lsmp_0_1:
	v_add_co_u32_e32 v156, vcc, 0x2000, v174
	v_mov_b32_e32 v227, v144
	s_nop 0
	v_addc_co_u32_e32 v157, vcc, 0, v175, vcc
	v_add_co_u32_e32 v168, vcc, 0x2000, v172
	global_load_dwordx4 v[156:159], v[156:157], off offset:3072
	s_nop 0
	v_addc_co_u32_e32 v169, vcc, 0, v173, vcc
	global_load_dwordx4 v[168:171], v[168:169], off offset:3072
	v_mov_b32_e32 v228, v144
	v_mov_b32_e32 v229, v145
	v_mov_b32_e32 v230, v145
	v_mov_b32_e32 v232, v146
	v_mov_b32_e32 v234, v147
	v_mov_b32_e32 v231, v146
	v_mov_b32_e32 v233, v147
	v_mov_b32_dpp v227, v227 row_ror:1 row_mask:0xf bank_mask:0xf
	v_mov_b32_dpp v228, v228 row_ror:2 row_mask:0xf bank_mask:0xf
	v_mov_b32_dpp v229, v229 row_ror:1 row_mask:0xf bank_mask:0xf
	v_mov_b32_dpp v230, v230 row_ror:2 row_mask:0xf bank_mask:0xf
	v_mov_b32_dpp v232, v232 row_ror:2 row_mask:0xf bank_mask:0xf
	v_mov_b32_dpp v234, v234 row_ror:2 row_mask:0xf bank_mask:0xf
	v_mov_b32_dpp v231, v231 row_ror:1 row_mask:0xf bank_mask:0xf
	v_mov_b32_dpp v233, v233 row_ror:1 row_mask:0xf bank_mask:0xf
	s_waitcnt vmcnt(1)
	v_cndmask_b32_e64 v228, v228, v156, s[14:15]
	v_cndmask_b32_e64 v156, v227, v156, s[12:13]
	v_cndmask_b32_e64 v227, v230, v157, s[14:15]
	v_cndmask_b32_e64 v157, v229, v157, s[12:13]
	v_cndmask_b32_e64 v229, v232, v158, s[14:15]
	v_cndmask_b32_e64 v230, v234, v159, s[14:15]
	v_cndmask_b32_e64 v158, v231, v158, s[12:13]
	v_cndmask_b32_e64 v159, v233, v159, s[12:13]
	s_waitcnt vmcnt(0)
	v_cndmask_b32_e64 v168, v228, v168, s[12:13]
	v_cndmask_b32_e64 v169, v227, v169, s[12:13]
	v_cndmask_b32_e64 v170, v229, v170, s[12:13]
	v_cndmask_b32_e64 v171, v230, v171, s[12:13]
	s_branch .LBB0_577
; template <int N> __device__ __forceinline__ float dpp_ror(float v) { const int i = __builtin_bit_cast(int, v); return __builtin_bit_cast(float, __builtin_amdgcn_update_dpp(i, i, 0x120 + N, 0xF, 0xF, false)); }
;     __device__ __forceinline__ void operator()(const f32x4 (&acc)[2][2][4][2], const pg8::Unit& u, int wr, int wc, int fr, int fq, PG8_LAS unsigned char* xl) const {
;     ...
;                         } else { const int t = fr & 3, b = (row - MP) >> 2;
; #pragma unroll
;                             for (int j = 0; j < 4; ++j) { p1[j] = dpp_ror<1>(cur[j]); p2[j] = dpp_ror<2>(cur[j]); }
;                             const f32x4 c1 = *(const f32x4*)(ctx_s + (size_t)(b * 2 + 1) * FF2 + bj * FF + jc0 + 4 * n), c0 = *(const f32x4*)(ctx_s + (size_t)(b * 2) * FF2 + bj * FF + jc0 + 4 * n);
; #pragma unroll
;                             for (int j = 0; j < 4; ++j) { p2[j] = t == 0 ? c0[j] : (t == 1 ? c1[j] : p2[j]); p1[j] = t == 0 ? c1[j] : p1[j]; }
;                         }
;     ...
;                     if (sample && (fr & 3) >= 2) { const int b = (row - MP) >> 2, t = fr & 3;
; #pragma unroll
;                         for (int bj = 0; bj < 2; ++bj) *(f32x4*)(nf_s + (size_t)(b * 2 + t - 2) * FF2 + bj * FF + jc0 + 4 * n) = acc[ai][bj][m][n];
;                     }
.Lnfs_0_1:
	v_mov_b64_e32 v[152:153], s[24:25]
	v_mad_i64_i32 v[152:153], vcc, v170, s36, v[152:153]
	v_lshl_add_u64 v[152:153], v[196:197], 2, v[152:153]
	global_store_dwordx4 v[152:153], v[148:151], off
	v_add_co_u32_e32 v152, vcc, 0x2000, v152
	s_nop 1
	v_addc_co_u32_e32 v153, vcc, 0, v153, vcc
	global_store_dwordx4 v[152:153], v[144:147], off offset:3072
	s_branch .LBB0_579
.Lsmp_0_2:
	v_or_b32_e32 v154, 1, v152
	v_mov_b64_e32 v[152:153], s[40:41]
	v_mad_i64_i32 v[154:155], vcc, v154, s36, v[152:153]
	v_mad_i64_i32 v[152:153], vcc, v171, s36, v[152:153]
	v_lshl_add_u64 v[166:167], v[154:155], 0, v[198:199]
	v_lshl_add_u64 v[164:165], v[152:153], 0, v[198:199]
	global_load_dwordx4 v[152:155], v[166:167], off
	global_load_dwordx4 v[156:159], v[164:165], off
	v_mov_b32_e32 v160, v140
	v_mov_b32_e32 v161, v140
	v_mov_b32_e32 v162, v141
	v_mov_b32_e32 v163, v141
	v_mov_b32_e32 v227, v142
	v_mov_b32_e32 v229, v143
	v_mov_b32_e32 v226, v142
	v_mov_b32_e32 v228, v143
	v_mov_b32_dpp v160, v160 row_ror:1 row_mask:0xf bank_mask:0xf
	v_mov_b32_dpp v161, v161 row_ror:2 row_mask:0xf bank_mask:0xf
	v_mov_b32_dpp v162, v162 row_ror:1 row_mask:0xf bank_mask:0xf
	v_mov_b32_dpp v163, v163 row_ror:2 row_mask:0xf bank_mask:0xf
	v_mov_b32_dpp v227, v227 row_ror:2 row_mask:0xf bank_mask:0xf
	v_mov_b32_dpp v229, v229 row_ror:2 row_mask:0xf bank_mask:0xf
	v_mov_b32_dpp v226, v226 row_ror:1 row_mask:0xf bank_mask:0xf
	v_mov_b32_dpp v228, v228 row_ror:1 row_mask:0xf bank_mask:0xf
	s_waitcnt vmcnt(1)
	v_cndmask_b32_e64 v161, v161, v152, s[14:15]
	v_cndmask_b32_e64 v152, v160, v152, s[12:13]
	v_cndmask_b32_e64 v160, v163, v153, s[14:15]
	v_cndmask_b32_e64 v153, v162, v153, s[12:13]
	v_cndmask_b32_e64 v162, v227, v154, s[14:15]
	v_cndmask_b32_e64 v163, v229, v155, s[14:15]
	v_cndmask_b32_e64 v154, v226, v154, s[12:13]
	v_cndmask_b32_e64 v155, v228, v155, s[12:13]
	s_waitcnt vmcnt(0)
	v_cndmask_b32_e64 v156, v161, v156, s[12:13]
	v_cndmask_b32_e64 v157, v160, v157, s[12:13]
	v_cndmask_b32_e64 v158, v162, v158, s[12:13]
	v_cndmask_b32_e64 v159, v163, v159, s[12:13]
	s_branch .LBB0_583
.Lsmp_0_3:
	v_add_co_u32_e32 v148, vcc, 0x2000, v166
	v_mov_b32_e32 v226, v136
	s_nop 0
	v_addc_co_u32_e32 v149, vcc, 0, v167, vcc
	v_add_co_u32_e32 v160, vcc, 0x2000, v164
	global_load_dwordx4 v[148:151], v[148:149], off offset:3072
	s_nop 0
	v_addc_co_u32_e32 v161, vcc, 0, v165, vcc
	global_load_dwordx4 v[160:163], v[160:161], off offset:3072
	v_mov_b32_e32 v227, v136
	v_mov_b32_e32 v228, v137
	v_mov_b32_e32 v229, v137
	v_mov_b32_e32 v231, v138
	v_mov_b32_e32 v233, v139
	v_mov_b32_e32 v230, v138
	v_mov_b32_e32 v232, v139
	v_mov_b32_dpp v226, v226 row_ror:1 row_mask:0xf bank_mask:0xf
	v_mov_b32_dpp v227, v227 row_ror:2 row_mask:0xf bank_mask:0xf
	v_mov_b32_dpp v228, v228 row_ror:1 row_mask:0xf bank_mask:0xf
	v_mov_b32_dpp v229, v229 row_ror:2 row_mask:0xf bank_mask:0xf
	v_mov_b32_dpp v231, v231 row_ror:2 row_mask:0xf bank_mask:0xf
	v_mov_b32_dpp v233, v233 row_ror:2 row_mask:0xf bank_mask:0xf
	v_mov_b32_dpp v230, v230 row_ror:1 row_mask:0xf bank_mask:0xf
	v_mov_b32_dpp v232, v232 row_ror:1 row_mask:0xf bank_mask:0xf
	s_waitcnt vmcnt(1)
	v_cndmask_b32_e64 v227, v227, v148, s[14:15]
	v_cndmask_b32_e64 v148, v226, v148, s[12:13]
	v_cndmask_b32_e64 v226, v229, v149, s[14:15]
	v_cndmask_b32_e64 v149, v228, v149, s[12:13]
	v_cndmask_b32_e64 v228, v231, v150, s[14:15]
	v_cndmask_b32_e64 v229, v233, v151, s[14:15]
	v_cndmask_b32_e64 v150, v230, v150, s[12:13]
	v_cndmask_b32_e64 v151, v232, v151, s[12:13]
	s_waitcnt vmcnt(0)
	v_cndmask_b32_e64 v160, v227, v160, s[12:13]
	v_cndmask_b32_e64 v161, v226, v161, s[12:13]
	v_cndmask_b32_e64 v162, v228, v162, s[12:13]
	v_cndmask_b32_e64 v163, v229, v163, s[12:13]
	s_branch .LBB0_587
.Lnfs_0_2:
	v_mov_b64_e32 v[144:145], s[24:25]
	v_mad_i64_i32 v[144:145], vcc, v162, s36, v[144:145]
	v_lshl_add_u64 v[144:145], v[196:197], 2, v[144:145]
	global_store_dwordx4 v[144:145], v[140:143], off
	v_add_co_u32_e32 v144, vcc, 0x2000, v144
	s_nop 1
	v_addc_co_u32_e32 v145, vcc, 0, v145, vcc
	global_store_dwordx4 v[144:145], v[136:139], off offset:3072
	s_branch .LBB0_589
.Lsmp_0_4:
	v_or_b32_e32 v146, 1, v144
	v_mov_b64_e32 v[144:145], s[40:41]
	v_mad_i64_i32 v[146:147], vcc, v146, s36, v[144:145]
	v_mad_i64_i32 v[144:145], vcc, v163, s36, v[144:145]
	v_lshl_add_u64 v[158:159], v[146:147], 0, v[198:199]
	v_lshl_add_u64 v[156:157], v[144:145], 0, v[198:199]
	global_load_dwordx4 v[144:147], v[158:159], off
	global_load_dwordx4 v[148:151], v[156:157], off
	v_mov_b32_e32 v152, v132
	v_mov_b32_e32 v153, v132
	v_mov_b32_e32 v154, v133
	v_mov_b32_e32 v155, v133
	v_mov_b32_e32 v226, v134
	v_mov_b32_e32 v228, v135
	v_mov_b32_e32 v171, v134
	v_mov_b32_e32 v227, v135
	v_mov_b32_dpp v152, v152 row_ror:1 row_mask:0xf bank_mask:0xf
	v_mov_b32_dpp v153, v153 row_ror:2 row_mask:0xf bank_mask:0xf
	v_mov_b32_dpp v154, v154 row_ror:1 row_mask:0xf bank_mask:0xf
	v_mov_b32_dpp v155, v155 row_ror:2 row_mask:0xf bank_mask:0xf
	v_mov_b32_dpp v226, v226 row_ror:2 row_mask:0xf bank_mask:0xf
	v_mov_b32_dpp v228, v228 row_ror:2 row_mask:0xf bank_mask:0xf
	v_mov_b32_dpp v171, v171 row_ror:1 row_mask:0xf bank_mask:0xf
	v_mov_b32_dpp v227, v227 row_ror:1 row_mask:0xf bank_mask:0xf
	s_waitcnt vmcnt(1)
	v_cndmask_b32_e64 v153, v153, v144, s[14:15]
	v_cndmask_b32_e64 v144, v152, v144, s[12:13]
	v_cndmask_b32_e64 v152, v155, v145, s[14:15]
	v_cndmask_b32_e64 v145, v154, v145, s[12:13]
	v_cndmask_b32_e64 v154, v226, v146, s[14:15]
	v_cndmask_b32_e64 v155, v228, v147, s[14:15]
	v_cndmask_b32_e64 v146, v171, v146, s[12:13]
	v_cndmask_b32_e64 v147, v227, v147, s[12:13]
	s_waitcnt vmcnt(0)
	v_cndmask_b32_e64 v148, v153, v148, s[12:13]
	v_cndmask_b32_e64 v149, v152, v149, s[12:13]
	v_cndmask_b32_e64 v150, v154, v150, s[12:13]
	v_cndmask_b32_e64 v151, v155, v151, s[12:13]
	s_branch .LBB0_593
; template <int N> __device__ __forceinline__ float dpp_ror(float v) { const int i = __builtin_bit_cast(int, v); return __builtin_bit_cast(float, __builtin_amdgcn_update_dpp(i, i, 0x120 + N, 0xF, 0xF, false)); }
;     __device__ __forceinline__ void operator()(const f32x4 (&acc)[2][2][4][2], const pg8::Unit& u, int wr, int wc, int fr, int fq, PG8_LAS unsigned char* xl) const {
;     ...
;                         } else { const int t = fr & 3, b = (row - MP) >> 2;
; #pragma unroll
;                             for (int j = 0; j < 4; ++j) { p1[j] = dpp_ror<1>(cur[j]); p2[j] = dpp_ror<2>(cur[j]); }
;                             const f32x4 c1 = *(const f32x4*)(ctx_s + (size_t)(b * 2 + 1) * FF2 + bj * FF + jc0 + 4 * n), c0 = *(const f32x4*)(ctx_s + (size_t)(b * 2) * FF2 + bj * FF + jc0 + 4 * n);
; #pragma unroll
;                             for (int j = 0; j < 4; ++j) { p2[j] = t == 0 ? c0[j] : (t == 1 ? c1[j] : p2[j]); p1[j] = t == 0 ? c1[j] : p1[j]; }
;                         }
;     ...
;                     if (sample && (fr & 3) >= 2) { const int b = (row - MP) >> 2, t = fr & 3;
; #pragma unroll
;                         for (int bj = 0; bj < 2; ++bj) *(f32x4*)(nf_s + (size_t)(b * 2 + t - 2) * FF2 + bj * FF + jc0 + 4 * n) = acc[ai][bj][m][n];
;                     }
.Lsmp_0_5:
	v_add_co_u32_e32 v140, vcc, 0x2000, v158
	v_mov_b32_e32 v171, v128
	s_nop 0
	v_addc_co_u32_e32 v141, vcc, 0, v159, vcc
	v_add_co_u32_e32 v152, vcc, 0x2000, v156
	global_load_dwordx4 v[140:143], v[140:141], off offset:3072
	s_nop 0
	v_addc_co_u32_e32 v153, vcc, 0, v157, vcc
	global_load_dwordx4 v[152:155], v[152:153], off offset:3072
	v_mov_b32_e32 v226, v128
	v_mov_b32_e32 v227, v129
	v_mov_b32_e32 v228, v129
	v_mov_b32_e32 v230, v130
	v_mov_b32_e32 v232, v131
	v_mov_b32_e32 v229, v130
	v_mov_b32_e32 v231, v131
	v_mov_b32_dpp v171, v171 row_ror:1 row_mask:0xf bank_mask:0xf
	v_mov_b32_dpp v226, v226 row_ror:2 row_mask:0xf bank_mask:0xf
	v_mov_b32_dpp v227, v227 row_ror:1 row_mask:0xf bank_mask:0xf
	v_mov_b32_dpp v228, v228 row_ror:2 row_mask:0xf bank_mask:0xf
	v_mov_b32_dpp v230, v230 row_ror:2 row_mask:0xf bank_mask:0xf
	v_mov_b32_dpp v232, v232 row_ror:2 row_mask:0xf bank_mask:0xf
	v_mov_b32_dpp v229, v229 row_ror:1 row_mask:0xf bank_mask:0xf
	v_mov_b32_dpp v231, v231 row_ror:1 row_mask:0xf bank_mask:0xf
	s_waitcnt vmcnt(1)
	v_cndmask_b32_e64 v226, v226, v140, s[14:15]
	v_cndmask_b32_e64 v140, v171, v140, s[12:13]
	v_cndmask_b32_e64 v171, v228, v141, s[14:15]
	v_cndmask_b32_e64 v141, v227, v141, s[12:13]
	v_cndmask_b32_e64 v227, v230, v142, s[14:15]
	v_cndmask_b32_e64 v228, v232, v143, s[14:15]
	v_cndmask_b32_e64 v142, v229, v142, s[12:13]
	v_cndmask_b32_e64 v143, v231, v143, s[12:13]
	s_waitcnt vmcnt(0)
	v_cndmask_b32_e64 v152, v226, v152, s[12:13]
	v_cndmask_b32_e64 v153, v171, v153, s[12:13]
	v_cndmask_b32_e64 v154, v227, v154, s[12:13]
	v_cndmask_b32_e64 v155, v228, v155, s[12:13]
	s_branch .LBB0_597
.Lnfs_0_3:
	v_mov_b64_e32 v[136:137], s[24:25]
	v_mad_i64_i32 v[136:137], vcc, v154, s36, v[136:137]
	v_lshl_add_u64 v[136:137], v[196:197], 2, v[136:137]
	global_store_dwordx4 v[136:137], v[132:135], off
	s_nop 1
	v_add_co_u32_e32 v132, vcc, 0x2000, v136
	s_nop 1
	v_addc_co_u32_e32 v133, vcc, 0, v137, vcc
	global_store_dwordx4 v[132:133], v[128:131], off offset:3072
	s_branch .LBB0_599
.Lsmp_0_6:
	v_or_b32_e32 v134, 1, v132
	v_mov_b64_e32 v[132:133], s[40:41]
	v_mad_i64_i32 v[134:135], vcc, v134, s36, v[132:133]
	v_mad_i64_i32 v[132:133], vcc, v155, s36, v[132:133]
	v_lshl_add_u64 v[150:151], v[134:135], 0, v[198:199]
	v_lshl_add_u64 v[148:149], v[132:133], 0, v[198:199]
	global_load_dwordx4 v[132:135], v[150:151], off
	global_load_dwordx4 v[136:139], v[148:149], off
	v_mov_b32_e32 v144, v124
	v_mov_b32_e32 v145, v124
	v_mov_b32_e32 v146, v125
	v_mov_b32_e32 v147, v125
	v_mov_b32_e32 v171, v126
	v_mov_b32_e32 v227, v127
	v_mov_b32_e32 v163, v126
	v_mov_b32_e32 v226, v127
	v_mov_b32_dpp v144, v144 row_ror:1 row_mask:0xf bank_mask:0xf
	v_mov_b32_dpp v145, v145 row_ror:2 row_mask:0xf bank_mask:0xf
	v_mov_b32_dpp v146, v146 row_ror:1 row_mask:0xf bank_mask:0xf
	v_mov_b32_dpp v147, v147 row_ror:2 row_mask:0xf bank_mask:0xf
	v_mov_b32_dpp v171, v171 row_ror:2 row_mask:0xf bank_mask:0xf
	v_mov_b32_dpp v227, v227 row_ror:2 row_mask:0xf bank_mask:0xf
	v_mov_b32_dpp v163, v163 row_ror:1 row_mask:0xf bank_mask:0xf
	v_mov_b32_dpp v226, v226 row_ror:1 row_mask:0xf bank_mask:0xf
	s_waitcnt vmcnt(1)
	v_cndmask_b32_e64 v145, v145, v132, s[14:15]
	v_cndmask_b32_e64 v132, v144, v132, s[12:13]
	v_cndmask_b32_e64 v144, v147, v133, s[14:15]
	v_cndmask_b32_e64 v133, v146, v133, s[12:13]
	v_cndmask_b32_e64 v146, v171, v134, s[14:15]
	v_cndmask_b32_e64 v147, v227, v135, s[14:15]
	v_cndmask_b32_e64 v134, v163, v134, s[12:13]
	v_cndmask_b32_e64 v135, v226, v135, s[12:13]
	s_waitcnt vmcnt(0)
	v_cndmask_b32_e64 v136, v145, v136, s[12:13]
	v_cndmask_b32_e64 v137, v144, v137, s[12:13]
	v_cndmask_b32_e64 v138, v146, v138, s[12:13]
	v_cndmask_b32_e64 v139, v147, v139, s[12:13]
	s_branch .LBB0_605
.Lsmp_0_7:
	s_waitcnt lgkmcnt(1)
	v_add_co_u32_e32 v140, vcc, 0x2000, v150
	v_mov_b32_e32 v163, v88
	s_nop 0
	v_addc_co_u32_e32 v141, vcc, 0, v151, vcc
	v_add_co_u32_e32 v144, vcc, 0x2000, v148
	global_load_dwordx4 v[140:143], v[140:141], off offset:3072
	s_nop 0
	v_addc_co_u32_e32 v145, vcc, 0, v149, vcc
	global_load_dwordx4 v[144:147], v[144:145], off offset:3072
	v_mov_b32_e32 v171, v88
	v_mov_b32_e32 v226, v89
	v_mov_b32_e32 v227, v89
	v_mov_b32_e32 v229, v90
	v_mov_b32_e32 v231, v91
	v_mov_b32_e32 v228, v90
	v_mov_b32_e32 v230, v91
	v_mov_b32_dpp v163, v163 row_ror:1 row_mask:0xf bank_mask:0xf
	v_mov_b32_dpp v171, v171 row_ror:2 row_mask:0xf bank_mask:0xf
	v_mov_b32_dpp v226, v226 row_ror:1 row_mask:0xf bank_mask:0xf
	v_mov_b32_dpp v227, v227 row_ror:2 row_mask:0xf bank_mask:0xf
	v_mov_b32_dpp v229, v229 row_ror:2 row_mask:0xf bank_mask:0xf
	v_mov_b32_dpp v231, v231 row_ror:2 row_mask:0xf bank_mask:0xf
	v_mov_b32_dpp v228, v228 row_ror:1 row_mask:0xf bank_mask:0xf
	v_mov_b32_dpp v230, v230 row_ror:1 row_mask:0xf bank_mask:0xf
	s_waitcnt vmcnt(1)
	v_cndmask_b32_e64 v171, v171, v140, s[14:15]
	v_cndmask_b32_e64 v140, v163, v140, s[12:13]
	v_cndmask_b32_e64 v163, v227, v141, s[14:15]
	v_cndmask_b32_e64 v141, v226, v141, s[12:13]
	v_cndmask_b32_e64 v226, v229, v142, s[14:15]
	v_cndmask_b32_e64 v227, v231, v143, s[14:15]
	v_cndmask_b32_e64 v142, v228, v142, s[12:13]
	v_cndmask_b32_e64 v143, v230, v143, s[12:13]
	s_waitcnt vmcnt(0)
	v_cndmask_b32_e64 v144, v171, v144, s[12:13]
	v_cndmask_b32_e64 v145, v163, v145, s[12:13]
	v_cndmask_b32_e64 v146, v226, v146, s[12:13]
	v_cndmask_b32_e64 v147, v227, v147, s[12:13]
	s_branch .LBB0_609
.Lnfs_0_4:
	v_mov_b64_e32 v[128:129], s[24:25]
	v_mad_i64_i32 v[128:129], vcc, v146, s36, v[128:129]
	v_lshl_add_u64 v[128:129], v[196:197], 2, v[128:129]
	global_store_dwordx4 v[128:129], v[124:127], off
	v_add_co_u32_e32 v128, vcc, 0x2000, v128
	s_nop 1
	v_addc_co_u32_e32 v129, vcc, 0, v129, vcc
	global_store_dwordx4 v[128:129], v[88:91], off offset:3072
	s_branch .LBB0_611
; template <int N> __device__ __forceinline__ float dpp_ror(float v) { const int i = __builtin_bit_cast(int, v); return __builtin_bit_cast(float, __builtin_amdgcn_update_dpp(i, i, 0x120 + N, 0xF, 0xF, false)); }
;     __device__ __forceinline__ void operator()(const f32x4 (&acc)[2][2][4][2], const pg8::Unit& u, int wr, int wc, int fr, int fq, PG8_LAS unsigned char* xl) const {
;     ...
;                         } else { const int t = fr & 3, b = (row - MP) >> 2;
; #pragma unroll
;                             for (int j = 0; j < 4; ++j) { p1[j] = dpp_ror<1>(cur[j]); p2[j] = dpp_ror<2>(cur[j]); }
;                             const f32x4 c1 = *(const f32x4*)(ctx_s + (size_t)(b * 2 + 1) * FF2 + bj * FF + jc0 + 4 * n), c0 = *(const f32x4*)(ctx_s + (size_t)(b * 2) * FF2 + bj * FF + jc0 + 4 * n);
; #pragma unroll
;                             for (int j = 0; j < 4; ++j) { p2[j] = t == 0 ? c0[j] : (t == 1 ? c1[j] : p2[j]); p1[j] = t == 0 ? c1[j] : p1[j]; }
;                         }
;     ...
;                     if (sample && (fr & 3) >= 2) { const int b = (row - MP) >> 2, t = fr & 3;
; #pragma unroll
;                         for (int bj = 0; bj < 2; ++bj) *(f32x4*)(nf_s + (size_t)(b * 2 + t - 2) * FF2 + bj * FF + jc0 + 4 * n) = acc[ai][bj][m][n];
;                     }
.Lsmp_0_8:
	v_or_b32_e32 v130, 1, v128
	v_mov_b64_e32 v[128:129], s[40:41]
	v_mad_i64_i32 v[130:131], vcc, v130, s36, v[128:129]
	v_mad_i64_i32 v[128:129], vcc, v147, s36, v[128:129]
	v_lshl_add_u64 v[142:143], v[130:131], 0, v[198:199]
	v_lshl_add_u64 v[140:141], v[128:129], 0, v[198:199]
	global_load_dwordx4 v[128:131], v[142:143], off
	global_load_dwordx4 v[132:135], v[140:141], off
	v_mov_b32_e32 v136, v84
	v_mov_b32_e32 v137, v84
	v_mov_b32_e32 v138, v85
	v_mov_b32_e32 v139, v85
	v_mov_b32_e32 v163, v86
	v_mov_b32_e32 v226, v87
	v_mov_b32_e32 v155, v86
	v_mov_b32_e32 v171, v87
	v_mov_b32_dpp v136, v136 row_ror:1 row_mask:0xf bank_mask:0xf
	v_mov_b32_dpp v137, v137 row_ror:2 row_mask:0xf bank_mask:0xf
	v_mov_b32_dpp v138, v138 row_ror:1 row_mask:0xf bank_mask:0xf
	v_mov_b32_dpp v139, v139 row_ror:2 row_mask:0xf bank_mask:0xf
	v_mov_b32_dpp v163, v163 row_ror:2 row_mask:0xf bank_mask:0xf
	v_mov_b32_dpp v226, v226 row_ror:2 row_mask:0xf bank_mask:0xf
	v_mov_b32_dpp v155, v155 row_ror:1 row_mask:0xf bank_mask:0xf
	v_mov_b32_dpp v171, v171 row_ror:1 row_mask:0xf bank_mask:0xf
	s_waitcnt vmcnt(1)
	v_cndmask_b32_e64 v137, v137, v128, s[14:15]
	v_cndmask_b32_e64 v128, v136, v128, s[12:13]
	v_cndmask_b32_e64 v136, v139, v129, s[14:15]
	v_cndmask_b32_e64 v129, v138, v129, s[12:13]
	v_cndmask_b32_e64 v138, v163, v130, s[14:15]
	v_cndmask_b32_e64 v139, v226, v131, s[14:15]
	v_cndmask_b32_e64 v130, v155, v130, s[12:13]
	v_cndmask_b32_e64 v131, v171, v131, s[12:13]
	s_waitcnt vmcnt(0)
	v_cndmask_b32_e64 v132, v137, v132, s[12:13]
	v_cndmask_b32_e64 v133, v136, v133, s[12:13]
	v_cndmask_b32_e64 v134, v138, v134, s[12:13]
	v_cndmask_b32_e64 v135, v139, v135, s[12:13]
	s_branch .LBB0_615
.Lsmp_0_9:
	v_add_co_u32_e32 v124, vcc, 0x2000, v142
	v_mov_b32_e32 v155, v80
	s_nop 0
	v_addc_co_u32_e32 v125, vcc, 0, v143, vcc
	v_add_co_u32_e32 v136, vcc, 0x2000, v140
	global_load_dwordx4 v[124:127], v[124:125], off offset:3072
	s_nop 0
	v_addc_co_u32_e32 v137, vcc, 0, v141, vcc
	global_load_dwordx4 v[136:139], v[136:137], off offset:3072
	v_mov_b32_e32 v163, v80
	v_mov_b32_e32 v171, v81
	v_mov_b32_e32 v226, v81
	v_mov_b32_e32 v228, v82
	v_mov_b32_e32 v230, v83
	v_mov_b32_e32 v227, v82
	v_mov_b32_e32 v229, v83
	v_mov_b32_dpp v155, v155 row_ror:1 row_mask:0xf bank_mask:0xf
	v_mov_b32_dpp v163, v163 row_ror:2 row_mask:0xf bank_mask:0xf
	v_mov_b32_dpp v171, v171 row_ror:1 row_mask:0xf bank_mask:0xf
	v_mov_b32_dpp v226, v226 row_ror:2 row_mask:0xf bank_mask:0xf
	v_mov_b32_dpp v228, v228 row_ror:2 row_mask:0xf bank_mask:0xf
	v_mov_b32_dpp v230, v230 row_ror:2 row_mask:0xf bank_mask:0xf
	v_mov_b32_dpp v227, v227 row_ror:1 row_mask:0xf bank_mask:0xf
	v_mov_b32_dpp v229, v229 row_ror:1 row_mask:0xf bank_mask:0xf
	s_waitcnt vmcnt(1)
	v_cndmask_b32_e64 v163, v163, v124, s[14:15]
	v_cndmask_b32_e64 v124, v155, v124, s[12:13]
	v_cndmask_b32_e64 v155, v226, v125, s[14:15]
	v_cndmask_b32_e64 v125, v171, v125, s[12:13]
	v_cndmask_b32_e64 v171, v228, v126, s[14:15]
	v_cndmask_b32_e64 v226, v230, v127, s[14:15]
	v_cndmask_b32_e64 v126, v227, v126, s[12:13]
	v_cndmask_b32_e64 v127, v229, v127, s[12:13]
	s_waitcnt vmcnt(0)
	v_cndmask_b32_e64 v136, v163, v136, s[12:13]
	v_cndmask_b32_e64 v137, v155, v137, s[12:13]
	v_cndmask_b32_e64 v138, v171, v138, s[12:13]
	v_cndmask_b32_e64 v139, v226, v139, s[12:13]
	s_branch .LBB0_619
.Lnfs_0_5:
	v_mov_b64_e32 v[88:89], s[24:25]
	v_mad_i64_i32 v[88:89], vcc, v138, s36, v[88:89]
	v_lshl_add_u64 v[88:89], v[196:197], 2, v[88:89]
	global_store_dwordx4 v[88:89], v[84:87], off
	v_add_co_u32_e32 v88, vcc, 0x2000, v88
	s_nop 1
	v_addc_co_u32_e32 v89, vcc, 0, v89, vcc
	global_store_dwordx4 v[88:89], v[80:83], off offset:3072
	s_branch .LBB0_621
.Lsmp_0_10:
	v_or_b32_e32 v90, 1, v88
	v_mov_b64_e32 v[88:89], s[40:41]
	v_mad_i64_i32 v[90:91], vcc, v90, s36, v[88:89]
	v_mad_i64_i32 v[88:89], vcc, v139, s36, v[88:89]
	v_lshl_add_u64 v[134:135], v[90:91], 0, v[198:199]
	v_lshl_add_u64 v[132:133], v[88:89], 0, v[198:199]
	global_load_dwordx4 v[88:91], v[134:135], off
	global_load_dwordx4 v[124:127], v[132:133], off
	v_mov_b32_e32 v128, v76
	v_mov_b32_e32 v129, v76
	v_mov_b32_e32 v130, v77
	v_mov_b32_e32 v131, v77
	v_mov_b32_e32 v155, v78
	v_mov_b32_e32 v171, v79
	v_mov_b32_e32 v147, v78
	v_mov_b32_e32 v163, v79
	v_mov_b32_dpp v128, v128 row_ror:1 row_mask:0xf bank_mask:0xf
	v_mov_b32_dpp v129, v129 row_ror:2 row_mask:0xf bank_mask:0xf
	v_mov_b32_dpp v130, v130 row_ror:1 row_mask:0xf bank_mask:0xf
	v_mov_b32_dpp v131, v131 row_ror:2 row_mask:0xf bank_mask:0xf
	v_mov_b32_dpp v155, v155 row_ror:2 row_mask:0xf bank_mask:0xf
	v_mov_b32_dpp v171, v171 row_ror:2 row_mask:0xf bank_mask:0xf
	v_mov_b32_dpp v147, v147 row_ror:1 row_mask:0xf bank_mask:0xf
	v_mov_b32_dpp v163, v163 row_ror:1 row_mask:0xf bank_mask:0xf
	s_waitcnt vmcnt(1)
	v_cndmask_b32_e64 v129, v129, v88, s[14:15]
	v_cndmask_b32_e64 v88, v128, v88, s[12:13]
	v_cndmask_b32_e64 v128, v131, v89, s[14:15]
	v_cndmask_b32_e64 v89, v130, v89, s[12:13]
	v_cndmask_b32_e64 v130, v155, v90, s[14:15]
	v_cndmask_b32_e64 v131, v171, v91, s[14:15]
	v_cndmask_b32_e64 v90, v147, v90, s[12:13]
	v_cndmask_b32_e64 v91, v163, v91, s[12:13]
	s_waitcnt vmcnt(0)
	v_cndmask_b32_e64 v124, v129, v124, s[12:13]
	v_cndmask_b32_e64 v125, v128, v125, s[12:13]
	v_cndmask_b32_e64 v126, v130, v126, s[12:13]
	v_cndmask_b32_e64 v127, v131, v127, s[12:13]
	s_branch .LBB0_625
; __device__ __forceinline__ unsigned pk2(float lo, float hi) { const f32x2 v = {lo, hi}; const bf16x2_t b = __builtin_convertvector(v, bf16x2_t); return __builtin_bit_cast(unsigned, b); }
; template <int N> __device__ __forceinline__ float dpp_ror(float v) { const int i = __builtin_bit_cast(int, v); return __builtin_bit_cast(float, __builtin_amdgcn_update_dpp(i, i, 0x120 + N, 0xF, 0xF, false)); }
;     __device__ __forceinline__ void operator()(const f32x4 (&acc)[2][2][4][2], const pg8::Unit& u, int wr, int wc, int fr, int fq, PG8_LAS unsigned char* xl) const {
;     ...
;                         } else { const int t = fr & 3, b = (row - MP) >> 2;
; #pragma unroll
;                             for (int j = 0; j < 4; ++j) { p1[j] = dpp_ror<1>(cur[j]); p2[j] = dpp_ror<2>(cur[j]); }
;                             const f32x4 c1 = *(const f32x4*)(ctx_s + (size_t)(b * 2 + 1) * FF2 + bj * FF + jc0 + 4 * n), c0 = *(const f32x4*)(ctx_s + (size_t)(b * 2) * FF2 + bj * FF + jc0 + 4 * n);
; #pragma unroll
;                             for (int j = 0; j < 4; ++j) { p2[j] = t == 0 ? c0[j] : (t == 1 ? c1[j] : p2[j]); p1[j] = t == 0 ? c1[j] : p1[j]; }
;                         }
;                         cc[bj] = bb[bj] + w0[bj] * p2 + w1[bj] * p1 + w2[bj] * cur;
;                     }
;                     const f32x4 gv = gelu_mul4(cc[0], cc[1]);
;                     u32x2 w; w.x = pk2(gv[0], gv[1]); w.y = pk2(gv[2], gv[3]);
;                     *(u32x2*)(G + (size_t)row * FF + jc0 + 4 * n) = w;
;                     if (!sample && ai == 0 && wr == 0 && m == 0 && fr < 2 && (pm & 7) != 0) {
; #pragma unroll
;                         for (int bj = 0; bj < 2; ++bj) *(f32x4*)(PH + (size_t)(pm * 2 + fr) * FF2 + bj * FF + jc0 + 4 * n) = cc[bj];
;                     }
;                     if (sample && (fr & 3) >= 2) { const int b = (row - MP) >> 2, t = fr & 3;
; #pragma unroll
;                         for (int bj = 0; bj < 2; ++bj) *(f32x4*)(nf_s + (size_t)(b * 2 + t - 2) * FF2 + bj * FF + jc0 + 4 * n) = acc[ai][bj][m][n];
;                     }
.Lsmp_0_11:
	v_add_co_u32_e32 v84, vcc, 0x2000, v134
	v_mov_b32_e32 v147, v72
	s_nop 0
	v_addc_co_u32_e32 v85, vcc, 0, v135, vcc
	v_add_co_u32_e32 v128, vcc, 0x2000, v132
	global_load_dwordx4 v[84:87], v[84:85], off offset:3072
	s_nop 0
	v_addc_co_u32_e32 v129, vcc, 0, v133, vcc
	global_load_dwordx4 v[128:131], v[128:129], off offset:3072
	v_mov_b32_e32 v155, v72
	v_mov_b32_e32 v163, v73
	v_mov_b32_e32 v171, v73
	v_mov_b32_e32 v227, v74
	v_mov_b32_e32 v229, v75
	v_mov_b32_e32 v226, v74
	v_mov_b32_e32 v228, v75
	v_mov_b32_dpp v147, v147 row_ror:1 row_mask:0xf bank_mask:0xf
	v_mov_b32_dpp v155, v155 row_ror:2 row_mask:0xf bank_mask:0xf
	v_mov_b32_dpp v163, v163 row_ror:1 row_mask:0xf bank_mask:0xf
	v_mov_b32_dpp v171, v171 row_ror:2 row_mask:0xf bank_mask:0xf
	v_mov_b32_dpp v227, v227 row_ror:2 row_mask:0xf bank_mask:0xf
	v_mov_b32_dpp v229, v229 row_ror:2 row_mask:0xf bank_mask:0xf
	v_mov_b32_dpp v226, v226 row_ror:1 row_mask:0xf bank_mask:0xf
	v_mov_b32_dpp v228, v228 row_ror:1 row_mask:0xf bank_mask:0xf
	s_waitcnt vmcnt(1)
	v_cndmask_b32_e64 v155, v155, v84, s[14:15]
	v_cndmask_b32_e64 v84, v147, v84, s[12:13]
	v_cndmask_b32_e64 v147, v171, v85, s[14:15]
	v_cndmask_b32_e64 v85, v163, v85, s[12:13]
	v_cndmask_b32_e64 v163, v227, v86, s[14:15]
	v_cndmask_b32_e64 v171, v229, v87, s[14:15]
	v_cndmask_b32_e64 v86, v226, v86, s[12:13]
	v_cndmask_b32_e64 v87, v228, v87, s[12:13]
	s_waitcnt vmcnt(0)
	v_cndmask_b32_e64 v128, v155, v128, s[12:13]
	v_cndmask_b32_e64 v129, v147, v129, s[12:13]
	v_cndmask_b32_e64 v130, v163, v130, s[12:13]
	v_cndmask_b32_e64 v131, v171, v131, s[12:13]
	s_branch .LBB0_629
.Lnfs_0_6:
	v_mov_b64_e32 v[80:81], s[24:25]
	v_mad_i64_i32 v[80:81], vcc, v139, s36, v[80:81]
	v_lshl_add_u64 v[80:81], v[196:197], 2, v[80:81]
	global_store_dwordx4 v[80:81], v[76:79], off
	v_add_co_u32_e32 v80, vcc, 0x2000, v80
	s_nop 1
	v_addc_co_u32_e32 v81, vcc, 0, v81, vcc
	global_store_dwordx4 v[80:81], v[72:75], off offset:3072
	s_branch .LBB0_631
.Lsmp_0_12:
	v_or_b32_e32 v82, 1, v80
	v_mov_b64_e32 v[80:81], s[40:41]
	v_mad_i64_i32 v[82:83], vcc, v82, s36, v[80:81]
	v_mad_i64_i32 v[80:81], vcc, v147, s36, v[80:81]
	v_lshl_add_u64 v[126:127], v[82:83], 0, v[198:199]
	v_lshl_add_u64 v[124:125], v[80:81], 0, v[198:199]
	global_load_dwordx4 v[80:83], v[126:127], off
	global_load_dwordx4 v[84:87], v[124:125], off
	v_mov_b32_e32 v88, v12
	v_mov_b32_e32 v89, v12
	v_mov_b32_e32 v90, v13
	v_mov_b32_e32 v91, v13
	v_mov_b32_e32 v131, v14
	v_mov_b32_e32 v163, v15
	v_mov_b32_e32 v130, v14
	v_mov_b32_e32 v155, v15
	v_mov_b32_dpp v88, v88 row_ror:1 row_mask:0xf bank_mask:0xf
	v_mov_b32_dpp v89, v89 row_ror:2 row_mask:0xf bank_mask:0xf
	v_mov_b32_dpp v90, v90 row_ror:1 row_mask:0xf bank_mask:0xf
	v_mov_b32_dpp v91, v91 row_ror:2 row_mask:0xf bank_mask:0xf
	v_mov_b32_dpp v131, v131 row_ror:2 row_mask:0xf bank_mask:0xf
	v_mov_b32_dpp v163, v163 row_ror:2 row_mask:0xf bank_mask:0xf
	v_mov_b32_dpp v130, v130 row_ror:1 row_mask:0xf bank_mask:0xf
	v_mov_b32_dpp v155, v155 row_ror:1 row_mask:0xf bank_mask:0xf
	s_waitcnt vmcnt(1)
	v_cndmask_b32_e64 v89, v89, v80, s[14:15]
	v_cndmask_b32_e64 v80, v88, v80, s[12:13]
	v_cndmask_b32_e64 v88, v91, v81, s[14:15]
	v_cndmask_b32_e64 v81, v90, v81, s[12:13]
	v_cndmask_b32_e64 v90, v131, v82, s[14:15]
	v_cndmask_b32_e64 v91, v163, v83, s[14:15]
	v_cndmask_b32_e64 v82, v130, v82, s[12:13]
	v_cndmask_b32_e64 v83, v155, v83, s[12:13]
	s_waitcnt vmcnt(0)
	v_cndmask_b32_e64 v84, v89, v84, s[12:13]
	v_cndmask_b32_e64 v85, v88, v85, s[12:13]
	v_cndmask_b32_e64 v86, v90, v86, s[12:13]
	v_cndmask_b32_e64 v87, v91, v87, s[12:13]
	s_branch .LBB0_635
.Lsmp_0_13:
	v_add_co_u32_e32 v76, vcc, 0x2000, v126
	v_mov_b32_e32 v130, v4
	s_nop 0
	v_addc_co_u32_e32 v77, vcc, 0, v127, vcc
	v_add_co_u32_e32 v88, vcc, 0x2000, v124
	global_load_dwordx4 v[76:79], v[76:77], off offset:3072
	s_nop 0
	v_addc_co_u32_e32 v89, vcc, 0, v125, vcc
	global_load_dwordx4 v[88:91], v[88:89], off offset:3072
	v_mov_b32_e32 v131, v4
	v_mov_b32_e32 v155, v5
	v_mov_b32_e32 v163, v5
	v_mov_b32_e32 v226, v6
	v_mov_b32_e32 v228, v7
	v_mov_b32_e32 v171, v6
	v_mov_b32_e32 v227, v7
	v_mov_b32_dpp v130, v130 row_ror:1 row_mask:0xf bank_mask:0xf
	v_mov_b32_dpp v131, v131 row_ror:2 row_mask:0xf bank_mask:0xf
	v_mov_b32_dpp v155, v155 row_ror:1 row_mask:0xf bank_mask:0xf
	v_mov_b32_dpp v163, v163 row_ror:2 row_mask:0xf bank_mask:0xf
	v_mov_b32_dpp v226, v226 row_ror:2 row_mask:0xf bank_mask:0xf
	v_mov_b32_dpp v228, v228 row_ror:2 row_mask:0xf bank_mask:0xf
	v_mov_b32_dpp v171, v171 row_ror:1 row_mask:0xf bank_mask:0xf
	v_mov_b32_dpp v227, v227 row_ror:1 row_mask:0xf bank_mask:0xf
	s_waitcnt vmcnt(1)
	v_cndmask_b32_e64 v131, v131, v76, s[14:15]
	v_cndmask_b32_e64 v76, v130, v76, s[12:13]
	v_cndmask_b32_e64 v130, v163, v77, s[14:15]
	v_cndmask_b32_e64 v77, v155, v77, s[12:13]
	v_cndmask_b32_e64 v155, v226, v78, s[14:15]
	v_cndmask_b32_e64 v163, v228, v79, s[14:15]
	v_cndmask_b32_e64 v78, v171, v78, s[12:13]
	v_cndmask_b32_e64 v79, v227, v79, s[12:13]
	s_waitcnt vmcnt(0)
	v_cndmask_b32_e64 v88, v131, v88, s[12:13]
	v_cndmask_b32_e64 v89, v130, v89, s[12:13]
	v_cndmask_b32_e64 v90, v155, v90, s[12:13]
	v_cndmask_b32_e64 v91, v163, v91, s[12:13]
	s_branch .LBB0_639
.Lnfs_0_7:
	v_mov_b64_e32 v[72:73], s[24:25]
	v_mad_i64_i32 v[72:73], vcc, v147, s36, v[72:73]
	v_lshl_add_u64 v[72:73], v[196:197], 2, v[72:73]
	global_store_dwordx4 v[72:73], v[12:15], off
	v_add_co_u32_e32 v72, vcc, 0x2000, v72
	s_nop 1
	v_addc_co_u32_e32 v73, vcc, 0, v73, vcc
	global_store_dwordx4 v[72:73], v[4:7], off offset:3072
	s_branch .LBB0_641
; template <int N> __device__ __forceinline__ float dpp_ror(float v) { const int i = __builtin_bit_cast(int, v); return __builtin_bit_cast(float, __builtin_amdgcn_update_dpp(i, i, 0x120 + N, 0xF, 0xF, false)); }
;     __device__ __forceinline__ void operator()(const f32x4 (&acc)[2][2][4][2], const pg8::Unit& u, int wr, int wc, int fr, int fq, PG8_LAS unsigned char* xl) const {
;     ...
;                         } else { const int t = fr & 3, b = (row - MP) >> 2;
; #pragma unroll
;                             for (int j = 0; j < 4; ++j) { p1[j] = dpp_ror<1>(cur[j]); p2[j] = dpp_ror<2>(cur[j]); }
;                             const f32x4 c1 = *(const f32x4*)(ctx_s + (size_t)(b * 2 + 1) * FF2 + bj * FF + jc0 + 4 * n), c0 = *(const f32x4*)(ctx_s + (size_t)(b * 2) * FF2 + bj * FF + jc0 + 4 * n);
; #pragma unroll
;                             for (int j = 0; j < 4; ++j) { p2[j] = t == 0 ? c0[j] : (t == 1 ? c1[j] : p2[j]); p1[j] = t == 0 ? c1[j] : p1[j]; }
;                         }
.Lsmp_0_14:
	global_load_dwordx4 v[108:111], v[202:203], off offset:16
	global_load_dwordx4 v[112:115], v[200:201], off offset:16
	v_mov_b32_e32 v120, v68
	v_mov_b32_e32 v121, v68
	v_mov_b32_e32 v122, v69
	v_mov_b32_e32 v123, v69
	v_mov_b32_e32 v163, v70
	v_mov_b32_e32 v204, v71
	v_mov_b32_e32 v155, v70
	v_mov_b32_e32 v171, v71
	v_mov_b32_dpp v120, v120 row_ror:1 row_mask:0xf bank_mask:0xf
	v_mov_b32_dpp v121, v121 row_ror:2 row_mask:0xf bank_mask:0xf
	v_mov_b32_dpp v122, v122 row_ror:1 row_mask:0xf bank_mask:0xf
	v_mov_b32_dpp v123, v123 row_ror:2 row_mask:0xf bank_mask:0xf
	v_mov_b32_dpp v163, v163 row_ror:2 row_mask:0xf bank_mask:0xf
	v_mov_b32_dpp v204, v204 row_ror:2 row_mask:0xf bank_mask:0xf
	v_mov_b32_dpp v155, v155 row_ror:1 row_mask:0xf bank_mask:0xf
	v_mov_b32_dpp v171, v171 row_ror:1 row_mask:0xf bank_mask:0xf
	s_waitcnt vmcnt(1)
	v_cndmask_b32_e64 v121, v121, v108, s[14:15]
	v_cndmask_b32_e64 v108, v120, v108, s[12:13]
	v_cndmask_b32_e64 v120, v123, v109, s[14:15]
	v_cndmask_b32_e64 v109, v122, v109, s[12:13]
	v_cndmask_b32_e64 v122, v163, v110, s[14:15]
	v_cndmask_b32_e64 v123, v204, v111, s[14:15]
	v_cndmask_b32_e64 v110, v155, v110, s[12:13]
	v_cndmask_b32_e64 v111, v171, v111, s[12:13]
	s_waitcnt vmcnt(0)
	v_cndmask_b32_e64 v112, v121, v112, s[12:13]
	v_cndmask_b32_e64 v113, v120, v113, s[12:13]
	v_cndmask_b32_e64 v114, v122, v114, s[12:13]
	v_cndmask_b32_e64 v115, v123, v115, s[12:13]
	s_branch .LBB0_647
.Lsmp_0_15:
	s_waitcnt lgkmcnt(1)
	v_add_co_u32_e32 v116, vcc, 0x2000, v202
	v_mov_b32_e32 v155, v64
	s_nop 0
	v_addc_co_u32_e32 v117, vcc, 0, v203, vcc
	v_add_co_u32_e32 v120, vcc, 0x2000, v200
	global_load_dwordx4 v[116:119], v[116:117], off offset:3088
	s_nop 0
	v_addc_co_u32_e32 v121, vcc, 0, v201, vcc
	global_load_dwordx4 v[120:123], v[120:121], off offset:3088
	v_mov_b32_e32 v163, v64
	v_mov_b32_e32 v171, v65
	v_mov_b32_e32 v200, v65
	v_mov_b32_e32 v202, v66
	v_mov_b32_e32 v204, v67
	v_mov_b32_e32 v201, v66
	v_mov_b32_e32 v203, v67
	v_mov_b32_dpp v155, v155 row_ror:1 row_mask:0xf bank_mask:0xf
	v_mov_b32_dpp v163, v163 row_ror:2 row_mask:0xf bank_mask:0xf
	v_mov_b32_dpp v171, v171 row_ror:1 row_mask:0xf bank_mask:0xf
	v_mov_b32_dpp v200, v200 row_ror:2 row_mask:0xf bank_mask:0xf
	v_mov_b32_dpp v202, v202 row_ror:2 row_mask:0xf bank_mask:0xf
	v_mov_b32_dpp v204, v204 row_ror:2 row_mask:0xf bank_mask:0xf
	v_mov_b32_dpp v201, v201 row_ror:1 row_mask:0xf bank_mask:0xf
	v_mov_b32_dpp v203, v203 row_ror:1 row_mask:0xf bank_mask:0xf
	s_waitcnt vmcnt(1)
	v_cndmask_b32_e64 v163, v163, v116, s[14:15]
	v_cndmask_b32_e64 v116, v155, v116, s[12:13]
	v_cndmask_b32_e64 v155, v200, v117, s[14:15]
	v_cndmask_b32_e64 v117, v171, v117, s[12:13]
	v_cndmask_b32_e64 v171, v202, v118, s[14:15]
	v_cndmask_b32_e64 v200, v204, v119, s[14:15]
	v_cndmask_b32_e64 v118, v201, v118, s[12:13]
	v_cndmask_b32_e64 v119, v203, v119, s[12:13]
	s_waitcnt vmcnt(0)
	v_cndmask_b32_e64 v120, v163, v120, s[12:13]
	v_cndmask_b32_e64 v121, v155, v121, s[12:13]
	v_cndmask_b32_e64 v122, v171, v122, s[12:13]
	v_cndmask_b32_e64 v123, v200, v123, s[12:13]
	s_branch .LBB0_651
.Lsmp_0_16:
	global_load_dwordx4 v[104:107], v[174:175], off offset:16
	global_load_dwordx4 v[108:111], v[172:173], off offset:16
	v_mov_b32_e32 v112, v60
	v_mov_b32_e32 v113, v60
	v_mov_b32_e32 v114, v61
	v_mov_b32_e32 v115, v61
	v_mov_b32_e32 v117, v62
	v_mov_b32_e32 v119, v63
	v_mov_b32_e32 v116, v62
	v_mov_b32_e32 v118, v63
	v_mov_b32_dpp v112, v112 row_ror:1 row_mask:0xf bank_mask:0xf
	v_mov_b32_dpp v113, v113 row_ror:2 row_mask:0xf bank_mask:0xf
	v_mov_b32_dpp v114, v114 row_ror:1 row_mask:0xf bank_mask:0xf
	v_mov_b32_dpp v115, v115 row_ror:2 row_mask:0xf bank_mask:0xf
	v_mov_b32_dpp v117, v117 row_ror:2 row_mask:0xf bank_mask:0xf
	v_mov_b32_dpp v119, v119 row_ror:2 row_mask:0xf bank_mask:0xf
	v_mov_b32_dpp v116, v116 row_ror:1 row_mask:0xf bank_mask:0xf
	v_mov_b32_dpp v118, v118 row_ror:1 row_mask:0xf bank_mask:0xf
	s_waitcnt vmcnt(1)
	v_cndmask_b32_e64 v113, v113, v104, s[14:15]
	v_cndmask_b32_e64 v104, v112, v104, s[12:13]
	v_cndmask_b32_e64 v112, v115, v105, s[14:15]
	v_cndmask_b32_e64 v105, v114, v105, s[12:13]
	v_cndmask_b32_e64 v114, v117, v106, s[14:15]
	v_cndmask_b32_e64 v115, v119, v107, s[14:15]
	v_cndmask_b32_e64 v106, v116, v106, s[12:13]
	v_cndmask_b32_e64 v107, v118, v107, s[12:13]
	s_waitcnt vmcnt(0)
	v_cndmask_b32_e64 v108, v113, v108, s[12:13]
	v_cndmask_b32_e64 v109, v112, v109, s[12:13]
	v_cndmask_b32_e64 v110, v114, v110, s[12:13]
	v_cndmask_b32_e64 v111, v115, v111, s[12:13]
	s_branch .LBB0_659
.Lsmp_0_17:
	v_add_co_u32_e32 v68, vcc, 0x2000, v174
	v_mov_b32_e32 v116, v56
	s_nop 0
	v_addc_co_u32_e32 v69, vcc, 0, v175, vcc
	v_add_co_u32_e32 v112, vcc, 0x2000, v172
	global_load_dwordx4 v[68:71], v[68:69], off offset:3088
	s_nop 0
	v_addc_co_u32_e32 v113, vcc, 0, v173, vcc
	global_load_dwordx4 v[112:115], v[112:113], off offset:3088
	v_mov_b32_e32 v117, v56
	v_mov_b32_e32 v118, v57
	v_mov_b32_e32 v119, v57
	v_mov_b32_e32 v121, v58
	v_mov_b32_e32 v123, v59
	v_mov_b32_e32 v120, v58
	v_mov_b32_e32 v122, v59
	v_mov_b32_dpp v116, v116 row_ror:1 row_mask:0xf bank_mask:0xf
	v_mov_b32_dpp v117, v117 row_ror:2 row_mask:0xf bank_mask:0xf
	v_mov_b32_dpp v118, v118 row_ror:1 row_mask:0xf bank_mask:0xf
	v_mov_b32_dpp v119, v119 row_ror:2 row_mask:0xf bank_mask:0xf
	v_mov_b32_dpp v121, v121 row_ror:2 row_mask:0xf bank_mask:0xf
	v_mov_b32_dpp v123, v123 row_ror:2 row_mask:0xf bank_mask:0xf
	v_mov_b32_dpp v120, v120 row_ror:1 row_mask:0xf bank_mask:0xf
	v_mov_b32_dpp v122, v122 row_ror:1 row_mask:0xf bank_mask:0xf
	s_waitcnt vmcnt(1)
	v_cndmask_b32_e64 v117, v117, v68, s[14:15]
	v_cndmask_b32_e64 v68, v116, v68, s[12:13]
	v_cndmask_b32_e64 v116, v119, v69, s[14:15]
	v_cndmask_b32_e64 v69, v118, v69, s[12:13]
	v_cndmask_b32_e64 v118, v121, v70, s[14:15]
	v_cndmask_b32_e64 v119, v123, v71, s[14:15]
	v_cndmask_b32_e64 v70, v120, v70, s[12:13]
	v_cndmask_b32_e64 v71, v122, v71, s[12:13]
	s_waitcnt vmcnt(0)
	v_cndmask_b32_e64 v112, v117, v112, s[12:13]
	v_cndmask_b32_e64 v113, v116, v113, s[12:13]
	v_cndmask_b32_e64 v114, v118, v114, s[12:13]
	v_cndmask_b32_e64 v115, v119, v115, s[12:13]
	s_branch .LBB0_663
; __device__ __forceinline__ unsigned pk2(float lo, float hi) { const f32x2 v = {lo, hi}; const bf16x2_t b = __builtin_convertvector(v, bf16x2_t); return __builtin_bit_cast(unsigned, b); }
; template <int N> __device__ __forceinline__ float dpp_ror(float v) { const int i = __builtin_bit_cast(int, v); return __builtin_bit_cast(float, __builtin_amdgcn_update_dpp(i, i, 0x120 + N, 0xF, 0xF, false)); }
;     __device__ __forceinline__ void operator()(const f32x4 (&acc)[2][2][4][2], const pg8::Unit& u, int wr, int wc, int fr, int fq, PG8_LAS unsigned char* xl) const {
;     ...
;                         } else { const int t = fr & 3, b = (row - MP) >> 2;
; #pragma unroll
;                             for (int j = 0; j < 4; ++j) { p1[j] = dpp_ror<1>(cur[j]); p2[j] = dpp_ror<2>(cur[j]); }
;                             const f32x4 c1 = *(const f32x4*)(ctx_s + (size_t)(b * 2 + 1) * FF2 + bj * FF + jc0 + 4 * n), c0 = *(const f32x4*)(ctx_s + (size_t)(b * 2) * FF2 + bj * FF + jc0 + 4 * n);
; #pragma unroll
;                             for (int j = 0; j < 4; ++j) { p2[j] = t == 0 ? c0[j] : (t == 1 ? c1[j] : p2[j]); p1[j] = t == 0 ? c1[j] : p1[j]; }
;                         }
;                         cc[bj] = bb[bj] + w0[bj] * p2 + w1[bj] * p1 + w2[bj] * cur;
;                     }
;                     const f32x4 gv = gelu_mul4(cc[0], cc[1]);
;                     u32x2 w; w.x = pk2(gv[0], gv[1]); w.y = pk2(gv[2], gv[3]);
;                     *(u32x2*)(G + (size_t)row * FF + jc0 + 4 * n) = w;
;                     if (!sample && ai == 0 && wr == 0 && m == 0 && fr < 2 && (pm & 7) != 0) {
; #pragma unroll
;                         for (int bj = 0; bj < 2; ++bj) *(f32x4*)(PH + (size_t)(pm * 2 + fr) * FF2 + bj * FF + jc0 + 4 * n) = cc[bj];
;                     }
;                     if (sample && (fr & 3) >= 2) { const int b = (row - MP) >> 2, t = fr & 3;
; #pragma unroll
;                         for (int bj = 0; bj < 2; ++bj) *(f32x4*)(nf_s + (size_t)(b * 2 + t - 2) * FF2 + bj * FF + jc0 + 4 * n) = acc[ai][bj][m][n];
;                     }
.Lnfs_0_8:
	v_mov_b64_e32 v[64:65], s[24:25]
	v_mad_i64_i32 v[64:65], s[58:59], v170, s36, v[64:65]
	v_lshl_add_u64 v[64:65], v[196:197], 2, v[64:65]
	global_store_dwordx4 v[64:65], v[60:63], off offset:16
	v_add_co_u32_e32 v64, vcc, 0x2000, v64
	s_nop 1
	v_addc_co_u32_e32 v65, vcc, 0, v65, vcc
	global_store_dwordx4 v[64:65], v[56:59], off offset:3088
	s_branch .LBB0_665
.Lsmp_0_18:
	global_load_dwordx4 v[64:67], v[166:167], off offset:16
	global_load_dwordx4 v[68:71], v[164:165], off offset:16
	v_mov_b32_e32 v104, v52
	v_mov_b32_e32 v105, v52
	v_mov_b32_e32 v106, v53
	v_mov_b32_e32 v107, v53
	v_mov_b32_e32 v109, v54
	v_mov_b32_e32 v111, v55
	v_mov_b32_e32 v108, v54
	v_mov_b32_e32 v110, v55
	v_mov_b32_dpp v104, v104 row_ror:1 row_mask:0xf bank_mask:0xf
	v_mov_b32_dpp v105, v105 row_ror:2 row_mask:0xf bank_mask:0xf
	v_mov_b32_dpp v106, v106 row_ror:1 row_mask:0xf bank_mask:0xf
	v_mov_b32_dpp v107, v107 row_ror:2 row_mask:0xf bank_mask:0xf
	v_mov_b32_dpp v109, v109 row_ror:2 row_mask:0xf bank_mask:0xf
	v_mov_b32_dpp v111, v111 row_ror:2 row_mask:0xf bank_mask:0xf
	v_mov_b32_dpp v108, v108 row_ror:1 row_mask:0xf bank_mask:0xf
	v_mov_b32_dpp v110, v110 row_ror:1 row_mask:0xf bank_mask:0xf
	s_waitcnt vmcnt(1)
	v_cndmask_b32_e64 v105, v105, v64, s[14:15]
	v_cndmask_b32_e64 v64, v104, v64, s[12:13]
	v_cndmask_b32_e64 v104, v107, v65, s[14:15]
	v_cndmask_b32_e64 v65, v106, v65, s[12:13]
	v_cndmask_b32_e64 v106, v109, v66, s[14:15]
	v_cndmask_b32_e64 v107, v111, v67, s[14:15]
	v_cndmask_b32_e64 v66, v108, v66, s[12:13]
	v_cndmask_b32_e64 v67, v110, v67, s[12:13]
	s_waitcnt vmcnt(0)
	v_cndmask_b32_e64 v68, v105, v68, s[12:13]
	v_cndmask_b32_e64 v69, v104, v69, s[12:13]
	v_cndmask_b32_e64 v70, v106, v70, s[12:13]
	v_cndmask_b32_e64 v71, v107, v71, s[12:13]
	s_branch .LBB0_669
.Lsmp_0_19:
	v_add_co_u32_e32 v60, vcc, 0x2000, v166
	v_mov_b32_e32 v108, v48
	s_nop 0
	v_addc_co_u32_e32 v61, vcc, 0, v167, vcc
	v_add_co_u32_e32 v104, vcc, 0x2000, v164
	global_load_dwordx4 v[60:63], v[60:61], off offset:3088
	s_nop 0
	v_addc_co_u32_e32 v105, vcc, 0, v165, vcc
	global_load_dwordx4 v[104:107], v[104:105], off offset:3088
	v_mov_b32_e32 v109, v48
	v_mov_b32_e32 v110, v49
	v_mov_b32_e32 v111, v49
	v_mov_b32_e32 v113, v50
	v_mov_b32_e32 v115, v51
	v_mov_b32_e32 v112, v50
	v_mov_b32_e32 v114, v51
	v_mov_b32_dpp v108, v108 row_ror:1 row_mask:0xf bank_mask:0xf
	v_mov_b32_dpp v109, v109 row_ror:2 row_mask:0xf bank_mask:0xf
	v_mov_b32_dpp v110, v110 row_ror:1 row_mask:0xf bank_mask:0xf
	v_mov_b32_dpp v111, v111 row_ror:2 row_mask:0xf bank_mask:0xf
	v_mov_b32_dpp v113, v113 row_ror:2 row_mask:0xf bank_mask:0xf
	v_mov_b32_dpp v115, v115 row_ror:2 row_mask:0xf bank_mask:0xf
	v_mov_b32_dpp v112, v112 row_ror:1 row_mask:0xf bank_mask:0xf
	v_mov_b32_dpp v114, v114 row_ror:1 row_mask:0xf bank_mask:0xf
	s_waitcnt vmcnt(1)
	v_cndmask_b32_e64 v109, v109, v60, s[14:15]
	v_cndmask_b32_e64 v60, v108, v60, s[12:13]
	v_cndmask_b32_e64 v108, v111, v61, s[14:15]
	v_cndmask_b32_e64 v61, v110, v61, s[12:13]
	v_cndmask_b32_e64 v110, v113, v62, s[14:15]
	v_cndmask_b32_e64 v111, v115, v63, s[14:15]
	v_cndmask_b32_e64 v62, v112, v62, s[12:13]
	v_cndmask_b32_e64 v63, v114, v63, s[12:13]
	s_waitcnt vmcnt(0)
	v_cndmask_b32_e64 v104, v109, v104, s[12:13]
	v_cndmask_b32_e64 v105, v108, v105, s[12:13]
	v_cndmask_b32_e64 v106, v110, v106, s[12:13]
	v_cndmask_b32_e64 v107, v111, v107, s[12:13]
	s_branch .LBB0_673
.Lnfs_0_9:
	v_mov_b64_e32 v[56:57], s[24:25]
	v_mad_i64_i32 v[56:57], s[58:59], v162, s36, v[56:57]
	v_lshl_add_u64 v[56:57], v[196:197], 2, v[56:57]
	global_store_dwordx4 v[56:57], v[52:55], off offset:16
	v_add_co_u32_e32 v56, vcc, 0x2000, v56
	s_nop 1
	v_addc_co_u32_e32 v57, vcc, 0, v57, vcc
	global_store_dwordx4 v[56:57], v[48:51], off offset:3088
	s_branch .LBB0_675
.Lsmp_0_20:
	global_load_dwordx4 v[56:59], v[158:159], off offset:16
	global_load_dwordx4 v[60:63], v[156:157], off offset:16
	v_mov_b32_e32 v64, v44
	v_mov_b32_e32 v65, v44
	v_mov_b32_e32 v66, v45
	v_mov_b32_e32 v67, v45
	v_mov_b32_e32 v69, v46
	v_mov_b32_e32 v71, v47
	v_mov_b32_e32 v68, v46
	v_mov_b32_e32 v70, v47
	v_mov_b32_dpp v64, v64 row_ror:1 row_mask:0xf bank_mask:0xf
	v_mov_b32_dpp v65, v65 row_ror:2 row_mask:0xf bank_mask:0xf
	v_mov_b32_dpp v66, v66 row_ror:1 row_mask:0xf bank_mask:0xf
	v_mov_b32_dpp v67, v67 row_ror:2 row_mask:0xf bank_mask:0xf
	v_mov_b32_dpp v69, v69 row_ror:2 row_mask:0xf bank_mask:0xf
	v_mov_b32_dpp v71, v71 row_ror:2 row_mask:0xf bank_mask:0xf
	v_mov_b32_dpp v68, v68 row_ror:1 row_mask:0xf bank_mask:0xf
	v_mov_b32_dpp v70, v70 row_ror:1 row_mask:0xf bank_mask:0xf
	s_waitcnt vmcnt(1)
	v_cndmask_b32_e64 v65, v65, v56, s[14:15]
	v_cndmask_b32_e64 v56, v64, v56, s[12:13]
	v_cndmask_b32_e64 v64, v67, v57, s[14:15]
	v_cndmask_b32_e64 v57, v66, v57, s[12:13]
	v_cndmask_b32_e64 v66, v69, v58, s[14:15]
	v_cndmask_b32_e64 v67, v71, v59, s[14:15]
	v_cndmask_b32_e64 v58, v68, v58, s[12:13]
	v_cndmask_b32_e64 v59, v70, v59, s[12:13]
	s_waitcnt vmcnt(0)
	v_cndmask_b32_e64 v60, v65, v60, s[12:13]
	v_cndmask_b32_e64 v61, v64, v61, s[12:13]
	v_cndmask_b32_e64 v62, v66, v62, s[12:13]
	v_cndmask_b32_e64 v63, v67, v63, s[12:13]
	s_branch .LBB0_679
; __device__ __forceinline__ unsigned pk2(float lo, float hi) { const f32x2 v = {lo, hi}; const bf16x2_t b = __builtin_convertvector(v, bf16x2_t); return __builtin_bit_cast(unsigned, b); }
; template <int N> __device__ __forceinline__ float dpp_ror(float v) { const int i = __builtin_bit_cast(int, v); return __builtin_bit_cast(float, __builtin_amdgcn_update_dpp(i, i, 0x120 + N, 0xF, 0xF, false)); }
;     __device__ __forceinline__ void operator()(const f32x4 (&acc)[2][2][4][2], const pg8::Unit& u, int wr, int wc, int fr, int fq, PG8_LAS unsigned char* xl) const {
;     ...
;                         } else { const int t = fr & 3, b = (row - MP) >> 2;
; #pragma unroll
;                             for (int j = 0; j < 4; ++j) { p1[j] = dpp_ror<1>(cur[j]); p2[j] = dpp_ror<2>(cur[j]); }
;                             const f32x4 c1 = *(const f32x4*)(ctx_s + (size_t)(b * 2 + 1) * FF2 + bj * FF + jc0 + 4 * n), c0 = *(const f32x4*)(ctx_s + (size_t)(b * 2) * FF2 + bj * FF + jc0 + 4 * n);
; #pragma unroll
;                             for (int j = 0; j < 4; ++j) { p2[j] = t == 0 ? c0[j] : (t == 1 ? c1[j] : p2[j]); p1[j] = t == 0 ? c1[j] : p1[j]; }
;                         }
;                         cc[bj] = bb[bj] + w0[bj] * p2 + w1[bj] * p1 + w2[bj] * cur;
;                     }
;                     const f32x4 gv = gelu_mul4(cc[0], cc[1]);
;                     u32x2 w; w.x = pk2(gv[0], gv[1]); w.y = pk2(gv[2], gv[3]);
;                     *(u32x2*)(G + (size_t)row * FF + jc0 + 4 * n) = w;
;                     if (!sample && ai == 0 && wr == 0 && m == 0 && fr < 2 && (pm & 7) != 0) {
; #pragma unroll
;                         for (int bj = 0; bj < 2; ++bj) *(f32x4*)(PH + (size_t)(pm * 2 + fr) * FF2 + bj * FF + jc0 + 4 * n) = cc[bj];
;                     }
;                     if (sample && (fr & 3) >= 2) { const int b = (row - MP) >> 2, t = fr & 3;
; #pragma unroll
;                         for (int bj = 0; bj < 2; ++bj) *(f32x4*)(nf_s + (size_t)(b * 2 + t - 2) * FF2 + bj * FF + jc0 + 4 * n) = acc[ai][bj][m][n];
;                     }
.Lsmp_0_21:
	v_add_co_u32_e32 v52, vcc, 0x2000, v158
	v_mov_b32_e32 v68, v40
	s_nop 0
	v_addc_co_u32_e32 v53, vcc, 0, v159, vcc
	v_add_co_u32_e32 v64, vcc, 0x2000, v156
	global_load_dwordx4 v[52:55], v[52:53], off offset:3088
	s_nop 0
	v_addc_co_u32_e32 v65, vcc, 0, v157, vcc
	global_load_dwordx4 v[64:67], v[64:65], off offset:3088
	v_mov_b32_e32 v69, v40
	v_mov_b32_e32 v70, v41
	v_mov_b32_e32 v71, v41
	v_mov_b32_e32 v105, v42
	v_mov_b32_e32 v107, v43
	v_mov_b32_e32 v104, v42
	v_mov_b32_e32 v106, v43
	v_mov_b32_dpp v68, v68 row_ror:1 row_mask:0xf bank_mask:0xf
	v_mov_b32_dpp v69, v69 row_ror:2 row_mask:0xf bank_mask:0xf
	v_mov_b32_dpp v70, v70 row_ror:1 row_mask:0xf bank_mask:0xf
	v_mov_b32_dpp v71, v71 row_ror:2 row_mask:0xf bank_mask:0xf
	v_mov_b32_dpp v105, v105 row_ror:2 row_mask:0xf bank_mask:0xf
	v_mov_b32_dpp v107, v107 row_ror:2 row_mask:0xf bank_mask:0xf
	v_mov_b32_dpp v104, v104 row_ror:1 row_mask:0xf bank_mask:0xf
	v_mov_b32_dpp v106, v106 row_ror:1 row_mask:0xf bank_mask:0xf
	s_waitcnt vmcnt(1)
	v_cndmask_b32_e64 v69, v69, v52, s[14:15]
	v_cndmask_b32_e64 v52, v68, v52, s[12:13]
	v_cndmask_b32_e64 v68, v71, v53, s[14:15]
	v_cndmask_b32_e64 v53, v70, v53, s[12:13]
	v_cndmask_b32_e64 v70, v105, v54, s[14:15]
	v_cndmask_b32_e64 v71, v107, v55, s[14:15]
	v_cndmask_b32_e64 v54, v104, v54, s[12:13]
	v_cndmask_b32_e64 v55, v106, v55, s[12:13]
	s_waitcnt vmcnt(0)
	v_cndmask_b32_e64 v64, v69, v64, s[12:13]
	v_cndmask_b32_e64 v65, v68, v65, s[12:13]
	v_cndmask_b32_e64 v66, v70, v66, s[12:13]
	v_cndmask_b32_e64 v67, v71, v67, s[12:13]
	s_branch .LBB0_683
.Lnfs_0_10:
	v_mov_b64_e32 v[48:49], s[24:25]
	v_mad_i64_i32 v[48:49], s[58:59], v154, s36, v[48:49]
	v_lshl_add_u64 v[48:49], v[196:197], 2, v[48:49]
	global_store_dwordx4 v[48:49], v[44:47], off offset:16
	s_nop 1
	v_add_co_u32_e32 v44, vcc, 0x2000, v48
	s_nop 1
	v_addc_co_u32_e32 v45, vcc, 0, v49, vcc
	global_store_dwordx4 v[44:45], v[40:43], off offset:3088
	s_branch .LBB0_685
.Lsmp_0_22:
	global_load_dwordx4 v[44:47], v[150:151], off offset:16
	global_load_dwordx4 v[48:51], v[148:149], off offset:16
	v_mov_b32_e32 v56, v36
	v_mov_b32_e32 v57, v36
	v_mov_b32_e32 v58, v37
	v_mov_b32_e32 v59, v37
	v_mov_b32_e32 v61, v38
	v_mov_b32_e32 v63, v39
	v_mov_b32_e32 v60, v38
	v_mov_b32_e32 v62, v39
	v_mov_b32_dpp v56, v56 row_ror:1 row_mask:0xf bank_mask:0xf
	v_mov_b32_dpp v57, v57 row_ror:2 row_mask:0xf bank_mask:0xf
	v_mov_b32_dpp v58, v58 row_ror:1 row_mask:0xf bank_mask:0xf
	v_mov_b32_dpp v59, v59 row_ror:2 row_mask:0xf bank_mask:0xf
	v_mov_b32_dpp v61, v61 row_ror:2 row_mask:0xf bank_mask:0xf
	v_mov_b32_dpp v63, v63 row_ror:2 row_mask:0xf bank_mask:0xf
	v_mov_b32_dpp v60, v60 row_ror:1 row_mask:0xf bank_mask:0xf
	v_mov_b32_dpp v62, v62 row_ror:1 row_mask:0xf bank_mask:0xf
	s_waitcnt vmcnt(1)
	v_cndmask_b32_e64 v57, v57, v44, s[14:15]
	v_cndmask_b32_e64 v44, v56, v44, s[12:13]
	v_cndmask_b32_e64 v56, v59, v45, s[14:15]
	v_cndmask_b32_e64 v45, v58, v45, s[12:13]
	v_cndmask_b32_e64 v58, v61, v46, s[14:15]
	v_cndmask_b32_e64 v59, v63, v47, s[14:15]
	v_cndmask_b32_e64 v46, v60, v46, s[12:13]
	v_cndmask_b32_e64 v47, v62, v47, s[12:13]
	s_waitcnt vmcnt(0)
	v_cndmask_b32_e64 v48, v57, v48, s[12:13]
	v_cndmask_b32_e64 v49, v56, v49, s[12:13]
	v_cndmask_b32_e64 v50, v58, v50, s[12:13]
	v_cndmask_b32_e64 v51, v59, v51, s[12:13]
	s_branch .LBB0_691
.Lsmp_0_23:
	s_waitcnt lgkmcnt(1)
	v_add_co_u32_e32 v52, vcc, 0x2000, v150
	v_mov_b32_e32 v60, v32
	s_nop 0
	v_addc_co_u32_e32 v53, vcc, 0, v151, vcc
	v_add_co_u32_e32 v56, vcc, 0x2000, v148
	global_load_dwordx4 v[52:55], v[52:53], off offset:3088
	s_nop 0
	v_addc_co_u32_e32 v57, vcc, 0, v149, vcc
	global_load_dwordx4 v[56:59], v[56:57], off offset:3088
	v_mov_b32_e32 v61, v32
	v_mov_b32_e32 v62, v33
	v_mov_b32_e32 v63, v33
	v_mov_b32_e32 v65, v34
	v_mov_b32_e32 v67, v35
	v_mov_b32_e32 v64, v34
	v_mov_b32_e32 v66, v35
	v_mov_b32_dpp v60, v60 row_ror:1 row_mask:0xf bank_mask:0xf
	v_mov_b32_dpp v61, v61 row_ror:2 row_mask:0xf bank_mask:0xf
	v_mov_b32_dpp v62, v62 row_ror:1 row_mask:0xf bank_mask:0xf
	v_mov_b32_dpp v63, v63 row_ror:2 row_mask:0xf bank_mask:0xf
	v_mov_b32_dpp v65, v65 row_ror:2 row_mask:0xf bank_mask:0xf
	v_mov_b32_dpp v67, v67 row_ror:2 row_mask:0xf bank_mask:0xf
	v_mov_b32_dpp v64, v64 row_ror:1 row_mask:0xf bank_mask:0xf
	v_mov_b32_dpp v66, v66 row_ror:1 row_mask:0xf bank_mask:0xf
	s_waitcnt vmcnt(1)
	v_cndmask_b32_e64 v61, v61, v52, s[14:15]
	v_cndmask_b32_e64 v52, v60, v52, s[12:13]
	v_cndmask_b32_e64 v60, v63, v53, s[14:15]
	v_cndmask_b32_e64 v53, v62, v53, s[12:13]
	v_cndmask_b32_e64 v62, v65, v54, s[14:15]
	v_cndmask_b32_e64 v63, v67, v55, s[14:15]
	v_cndmask_b32_e64 v54, v64, v54, s[12:13]
	v_cndmask_b32_e64 v55, v66, v55, s[12:13]
	s_waitcnt vmcnt(0)
	v_cndmask_b32_e64 v56, v61, v56, s[12:13]
	v_cndmask_b32_e64 v57, v60, v57, s[12:13]
	v_cndmask_b32_e64 v58, v62, v58, s[12:13]
	v_cndmask_b32_e64 v59, v63, v59, s[12:13]
	s_branch .LBB0_695
.Lnfs_0_11:
	v_mov_b64_e32 v[40:41], s[24:25]
	v_mad_i64_i32 v[40:41], s[10:11], v146, s36, v[40:41]
	v_lshl_add_u64 v[40:41], v[196:197], 2, v[40:41]
	global_store_dwordx4 v[40:41], v[36:39], off offset:16
	v_add_co_u32_e32 v40, vcc, 0x2000, v40
	s_nop 1
	v_addc_co_u32_e32 v41, vcc, 0, v41, vcc
	global_store_dwordx4 v[40:41], v[32:35], off offset:3088
	s_branch .LBB0_697
; __device__ __forceinline__ unsigned pk2(float lo, float hi) { const f32x2 v = {lo, hi}; const bf16x2_t b = __builtin_convertvector(v, bf16x2_t); return __builtin_bit_cast(unsigned, b); }
; template <int N> __device__ __forceinline__ float dpp_ror(float v) { const int i = __builtin_bit_cast(int, v); return __builtin_bit_cast(float, __builtin_amdgcn_update_dpp(i, i, 0x120 + N, 0xF, 0xF, false)); }
;     __device__ __forceinline__ void operator()(const f32x4 (&acc)[2][2][4][2], const pg8::Unit& u, int wr, int wc, int fr, int fq, PG8_LAS unsigned char* xl) const {
;     ...
;                         } else { const int t = fr & 3, b = (row - MP) >> 2;
; #pragma unroll
;                             for (int j = 0; j < 4; ++j) { p1[j] = dpp_ror<1>(cur[j]); p2[j] = dpp_ror<2>(cur[j]); }
;                             const f32x4 c1 = *(const f32x4*)(ctx_s + (size_t)(b * 2 + 1) * FF2 + bj * FF + jc0 + 4 * n), c0 = *(const f32x4*)(ctx_s + (size_t)(b * 2) * FF2 + bj * FF + jc0 + 4 * n);
; #pragma unroll
;                             for (int j = 0; j < 4; ++j) { p2[j] = t == 0 ? c0[j] : (t == 1 ? c1[j] : p2[j]); p1[j] = t == 0 ? c1[j] : p1[j]; }
;                         }
;                         cc[bj] = bb[bj] + w0[bj] * p2 + w1[bj] * p1 + w2[bj] * cur;
;                     }
;                     const f32x4 gv = gelu_mul4(cc[0], cc[1]);
;                     u32x2 w; w.x = pk2(gv[0], gv[1]); w.y = pk2(gv[2], gv[3]);
;                     *(u32x2*)(G + (size_t)row * FF + jc0 + 4 * n) = w;
;                     if (!sample && ai == 0 && wr == 0 && m == 0 && fr < 2 && (pm & 7) != 0) {
; #pragma unroll
;                         for (int bj = 0; bj < 2; ++bj) *(f32x4*)(PH + (size_t)(pm * 2 + fr) * FF2 + bj * FF + jc0 + 4 * n) = cc[bj];
;                     }
;                     if (sample && (fr & 3) >= 2) { const int b = (row - MP) >> 2, t = fr & 3;
; #pragma unroll
;                         for (int bj = 0; bj < 2; ++bj) *(f32x4*)(nf_s + (size_t)(b * 2 + t - 2) * FF2 + bj * FF + jc0 + 4 * n) = acc[ai][bj][m][n];
;                     }
.Lsmp_0_24:
	global_load_dwordx4 v[40:43], v[142:143], off offset:16
	global_load_dwordx4 v[44:47], v[140:141], off offset:16
	v_mov_b32_e32 v48, v28
	v_mov_b32_e32 v49, v28
	v_mov_b32_e32 v50, v29
	v_mov_b32_e32 v51, v29
	v_mov_b32_e32 v53, v30
	v_mov_b32_e32 v55, v31
	v_mov_b32_e32 v52, v30
	v_mov_b32_e32 v54, v31
	v_mov_b32_dpp v48, v48 row_ror:1 row_mask:0xf bank_mask:0xf
	v_mov_b32_dpp v49, v49 row_ror:2 row_mask:0xf bank_mask:0xf
	v_mov_b32_dpp v50, v50 row_ror:1 row_mask:0xf bank_mask:0xf
	v_mov_b32_dpp v51, v51 row_ror:2 row_mask:0xf bank_mask:0xf
	v_mov_b32_dpp v53, v53 row_ror:2 row_mask:0xf bank_mask:0xf
	v_mov_b32_dpp v55, v55 row_ror:2 row_mask:0xf bank_mask:0xf
	v_mov_b32_dpp v52, v52 row_ror:1 row_mask:0xf bank_mask:0xf
	v_mov_b32_dpp v54, v54 row_ror:1 row_mask:0xf bank_mask:0xf
	s_waitcnt vmcnt(1)
	v_cndmask_b32_e64 v49, v49, v40, s[14:15]
	v_cndmask_b32_e64 v40, v48, v40, s[12:13]
	v_cndmask_b32_e64 v48, v51, v41, s[14:15]
	v_cndmask_b32_e64 v41, v50, v41, s[12:13]
	v_cndmask_b32_e64 v50, v53, v42, s[14:15]
	v_cndmask_b32_e64 v51, v55, v43, s[14:15]
	v_cndmask_b32_e64 v42, v52, v42, s[12:13]
	v_cndmask_b32_e64 v43, v54, v43, s[12:13]
	s_waitcnt vmcnt(0)
	v_cndmask_b32_e64 v44, v49, v44, s[12:13]
	v_cndmask_b32_e64 v45, v48, v45, s[12:13]
	v_cndmask_b32_e64 v46, v50, v46, s[12:13]
	v_cndmask_b32_e64 v47, v51, v47, s[12:13]
	s_branch .LBB0_701
.Lsmp_0_25:
	v_add_co_u32_e32 v36, vcc, 0x2000, v142
	v_mov_b32_e32 v52, v24
	s_nop 0
	v_addc_co_u32_e32 v37, vcc, 0, v143, vcc
	v_add_co_u32_e32 v48, vcc, 0x2000, v140
	global_load_dwordx4 v[36:39], v[36:37], off offset:3088
	s_nop 0
	v_addc_co_u32_e32 v49, vcc, 0, v141, vcc
	global_load_dwordx4 v[48:51], v[48:49], off offset:3088
	v_mov_b32_e32 v53, v24
	v_mov_b32_e32 v54, v25
	v_mov_b32_e32 v55, v25
	v_mov_b32_e32 v57, v26
	v_mov_b32_e32 v59, v27
	v_mov_b32_e32 v56, v26
	v_mov_b32_e32 v58, v27
	v_mov_b32_dpp v52, v52 row_ror:1 row_mask:0xf bank_mask:0xf
	v_mov_b32_dpp v53, v53 row_ror:2 row_mask:0xf bank_mask:0xf
	v_mov_b32_dpp v54, v54 row_ror:1 row_mask:0xf bank_mask:0xf
	v_mov_b32_dpp v55, v55 row_ror:2 row_mask:0xf bank_mask:0xf
	v_mov_b32_dpp v57, v57 row_ror:2 row_mask:0xf bank_mask:0xf
	v_mov_b32_dpp v59, v59 row_ror:2 row_mask:0xf bank_mask:0xf
	v_mov_b32_dpp v56, v56 row_ror:1 row_mask:0xf bank_mask:0xf
	v_mov_b32_dpp v58, v58 row_ror:1 row_mask:0xf bank_mask:0xf
	s_waitcnt vmcnt(1)
	v_cndmask_b32_e64 v53, v53, v36, s[14:15]
	v_cndmask_b32_e64 v36, v52, v36, s[12:13]
	v_cndmask_b32_e64 v52, v55, v37, s[14:15]
	v_cndmask_b32_e64 v37, v54, v37, s[12:13]
	v_cndmask_b32_e64 v54, v57, v38, s[14:15]
	v_cndmask_b32_e64 v55, v59, v39, s[14:15]
	v_cndmask_b32_e64 v38, v56, v38, s[12:13]
	v_cndmask_b32_e64 v39, v58, v39, s[12:13]
	s_waitcnt vmcnt(0)
	v_cndmask_b32_e64 v48, v53, v48, s[12:13]
	v_cndmask_b32_e64 v49, v52, v49, s[12:13]
	v_cndmask_b32_e64 v50, v54, v50, s[12:13]
	v_cndmask_b32_e64 v51, v55, v51, s[12:13]
	s_branch .LBB0_705
.Lnfs_0_12:
	v_mov_b64_e32 v[32:33], s[24:25]
	v_mad_i64_i32 v[32:33], s[10:11], v138, s36, v[32:33]
	v_lshl_add_u64 v[32:33], v[196:197], 2, v[32:33]
	global_store_dwordx4 v[32:33], v[28:31], off offset:16
	v_add_co_u32_e32 v32, vcc, 0x2000, v32
	s_nop 1
	v_addc_co_u32_e32 v33, vcc, 0, v33, vcc
	global_store_dwordx4 v[32:33], v[24:27], off offset:3088
	s_branch .LBB0_707
.Lsmp_0_26:
	global_load_dwordx4 v[32:35], v[134:135], off offset:16
	global_load_dwordx4 v[36:39], v[132:133], off offset:16
	v_mov_b32_e32 v40, v20
	v_mov_b32_e32 v41, v20
	v_mov_b32_e32 v42, v21
	v_mov_b32_e32 v43, v21
	v_mov_b32_e32 v45, v22
	v_mov_b32_e32 v47, v23
	v_mov_b32_e32 v44, v22
	v_mov_b32_e32 v46, v23
	v_mov_b32_dpp v40, v40 row_ror:1 row_mask:0xf bank_mask:0xf
	v_mov_b32_dpp v41, v41 row_ror:2 row_mask:0xf bank_mask:0xf
	v_mov_b32_dpp v42, v42 row_ror:1 row_mask:0xf bank_mask:0xf
	v_mov_b32_dpp v43, v43 row_ror:2 row_mask:0xf bank_mask:0xf
	v_mov_b32_dpp v45, v45 row_ror:2 row_mask:0xf bank_mask:0xf
	v_mov_b32_dpp v47, v47 row_ror:2 row_mask:0xf bank_mask:0xf
	v_mov_b32_dpp v44, v44 row_ror:1 row_mask:0xf bank_mask:0xf
	v_mov_b32_dpp v46, v46 row_ror:1 row_mask:0xf bank_mask:0xf
	s_waitcnt vmcnt(1)
	v_cndmask_b32_e64 v41, v41, v32, s[14:15]
	v_cndmask_b32_e64 v32, v40, v32, s[12:13]
	v_cndmask_b32_e64 v40, v43, v33, s[14:15]
	v_cndmask_b32_e64 v33, v42, v33, s[12:13]
	v_cndmask_b32_e64 v42, v45, v34, s[14:15]
	v_cndmask_b32_e64 v43, v47, v35, s[14:15]
	v_cndmask_b32_e64 v34, v44, v34, s[12:13]
	v_cndmask_b32_e64 v35, v46, v35, s[12:13]
	s_waitcnt vmcnt(0)
	v_cndmask_b32_e64 v36, v41, v36, s[12:13]
	v_cndmask_b32_e64 v37, v40, v37, s[12:13]
	v_cndmask_b32_e64 v38, v42, v38, s[12:13]
	v_cndmask_b32_e64 v39, v43, v39, s[12:13]
	s_branch .LBB0_711
; __device__ __forceinline__ unsigned pk2(float lo, float hi) { const f32x2 v = {lo, hi}; const bf16x2_t b = __builtin_convertvector(v, bf16x2_t); return __builtin_bit_cast(unsigned, b); }
; template <int N> __device__ __forceinline__ float dpp_ror(float v) { const int i = __builtin_bit_cast(int, v); return __builtin_bit_cast(float, __builtin_amdgcn_update_dpp(i, i, 0x120 + N, 0xF, 0xF, false)); }
;     __device__ __forceinline__ void operator()(const f32x4 (&acc)[2][2][4][2], const pg8::Unit& u, int wr, int wc, int fr, int fq, PG8_LAS unsigned char* xl) const {
;     ...
;                         } else { const int t = fr & 3, b = (row - MP) >> 2;
; #pragma unroll
;                             for (int j = 0; j < 4; ++j) { p1[j] = dpp_ror<1>(cur[j]); p2[j] = dpp_ror<2>(cur[j]); }
;                             const f32x4 c1 = *(const f32x4*)(ctx_s + (size_t)(b * 2 + 1) * FF2 + bj * FF + jc0 + 4 * n), c0 = *(const f32x4*)(ctx_s + (size_t)(b * 2) * FF2 + bj * FF + jc0 + 4 * n);
; #pragma unroll
;                             for (int j = 0; j < 4; ++j) { p2[j] = t == 0 ? c0[j] : (t == 1 ? c1[j] : p2[j]); p1[j] = t == 0 ? c1[j] : p1[j]; }
;                         }
;                         cc[bj] = bb[bj] + w0[bj] * p2 + w1[bj] * p1 + w2[bj] * cur;
;                     }
;                     const f32x4 gv = gelu_mul4(cc[0], cc[1]);
;                     u32x2 w; w.x = pk2(gv[0], gv[1]); w.y = pk2(gv[2], gv[3]);
;                     *(u32x2*)(G + (size_t)row * FF + jc0 + 4 * n) = w;
;                     if (!sample && ai == 0 && wr == 0 && m == 0 && fr < 2 && (pm & 7) != 0) {
; #pragma unroll
;                         for (int bj = 0; bj < 2; ++bj) *(f32x4*)(PH + (size_t)(pm * 2 + fr) * FF2 + bj * FF + jc0 + 4 * n) = cc[bj];
;                     }
;                     if (sample && (fr & 3) >= 2) { const int b = (row - MP) >> 2, t = fr & 3;
; #pragma unroll
;                         for (int bj = 0; bj < 2; ++bj) *(f32x4*)(nf_s + (size_t)(b * 2 + t - 2) * FF2 + bj * FF + jc0 + 4 * n) = acc[ai][bj][m][n];
;                     }
.Lsmp_0_27:
	v_add_co_u32_e32 v28, vcc, 0x2000, v134
	v_mov_b32_e32 v44, v16
	s_nop 0
	v_addc_co_u32_e32 v29, vcc, 0, v135, vcc
	v_add_co_u32_e32 v40, vcc, 0x2000, v132
	global_load_dwordx4 v[28:31], v[28:29], off offset:3088
	s_nop 0
	v_addc_co_u32_e32 v41, vcc, 0, v133, vcc
	global_load_dwordx4 v[40:43], v[40:41], off offset:3088
	v_mov_b32_e32 v45, v16
	v_mov_b32_e32 v46, v17
	v_mov_b32_e32 v47, v17
	v_mov_b32_e32 v49, v18
	v_mov_b32_e32 v51, v19
	v_mov_b32_e32 v48, v18
	v_mov_b32_e32 v50, v19
	v_mov_b32_dpp v44, v44 row_ror:1 row_mask:0xf bank_mask:0xf
	v_mov_b32_dpp v45, v45 row_ror:2 row_mask:0xf bank_mask:0xf
	v_mov_b32_dpp v46, v46 row_ror:1 row_mask:0xf bank_mask:0xf
	v_mov_b32_dpp v47, v47 row_ror:2 row_mask:0xf bank_mask:0xf
	v_mov_b32_dpp v49, v49 row_ror:2 row_mask:0xf bank_mask:0xf
	v_mov_b32_dpp v51, v51 row_ror:2 row_mask:0xf bank_mask:0xf
	v_mov_b32_dpp v48, v48 row_ror:1 row_mask:0xf bank_mask:0xf
	v_mov_b32_dpp v50, v50 row_ror:1 row_mask:0xf bank_mask:0xf
	s_waitcnt vmcnt(1)
	v_cndmask_b32_e64 v45, v45, v28, s[14:15]
	v_cndmask_b32_e64 v28, v44, v28, s[12:13]
	v_cndmask_b32_e64 v44, v47, v29, s[14:15]
	v_cndmask_b32_e64 v29, v46, v29, s[12:13]
	v_cndmask_b32_e64 v46, v49, v30, s[14:15]
	v_cndmask_b32_e64 v47, v51, v31, s[14:15]
	v_cndmask_b32_e64 v30, v48, v30, s[12:13]
	v_cndmask_b32_e64 v31, v50, v31, s[12:13]
	s_waitcnt vmcnt(0)
	v_cndmask_b32_e64 v40, v45, v40, s[12:13]
	v_cndmask_b32_e64 v41, v44, v41, s[12:13]
	v_cndmask_b32_e64 v42, v46, v42, s[12:13]
	v_cndmask_b32_e64 v43, v47, v43, s[12:13]
	s_branch .LBB0_715
.Lnfs_0_13:
	v_mov_b64_e32 v[24:25], s[24:25]
	v_mad_i64_i32 v[24:25], s[10:11], v139, s36, v[24:25]
	v_lshl_add_u64 v[24:25], v[196:197], 2, v[24:25]
	global_store_dwordx4 v[24:25], v[20:23], off offset:16
	v_add_co_u32_e32 v24, vcc, 0x2000, v24
	s_nop 1
	v_addc_co_u32_e32 v25, vcc, 0, v25, vcc
	global_store_dwordx4 v[24:25], v[16:19], off offset:3088
	s_branch .LBB0_717
.Lsmp_0_28:
	global_load_dwordx4 v[24:27], v[126:127], off offset:16
	global_load_dwordx4 v[28:31], v[124:125], off offset:16
	v_mov_b32_e32 v32, v8
	v_mov_b32_e32 v33, v8
	v_mov_b32_e32 v34, v9
	v_mov_b32_e32 v35, v9
	v_mov_b32_e32 v37, v10
	v_mov_b32_e32 v39, v11
	v_mov_b32_e32 v36, v10
	v_mov_b32_e32 v38, v11
	v_mov_b32_dpp v32, v32 row_ror:1 row_mask:0xf bank_mask:0xf
	v_mov_b32_dpp v33, v33 row_ror:2 row_mask:0xf bank_mask:0xf
	v_mov_b32_dpp v34, v34 row_ror:1 row_mask:0xf bank_mask:0xf
	v_mov_b32_dpp v35, v35 row_ror:2 row_mask:0xf bank_mask:0xf
	v_mov_b32_dpp v37, v37 row_ror:2 row_mask:0xf bank_mask:0xf
	v_mov_b32_dpp v39, v39 row_ror:2 row_mask:0xf bank_mask:0xf
	v_mov_b32_dpp v36, v36 row_ror:1 row_mask:0xf bank_mask:0xf
	v_mov_b32_dpp v38, v38 row_ror:1 row_mask:0xf bank_mask:0xf
	s_waitcnt vmcnt(1)
	v_cndmask_b32_e64 v33, v33, v24, s[14:15]
	v_cndmask_b32_e64 v24, v32, v24, s[12:13]
	v_cndmask_b32_e64 v32, v35, v25, s[14:15]
	v_cndmask_b32_e64 v25, v34, v25, s[12:13]
	v_cndmask_b32_e64 v34, v37, v26, s[14:15]
	v_cndmask_b32_e64 v35, v39, v27, s[14:15]
	v_cndmask_b32_e64 v26, v36, v26, s[12:13]
	v_cndmask_b32_e64 v27, v38, v27, s[12:13]
	s_waitcnt vmcnt(0)
	v_cndmask_b32_e64 v28, v33, v28, s[12:13]
	v_cndmask_b32_e64 v29, v32, v29, s[12:13]
	v_cndmask_b32_e64 v30, v34, v30, s[12:13]
	v_cndmask_b32_e64 v31, v35, v31, s[12:13]
	s_branch .LBB0_721
.Lsmp_0_29:
	v_add_co_u32_e32 v20, vcc, 0x2000, v126
	v_mov_b32_e32 v36, v0
	s_nop 0
	v_addc_co_u32_e32 v21, vcc, 0, v127, vcc
	v_add_co_u32_e32 v32, vcc, 0x2000, v124
	global_load_dwordx4 v[20:23], v[20:21], off offset:3088
	s_nop 0
	v_addc_co_u32_e32 v33, vcc, 0, v125, vcc
	global_load_dwordx4 v[32:35], v[32:33], off offset:3088
	v_mov_b32_e32 v37, v0
	v_mov_b32_e32 v38, v1
	v_mov_b32_e32 v39, v1
	v_mov_b32_e32 v41, v2
	v_mov_b32_e32 v43, v3
	v_mov_b32_e32 v40, v2
	v_mov_b32_e32 v42, v3
	v_mov_b32_dpp v36, v36 row_ror:1 row_mask:0xf bank_mask:0xf
	v_mov_b32_dpp v37, v37 row_ror:2 row_mask:0xf bank_mask:0xf
	v_mov_b32_dpp v38, v38 row_ror:1 row_mask:0xf bank_mask:0xf
	v_mov_b32_dpp v39, v39 row_ror:2 row_mask:0xf bank_mask:0xf
	v_mov_b32_dpp v41, v41 row_ror:2 row_mask:0xf bank_mask:0xf
	v_mov_b32_dpp v43, v43 row_ror:2 row_mask:0xf bank_mask:0xf
	v_mov_b32_dpp v40, v40 row_ror:1 row_mask:0xf bank_mask:0xf
	v_mov_b32_dpp v42, v42 row_ror:1 row_mask:0xf bank_mask:0xf
	s_waitcnt vmcnt(1)
	v_cndmask_b32_e64 v37, v37, v20, s[14:15]
	v_cndmask_b32_e64 v20, v36, v20, s[12:13]
	v_cndmask_b32_e64 v36, v39, v21, s[14:15]
	v_cndmask_b32_e64 v21, v38, v21, s[12:13]
	v_cndmask_b32_e64 v38, v41, v22, s[14:15]
	v_cndmask_b32_e64 v39, v43, v23, s[14:15]
	v_cndmask_b32_e64 v22, v40, v22, s[12:13]
	v_cndmask_b32_e64 v23, v42, v23, s[12:13]
	s_waitcnt vmcnt(0)
	v_cndmask_b32_e64 v32, v37, v32, s[12:13]
	v_cndmask_b32_e64 v33, v36, v33, s[12:13]
	v_cndmask_b32_e64 v34, v38, v34, s[12:13]
	v_cndmask_b32_e64 v35, v39, v35, s[12:13]
	s_branch .LBB0_725
.Lnfs_0_14:
	v_mov_b64_e32 v[16:17], s[24:25]
	v_mad_i64_i32 v[16:17], s[10:11], v147, s36, v[16:17]
	v_lshl_add_u64 v[16:17], v[196:197], 2, v[16:17]
	global_store_dwordx4 v[16:17], v[8:11], off offset:16
	v_add_co_u32_e32 v16, vcc, 0x2000, v16
	s_nop 1
	v_addc_co_u32_e32 v17, vcc, 0, v17, vcc
	global_store_dwordx4 v[16:17], v[0:3], off offset:3088
	s_branch .LBB0_727
.Lisl_end_0:
	s_and_saveexec_b64 s[6:7], s[34:35]
	s_cbranch_execnz .Lnfs_0_14

; template <int N> __device__ __forceinline__ float dpp_ror(float v) { const int i = __builtin_bit_cast(int, v); return __builtin_bit_cast(float, __builtin_amdgcn_update_dpp(i, i, 0x120 + N, 0xF, 0xF, false)); }
;     __device__ __forceinline__ void operator()(const f32x4 (&acc)[2][2][4][2], const pg8::Unit& u, int wr, int wc, int fr, int fq, PG8_LAS unsigned char* xl) const {
;     ...
;                         const f32x4 cur = acc[ai][bj][m][n]; f32x4 p1, p2;
;                         if (!sample) { const f32x4 prv = (m == 0) ? hb[bj] : acc[ai][bj][m == 0 ? 0 : m - 1][n];
; #pragma unroll
;                             for (int j = 0; j < 4; ++j) { const float s1 = fr == 15 ? prv[j] : cur[j], s2 = fr >= 14 ? prv[j] : cur[j]; p1[j] = dpp_ror<1>(s1); p2[j] = dpp_ror<2>(s2); }
;                         } else { const int t = fr & 3, b = (row - MP) >> 2;
; #pragma unroll
;                             for (int j = 0; j < 4; ++j) { p1[j] = dpp_ror<1>(cur[j]); p2[j] = dpp_ror<2>(cur[j]); }
;                             const f32x4 c1 = *(const f32x4*)(ctx_s + (size_t)(b * 2 + 1) * FF2 + bj * FF + jc0 + 4 * n), c0 = *(const f32x4*)(ctx_s + (size_t)(b * 2) * FF2 + bj * FF + jc0 + 4 * n);
; #pragma unroll
;                             for (int j = 0; j < 4; ++j) { p2[j] = t == 0 ? c0[j] : (t == 1 ? c1[j] : p2[j]); p1[j] = t == 0 ? c1[j] : p1[j]; }
;                         }
;     ...
;                     if (sample && (fr & 3) >= 2) { const int b = (row - MP) >> 2, t = fr & 3;
; #pragma unroll
;                         for (int bj = 0; bj < 2; ++bj) *(f32x4*)(nf_s + (size_t)(b * 2 + t - 2) * FF2 + bj * FF + jc0 + 4 * n) = acc[ai][bj][m][n];
.LBB0_1685:
	s_or_b64 exec, exec, s[6:7]
	s_nor_b64 s[96:97], s[94:95], s[20:21]
	v_add_u32_e32 v220, v220, v211
	s_and_saveexec_b64 s[6:7], s[96:97]
	s_cbranch_execnz .Lnfs_1_15
.LBB0_1687:
	s_or_b64 exec, exec, s[6:7]
	v_add_u32_e32 v160, 0xffffc010, v221
	v_ashrrev_i32_e32 v160, 1, v160
	v_and_b32_e32 v222, 0xffffffee, v160
	s_and_b64 vcc, exec, s[22:23]
	s_mov_b64 s[6:7], -1
	s_cbranch_vccz .Lsmp_1_30
.LBB0_1689:
.LBB0_1690:
	v_cndmask_b32_e64 v160, v148, v156, s[16:17]
	v_cndmask_b32_e64 v164, v148, v156, s[10:11]
	v_cndmask_b32_e64 v161, v149, v157, s[16:17]
	v_cndmask_b32_e64 v165, v149, v157, s[10:11]
	v_cndmask_b32_e64 v162, v150, v158, s[16:17]
	v_cndmask_b32_e64 v166, v150, v158, s[10:11]
	v_cndmask_b32_e64 v163, v151, v159, s[16:17]
	v_cndmask_b32_e64 v167, v151, v159, s[10:11]
	v_mov_b32_dpp v160, v160 row_ror:1 row_mask:0xf bank_mask:0xf
	v_mov_b32_dpp v164, v164 row_ror:2 row_mask:0xf bank_mask:0xf
	v_mov_b32_dpp v161, v161 row_ror:1 row_mask:0xf bank_mask:0xf
	v_mov_b32_dpp v165, v165 row_ror:2 row_mask:0xf bank_mask:0xf
	v_mov_b32_dpp v162, v162 row_ror:1 row_mask:0xf bank_mask:0xf
	v_mov_b32_dpp v166, v166 row_ror:2 row_mask:0xf bank_mask:0xf
	v_mov_b32_dpp v163, v163 row_ror:1 row_mask:0xf bank_mask:0xf
	v_mov_b32_dpp v167, v167 row_ror:2 row_mask:0xf bank_mask:0xf

; __device__ __forceinline__ unsigned pk2(float lo, float hi) { const f32x2 v = {lo, hi}; const bf16x2_t b = __builtin_convertvector(v, bf16x2_t); return __builtin_bit_cast(unsigned, b); }
;     __device__ __forceinline__ void operator()(const f32x4 (&acc)[2][2][4][2], const pg8::Unit& u, int wr, int wc, int fr, int fq, PG8_LAS unsigned char* xl) const {
;     ...
;                         const f32x4 cur = acc[ai][bj][m][n]; f32x4 p1, p2;
;                         if (!sample) { const f32x4 prv = (m == 0) ? hb[bj] : acc[ai][bj][m == 0 ? 0 : m - 1][n];
; #pragma unroll
;                             for (int j = 0; j < 4; ++j) { const float s1 = fr == 15 ? prv[j] : cur[j], s2 = fr >= 14 ? prv[j] : cur[j]; p1[j] = dpp_ror<1>(s1); p2[j] = dpp_ror<2>(s2); }
;                         } else { const int t = fr & 3, b = (row - MP) >> 2;
; #pragma unroll
;                             for (int j = 0; j < 4; ++j) { p1[j] = dpp_ror<1>(cur[j]); p2[j] = dpp_ror<2>(cur[j]); }
;                             const f32x4 c1 = *(const f32x4*)(ctx_s + (size_t)(b * 2 + 1) * FF2 + bj * FF + jc0 + 4 * n), c0 = *(const f32x4*)(ctx_s + (size_t)(b * 2) * FF2 + bj * FF + jc0 + 4 * n);
; #pragma unroll
;                             for (int j = 0; j < 4; ++j) { p2[j] = t == 0 ? c0[j] : (t == 1 ? c1[j] : p2[j]); p1[j] = t == 0 ? c1[j] : p1[j]; }
;                         }
;                         cc[bj] = bb[bj] + w0[bj] * p2 + w1[bj] * p1 + w2[bj] * cur;
;                     }
;                     const f32x4 gv = gelu_mul4(cc[0], cc[1]);
;                     u32x2 w; w.x = pk2(gv[0], gv[1]); w.y = pk2(gv[2], gv[3]);
;                     *(u32x2*)(G + (size_t)row * FF + jc0 + 4 * n) = w;
;                     if (!sample && ai == 0 && wr == 0 && m == 0 && fr < 2 && (pm & 7) != 0) {
; #pragma unroll
;                         for (int bj = 0; bj < 2; ++bj) *(f32x4*)(PH + (size_t)(pm * 2 + fr) * FF2 + bj * FF + jc0 + 4 * n) = cc[bj];
;                     }
;                     if (sample && (fr & 3) >= 2) { const int b = (row - MP) >> 2, t = fr & 3;
; #pragma unroll
;                         for (int bj = 0; bj < 2; ++bj) *(f32x4*)(nf_s + (size_t)(b * 2 + t - 2) * FF2 + bj * FF + jc0 + 4 * n) = acc[ai][bj][m][n];
.LBB0_1693:
.LBB0_1694:
	v_cndmask_b32_e64 v156, v144, v152, s[16:17]
	v_cndmask_b32_e64 v168, v144, v152, s[10:11]
	v_cndmask_b32_e64 v157, v145, v153, s[16:17]
	v_cndmask_b32_e64 v169, v145, v153, s[10:11]
	v_cndmask_b32_e64 v158, v146, v154, s[16:17]
	v_cndmask_b32_e64 v170, v146, v154, s[10:11]
	v_cndmask_b32_e64 v159, v147, v155, s[16:17]
	v_cndmask_b32_e64 v171, v147, v155, s[10:11]
	v_mov_b32_dpp v156, v156 row_ror:1 row_mask:0xf bank_mask:0xf
	v_mov_b32_dpp v168, v168 row_ror:2 row_mask:0xf bank_mask:0xf
	v_mov_b32_dpp v157, v157 row_ror:1 row_mask:0xf bank_mask:0xf
	v_mov_b32_dpp v169, v169 row_ror:2 row_mask:0xf bank_mask:0xf
	v_mov_b32_dpp v158, v158 row_ror:1 row_mask:0xf bank_mask:0xf
	v_mov_b32_dpp v170, v170 row_ror:2 row_mask:0xf bank_mask:0xf
	v_mov_b32_dpp v159, v159 row_ror:1 row_mask:0xf bank_mask:0xf
	v_mov_b32_dpp v171, v171 row_ror:2 row_mask:0xf bank_mask:0xf
.LBB0_1695:
	v_pk_fma_f32 v[152:153], v[114:115], v[166:167], v[118:119]
	v_pk_fma_f32 v[154:155], v[112:113], v[164:165], v[116:117]
	v_pk_fma_f32 v[152:153], v[106:107], v[162:163], v[152:153]
	v_pk_fma_f32 v[154:155], v[104:105], v[160:161], v[154:155]
	v_pk_fma_f32 v[152:153], v[150:151], v[98:99], v[152:153]
	v_pk_fma_f32 v[154:155], v[148:149], v[96:97], v[154:155]
	v_pk_fma_f32 v[160:161], v[110:111], v[170:171], v[122:123]
	v_pk_fma_f32 v[162:163], v[108:109], v[168:169], v[120:121]
	v_pk_fma_f32 v[158:159], v[102:103], v[158:159], v[160:161]
	v_pk_fma_f32 v[156:157], v[100:101], v[156:157], v[162:163]
	v_pk_mul_f32 v[160:161], v[152:153], v[152:153]
	v_pk_mul_f32 v[162:163], v[154:155], v[154:155]
	v_pk_fma_f32 v[160:161], v[160:161], s[82:83], v[246:247] op_sel_hi:[1,0,0]
	v_pk_fma_f32 v[162:163], v[162:163], s[82:83], v[246:247] op_sel_hi:[1,0,0]
	v_pk_mul_f32 v[160:161], v[152:153], v[160:161]
	v_pk_mul_f32 v[162:163], v[154:155], v[162:163]
	v_exp_f32_e32 v160, v160
	v_exp_f32_e32 v162, v162
	v_exp_f32_e32 v161, v161
	v_exp_f32_e32 v163, v163
	v_pk_fma_f32 v[158:159], v[146:147], v[94:95], v[158:159]
	v_pk_fma_f32 v[156:157], v[144:145], v[92:93], v[156:157]
	v_pk_add_f32 v[160:161], v[160:161], 1.0 op_sel_hi:[1,0]
	v_pk_add_f32 v[162:163], v[162:163], 1.0 op_sel_hi:[1,0]
	v_rcp_f32_e32 v160, v160
	v_rcp_f32_e32 v162, v162
	v_rcp_f32_e32 v161, v161
	v_rcp_f32_e32 v163, v163
	v_pk_mul_f32 v[152:153], v[152:153], v[158:159]
	v_pk_mul_f32 v[154:155], v[154:155], v[156:157]
	v_pk_mul_f32 v[152:153], v[152:153], v[160:161]
	v_pk_mul_f32 v[154:155], v[154:155], v[162:163]
	v_cvt_pk_bf16_f32 v154, v154, v155
	v_cvt_pk_bf16_f32 v155, v152, v153
	s_mul_i32 s100, s77, 16
	v_lshl_add_u64 v[168:169], v[178:179], 0, s[100:101]
	v_add_u32_e32 v170, v222, v211
	ds_bpermute_b32 v236, v244, v168
	ds_bpermute_b32 v237, v244, v169
	ds_bpermute_b32 v238, v244, v154
	ds_bpermute_b32 v239, v244, v155
	s_waitcnt lgkmcnt(0)
	global_store_dwordx2 v[236:237], v[238:239], off
	s_and_saveexec_b64 s[6:7], s[96:97]
	s_cbranch_execnz .Lnfs_1_16
.LBB0_1697:
	s_or_b64 exec, exec, s[6:7]
	v_add_u32_e32 v152, 0xffffc020, v221
	v_ashrrev_i32_e32 v152, 1, v152
	v_and_b32_e32 v171, -10, v152
	s_and_b64 vcc, exec, s[22:23]
	s_mov_b64 s[6:7], -1
	s_cbranch_vccz .Lsmp_1_32
.LBB0_1699:
.LBB0_1700:
	v_cndmask_b32_e64 v152, v140, v148, s[16:17]
	v_cndmask_b32_e64 v156, v140, v148, s[10:11]
	v_cndmask_b32_e64 v153, v141, v149, s[16:17]
	v_cndmask_b32_e64 v157, v141, v149, s[10:11]
	v_cndmask_b32_e64 v154, v142, v150, s[16:17]
	v_cndmask_b32_e64 v158, v142, v150, s[10:11]
	v_cndmask_b32_e64 v155, v143, v151, s[16:17]
	v_cndmask_b32_e64 v159, v143, v151, s[10:11]
	v_mov_b32_dpp v152, v152 row_ror:1 row_mask:0xf bank_mask:0xf
	v_mov_b32_dpp v156, v156 row_ror:2 row_mask:0xf bank_mask:0xf
	v_mov_b32_dpp v153, v153 row_ror:1 row_mask:0xf bank_mask:0xf
	v_mov_b32_dpp v157, v157 row_ror:2 row_mask:0xf bank_mask:0xf
	v_mov_b32_dpp v154, v154 row_ror:1 row_mask:0xf bank_mask:0xf
	v_mov_b32_dpp v158, v158 row_ror:2 row_mask:0xf bank_mask:0xf
	v_mov_b32_dpp v155, v155 row_ror:1 row_mask:0xf bank_mask:0xf
	v_mov_b32_dpp v159, v159 row_ror:2 row_mask:0xf bank_mask:0xf

; __device__ __forceinline__ unsigned pk2(float lo, float hi) { const f32x2 v = {lo, hi}; const bf16x2_t b = __builtin_convertvector(v, bf16x2_t); return __builtin_bit_cast(unsigned, b); }
;     __device__ __forceinline__ void operator()(const f32x4 (&acc)[2][2][4][2], const pg8::Unit& u, int wr, int wc, int fr, int fq, PG8_LAS unsigned char* xl) const {
;     ...
;                         const f32x4 cur = acc[ai][bj][m][n]; f32x4 p1, p2;
;                         if (!sample) { const f32x4 prv = (m == 0) ? hb[bj] : acc[ai][bj][m == 0 ? 0 : m - 1][n];
; #pragma unroll
;                             for (int j = 0; j < 4; ++j) { const float s1 = fr == 15 ? prv[j] : cur[j], s2 = fr >= 14 ? prv[j] : cur[j]; p1[j] = dpp_ror<1>(s1); p2[j] = dpp_ror<2>(s2); }
;                         } else { const int t = fr & 3, b = (row - MP) >> 2;
; #pragma unroll
;                             for (int j = 0; j < 4; ++j) { p1[j] = dpp_ror<1>(cur[j]); p2[j] = dpp_ror<2>(cur[j]); }
;                             const f32x4 c1 = *(const f32x4*)(ctx_s + (size_t)(b * 2 + 1) * FF2 + bj * FF + jc0 + 4 * n), c0 = *(const f32x4*)(ctx_s + (size_t)(b * 2) * FF2 + bj * FF + jc0 + 4 * n);
; #pragma unroll
;                             for (int j = 0; j < 4; ++j) { p2[j] = t == 0 ? c0[j] : (t == 1 ? c1[j] : p2[j]); p1[j] = t == 0 ? c1[j] : p1[j]; }
;                         }
;                         cc[bj] = bb[bj] + w0[bj] * p2 + w1[bj] * p1 + w2[bj] * cur;
;                     }
;                     const f32x4 gv = gelu_mul4(cc[0], cc[1]);
;                     u32x2 w; w.x = pk2(gv[0], gv[1]); w.y = pk2(gv[2], gv[3]);
;                     *(u32x2*)(G + (size_t)row * FF + jc0 + 4 * n) = w;
;                     if (!sample && ai == 0 && wr == 0 && m == 0 && fr < 2 && (pm & 7) != 0) {
; #pragma unroll
;                         for (int bj = 0; bj < 2; ++bj) *(f32x4*)(PH + (size_t)(pm * 2 + fr) * FF2 + bj * FF + jc0 + 4 * n) = cc[bj];
;                     }
;                     if (sample && (fr & 3) >= 2) { const int b = (row - MP) >> 2, t = fr & 3;
; #pragma unroll
;                         for (int bj = 0; bj < 2; ++bj) *(f32x4*)(nf_s + (size_t)(b * 2 + t - 2) * FF2 + bj * FF + jc0 + 4 * n) = acc[ai][bj][m][n];
.LBB0_1703:
.LBB0_1704:
	v_cndmask_b32_e64 v148, v136, v144, s[16:17]
	v_cndmask_b32_e64 v160, v136, v144, s[10:11]
	v_cndmask_b32_e64 v149, v137, v145, s[16:17]
	v_cndmask_b32_e64 v161, v137, v145, s[10:11]
	v_cndmask_b32_e64 v150, v138, v146, s[16:17]
	v_cndmask_b32_e64 v162, v138, v146, s[10:11]
	v_cndmask_b32_e64 v151, v139, v147, s[16:17]
	v_cndmask_b32_e64 v163, v139, v147, s[10:11]
	v_mov_b32_dpp v148, v148 row_ror:1 row_mask:0xf bank_mask:0xf
	v_mov_b32_dpp v160, v160 row_ror:2 row_mask:0xf bank_mask:0xf
	v_mov_b32_dpp v149, v149 row_ror:1 row_mask:0xf bank_mask:0xf
	v_mov_b32_dpp v161, v161 row_ror:2 row_mask:0xf bank_mask:0xf
	v_mov_b32_dpp v150, v150 row_ror:1 row_mask:0xf bank_mask:0xf
	v_mov_b32_dpp v162, v162 row_ror:2 row_mask:0xf bank_mask:0xf
	v_mov_b32_dpp v151, v151 row_ror:1 row_mask:0xf bank_mask:0xf
	v_mov_b32_dpp v163, v163 row_ror:2 row_mask:0xf bank_mask:0xf
.LBB0_1705:
	v_pk_fma_f32 v[144:145], v[114:115], v[158:159], v[118:119]
	v_pk_fma_f32 v[146:147], v[112:113], v[156:157], v[116:117]
	v_pk_fma_f32 v[144:145], v[106:107], v[154:155], v[144:145]
	v_pk_fma_f32 v[146:147], v[104:105], v[152:153], v[146:147]
	v_pk_fma_f32 v[144:145], v[142:143], v[98:99], v[144:145]
	v_pk_fma_f32 v[146:147], v[140:141], v[96:97], v[146:147]
	v_pk_fma_f32 v[152:153], v[110:111], v[162:163], v[122:123]
	v_pk_fma_f32 v[154:155], v[108:109], v[160:161], v[120:121]
	v_pk_fma_f32 v[150:151], v[102:103], v[150:151], v[152:153]
	v_pk_fma_f32 v[148:149], v[100:101], v[148:149], v[154:155]
	v_pk_mul_f32 v[152:153], v[144:145], v[144:145]
	v_pk_mul_f32 v[154:155], v[146:147], v[146:147]
	v_pk_fma_f32 v[152:153], v[152:153], s[82:83], v[246:247] op_sel_hi:[1,0,0]
	v_pk_fma_f32 v[154:155], v[154:155], s[82:83], v[246:247] op_sel_hi:[1,0,0]
	v_pk_mul_f32 v[152:153], v[144:145], v[152:153]
	v_pk_mul_f32 v[154:155], v[146:147], v[154:155]
	v_exp_f32_e32 v152, v152
	v_exp_f32_e32 v154, v154
	v_exp_f32_e32 v153, v153
	v_exp_f32_e32 v155, v155
	v_pk_fma_f32 v[150:151], v[138:139], v[94:95], v[150:151]
	v_pk_fma_f32 v[148:149], v[136:137], v[92:93], v[148:149]
	v_pk_add_f32 v[152:153], v[152:153], 1.0 op_sel_hi:[1,0]
	v_pk_add_f32 v[154:155], v[154:155], 1.0 op_sel_hi:[1,0]
	v_rcp_f32_e32 v152, v152
	v_rcp_f32_e32 v154, v154
	v_rcp_f32_e32 v153, v153
	v_rcp_f32_e32 v155, v155
	v_pk_mul_f32 v[144:145], v[144:145], v[150:151]
	v_pk_mul_f32 v[146:147], v[146:147], v[148:149]
	v_pk_mul_f32 v[144:145], v[144:145], v[152:153]
	v_pk_mul_f32 v[146:147], v[146:147], v[154:155]
	v_cvt_pk_bf16_f32 v146, v146, v147
	v_cvt_pk_bf16_f32 v147, v144, v145
	s_mul_i32 s100, s77, 32
	v_lshl_add_u64 v[160:161], v[178:179], 0, s[100:101]
	v_add_u32_e32 v162, v171, v211
	ds_bpermute_b32 v236, v244, v160
	ds_bpermute_b32 v237, v244, v161
	ds_bpermute_b32 v238, v244, v146
	ds_bpermute_b32 v239, v244, v147
	s_waitcnt lgkmcnt(0)
	global_store_dwordx2 v[236:237], v[238:239], off
	s_and_saveexec_b64 s[6:7], s[96:97]
	s_cbranch_execnz .Lnfs_1_17
.LBB0_1707:
	s_or_b64 exec, exec, s[6:7]
	v_add_u32_e32 v144, 0xffffc030, v221
	v_ashrrev_i32_e32 v144, 1, v144
	v_and_b32_e32 v163, -2, v144
	s_and_b64 vcc, exec, s[22:23]
	s_mov_b64 s[6:7], -1
	s_cbranch_vccz .Lsmp_1_34
.LBB0_1709:
.LBB0_1710:
	v_cndmask_b32_e64 v144, v132, v140, s[16:17]
	v_cndmask_b32_e64 v148, v132, v140, s[10:11]
	v_cndmask_b32_e64 v145, v133, v141, s[16:17]
	v_cndmask_b32_e64 v149, v133, v141, s[10:11]
	v_cndmask_b32_e64 v146, v134, v142, s[16:17]
	v_cndmask_b32_e64 v150, v134, v142, s[10:11]
	v_cndmask_b32_e64 v147, v135, v143, s[16:17]
	v_cndmask_b32_e64 v151, v135, v143, s[10:11]
	v_mov_b32_dpp v144, v144 row_ror:1 row_mask:0xf bank_mask:0xf
	v_mov_b32_dpp v148, v148 row_ror:2 row_mask:0xf bank_mask:0xf
	v_mov_b32_dpp v145, v145 row_ror:1 row_mask:0xf bank_mask:0xf
	v_mov_b32_dpp v149, v149 row_ror:2 row_mask:0xf bank_mask:0xf
	v_mov_b32_dpp v146, v146 row_ror:1 row_mask:0xf bank_mask:0xf
	v_mov_b32_dpp v150, v150 row_ror:2 row_mask:0xf bank_mask:0xf
	v_mov_b32_dpp v147, v147 row_ror:1 row_mask:0xf bank_mask:0xf
	v_mov_b32_dpp v151, v151 row_ror:2 row_mask:0xf bank_mask:0xf

; __device__ __forceinline__ unsigned pk2(float lo, float hi) { const f32x2 v = {lo, hi}; const bf16x2_t b = __builtin_convertvector(v, bf16x2_t); return __builtin_bit_cast(unsigned, b); }
;     __device__ __forceinline__ void operator()(const f32x4 (&acc)[2][2][4][2], const pg8::Unit& u, int wr, int wc, int fr, int fq, PG8_LAS unsigned char* xl) const {
;     ...
;                         const f32x4 cur = acc[ai][bj][m][n]; f32x4 p1, p2;
;                         if (!sample) { const f32x4 prv = (m == 0) ? hb[bj] : acc[ai][bj][m == 0 ? 0 : m - 1][n];
; #pragma unroll
;                             for (int j = 0; j < 4; ++j) { const float s1 = fr == 15 ? prv[j] : cur[j], s2 = fr >= 14 ? prv[j] : cur[j]; p1[j] = dpp_ror<1>(s1); p2[j] = dpp_ror<2>(s2); }
;                         } else { const int t = fr & 3, b = (row - MP) >> 2;
; #pragma unroll
;                             for (int j = 0; j < 4; ++j) { p1[j] = dpp_ror<1>(cur[j]); p2[j] = dpp_ror<2>(cur[j]); }
;                             const f32x4 c1 = *(const f32x4*)(ctx_s + (size_t)(b * 2 + 1) * FF2 + bj * FF + jc0 + 4 * n), c0 = *(const f32x4*)(ctx_s + (size_t)(b * 2) * FF2 + bj * FF + jc0 + 4 * n);
; #pragma unroll
;                             for (int j = 0; j < 4; ++j) { p2[j] = t == 0 ? c0[j] : (t == 1 ? c1[j] : p2[j]); p1[j] = t == 0 ? c1[j] : p1[j]; }
;                         }
;                         cc[bj] = bb[bj] + w0[bj] * p2 + w1[bj] * p1 + w2[bj] * cur;
;                     }
;                     const f32x4 gv = gelu_mul4(cc[0], cc[1]);
;                     u32x2 w; w.x = pk2(gv[0], gv[1]); w.y = pk2(gv[2], gv[3]);
;                     *(u32x2*)(G + (size_t)row * FF + jc0 + 4 * n) = w;
;                     if (!sample && ai == 0 && wr == 0 && m == 0 && fr < 2 && (pm & 7) != 0) {
; #pragma unroll
;                         for (int bj = 0; bj < 2; ++bj) *(f32x4*)(PH + (size_t)(pm * 2 + fr) * FF2 + bj * FF + jc0 + 4 * n) = cc[bj];
;                     }
;                     if (sample && (fr & 3) >= 2) { const int b = (row - MP) >> 2, t = fr & 3;
; #pragma unroll
;                         for (int bj = 0; bj < 2; ++bj) *(f32x4*)(nf_s + (size_t)(b * 2 + t - 2) * FF2 + bj * FF + jc0 + 4 * n) = acc[ai][bj][m][n];
.LBB0_1713:
.LBB0_1714:
	v_cndmask_b32_e64 v140, v128, v136, s[16:17]
	v_cndmask_b32_e64 v152, v128, v136, s[10:11]
	v_cndmask_b32_e64 v141, v129, v137, s[16:17]
	v_cndmask_b32_e64 v153, v129, v137, s[10:11]
	v_cndmask_b32_e64 v142, v130, v138, s[16:17]
	v_cndmask_b32_e64 v154, v130, v138, s[10:11]
	v_cndmask_b32_e64 v143, v131, v139, s[16:17]
	v_cndmask_b32_e64 v155, v131, v139, s[10:11]
	v_mov_b32_dpp v140, v140 row_ror:1 row_mask:0xf bank_mask:0xf
	v_mov_b32_dpp v152, v152 row_ror:2 row_mask:0xf bank_mask:0xf
	v_mov_b32_dpp v141, v141 row_ror:1 row_mask:0xf bank_mask:0xf
	v_mov_b32_dpp v153, v153 row_ror:2 row_mask:0xf bank_mask:0xf
	v_mov_b32_dpp v142, v142 row_ror:1 row_mask:0xf bank_mask:0xf
	v_mov_b32_dpp v154, v154 row_ror:2 row_mask:0xf bank_mask:0xf
	v_mov_b32_dpp v143, v143 row_ror:1 row_mask:0xf bank_mask:0xf
	v_mov_b32_dpp v155, v155 row_ror:2 row_mask:0xf bank_mask:0xf
.LBB0_1715:
	v_pk_fma_f32 v[136:137], v[114:115], v[150:151], v[118:119]
	v_pk_fma_f32 v[138:139], v[112:113], v[148:149], v[116:117]
	v_pk_fma_f32 v[136:137], v[106:107], v[146:147], v[136:137]
	v_pk_fma_f32 v[138:139], v[104:105], v[144:145], v[138:139]
	v_pk_fma_f32 v[136:137], v[134:135], v[98:99], v[136:137]
	v_pk_fma_f32 v[138:139], v[132:133], v[96:97], v[138:139]
	v_pk_fma_f32 v[144:145], v[110:111], v[154:155], v[122:123]
	v_pk_fma_f32 v[146:147], v[108:109], v[152:153], v[120:121]
	v_pk_fma_f32 v[142:143], v[102:103], v[142:143], v[144:145]
	v_pk_fma_f32 v[140:141], v[100:101], v[140:141], v[146:147]
	v_pk_mul_f32 v[144:145], v[136:137], v[136:137]
	v_pk_mul_f32 v[146:147], v[138:139], v[138:139]
	v_pk_fma_f32 v[144:145], v[144:145], s[82:83], v[246:247] op_sel_hi:[1,0,0]
	v_pk_fma_f32 v[146:147], v[146:147], s[82:83], v[246:247] op_sel_hi:[1,0,0]
	v_pk_mul_f32 v[144:145], v[136:137], v[144:145]
	v_pk_mul_f32 v[146:147], v[138:139], v[146:147]
	v_exp_f32_e32 v144, v144
	v_exp_f32_e32 v146, v146
	v_exp_f32_e32 v145, v145
	v_exp_f32_e32 v147, v147
	v_pk_fma_f32 v[142:143], v[130:131], v[94:95], v[142:143]
	v_pk_fma_f32 v[140:141], v[128:129], v[92:93], v[140:141]
	v_pk_add_f32 v[144:145], v[144:145], 1.0 op_sel_hi:[1,0]
	v_pk_add_f32 v[146:147], v[146:147], 1.0 op_sel_hi:[1,0]
	v_rcp_f32_e32 v144, v144
	v_rcp_f32_e32 v146, v146
	v_rcp_f32_e32 v145, v145
	v_rcp_f32_e32 v147, v147
	v_pk_mul_f32 v[136:137], v[136:137], v[142:143]
	v_pk_mul_f32 v[138:139], v[138:139], v[140:141]
	v_pk_mul_f32 v[136:137], v[136:137], v[144:145]
	v_pk_mul_f32 v[138:139], v[138:139], v[146:147]
	v_cvt_pk_bf16_f32 v138, v138, v139
	v_cvt_pk_bf16_f32 v139, v136, v137
	s_mul_i32 s100, s77, 48
	v_lshl_add_u64 v[152:153], v[178:179], 0, s[100:101]
	v_add_u32_e32 v154, v163, v211
	ds_bpermute_b32 v236, v244, v152
	ds_bpermute_b32 v237, v244, v153
	ds_bpermute_b32 v238, v244, v138
	ds_bpermute_b32 v239, v244, v139
	s_waitcnt lgkmcnt(0)
	global_store_dwordx2 v[236:237], v[238:239], off
	s_and_saveexec_b64 s[6:7], s[96:97]
	s_cbranch_execnz .Lnfs_1_18

; template <int N> __device__ __forceinline__ float dpp_ror(float v) { const int i = __builtin_bit_cast(int, v); return __builtin_bit_cast(float, __builtin_amdgcn_update_dpp(i, i, 0x120 + N, 0xF, 0xF, false)); }
;     __device__ __forceinline__ void operator()(const f32x4 (&acc)[2][2][4][2], const pg8::Unit& u, int wr, int wc, int fr, int fq, PG8_LAS unsigned char* xl) const {
;     ...
;                         if (!sample) { const f32x4 prv = (m == 0) ? hb[bj] : acc[ai][bj][m == 0 ? 0 : m - 1][n];
; #pragma unroll
;                             for (int j = 0; j < 4; ++j) { const float s1 = fr == 15 ? prv[j] : cur[j], s2 = fr >= 14 ? prv[j] : cur[j]; p1[j] = dpp_ror<1>(s1); p2[j] = dpp_ror<2>(s2); }
;                         } else { const int t = fr & 3, b = (row - MP) >> 2;
; #pragma unroll
;                             for (int j = 0; j < 4; ++j) { p1[j] = dpp_ror<1>(cur[j]); p2[j] = dpp_ror<2>(cur[j]); }
;                             const f32x4 c1 = *(const f32x4*)(ctx_s + (size_t)(b * 2 + 1) * FF2 + bj * FF + jc0 + 4 * n), c0 = *(const f32x4*)(ctx_s + (size_t)(b * 2) * FF2 + bj * FF + jc0 + 4 * n);
; #pragma unroll
;                             for (int j = 0; j < 4; ++j) { p2[j] = t == 0 ? c0[j] : (t == 1 ? c1[j] : p2[j]); p1[j] = t == 0 ? c1[j] : p1[j]; }
;                         }
.LBB0_1719:
	s_or_b64 exec, exec, s[6:7]
	v_add_u32_e32 v132, 0xffffc080, v221
	v_ashrrev_i32_e32 v132, 1, v132
	v_and_b32_e32 v155, 0xffffffe6, v132
	s_and_b64 vcc, exec, s[22:23]
	s_mov_b64 s[6:7], -1
	s_cbranch_vccz .Lsmp_1_36
.LBB0_1721:
.LBB0_1722:
	s_waitcnt lgkmcnt(1)
	v_cndmask_b32_e64 v132, v124, v140, s[16:17]
	v_cndmask_b32_e64 v136, v124, v140, s[10:11]
	v_cndmask_b32_e64 v133, v125, v141, s[16:17]
	v_cndmask_b32_e64 v137, v125, v141, s[10:11]
	v_cndmask_b32_e64 v134, v126, v142, s[16:17]
	v_cndmask_b32_e64 v138, v126, v142, s[10:11]
	v_cndmask_b32_e64 v135, v127, v143, s[16:17]
	v_cndmask_b32_e64 v139, v127, v143, s[10:11]
	v_mov_b32_dpp v132, v132 row_ror:1 row_mask:0xf bank_mask:0xf
	v_mov_b32_dpp v136, v136 row_ror:2 row_mask:0xf bank_mask:0xf
	v_mov_b32_dpp v133, v133 row_ror:1 row_mask:0xf bank_mask:0xf
	v_mov_b32_dpp v137, v137 row_ror:2 row_mask:0xf bank_mask:0xf
	v_mov_b32_dpp v134, v134 row_ror:1 row_mask:0xf bank_mask:0xf
	v_mov_b32_dpp v138, v138 row_ror:2 row_mask:0xf bank_mask:0xf
	v_mov_b32_dpp v135, v135 row_ror:1 row_mask:0xf bank_mask:0xf
	v_mov_b32_dpp v139, v139 row_ror:2 row_mask:0xf bank_mask:0xf

; template <int N> __device__ __forceinline__ float dpp_ror(float v) { const int i = __builtin_bit_cast(int, v); return __builtin_bit_cast(float, __builtin_amdgcn_update_dpp(i, i, 0x120 + N, 0xF, 0xF, false)); }
;     __device__ __forceinline__ void operator()(const f32x4 (&acc)[2][2][4][2], const pg8::Unit& u, int wr, int wc, int fr, int fq, PG8_LAS unsigned char* xl) const {
;     ...
;                         const f32x4 cur = acc[ai][bj][m][n]; f32x4 p1, p2;
;                         if (!sample) { const f32x4 prv = (m == 0) ? hb[bj] : acc[ai][bj][m == 0 ? 0 : m - 1][n];
; #pragma unroll
;                             for (int j = 0; j < 4; ++j) { const float s1 = fr == 15 ? prv[j] : cur[j], s2 = fr >= 14 ? prv[j] : cur[j]; p1[j] = dpp_ror<1>(s1); p2[j] = dpp_ror<2>(s2); }
;                         } else { const int t = fr & 3, b = (row - MP) >> 2;
; #pragma unroll
;                             for (int j = 0; j < 4; ++j) { p1[j] = dpp_ror<1>(cur[j]); p2[j] = dpp_ror<2>(cur[j]); }
;                             const f32x4 c1 = *(const f32x4*)(ctx_s + (size_t)(b * 2 + 1) * FF2 + bj * FF + jc0 + 4 * n), c0 = *(const f32x4*)(ctx_s + (size_t)(b * 2) * FF2 + bj * FF + jc0 + 4 * n);
; #pragma unroll
;                             for (int j = 0; j < 4; ++j) { p2[j] = t == 0 ? c0[j] : (t == 1 ? c1[j] : p2[j]); p1[j] = t == 0 ? c1[j] : p1[j]; }
;                         }
;     ...
;                     if (sample && (fr & 3) >= 2) { const int b = (row - MP) >> 2, t = fr & 3;
; #pragma unroll
;                         for (int bj = 0; bj < 2; ++bj) *(f32x4*)(nf_s + (size_t)(b * 2 + t - 2) * FF2 + bj * FF + jc0 + 4 * n) = acc[ai][bj][m][n];
.LBB0_1725:
.LBB0_1726:
	s_waitcnt lgkmcnt(0)
	v_cndmask_b32_e64 v140, v88, v128, s[16:17]
	v_cndmask_b32_e64 v144, v88, v128, s[10:11]
	v_cndmask_b32_e64 v141, v89, v129, s[16:17]
	v_cndmask_b32_e64 v145, v89, v129, s[10:11]
	v_cndmask_b32_e64 v142, v90, v130, s[16:17]
	v_cndmask_b32_e64 v146, v90, v130, s[10:11]
	v_cndmask_b32_e64 v143, v91, v131, s[16:17]
	v_cndmask_b32_e64 v147, v91, v131, s[10:11]
	v_mov_b32_dpp v140, v140 row_ror:1 row_mask:0xf bank_mask:0xf
	v_mov_b32_dpp v144, v144 row_ror:2 row_mask:0xf bank_mask:0xf
	v_mov_b32_dpp v141, v141 row_ror:1 row_mask:0xf bank_mask:0xf
	v_mov_b32_dpp v145, v145 row_ror:2 row_mask:0xf bank_mask:0xf
	v_mov_b32_dpp v142, v142 row_ror:1 row_mask:0xf bank_mask:0xf
	v_mov_b32_dpp v146, v146 row_ror:2 row_mask:0xf bank_mask:0xf
	v_mov_b32_dpp v143, v143 row_ror:1 row_mask:0xf bank_mask:0xf
	v_mov_b32_dpp v147, v147 row_ror:2 row_mask:0xf bank_mask:0xf
.LBB0_1727:
	s_waitcnt lgkmcnt(0)
	v_pk_fma_f32 v[128:129], v[114:115], v[138:139], v[118:119]
	v_pk_fma_f32 v[130:131], v[112:113], v[136:137], v[116:117]
	v_pk_fma_f32 v[128:129], v[106:107], v[134:135], v[128:129]
	v_pk_fma_f32 v[130:131], v[104:105], v[132:133], v[130:131]
	v_pk_fma_f32 v[128:129], v[126:127], v[98:99], v[128:129]
	v_pk_fma_f32 v[130:131], v[124:125], v[96:97], v[130:131]
	v_pk_fma_f32 v[134:135], v[108:109], v[144:145], v[120:121]
	v_pk_mul_f32 v[136:137], v[128:129], v[128:129]
	v_pk_fma_f32 v[134:135], v[100:101], v[140:141], v[134:135]
	v_pk_mul_f32 v[138:139], v[130:131], v[130:131]
	v_pk_fma_f32 v[136:137], v[136:137], s[82:83], v[246:247] op_sel_hi:[1,0,0]
	v_pk_fma_f32 v[138:139], v[138:139], s[82:83], v[246:247] op_sel_hi:[1,0,0]
	v_pk_mul_f32 v[136:137], v[128:129], v[136:137]
	v_pk_mul_f32 v[138:139], v[130:131], v[138:139]
	v_exp_f32_e32 v136, v136
	v_exp_f32_e32 v138, v138
	v_exp_f32_e32 v137, v137
	v_exp_f32_e32 v139, v139
	v_pk_fma_f32 v[132:133], v[110:111], v[146:147], v[122:123]
	v_pk_fma_f32 v[134:135], v[88:89], v[92:93], v[134:135]
	v_pk_add_f32 v[136:137], v[136:137], 1.0 op_sel_hi:[1,0]
	v_pk_add_f32 v[138:139], v[138:139], 1.0 op_sel_hi:[1,0]
	v_rcp_f32_e32 v136, v136
	v_rcp_f32_e32 v138, v138
	v_rcp_f32_e32 v137, v137
	v_rcp_f32_e32 v139, v139
	v_pk_fma_f32 v[132:133], v[102:103], v[142:143], v[132:133]
	v_pk_mul_f32 v[130:131], v[130:131], v[134:135]
	v_pk_fma_f32 v[132:133], v[90:91], v[94:95], v[132:133]
	v_pk_mul_f32 v[130:131], v[130:131], v[138:139]
	v_pk_mul_f32 v[128:129], v[128:129], v[132:133]
	v_pk_mul_f32 v[128:129], v[128:129], v[136:137]
	v_cvt_pk_bf16_f32 v130, v130, v131
	v_cvt_pk_bf16_f32 v131, v128, v129
	s_mul_i32 s100, s77, 0x80
	v_lshl_add_u64 v[144:145], v[178:179], 0, s[100:101]
	v_add_u32_e32 v146, v155, v211
	ds_bpermute_b32 v236, v244, v144
	ds_bpermute_b32 v237, v244, v145
	ds_bpermute_b32 v238, v244, v130
	ds_bpermute_b32 v239, v244, v131
	s_waitcnt lgkmcnt(0)
	global_store_dwordx2 v[236:237], v[238:239], off
	s_and_saveexec_b64 s[6:7], s[96:97]
	s_cbranch_execnz .Lnfs_1_19
.LBB0_1729:
	s_or_b64 exec, exec, s[6:7]
	v_add_u32_e32 v128, 0xffffc090, v221
	v_ashrrev_i32_e32 v128, 1, v128
	v_and_b32_e32 v147, 0xffffffee, v128
	s_and_b64 vcc, exec, s[22:23]
	s_mov_b64 s[6:7], -1
	s_cbranch_vccz .Lsmp_1_38
.LBB0_1731:
.LBB0_1732:
	v_cndmask_b32_e64 v128, v84, v124, s[16:17]
	v_cndmask_b32_e64 v132, v84, v124, s[10:11]
	v_cndmask_b32_e64 v129, v85, v125, s[16:17]
	v_cndmask_b32_e64 v133, v85, v125, s[10:11]
	v_cndmask_b32_e64 v130, v86, v126, s[16:17]
	v_cndmask_b32_e64 v134, v86, v126, s[10:11]
	v_cndmask_b32_e64 v131, v87, v127, s[16:17]
	v_cndmask_b32_e64 v135, v87, v127, s[10:11]
	v_mov_b32_dpp v128, v128 row_ror:1 row_mask:0xf bank_mask:0xf
	v_mov_b32_dpp v132, v132 row_ror:2 row_mask:0xf bank_mask:0xf
	v_mov_b32_dpp v129, v129 row_ror:1 row_mask:0xf bank_mask:0xf
	v_mov_b32_dpp v133, v133 row_ror:2 row_mask:0xf bank_mask:0xf
	v_mov_b32_dpp v130, v130 row_ror:1 row_mask:0xf bank_mask:0xf
	v_mov_b32_dpp v134, v134 row_ror:2 row_mask:0xf bank_mask:0xf
	v_mov_b32_dpp v131, v131 row_ror:1 row_mask:0xf bank_mask:0xf
	v_mov_b32_dpp v135, v135 row_ror:2 row_mask:0xf bank_mask:0xf

; __device__ __forceinline__ unsigned pk2(float lo, float hi) { const f32x2 v = {lo, hi}; const bf16x2_t b = __builtin_convertvector(v, bf16x2_t); return __builtin_bit_cast(unsigned, b); }
;     __device__ __forceinline__ void operator()(const f32x4 (&acc)[2][2][4][2], const pg8::Unit& u, int wr, int wc, int fr, int fq, PG8_LAS unsigned char* xl) const {
;     ...
;                         const f32x4 cur = acc[ai][bj][m][n]; f32x4 p1, p2;
;                         if (!sample) { const f32x4 prv = (m == 0) ? hb[bj] : acc[ai][bj][m == 0 ? 0 : m - 1][n];
; #pragma unroll
;                             for (int j = 0; j < 4; ++j) { const float s1 = fr == 15 ? prv[j] : cur[j], s2 = fr >= 14 ? prv[j] : cur[j]; p1[j] = dpp_ror<1>(s1); p2[j] = dpp_ror<2>(s2); }
;                         } else { const int t = fr & 3, b = (row - MP) >> 2;
; #pragma unroll
;                             for (int j = 0; j < 4; ++j) { p1[j] = dpp_ror<1>(cur[j]); p2[j] = dpp_ror<2>(cur[j]); }
;                             const f32x4 c1 = *(const f32x4*)(ctx_s + (size_t)(b * 2 + 1) * FF2 + bj * FF + jc0 + 4 * n), c0 = *(const f32x4*)(ctx_s + (size_t)(b * 2) * FF2 + bj * FF + jc0 + 4 * n);
; #pragma unroll
;                             for (int j = 0; j < 4; ++j) { p2[j] = t == 0 ? c0[j] : (t == 1 ? c1[j] : p2[j]); p1[j] = t == 0 ? c1[j] : p1[j]; }
;                         }
;                         cc[bj] = bb[bj] + w0[bj] * p2 + w1[bj] * p1 + w2[bj] * cur;
;                     }
;                     const f32x4 gv = gelu_mul4(cc[0], cc[1]);
;                     u32x2 w; w.x = pk2(gv[0], gv[1]); w.y = pk2(gv[2], gv[3]);
;                     *(u32x2*)(G + (size_t)row * FF + jc0 + 4 * n) = w;
;                     if (!sample && ai == 0 && wr == 0 && m == 0 && fr < 2 && (pm & 7) != 0) {
; #pragma unroll
;                         for (int bj = 0; bj < 2; ++bj) *(f32x4*)(PH + (size_t)(pm * 2 + fr) * FF2 + bj * FF + jc0 + 4 * n) = cc[bj];
;                     }
;                     if (sample && (fr & 3) >= 2) { const int b = (row - MP) >> 2, t = fr & 3;
; #pragma unroll
;                         for (int bj = 0; bj < 2; ++bj) *(f32x4*)(nf_s + (size_t)(b * 2 + t - 2) * FF2 + bj * FF + jc0 + 4 * n) = acc[ai][bj][m][n];
.LBB0_1735:
.LBB0_1736:
	v_cndmask_b32_e64 v124, v80, v88, s[16:17]
	v_cndmask_b32_e64 v136, v80, v88, s[10:11]
	v_cndmask_b32_e64 v125, v81, v89, s[16:17]
	v_cndmask_b32_e64 v137, v81, v89, s[10:11]
	v_cndmask_b32_e64 v126, v82, v90, s[16:17]
	v_cndmask_b32_e64 v138, v82, v90, s[10:11]
	v_cndmask_b32_e64 v127, v83, v91, s[16:17]
	v_cndmask_b32_e64 v139, v83, v91, s[10:11]
	v_mov_b32_dpp v124, v124 row_ror:1 row_mask:0xf bank_mask:0xf
	v_mov_b32_dpp v136, v136 row_ror:2 row_mask:0xf bank_mask:0xf
	v_mov_b32_dpp v125, v125 row_ror:1 row_mask:0xf bank_mask:0xf
	v_mov_b32_dpp v137, v137 row_ror:2 row_mask:0xf bank_mask:0xf
	v_mov_b32_dpp v126, v126 row_ror:1 row_mask:0xf bank_mask:0xf
	v_mov_b32_dpp v138, v138 row_ror:2 row_mask:0xf bank_mask:0xf
	v_mov_b32_dpp v127, v127 row_ror:1 row_mask:0xf bank_mask:0xf
	v_mov_b32_dpp v139, v139 row_ror:2 row_mask:0xf bank_mask:0xf
.LBB0_1737:
	v_pk_fma_f32 v[88:89], v[114:115], v[134:135], v[118:119]
	v_pk_fma_f32 v[90:91], v[112:113], v[132:133], v[116:117]
	v_pk_fma_f32 v[88:89], v[106:107], v[130:131], v[88:89]
	v_pk_fma_f32 v[90:91], v[104:105], v[128:129], v[90:91]
	v_pk_fma_f32 v[88:89], v[86:87], v[98:99], v[88:89]
	v_pk_fma_f32 v[90:91], v[84:85], v[96:97], v[90:91]
	v_pk_fma_f32 v[128:129], v[110:111], v[138:139], v[122:123]
	v_pk_fma_f32 v[130:131], v[108:109], v[136:137], v[120:121]
	v_pk_fma_f32 v[126:127], v[102:103], v[126:127], v[128:129]
	v_pk_fma_f32 v[124:125], v[100:101], v[124:125], v[130:131]
	v_pk_mul_f32 v[128:129], v[88:89], v[88:89]
	v_pk_mul_f32 v[130:131], v[90:91], v[90:91]
	v_pk_fma_f32 v[128:129], v[128:129], s[82:83], v[246:247] op_sel_hi:[1,0,0]
	v_pk_fma_f32 v[130:131], v[130:131], s[82:83], v[246:247] op_sel_hi:[1,0,0]
	v_pk_mul_f32 v[128:129], v[88:89], v[128:129]
	v_pk_mul_f32 v[130:131], v[90:91], v[130:131]
	v_exp_f32_e32 v128, v128
	v_exp_f32_e32 v130, v130
	v_exp_f32_e32 v129, v129
	v_exp_f32_e32 v131, v131
	v_pk_fma_f32 v[126:127], v[82:83], v[94:95], v[126:127]
	v_pk_fma_f32 v[124:125], v[80:81], v[92:93], v[124:125]
	v_pk_add_f32 v[128:129], v[128:129], 1.0 op_sel_hi:[1,0]
	v_pk_add_f32 v[130:131], v[130:131], 1.0 op_sel_hi:[1,0]
	v_rcp_f32_e32 v128, v128
	v_rcp_f32_e32 v130, v130
	v_rcp_f32_e32 v129, v129
	v_rcp_f32_e32 v131, v131
	v_pk_mul_f32 v[88:89], v[88:89], v[126:127]
	v_pk_mul_f32 v[90:91], v[90:91], v[124:125]
	v_pk_mul_f32 v[88:89], v[88:89], v[128:129]
	v_pk_mul_f32 v[90:91], v[90:91], v[130:131]
	v_cvt_pk_bf16_f32 v90, v90, v91
	v_cvt_pk_bf16_f32 v91, v88, v89
	s_mul_i32 s100, s77, 0x90
	v_lshl_add_u64 v[136:137], v[178:179], 0, s[100:101]
	v_add_u32_e32 v138, v147, v211
	ds_bpermute_b32 v236, v244, v136
	ds_bpermute_b32 v237, v244, v137
	ds_bpermute_b32 v238, v244, v90
	ds_bpermute_b32 v239, v244, v91
	s_waitcnt lgkmcnt(0)
	global_store_dwordx2 v[236:237], v[238:239], off
	s_and_saveexec_b64 s[6:7], s[96:97]
	s_cbranch_execnz .Lnfs_1_20
.LBB0_1739:
	s_or_b64 exec, exec, s[6:7]
	v_add_u32_e32 v88, 0xffffc0a0, v221
	v_ashrrev_i32_e32 v88, 1, v88
	v_and_b32_e32 v139, -10, v88
	s_and_b64 vcc, exec, s[22:23]
	s_mov_b64 s[6:7], -1
	s_cbranch_vccz .Lsmp_1_40
.LBB0_1741:
.LBB0_1742:
	v_cndmask_b32_e64 v88, v76, v84, s[16:17]
	v_cndmask_b32_e64 v124, v76, v84, s[10:11]
	v_cndmask_b32_e64 v89, v77, v85, s[16:17]
	v_cndmask_b32_e64 v125, v77, v85, s[10:11]
	v_cndmask_b32_e64 v90, v78, v86, s[16:17]
	v_cndmask_b32_e64 v126, v78, v86, s[10:11]
	v_cndmask_b32_e64 v91, v79, v87, s[16:17]
	v_cndmask_b32_e64 v127, v79, v87, s[10:11]
	v_mov_b32_dpp v88, v88 row_ror:1 row_mask:0xf bank_mask:0xf
	v_mov_b32_dpp v124, v124 row_ror:2 row_mask:0xf bank_mask:0xf
	v_mov_b32_dpp v89, v89 row_ror:1 row_mask:0xf bank_mask:0xf
	v_mov_b32_dpp v125, v125 row_ror:2 row_mask:0xf bank_mask:0xf
	v_mov_b32_dpp v90, v90 row_ror:1 row_mask:0xf bank_mask:0xf
	v_mov_b32_dpp v126, v126 row_ror:2 row_mask:0xf bank_mask:0xf
	v_mov_b32_dpp v91, v91 row_ror:1 row_mask:0xf bank_mask:0xf
	v_mov_b32_dpp v127, v127 row_ror:2 row_mask:0xf bank_mask:0xf

; __device__ __forceinline__ unsigned pk2(float lo, float hi) { const f32x2 v = {lo, hi}; const bf16x2_t b = __builtin_convertvector(v, bf16x2_t); return __builtin_bit_cast(unsigned, b); }
;     __device__ __forceinline__ void operator()(const f32x4 (&acc)[2][2][4][2], const pg8::Unit& u, int wr, int wc, int fr, int fq, PG8_LAS unsigned char* xl) const {
;     ...
;                         const f32x4 cur = acc[ai][bj][m][n]; f32x4 p1, p2;
;                         if (!sample) { const f32x4 prv = (m == 0) ? hb[bj] : acc[ai][bj][m == 0 ? 0 : m - 1][n];
; #pragma unroll
;                             for (int j = 0; j < 4; ++j) { const float s1 = fr == 15 ? prv[j] : cur[j], s2 = fr >= 14 ? prv[j] : cur[j]; p1[j] = dpp_ror<1>(s1); p2[j] = dpp_ror<2>(s2); }
;                         } else { const int t = fr & 3, b = (row - MP) >> 2;
; #pragma unroll
;                             for (int j = 0; j < 4; ++j) { p1[j] = dpp_ror<1>(cur[j]); p2[j] = dpp_ror<2>(cur[j]); }
;                             const f32x4 c1 = *(const f32x4*)(ctx_s + (size_t)(b * 2 + 1) * FF2 + bj * FF + jc0 + 4 * n), c0 = *(const f32x4*)(ctx_s + (size_t)(b * 2) * FF2 + bj * FF + jc0 + 4 * n);
; #pragma unroll
;                             for (int j = 0; j < 4; ++j) { p2[j] = t == 0 ? c0[j] : (t == 1 ? c1[j] : p2[j]); p1[j] = t == 0 ? c1[j] : p1[j]; }
;                         }
;                         cc[bj] = bb[bj] + w0[bj] * p2 + w1[bj] * p1 + w2[bj] * cur;
;                     }
;                     const f32x4 gv = gelu_mul4(cc[0], cc[1]);
;                     u32x2 w; w.x = pk2(gv[0], gv[1]); w.y = pk2(gv[2], gv[3]);
;                     *(u32x2*)(G + (size_t)row * FF + jc0 + 4 * n) = w;
;                     if (!sample && ai == 0 && wr == 0 && m == 0 && fr < 2 && (pm & 7) != 0) {
; #pragma unroll
;                         for (int bj = 0; bj < 2; ++bj) *(f32x4*)(PH + (size_t)(pm * 2 + fr) * FF2 + bj * FF + jc0 + 4 * n) = cc[bj];
;                     }
;                     if (sample && (fr & 3) >= 2) { const int b = (row - MP) >> 2, t = fr & 3;
; #pragma unroll
;                         for (int bj = 0; bj < 2; ++bj) *(f32x4*)(nf_s + (size_t)(b * 2 + t - 2) * FF2 + bj * FF + jc0 + 4 * n) = acc[ai][bj][m][n];
.LBB0_1745:
.LBB0_1746:
	v_cndmask_b32_e64 v84, v72, v80, s[16:17]
	v_cndmask_b32_e64 v128, v72, v80, s[10:11]
	v_cndmask_b32_e64 v85, v73, v81, s[16:17]
	v_cndmask_b32_e64 v129, v73, v81, s[10:11]
	v_cndmask_b32_e64 v86, v74, v82, s[16:17]
	v_cndmask_b32_e64 v130, v74, v82, s[10:11]
	v_cndmask_b32_e64 v87, v75, v83, s[16:17]
	v_cndmask_b32_e64 v131, v75, v83, s[10:11]
	v_mov_b32_dpp v84, v84 row_ror:1 row_mask:0xf bank_mask:0xf
	v_mov_b32_dpp v128, v128 row_ror:2 row_mask:0xf bank_mask:0xf
	v_mov_b32_dpp v85, v85 row_ror:1 row_mask:0xf bank_mask:0xf
	v_mov_b32_dpp v129, v129 row_ror:2 row_mask:0xf bank_mask:0xf
	v_mov_b32_dpp v86, v86 row_ror:1 row_mask:0xf bank_mask:0xf
	v_mov_b32_dpp v130, v130 row_ror:2 row_mask:0xf bank_mask:0xf
	v_mov_b32_dpp v87, v87 row_ror:1 row_mask:0xf bank_mask:0xf
	v_mov_b32_dpp v131, v131 row_ror:2 row_mask:0xf bank_mask:0xf
.LBB0_1747:
	v_pk_fma_f32 v[80:81], v[114:115], v[126:127], v[118:119]
	v_pk_fma_f32 v[82:83], v[112:113], v[124:125], v[116:117]
	v_pk_fma_f32 v[80:81], v[106:107], v[90:91], v[80:81]
	v_pk_fma_f32 v[82:83], v[104:105], v[88:89], v[82:83]
	v_pk_fma_f32 v[80:81], v[78:79], v[98:99], v[80:81]
	v_pk_fma_f32 v[82:83], v[76:77], v[96:97], v[82:83]
	v_pk_fma_f32 v[88:89], v[110:111], v[130:131], v[122:123]
	v_pk_fma_f32 v[90:91], v[108:109], v[128:129], v[120:121]
	v_pk_fma_f32 v[86:87], v[102:103], v[86:87], v[88:89]
	v_pk_fma_f32 v[84:85], v[100:101], v[84:85], v[90:91]
	v_pk_mul_f32 v[88:89], v[80:81], v[80:81]
	v_pk_mul_f32 v[90:91], v[82:83], v[82:83]
	v_pk_fma_f32 v[88:89], v[88:89], s[82:83], v[246:247] op_sel_hi:[1,0,0]
	v_pk_fma_f32 v[90:91], v[90:91], s[82:83], v[246:247] op_sel_hi:[1,0,0]
	v_pk_mul_f32 v[88:89], v[80:81], v[88:89]
	v_pk_mul_f32 v[90:91], v[82:83], v[90:91]
	v_exp_f32_e32 v88, v88
	v_exp_f32_e32 v90, v90
	v_exp_f32_e32 v89, v89
	v_exp_f32_e32 v91, v91
	v_pk_fma_f32 v[86:87], v[74:75], v[94:95], v[86:87]
	v_pk_fma_f32 v[84:85], v[72:73], v[92:93], v[84:85]
	v_pk_add_f32 v[88:89], v[88:89], 1.0 op_sel_hi:[1,0]
	v_pk_add_f32 v[90:91], v[90:91], 1.0 op_sel_hi:[1,0]
	v_rcp_f32_e32 v88, v88
	v_rcp_f32_e32 v90, v90
	v_rcp_f32_e32 v89, v89
	v_rcp_f32_e32 v91, v91
	v_pk_mul_f32 v[80:81], v[80:81], v[86:87]
	v_pk_mul_f32 v[82:83], v[82:83], v[84:85]
	v_pk_mul_f32 v[80:81], v[80:81], v[88:89]
	v_pk_mul_f32 v[82:83], v[82:83], v[90:91]
	v_cvt_pk_bf16_f32 v82, v82, v83
	v_cvt_pk_bf16_f32 v83, v80, v81
	s_mul_i32 s100, s77, 0xa0
	v_lshl_add_u64 v[128:129], v[178:179], 0, s[100:101]
	v_add_u32_e32 v139, v139, v211
	ds_bpermute_b32 v236, v244, v128
	ds_bpermute_b32 v237, v244, v129
	ds_bpermute_b32 v238, v244, v82
	ds_bpermute_b32 v239, v244, v83
	s_waitcnt lgkmcnt(0)
	global_store_dwordx2 v[236:237], v[238:239], off
	s_and_saveexec_b64 s[6:7], s[96:97]
	s_cbranch_execnz .Lnfs_1_21
.LBB0_1749:
	s_or_b64 exec, exec, s[6:7]
	v_add_u32_e32 v80, 0xffffc0b0, v221
	v_ashrrev_i32_e32 v80, 1, v80
	v_and_b32_e32 v147, -2, v80
	s_and_b64 vcc, exec, s[22:23]
	s_mov_b64 s[6:7], -1
	s_cbranch_vccz .Lsmp_1_42
.LBB0_1751:
.LBB0_1752:
	v_cndmask_b32_e64 v80, v12, v76, s[16:17]
	v_cndmask_b32_e64 v84, v12, v76, s[10:11]
	v_cndmask_b32_e64 v81, v13, v77, s[16:17]
	v_cndmask_b32_e64 v85, v13, v77, s[10:11]
	v_cndmask_b32_e64 v82, v14, v78, s[16:17]
	v_cndmask_b32_e64 v86, v14, v78, s[10:11]
	v_cndmask_b32_e64 v83, v15, v79, s[16:17]
	v_cndmask_b32_e64 v87, v15, v79, s[10:11]
	v_mov_b32_dpp v80, v80 row_ror:1 row_mask:0xf bank_mask:0xf
	v_mov_b32_dpp v84, v84 row_ror:2 row_mask:0xf bank_mask:0xf
	v_mov_b32_dpp v81, v81 row_ror:1 row_mask:0xf bank_mask:0xf
	v_mov_b32_dpp v85, v85 row_ror:2 row_mask:0xf bank_mask:0xf
	v_mov_b32_dpp v82, v82 row_ror:1 row_mask:0xf bank_mask:0xf
	v_mov_b32_dpp v86, v86 row_ror:2 row_mask:0xf bank_mask:0xf
	v_mov_b32_dpp v83, v83 row_ror:1 row_mask:0xf bank_mask:0xf
	v_mov_b32_dpp v87, v87 row_ror:2 row_mask:0xf bank_mask:0xf

; __device__ __forceinline__ unsigned pk2(float lo, float hi) { const f32x2 v = {lo, hi}; const bf16x2_t b = __builtin_convertvector(v, bf16x2_t); return __builtin_bit_cast(unsigned, b); }
;     __device__ __forceinline__ void operator()(const f32x4 (&acc)[2][2][4][2], const pg8::Unit& u, int wr, int wc, int fr, int fq, PG8_LAS unsigned char* xl) const {
;     ...
;                         const f32x4 cur = acc[ai][bj][m][n]; f32x4 p1, p2;
;                         if (!sample) { const f32x4 prv = (m == 0) ? hb[bj] : acc[ai][bj][m == 0 ? 0 : m - 1][n];
; #pragma unroll
;                             for (int j = 0; j < 4; ++j) { const float s1 = fr == 15 ? prv[j] : cur[j], s2 = fr >= 14 ? prv[j] : cur[j]; p1[j] = dpp_ror<1>(s1); p2[j] = dpp_ror<2>(s2); }
;                         } else { const int t = fr & 3, b = (row - MP) >> 2;
; #pragma unroll
;                             for (int j = 0; j < 4; ++j) { p1[j] = dpp_ror<1>(cur[j]); p2[j] = dpp_ror<2>(cur[j]); }
;                             const f32x4 c1 = *(const f32x4*)(ctx_s + (size_t)(b * 2 + 1) * FF2 + bj * FF + jc0 + 4 * n), c0 = *(const f32x4*)(ctx_s + (size_t)(b * 2) * FF2 + bj * FF + jc0 + 4 * n);
; #pragma unroll
;                             for (int j = 0; j < 4; ++j) { p2[j] = t == 0 ? c0[j] : (t == 1 ? c1[j] : p2[j]); p1[j] = t == 0 ? c1[j] : p1[j]; }
;                         }
;                         cc[bj] = bb[bj] + w0[bj] * p2 + w1[bj] * p1 + w2[bj] * cur;
;                     }
;                     const f32x4 gv = gelu_mul4(cc[0], cc[1]);
;                     u32x2 w; w.x = pk2(gv[0], gv[1]); w.y = pk2(gv[2], gv[3]);
;                     *(u32x2*)(G + (size_t)row * FF + jc0 + 4 * n) = w;
;                     if (!sample && ai == 0 && wr == 0 && m == 0 && fr < 2 && (pm & 7) != 0) {
; #pragma unroll
;                         for (int bj = 0; bj < 2; ++bj) *(f32x4*)(PH + (size_t)(pm * 2 + fr) * FF2 + bj * FF + jc0 + 4 * n) = cc[bj];
;                     }
;                     if (sample && (fr & 3) >= 2) { const int b = (row - MP) >> 2, t = fr & 3;
; #pragma unroll
;                         for (int bj = 0; bj < 2; ++bj) *(f32x4*)(nf_s + (size_t)(b * 2 + t - 2) * FF2 + bj * FF + jc0 + 4 * n) = acc[ai][bj][m][n];
.LBB0_1755:
.LBB0_1756:
	v_cndmask_b32_e64 v76, v4, v72, s[16:17]
	v_cndmask_b32_e64 v88, v4, v72, s[10:11]
	v_cndmask_b32_e64 v77, v5, v73, s[16:17]
	v_cndmask_b32_e64 v89, v5, v73, s[10:11]
	v_cndmask_b32_e64 v78, v6, v74, s[16:17]
	v_cndmask_b32_e64 v90, v6, v74, s[10:11]
	v_cndmask_b32_e64 v79, v7, v75, s[16:17]
	v_cndmask_b32_e64 v91, v7, v75, s[10:11]
	v_mov_b32_dpp v76, v76 row_ror:1 row_mask:0xf bank_mask:0xf
	v_mov_b32_dpp v88, v88 row_ror:2 row_mask:0xf bank_mask:0xf
	v_mov_b32_dpp v77, v77 row_ror:1 row_mask:0xf bank_mask:0xf
	v_mov_b32_dpp v89, v89 row_ror:2 row_mask:0xf bank_mask:0xf
	v_mov_b32_dpp v78, v78 row_ror:1 row_mask:0xf bank_mask:0xf
	v_mov_b32_dpp v90, v90 row_ror:2 row_mask:0xf bank_mask:0xf
	v_mov_b32_dpp v79, v79 row_ror:1 row_mask:0xf bank_mask:0xf
	v_mov_b32_dpp v91, v91 row_ror:2 row_mask:0xf bank_mask:0xf
.LBB0_1757:
	v_pk_fma_f32 v[72:73], v[114:115], v[86:87], v[118:119]
	v_pk_fma_f32 v[74:75], v[112:113], v[84:85], v[116:117]
	v_pk_fma_f32 v[72:73], v[106:107], v[82:83], v[72:73]
	v_pk_fma_f32 v[74:75], v[104:105], v[80:81], v[74:75]
	v_pk_fma_f32 v[72:73], v[14:15], v[98:99], v[72:73]
	v_pk_fma_f32 v[74:75], v[12:13], v[96:97], v[74:75]
	v_pk_fma_f32 v[80:81], v[110:111], v[90:91], v[122:123]
	v_pk_fma_f32 v[82:83], v[108:109], v[88:89], v[120:121]
	v_pk_fma_f32 v[78:79], v[102:103], v[78:79], v[80:81]
	v_pk_fma_f32 v[76:77], v[100:101], v[76:77], v[82:83]
	v_pk_mul_f32 v[80:81], v[72:73], v[72:73]
	v_pk_mul_f32 v[82:83], v[74:75], v[74:75]
	v_pk_fma_f32 v[80:81], v[80:81], s[82:83], v[246:247] op_sel_hi:[1,0,0]
	v_pk_fma_f32 v[82:83], v[82:83], s[82:83], v[246:247] op_sel_hi:[1,0,0]
	v_pk_mul_f32 v[80:81], v[72:73], v[80:81]
	v_pk_mul_f32 v[82:83], v[74:75], v[82:83]
	v_exp_f32_e32 v80, v80
	v_exp_f32_e32 v82, v82
	v_exp_f32_e32 v81, v81
	v_exp_f32_e32 v83, v83
	v_pk_fma_f32 v[78:79], v[6:7], v[94:95], v[78:79]
	v_pk_fma_f32 v[76:77], v[4:5], v[92:93], v[76:77]
	v_pk_add_f32 v[80:81], v[80:81], 1.0 op_sel_hi:[1,0]
	v_pk_add_f32 v[82:83], v[82:83], 1.0 op_sel_hi:[1,0]
	v_rcp_f32_e32 v80, v80
	v_rcp_f32_e32 v82, v82
	v_rcp_f32_e32 v81, v81
	v_rcp_f32_e32 v83, v83
	v_pk_mul_f32 v[72:73], v[72:73], v[78:79]
	v_pk_mul_f32 v[74:75], v[74:75], v[76:77]
	v_pk_mul_f32 v[72:73], v[72:73], v[80:81]
	v_pk_mul_f32 v[74:75], v[74:75], v[82:83]
	v_cvt_pk_bf16_f32 v74, v74, v75
	v_cvt_pk_bf16_f32 v75, v72, v73
	s_mul_i32 s100, s77, 0xb0
	v_lshl_add_u64 v[130:131], v[178:179], 0, s[100:101]
	v_add_u32_e32 v147, v147, v211
	ds_bpermute_b32 v236, v244, v130
	ds_bpermute_b32 v237, v244, v131
	ds_bpermute_b32 v238, v244, v74
	ds_bpermute_b32 v239, v244, v75
	s_waitcnt lgkmcnt(0)
	global_store_dwordx2 v[236:237], v[238:239], off
	s_and_saveexec_b64 s[6:7], s[96:97]
	s_cbranch_execnz .Lnfs_1_22

; template <int N> __device__ __forceinline__ float dpp_ror(float v) { const int i = __builtin_bit_cast(int, v); return __builtin_bit_cast(float, __builtin_amdgcn_update_dpp(i, i, 0x120 + N, 0xF, 0xF, false)); }
;     __device__ __forceinline__ void operator()(const f32x4 (&acc)[2][2][4][2], const pg8::Unit& u, int wr, int wc, int fr, int fq, PG8_LAS unsigned char* xl) const {
;     ...
;                         if (!sample) { const f32x4 prv = (m == 0) ? hb[bj] : acc[ai][bj][m == 0 ? 0 : m - 1][n];
; #pragma unroll
;                             for (int j = 0; j < 4; ++j) { const float s1 = fr == 15 ? prv[j] : cur[j], s2 = fr >= 14 ? prv[j] : cur[j]; p1[j] = dpp_ror<1>(s1); p2[j] = dpp_ror<2>(s2); }
.LBB0_1763:
.LBB0_1764:
	s_waitcnt lgkmcnt(1)
	v_cndmask_b32_e64 v108, v68, v116, s[16:17]
	v_cndmask_b32_e64 v112, v68, v116, s[10:11]
	v_cndmask_b32_e64 v109, v69, v117, s[16:17]
	v_cndmask_b32_e64 v113, v69, v117, s[10:11]
	v_cndmask_b32_e64 v110, v70, v118, s[16:17]
	v_cndmask_b32_e64 v114, v70, v118, s[10:11]
	v_cndmask_b32_e64 v111, v71, v119, s[16:17]
	v_cndmask_b32_e64 v115, v71, v119, s[10:11]
	v_mov_b32_dpp v108, v108 row_ror:1 row_mask:0xf bank_mask:0xf
	v_mov_b32_dpp v112, v112 row_ror:2 row_mask:0xf bank_mask:0xf
	v_mov_b32_dpp v109, v109 row_ror:1 row_mask:0xf bank_mask:0xf
	v_mov_b32_dpp v113, v113 row_ror:2 row_mask:0xf bank_mask:0xf
	v_mov_b32_dpp v110, v110 row_ror:1 row_mask:0xf bank_mask:0xf
	v_mov_b32_dpp v114, v114 row_ror:2 row_mask:0xf bank_mask:0xf
	v_mov_b32_dpp v111, v111 row_ror:1 row_mask:0xf bank_mask:0xf
	v_mov_b32_dpp v115, v115 row_ror:2 row_mask:0xf bank_mask:0xf

; template <int N> __device__ __forceinline__ float dpp_ror(float v) { const int i = __builtin_bit_cast(int, v); return __builtin_bit_cast(float, __builtin_amdgcn_update_dpp(i, i, 0x120 + N, 0xF, 0xF, false)); }
;     __device__ __forceinline__ void operator()(const f32x4 (&acc)[2][2][4][2], const pg8::Unit& u, int wr, int wc, int fr, int fq, PG8_LAS unsigned char* xl) const {
;     ...
;                         if (!sample) { const f32x4 prv = (m == 0) ? hb[bj] : acc[ai][bj][m == 0 ? 0 : m - 1][n];
; #pragma unroll
;                             for (int j = 0; j < 4; ++j) { const float s1 = fr == 15 ? prv[j] : cur[j], s2 = fr >= 14 ? prv[j] : cur[j]; p1[j] = dpp_ror<1>(s1); p2[j] = dpp_ror<2>(s2); }
.LBB0_1767:
.LBB0_1768:
	s_waitcnt lgkmcnt(0)
	v_cndmask_b32_e64 v116, v64, v104, s[16:17]
	v_cndmask_b32_e64 v120, v64, v104, s[10:11]
	v_cndmask_b32_e64 v117, v65, v105, s[16:17]
	v_cndmask_b32_e64 v121, v65, v105, s[10:11]
	v_cndmask_b32_e64 v118, v66, v106, s[16:17]
	v_cndmask_b32_e64 v122, v66, v106, s[10:11]
	v_cndmask_b32_e64 v119, v67, v107, s[16:17]
	v_cndmask_b32_e64 v123, v67, v107, s[10:11]
	v_mov_b32_dpp v116, v116 row_ror:1 row_mask:0xf bank_mask:0xf
	v_mov_b32_dpp v120, v120 row_ror:2 row_mask:0xf bank_mask:0xf
	v_mov_b32_dpp v117, v117 row_ror:1 row_mask:0xf bank_mask:0xf
	v_mov_b32_dpp v121, v121 row_ror:2 row_mask:0xf bank_mask:0xf
	v_mov_b32_dpp v118, v118 row_ror:1 row_mask:0xf bank_mask:0xf
	v_mov_b32_dpp v122, v122 row_ror:2 row_mask:0xf bank_mask:0xf
	v_mov_b32_dpp v119, v119 row_ror:1 row_mask:0xf bank_mask:0xf
	v_mov_b32_dpp v123, v123 row_ror:2 row_mask:0xf bank_mask:0xf

; template <int N> __device__ __forceinline__ float dpp_ror(float v) { const int i = __builtin_bit_cast(int, v); return __builtin_bit_cast(float, __builtin_amdgcn_update_dpp(i, i, 0x120 + N, 0xF, 0xF, false)); }
;     __device__ __forceinline__ void operator()(const f32x4 (&acc)[2][2][4][2], const pg8::Unit& u, int wr, int wc, int fr, int fq, PG8_LAS unsigned char* xl) const {
;     ...
;                         if (!sample) { const f32x4 prv = (m == 0) ? hb[bj] : acc[ai][bj][m == 0 ? 0 : m - 1][n];
; #pragma unroll
;                             for (int j = 0; j < 4; ++j) { const float s1 = fr == 15 ? prv[j] : cur[j], s2 = fr >= 14 ? prv[j] : cur[j]; p1[j] = dpp_ror<1>(s1); p2[j] = dpp_ror<2>(s2); }
.LBB0_1775:
.LBB0_1776:
	v_cndmask_b32_e64 v104, v60, v68, s[16:17]
	v_cndmask_b32_e64 v108, v60, v68, s[10:11]
	v_cndmask_b32_e64 v105, v61, v69, s[16:17]
	v_cndmask_b32_e64 v109, v61, v69, s[10:11]
	v_cndmask_b32_e64 v106, v62, v70, s[16:17]
	v_cndmask_b32_e64 v110, v62, v70, s[10:11]
	v_cndmask_b32_e64 v107, v63, v71, s[16:17]
	v_cndmask_b32_e64 v111, v63, v71, s[10:11]
	v_mov_b32_dpp v104, v104 row_ror:1 row_mask:0xf bank_mask:0xf
	v_mov_b32_dpp v108, v108 row_ror:2 row_mask:0xf bank_mask:0xf
	v_mov_b32_dpp v105, v105 row_ror:1 row_mask:0xf bank_mask:0xf
	v_mov_b32_dpp v109, v109 row_ror:2 row_mask:0xf bank_mask:0xf
	v_mov_b32_dpp v106, v106 row_ror:1 row_mask:0xf bank_mask:0xf
	v_mov_b32_dpp v110, v110 row_ror:2 row_mask:0xf bank_mask:0xf
	v_mov_b32_dpp v107, v107 row_ror:1 row_mask:0xf bank_mask:0xf
	v_mov_b32_dpp v111, v111 row_ror:2 row_mask:0xf bank_mask:0xf

; __device__ __forceinline__ unsigned pk2(float lo, float hi) { const f32x2 v = {lo, hi}; const bf16x2_t b = __builtin_convertvector(v, bf16x2_t); return __builtin_bit_cast(unsigned, b); }
;     __device__ __forceinline__ void operator()(const f32x4 (&acc)[2][2][4][2], const pg8::Unit& u, int wr, int wc, int fr, int fq, PG8_LAS unsigned char* xl) const {
;     ...
;                         const f32x4 cur = acc[ai][bj][m][n]; f32x4 p1, p2;
;                         if (!sample) { const f32x4 prv = (m == 0) ? hb[bj] : acc[ai][bj][m == 0 ? 0 : m - 1][n];
; #pragma unroll
;                             for (int j = 0; j < 4; ++j) { const float s1 = fr == 15 ? prv[j] : cur[j], s2 = fr >= 14 ? prv[j] : cur[j]; p1[j] = dpp_ror<1>(s1); p2[j] = dpp_ror<2>(s2); }
;                         } else { const int t = fr & 3, b = (row - MP) >> 2;
; #pragma unroll
;                             for (int j = 0; j < 4; ++j) { p1[j] = dpp_ror<1>(cur[j]); p2[j] = dpp_ror<2>(cur[j]); }
;                             const f32x4 c1 = *(const f32x4*)(ctx_s + (size_t)(b * 2 + 1) * FF2 + bj * FF + jc0 + 4 * n), c0 = *(const f32x4*)(ctx_s + (size_t)(b * 2) * FF2 + bj * FF + jc0 + 4 * n);
; #pragma unroll
;                             for (int j = 0; j < 4; ++j) { p2[j] = t == 0 ? c0[j] : (t == 1 ? c1[j] : p2[j]); p1[j] = t == 0 ? c1[j] : p1[j]; }
;                         }
;                         cc[bj] = bb[bj] + w0[bj] * p2 + w1[bj] * p1 + w2[bj] * cur;
;                     }
;                     const f32x4 gv = gelu_mul4(cc[0], cc[1]);
;                     u32x2 w; w.x = pk2(gv[0], gv[1]); w.y = pk2(gv[2], gv[3]);
;                     *(u32x2*)(G + (size_t)row * FF + jc0 + 4 * n) = w;
;                     if (!sample && ai == 0 && wr == 0 && m == 0 && fr < 2 && (pm & 7) != 0) {
; #pragma unroll
;                         for (int bj = 0; bj < 2; ++bj) *(f32x4*)(PH + (size_t)(pm * 2 + fr) * FF2 + bj * FF + jc0 + 4 * n) = cc[bj];
;                     }
;                     if (sample && (fr & 3) >= 2) { const int b = (row - MP) >> 2, t = fr & 3;
; #pragma unroll
;                         for (int bj = 0; bj < 2; ++bj) *(f32x4*)(nf_s + (size_t)(b * 2 + t - 2) * FF2 + bj * FF + jc0 + 4 * n) = acc[ai][bj][m][n];
.LBB0_1779:
.LBB0_1780:
	v_cndmask_b32_e64 v68, v56, v64, s[16:17]
	v_cndmask_b32_e64 v112, v56, v64, s[10:11]
	v_cndmask_b32_e64 v69, v57, v65, s[16:17]
	v_cndmask_b32_e64 v113, v57, v65, s[10:11]
	v_cndmask_b32_e64 v70, v58, v66, s[16:17]
	v_cndmask_b32_e64 v114, v58, v66, s[10:11]
	v_cndmask_b32_e64 v71, v59, v67, s[16:17]
	v_cndmask_b32_e64 v115, v59, v67, s[10:11]
	v_mov_b32_dpp v68, v68 row_ror:1 row_mask:0xf bank_mask:0xf
	v_mov_b32_dpp v112, v112 row_ror:2 row_mask:0xf bank_mask:0xf
	v_mov_b32_dpp v69, v69 row_ror:1 row_mask:0xf bank_mask:0xf
	v_mov_b32_dpp v113, v113 row_ror:2 row_mask:0xf bank_mask:0xf
	v_mov_b32_dpp v70, v70 row_ror:1 row_mask:0xf bank_mask:0xf
	v_mov_b32_dpp v114, v114 row_ror:2 row_mask:0xf bank_mask:0xf
	v_mov_b32_dpp v71, v71 row_ror:1 row_mask:0xf bank_mask:0xf
	v_mov_b32_dpp v115, v115 row_ror:2 row_mask:0xf bank_mask:0xf
.LBB0_1781:
	v_pk_fma_f32 v[64:65], v[98:99], v[110:111], v[102:103]
	v_pk_fma_f32 v[66:67], v[96:97], v[108:109], v[100:101]
	v_pk_fma_f32 v[64:65], v[90:91], v[106:107], v[64:65]
	v_pk_fma_f32 v[66:67], v[88:89], v[104:105], v[66:67]
	v_pk_fma_f32 v[64:65], v[62:63], v[82:83], v[64:65]
	v_pk_fma_f32 v[66:67], v[60:61], v[80:81], v[66:67]
	v_pk_fma_f32 v[104:105], v[86:87], v[114:115], v[94:95]
	v_pk_fma_f32 v[106:107], v[84:85], v[112:113], v[92:93]
	v_pk_fma_f32 v[70:71], v[78:79], v[70:71], v[104:105]
	v_pk_fma_f32 v[68:69], v[76:77], v[68:69], v[106:107]
	v_pk_mul_f32 v[104:105], v[64:65], v[64:65]
	v_pk_mul_f32 v[106:107], v[66:67], v[66:67]
	v_pk_fma_f32 v[104:105], v[104:105], s[82:83], v[246:247] op_sel_hi:[1,0,0]
	v_pk_fma_f32 v[106:107], v[106:107], s[82:83], v[246:247] op_sel_hi:[1,0,0]
	v_pk_mul_f32 v[104:105], v[64:65], v[104:105]
	v_pk_mul_f32 v[106:107], v[66:67], v[106:107]
	v_exp_f32_e32 v104, v104
	v_exp_f32_e32 v106, v106
	v_exp_f32_e32 v105, v105
	v_exp_f32_e32 v107, v107
	v_pk_fma_f32 v[70:71], v[58:59], v[74:75], v[70:71]
	v_pk_fma_f32 v[68:69], v[56:57], v[72:73], v[68:69]
	v_pk_add_f32 v[104:105], v[104:105], 1.0 op_sel_hi:[1,0]
	v_pk_add_f32 v[106:107], v[106:107], 1.0 op_sel_hi:[1,0]
	v_rcp_f32_e32 v104, v104
	v_rcp_f32_e32 v106, v106
	v_rcp_f32_e32 v105, v105
	v_rcp_f32_e32 v107, v107
	v_pk_mul_f32 v[64:65], v[64:65], v[70:71]
	v_pk_mul_f32 v[66:67], v[66:67], v[68:69]
	v_pk_mul_f32 v[64:65], v[64:65], v[104:105]
	v_pk_mul_f32 v[66:67], v[66:67], v[106:107]
	s_nop 0
	v_cvt_pk_bf16_f32 v66, v66, v67
	v_cvt_pk_bf16_f32 v67, v64, v65
	ds_bpermute_b32 v236, v244, v168
	ds_bpermute_b32 v237, v244, v169
	ds_bpermute_b32 v238, v244, v66
	ds_bpermute_b32 v239, v244, v67
	s_waitcnt lgkmcnt(0)
	global_store_dwordx2 v[236:237], v[238:239], off offset:8
	s_and_saveexec_b64 s[6:7], s[96:97]
	s_cbranch_execnz .Lnfs_1_23

; template <int N> __device__ __forceinline__ float dpp_ror(float v) { const int i = __builtin_bit_cast(int, v); return __builtin_bit_cast(float, __builtin_amdgcn_update_dpp(i, i, 0x120 + N, 0xF, 0xF, false)); }
;     __device__ __forceinline__ void operator()(const f32x4 (&acc)[2][2][4][2], const pg8::Unit& u, int wr, int wc, int fr, int fq, PG8_LAS unsigned char* xl) const {
;     ...
;                         if (!sample) { const f32x4 prv = (m == 0) ? hb[bj] : acc[ai][bj][m == 0 ? 0 : m - 1][n];
; #pragma unroll
;                             for (int j = 0; j < 4; ++j) { const float s1 = fr == 15 ? prv[j] : cur[j], s2 = fr >= 14 ? prv[j] : cur[j]; p1[j] = dpp_ror<1>(s1); p2[j] = dpp_ror<2>(s2); }
.LBB0_1785:
.LBB0_1786:
	v_cndmask_b32_e64 v64, v52, v60, s[16:17]
	v_cndmask_b32_e64 v68, v52, v60, s[10:11]
	v_cndmask_b32_e64 v65, v53, v61, s[16:17]
	v_cndmask_b32_e64 v69, v53, v61, s[10:11]
	v_cndmask_b32_e64 v66, v54, v62, s[16:17]
	v_cndmask_b32_e64 v70, v54, v62, s[10:11]
	v_cndmask_b32_e64 v67, v55, v63, s[16:17]
	v_cndmask_b32_e64 v71, v55, v63, s[10:11]
	v_mov_b32_dpp v64, v64 row_ror:1 row_mask:0xf bank_mask:0xf
	v_mov_b32_dpp v68, v68 row_ror:2 row_mask:0xf bank_mask:0xf
	v_mov_b32_dpp v65, v65 row_ror:1 row_mask:0xf bank_mask:0xf
	v_mov_b32_dpp v69, v69 row_ror:2 row_mask:0xf bank_mask:0xf
	v_mov_b32_dpp v66, v66 row_ror:1 row_mask:0xf bank_mask:0xf
	v_mov_b32_dpp v70, v70 row_ror:2 row_mask:0xf bank_mask:0xf
	v_mov_b32_dpp v67, v67 row_ror:1 row_mask:0xf bank_mask:0xf
	v_mov_b32_dpp v71, v71 row_ror:2 row_mask:0xf bank_mask:0xf

; __device__ __forceinline__ unsigned pk2(float lo, float hi) { const f32x2 v = {lo, hi}; const bf16x2_t b = __builtin_convertvector(v, bf16x2_t); return __builtin_bit_cast(unsigned, b); }
;     __device__ __forceinline__ void operator()(const f32x4 (&acc)[2][2][4][2], const pg8::Unit& u, int wr, int wc, int fr, int fq, PG8_LAS unsigned char* xl) const {
;     ...
;                         const f32x4 cur = acc[ai][bj][m][n]; f32x4 p1, p2;
;                         if (!sample) { const f32x4 prv = (m == 0) ? hb[bj] : acc[ai][bj][m == 0 ? 0 : m - 1][n];
; #pragma unroll
;                             for (int j = 0; j < 4; ++j) { const float s1 = fr == 15 ? prv[j] : cur[j], s2 = fr >= 14 ? prv[j] : cur[j]; p1[j] = dpp_ror<1>(s1); p2[j] = dpp_ror<2>(s2); }
;                         } else { const int t = fr & 3, b = (row - MP) >> 2;
; #pragma unroll
;                             for (int j = 0; j < 4; ++j) { p1[j] = dpp_ror<1>(cur[j]); p2[j] = dpp_ror<2>(cur[j]); }
;                             const f32x4 c1 = *(const f32x4*)(ctx_s + (size_t)(b * 2 + 1) * FF2 + bj * FF + jc0 + 4 * n), c0 = *(const f32x4*)(ctx_s + (size_t)(b * 2) * FF2 + bj * FF + jc0 + 4 * n);
; #pragma unroll
;                             for (int j = 0; j < 4; ++j) { p2[j] = t == 0 ? c0[j] : (t == 1 ? c1[j] : p2[j]); p1[j] = t == 0 ? c1[j] : p1[j]; }
;                         }
;                         cc[bj] = bb[bj] + w0[bj] * p2 + w1[bj] * p1 + w2[bj] * cur;
;                     }
;                     const f32x4 gv = gelu_mul4(cc[0], cc[1]);
;                     u32x2 w; w.x = pk2(gv[0], gv[1]); w.y = pk2(gv[2], gv[3]);
;                     *(u32x2*)(G + (size_t)row * FF + jc0 + 4 * n) = w;
;                     if (!sample && ai == 0 && wr == 0 && m == 0 && fr < 2 && (pm & 7) != 0) {
; #pragma unroll
;                         for (int bj = 0; bj < 2; ++bj) *(f32x4*)(PH + (size_t)(pm * 2 + fr) * FF2 + bj * FF + jc0 + 4 * n) = cc[bj];
;                     }
;                     if (sample && (fr & 3) >= 2) { const int b = (row - MP) >> 2, t = fr & 3;
; #pragma unroll
;                         for (int bj = 0; bj < 2; ++bj) *(f32x4*)(nf_s + (size_t)(b * 2 + t - 2) * FF2 + bj * FF + jc0 + 4 * n) = acc[ai][bj][m][n];
.LBB0_1789:
.LBB0_1790:
	v_cndmask_b32_e64 v60, v48, v56, s[16:17]
	v_cndmask_b32_e64 v104, v48, v56, s[10:11]
	v_cndmask_b32_e64 v61, v49, v57, s[16:17]
	v_cndmask_b32_e64 v105, v49, v57, s[10:11]
	v_cndmask_b32_e64 v62, v50, v58, s[16:17]
	v_cndmask_b32_e64 v106, v50, v58, s[10:11]
	v_cndmask_b32_e64 v63, v51, v59, s[16:17]
	v_cndmask_b32_e64 v107, v51, v59, s[10:11]
	v_mov_b32_dpp v60, v60 row_ror:1 row_mask:0xf bank_mask:0xf
	v_mov_b32_dpp v104, v104 row_ror:2 row_mask:0xf bank_mask:0xf
	v_mov_b32_dpp v61, v61 row_ror:1 row_mask:0xf bank_mask:0xf
	v_mov_b32_dpp v105, v105 row_ror:2 row_mask:0xf bank_mask:0xf
	v_mov_b32_dpp v62, v62 row_ror:1 row_mask:0xf bank_mask:0xf
	v_mov_b32_dpp v106, v106 row_ror:2 row_mask:0xf bank_mask:0xf
	v_mov_b32_dpp v63, v63 row_ror:1 row_mask:0xf bank_mask:0xf
	v_mov_b32_dpp v107, v107 row_ror:2 row_mask:0xf bank_mask:0xf
.LBB0_1791:
	v_pk_fma_f32 v[56:57], v[98:99], v[70:71], v[102:103]
	v_pk_fma_f32 v[58:59], v[96:97], v[68:69], v[100:101]
	v_pk_fma_f32 v[56:57], v[90:91], v[66:67], v[56:57]
	v_pk_fma_f32 v[58:59], v[88:89], v[64:65], v[58:59]
	v_pk_fma_f32 v[56:57], v[54:55], v[82:83], v[56:57]
	v_pk_fma_f32 v[58:59], v[52:53], v[80:81], v[58:59]
	v_pk_fma_f32 v[64:65], v[86:87], v[106:107], v[94:95]
	v_pk_fma_f32 v[66:67], v[84:85], v[104:105], v[92:93]
	v_pk_fma_f32 v[62:63], v[78:79], v[62:63], v[64:65]
	v_pk_fma_f32 v[60:61], v[76:77], v[60:61], v[66:67]
	v_pk_mul_f32 v[64:65], v[56:57], v[56:57]
	v_pk_mul_f32 v[66:67], v[58:59], v[58:59]
	v_pk_fma_f32 v[64:65], v[64:65], s[82:83], v[246:247] op_sel_hi:[1,0,0]
	v_pk_fma_f32 v[66:67], v[66:67], s[82:83], v[246:247] op_sel_hi:[1,0,0]
	v_pk_mul_f32 v[64:65], v[56:57], v[64:65]
	v_pk_mul_f32 v[66:67], v[58:59], v[66:67]
	v_exp_f32_e32 v64, v64
	v_exp_f32_e32 v66, v66
	v_exp_f32_e32 v65, v65
	v_exp_f32_e32 v67, v67
	v_pk_fma_f32 v[62:63], v[50:51], v[74:75], v[62:63]
	v_pk_fma_f32 v[60:61], v[48:49], v[72:73], v[60:61]
	v_pk_add_f32 v[64:65], v[64:65], 1.0 op_sel_hi:[1,0]
	v_pk_add_f32 v[66:67], v[66:67], 1.0 op_sel_hi:[1,0]
	v_rcp_f32_e32 v64, v64
	v_rcp_f32_e32 v66, v66
	v_rcp_f32_e32 v65, v65
	v_rcp_f32_e32 v67, v67
	v_pk_mul_f32 v[56:57], v[56:57], v[62:63]
	v_pk_mul_f32 v[58:59], v[58:59], v[60:61]
	v_pk_mul_f32 v[56:57], v[56:57], v[64:65]
	v_pk_mul_f32 v[58:59], v[58:59], v[66:67]
	s_nop 0
	v_cvt_pk_bf16_f32 v58, v58, v59
	v_cvt_pk_bf16_f32 v59, v56, v57
	ds_bpermute_b32 v236, v244, v160
	ds_bpermute_b32 v237, v244, v161
	ds_bpermute_b32 v238, v244, v58
	ds_bpermute_b32 v239, v244, v59
	s_waitcnt lgkmcnt(0)
	global_store_dwordx2 v[236:237], v[238:239], off offset:8
	s_and_saveexec_b64 s[6:7], s[96:97]
	s_cbranch_execnz .Lnfs_1_24

; template <int N> __device__ __forceinline__ float dpp_ror(float v) { const int i = __builtin_bit_cast(int, v); return __builtin_bit_cast(float, __builtin_amdgcn_update_dpp(i, i, 0x120 + N, 0xF, 0xF, false)); }
;     __device__ __forceinline__ void operator()(const f32x4 (&acc)[2][2][4][2], const pg8::Unit& u, int wr, int wc, int fr, int fq, PG8_LAS unsigned char* xl) const {
;     ...
;                         if (!sample) { const f32x4 prv = (m == 0) ? hb[bj] : acc[ai][bj][m == 0 ? 0 : m - 1][n];
; #pragma unroll
;                             for (int j = 0; j < 4; ++j) { const float s1 = fr == 15 ? prv[j] : cur[j], s2 = fr >= 14 ? prv[j] : cur[j]; p1[j] = dpp_ror<1>(s1); p2[j] = dpp_ror<2>(s2); }
.LBB0_1795:
.LBB0_1796:
	v_cndmask_b32_e64 v56, v44, v52, s[16:17]
	v_cndmask_b32_e64 v60, v44, v52, s[10:11]
	v_cndmask_b32_e64 v57, v45, v53, s[16:17]
	v_cndmask_b32_e64 v61, v45, v53, s[10:11]
	v_cndmask_b32_e64 v58, v46, v54, s[16:17]
	v_cndmask_b32_e64 v62, v46, v54, s[10:11]
	v_cndmask_b32_e64 v59, v47, v55, s[16:17]
	v_cndmask_b32_e64 v63, v47, v55, s[10:11]
	v_mov_b32_dpp v56, v56 row_ror:1 row_mask:0xf bank_mask:0xf
	v_mov_b32_dpp v60, v60 row_ror:2 row_mask:0xf bank_mask:0xf
	v_mov_b32_dpp v57, v57 row_ror:1 row_mask:0xf bank_mask:0xf
	v_mov_b32_dpp v61, v61 row_ror:2 row_mask:0xf bank_mask:0xf
	v_mov_b32_dpp v58, v58 row_ror:1 row_mask:0xf bank_mask:0xf
	v_mov_b32_dpp v62, v62 row_ror:2 row_mask:0xf bank_mask:0xf
	v_mov_b32_dpp v59, v59 row_ror:1 row_mask:0xf bank_mask:0xf
	v_mov_b32_dpp v63, v63 row_ror:2 row_mask:0xf bank_mask:0xf

; __device__ __forceinline__ unsigned pk2(float lo, float hi) { const f32x2 v = {lo, hi}; const bf16x2_t b = __builtin_convertvector(v, bf16x2_t); return __builtin_bit_cast(unsigned, b); }
;     __device__ __forceinline__ void operator()(const f32x4 (&acc)[2][2][4][2], const pg8::Unit& u, int wr, int wc, int fr, int fq, PG8_LAS unsigned char* xl) const {
;     ...
;                         const f32x4 cur = acc[ai][bj][m][n]; f32x4 p1, p2;
;                         if (!sample) { const f32x4 prv = (m == 0) ? hb[bj] : acc[ai][bj][m == 0 ? 0 : m - 1][n];
; #pragma unroll
;                             for (int j = 0; j < 4; ++j) { const float s1 = fr == 15 ? prv[j] : cur[j], s2 = fr >= 14 ? prv[j] : cur[j]; p1[j] = dpp_ror<1>(s1); p2[j] = dpp_ror<2>(s2); }
;                         } else { const int t = fr & 3, b = (row - MP) >> 2;
; #pragma unroll
;                             for (int j = 0; j < 4; ++j) { p1[j] = dpp_ror<1>(cur[j]); p2[j] = dpp_ror<2>(cur[j]); }
;                             const f32x4 c1 = *(const f32x4*)(ctx_s + (size_t)(b * 2 + 1) * FF2 + bj * FF + jc0 + 4 * n), c0 = *(const f32x4*)(ctx_s + (size_t)(b * 2) * FF2 + bj * FF + jc0 + 4 * n);
; #pragma unroll
;                             for (int j = 0; j < 4; ++j) { p2[j] = t == 0 ? c0[j] : (t == 1 ? c1[j] : p2[j]); p1[j] = t == 0 ? c1[j] : p1[j]; }
;                         }
;                         cc[bj] = bb[bj] + w0[bj] * p2 + w1[bj] * p1 + w2[bj] * cur;
;                     }
;                     const f32x4 gv = gelu_mul4(cc[0], cc[1]);
;                     u32x2 w; w.x = pk2(gv[0], gv[1]); w.y = pk2(gv[2], gv[3]);
;                     *(u32x2*)(G + (size_t)row * FF + jc0 + 4 * n) = w;
;                     if (!sample && ai == 0 && wr == 0 && m == 0 && fr < 2 && (pm & 7) != 0) {
; #pragma unroll
;                         for (int bj = 0; bj < 2; ++bj) *(f32x4*)(PH + (size_t)(pm * 2 + fr) * FF2 + bj * FF + jc0 + 4 * n) = cc[bj];
;                     }
;                     if (sample && (fr & 3) >= 2) { const int b = (row - MP) >> 2, t = fr & 3;
; #pragma unroll
;                         for (int bj = 0; bj < 2; ++bj) *(f32x4*)(nf_s + (size_t)(b * 2 + t - 2) * FF2 + bj * FF + jc0 + 4 * n) = acc[ai][bj][m][n];
.LBB0_1799:
.LBB0_1800:
	v_cndmask_b32_e64 v52, v40, v48, s[16:17]
	v_cndmask_b32_e64 v64, v40, v48, s[10:11]
	v_cndmask_b32_e64 v53, v41, v49, s[16:17]
	v_cndmask_b32_e64 v65, v41, v49, s[10:11]
	v_cndmask_b32_e64 v54, v42, v50, s[16:17]
	v_cndmask_b32_e64 v66, v42, v50, s[10:11]
	v_cndmask_b32_e64 v55, v43, v51, s[16:17]
	v_cndmask_b32_e64 v67, v43, v51, s[10:11]
	v_mov_b32_dpp v52, v52 row_ror:1 row_mask:0xf bank_mask:0xf
	v_mov_b32_dpp v64, v64 row_ror:2 row_mask:0xf bank_mask:0xf
	v_mov_b32_dpp v53, v53 row_ror:1 row_mask:0xf bank_mask:0xf
	v_mov_b32_dpp v65, v65 row_ror:2 row_mask:0xf bank_mask:0xf
	v_mov_b32_dpp v54, v54 row_ror:1 row_mask:0xf bank_mask:0xf
	v_mov_b32_dpp v66, v66 row_ror:2 row_mask:0xf bank_mask:0xf
	v_mov_b32_dpp v55, v55 row_ror:1 row_mask:0xf bank_mask:0xf
	v_mov_b32_dpp v67, v67 row_ror:2 row_mask:0xf bank_mask:0xf
.LBB0_1801:
	v_pk_fma_f32 v[48:49], v[98:99], v[62:63], v[102:103]
	v_pk_fma_f32 v[50:51], v[96:97], v[60:61], v[100:101]
	v_pk_fma_f32 v[48:49], v[90:91], v[58:59], v[48:49]
	v_pk_fma_f32 v[50:51], v[88:89], v[56:57], v[50:51]
	v_pk_fma_f32 v[48:49], v[46:47], v[82:83], v[48:49]
	v_pk_fma_f32 v[50:51], v[44:45], v[80:81], v[50:51]
	v_pk_fma_f32 v[56:57], v[86:87], v[66:67], v[94:95]
	v_pk_fma_f32 v[58:59], v[84:85], v[64:65], v[92:93]
	v_pk_fma_f32 v[54:55], v[78:79], v[54:55], v[56:57]
	v_pk_fma_f32 v[52:53], v[76:77], v[52:53], v[58:59]
	v_pk_mul_f32 v[56:57], v[48:49], v[48:49]
	v_pk_mul_f32 v[58:59], v[50:51], v[50:51]
	v_pk_fma_f32 v[56:57], v[56:57], s[82:83], v[246:247] op_sel_hi:[1,0,0]
	v_pk_fma_f32 v[58:59], v[58:59], s[82:83], v[246:247] op_sel_hi:[1,0,0]
	v_pk_mul_f32 v[56:57], v[48:49], v[56:57]
	v_pk_mul_f32 v[58:59], v[50:51], v[58:59]
	v_exp_f32_e32 v56, v56
	v_exp_f32_e32 v58, v58
	v_exp_f32_e32 v57, v57
	v_exp_f32_e32 v59, v59
	v_pk_fma_f32 v[54:55], v[42:43], v[74:75], v[54:55]
	v_pk_fma_f32 v[52:53], v[40:41], v[72:73], v[52:53]
	v_pk_add_f32 v[56:57], v[56:57], 1.0 op_sel_hi:[1,0]
	v_pk_add_f32 v[58:59], v[58:59], 1.0 op_sel_hi:[1,0]
	v_rcp_f32_e32 v56, v56
	v_rcp_f32_e32 v58, v58
	v_rcp_f32_e32 v57, v57
	v_rcp_f32_e32 v59, v59
	v_pk_mul_f32 v[48:49], v[48:49], v[54:55]
	v_pk_mul_f32 v[50:51], v[50:51], v[52:53]
	v_pk_mul_f32 v[48:49], v[48:49], v[56:57]
	v_pk_mul_f32 v[50:51], v[50:51], v[58:59]
	s_nop 0
	v_cvt_pk_bf16_f32 v50, v50, v51
	v_cvt_pk_bf16_f32 v51, v48, v49
	ds_bpermute_b32 v236, v244, v152
	ds_bpermute_b32 v237, v244, v153
	ds_bpermute_b32 v238, v244, v50
	ds_bpermute_b32 v239, v244, v51
	s_waitcnt lgkmcnt(0)
	global_store_dwordx2 v[236:237], v[238:239], off offset:8
	s_and_saveexec_b64 s[6:7], s[96:97]
	s_cbranch_execnz .Lnfs_1_25

; template <int N> __device__ __forceinline__ float dpp_ror(float v) { const int i = __builtin_bit_cast(int, v); return __builtin_bit_cast(float, __builtin_amdgcn_update_dpp(i, i, 0x120 + N, 0xF, 0xF, false)); }
;     __device__ __forceinline__ void operator()(const f32x4 (&acc)[2][2][4][2], const pg8::Unit& u, int wr, int wc, int fr, int fq, PG8_LAS unsigned char* xl) const {
;     ...
;                         if (!sample) { const f32x4 prv = (m == 0) ? hb[bj] : acc[ai][bj][m == 0 ? 0 : m - 1][n];
; #pragma unroll
;                             for (int j = 0; j < 4; ++j) { const float s1 = fr == 15 ? prv[j] : cur[j], s2 = fr >= 14 ? prv[j] : cur[j]; p1[j] = dpp_ror<1>(s1); p2[j] = dpp_ror<2>(s2); }
.LBB0_1807:
.LBB0_1808:
	s_waitcnt lgkmcnt(1)
	v_cndmask_b32_e64 v44, v36, v52, s[16:17]
	v_cndmask_b32_e64 v48, v36, v52, s[10:11]
	v_cndmask_b32_e64 v45, v37, v53, s[16:17]
	v_cndmask_b32_e64 v49, v37, v53, s[10:11]
	v_cndmask_b32_e64 v46, v38, v54, s[16:17]
	v_cndmask_b32_e64 v50, v38, v54, s[10:11]
	v_cndmask_b32_e64 v47, v39, v55, s[16:17]
	v_cndmask_b32_e64 v51, v39, v55, s[10:11]
	v_mov_b32_dpp v44, v44 row_ror:1 row_mask:0xf bank_mask:0xf
	v_mov_b32_dpp v48, v48 row_ror:2 row_mask:0xf bank_mask:0xf
	v_mov_b32_dpp v45, v45 row_ror:1 row_mask:0xf bank_mask:0xf
	v_mov_b32_dpp v49, v49 row_ror:2 row_mask:0xf bank_mask:0xf
	v_mov_b32_dpp v46, v46 row_ror:1 row_mask:0xf bank_mask:0xf
	v_mov_b32_dpp v50, v50 row_ror:2 row_mask:0xf bank_mask:0xf
	v_mov_b32_dpp v47, v47 row_ror:1 row_mask:0xf bank_mask:0xf
	v_mov_b32_dpp v51, v51 row_ror:2 row_mask:0xf bank_mask:0xf

; __device__ __forceinline__ unsigned pk2(float lo, float hi) { const f32x2 v = {lo, hi}; const bf16x2_t b = __builtin_convertvector(v, bf16x2_t); return __builtin_bit_cast(unsigned, b); }
;     __device__ __forceinline__ void operator()(const f32x4 (&acc)[2][2][4][2], const pg8::Unit& u, int wr, int wc, int fr, int fq, PG8_LAS unsigned char* xl) const {
;     ...
;                         const f32x4 cur = acc[ai][bj][m][n]; f32x4 p1, p2;
;                         if (!sample) { const f32x4 prv = (m == 0) ? hb[bj] : acc[ai][bj][m == 0 ? 0 : m - 1][n];
; #pragma unroll
;                             for (int j = 0; j < 4; ++j) { const float s1 = fr == 15 ? prv[j] : cur[j], s2 = fr >= 14 ? prv[j] : cur[j]; p1[j] = dpp_ror<1>(s1); p2[j] = dpp_ror<2>(s2); }
;                         } else { const int t = fr & 3, b = (row - MP) >> 2;
; #pragma unroll
;                             for (int j = 0; j < 4; ++j) { p1[j] = dpp_ror<1>(cur[j]); p2[j] = dpp_ror<2>(cur[j]); }
;                             const f32x4 c1 = *(const f32x4*)(ctx_s + (size_t)(b * 2 + 1) * FF2 + bj * FF + jc0 + 4 * n), c0 = *(const f32x4*)(ctx_s + (size_t)(b * 2) * FF2 + bj * FF + jc0 + 4 * n);
; #pragma unroll
;                             for (int j = 0; j < 4; ++j) { p2[j] = t == 0 ? c0[j] : (t == 1 ? c1[j] : p2[j]); p1[j] = t == 0 ? c1[j] : p1[j]; }
;                         }
;                         cc[bj] = bb[bj] + w0[bj] * p2 + w1[bj] * p1 + w2[bj] * cur;
;                     }
;                     const f32x4 gv = gelu_mul4(cc[0], cc[1]);
;                     u32x2 w; w.x = pk2(gv[0], gv[1]); w.y = pk2(gv[2], gv[3]);
;                     *(u32x2*)(G + (size_t)row * FF + jc0 + 4 * n) = w;
;                     if (!sample && ai == 0 && wr == 0 && m == 0 && fr < 2 && (pm & 7) != 0) {
; #pragma unroll
;                         for (int bj = 0; bj < 2; ++bj) *(f32x4*)(PH + (size_t)(pm * 2 + fr) * FF2 + bj * FF + jc0 + 4 * n) = cc[bj];
;                     }
;                     if (sample && (fr & 3) >= 2) { const int b = (row - MP) >> 2, t = fr & 3;
; #pragma unroll
;                         for (int bj = 0; bj < 2; ++bj) *(f32x4*)(nf_s + (size_t)(b * 2 + t - 2) * FF2 + bj * FF + jc0 + 4 * n) = acc[ai][bj][m][n];
.LBB0_1811:
.LBB0_1812:
	s_waitcnt lgkmcnt(0)
	v_cndmask_b32_e64 v52, v32, v40, s[16:17]
	v_cndmask_b32_e64 v56, v32, v40, s[10:11]
	v_cndmask_b32_e64 v53, v33, v41, s[16:17]
	v_cndmask_b32_e64 v57, v33, v41, s[10:11]
	v_cndmask_b32_e64 v54, v34, v42, s[16:17]
	v_cndmask_b32_e64 v58, v34, v42, s[10:11]
	v_cndmask_b32_e64 v55, v35, v43, s[16:17]
	v_cndmask_b32_e64 v59, v35, v43, s[10:11]
	v_mov_b32_dpp v52, v52 row_ror:1 row_mask:0xf bank_mask:0xf
	v_mov_b32_dpp v56, v56 row_ror:2 row_mask:0xf bank_mask:0xf
	v_mov_b32_dpp v53, v53 row_ror:1 row_mask:0xf bank_mask:0xf
	v_mov_b32_dpp v57, v57 row_ror:2 row_mask:0xf bank_mask:0xf
	v_mov_b32_dpp v54, v54 row_ror:1 row_mask:0xf bank_mask:0xf
	v_mov_b32_dpp v58, v58 row_ror:2 row_mask:0xf bank_mask:0xf
	v_mov_b32_dpp v55, v55 row_ror:1 row_mask:0xf bank_mask:0xf
	v_mov_b32_dpp v59, v59 row_ror:2 row_mask:0xf bank_mask:0xf
.LBB0_1813:
	s_waitcnt lgkmcnt(0)
	v_pk_fma_f32 v[40:41], v[98:99], v[50:51], v[102:103]
	v_pk_fma_f32 v[42:43], v[96:97], v[48:49], v[100:101]
	v_pk_fma_f32 v[40:41], v[90:91], v[46:47], v[40:41]
	v_pk_fma_f32 v[42:43], v[88:89], v[44:45], v[42:43]
	v_pk_fma_f32 v[40:41], v[38:39], v[82:83], v[40:41]
	v_pk_fma_f32 v[42:43], v[36:37], v[80:81], v[42:43]
	v_pk_fma_f32 v[46:47], v[84:85], v[56:57], v[92:93]
	v_pk_mul_f32 v[48:49], v[40:41], v[40:41]
	v_pk_fma_f32 v[46:47], v[76:77], v[52:53], v[46:47]
	v_pk_mul_f32 v[50:51], v[42:43], v[42:43]
	v_pk_fma_f32 v[48:49], v[48:49], s[82:83], v[246:247] op_sel_hi:[1,0,0]
	v_pk_fma_f32 v[50:51], v[50:51], s[82:83], v[246:247] op_sel_hi:[1,0,0]
	v_pk_mul_f32 v[48:49], v[40:41], v[48:49]
	v_pk_mul_f32 v[50:51], v[42:43], v[50:51]
	v_exp_f32_e32 v48, v48
	v_exp_f32_e32 v50, v50
	v_exp_f32_e32 v49, v49
	v_exp_f32_e32 v51, v51
	v_pk_fma_f32 v[44:45], v[86:87], v[58:59], v[94:95]
	v_pk_fma_f32 v[46:47], v[32:33], v[72:73], v[46:47]
	v_pk_add_f32 v[48:49], v[48:49], 1.0 op_sel_hi:[1,0]
	v_pk_add_f32 v[50:51], v[50:51], 1.0 op_sel_hi:[1,0]
	v_rcp_f32_e32 v48, v48
	v_rcp_f32_e32 v50, v50
	v_rcp_f32_e32 v49, v49
	v_rcp_f32_e32 v51, v51
	v_pk_fma_f32 v[44:45], v[78:79], v[54:55], v[44:45]
	v_pk_mul_f32 v[42:43], v[42:43], v[46:47]
	v_pk_fma_f32 v[44:45], v[34:35], v[74:75], v[44:45]
	v_pk_mul_f32 v[42:43], v[42:43], v[50:51]
	v_pk_mul_f32 v[40:41], v[40:41], v[44:45]
	v_cvt_pk_bf16_f32 v42, v42, v43
	v_pk_mul_f32 v[40:41], v[40:41], v[48:49]
	s_nop 0
	v_cvt_pk_bf16_f32 v43, v40, v41
	ds_bpermute_b32 v236, v244, v144
	ds_bpermute_b32 v237, v244, v145
	ds_bpermute_b32 v238, v244, v42
	ds_bpermute_b32 v239, v244, v43
	s_waitcnt lgkmcnt(0)
	global_store_dwordx2 v[236:237], v[238:239], off offset:8
	s_and_saveexec_b64 s[6:7], s[96:97]
	s_cbranch_execnz .Lnfs_1_26

; template <int N> __device__ __forceinline__ float dpp_ror(float v) { const int i = __builtin_bit_cast(int, v); return __builtin_bit_cast(float, __builtin_amdgcn_update_dpp(i, i, 0x120 + N, 0xF, 0xF, false)); }
;     __device__ __forceinline__ void operator()(const f32x4 (&acc)[2][2][4][2], const pg8::Unit& u, int wr, int wc, int fr, int fq, PG8_LAS unsigned char* xl) const {
;     ...
;                         if (!sample) { const f32x4 prv = (m == 0) ? hb[bj] : acc[ai][bj][m == 0 ? 0 : m - 1][n];
; #pragma unroll
;                             for (int j = 0; j < 4; ++j) { const float s1 = fr == 15 ? prv[j] : cur[j], s2 = fr >= 14 ? prv[j] : cur[j]; p1[j] = dpp_ror<1>(s1); p2[j] = dpp_ror<2>(s2); }
.LBB0_1817:
.LBB0_1818:
	v_cndmask_b32_e64 v40, v28, v36, s[16:17]
	v_cndmask_b32_e64 v44, v28, v36, s[10:11]
	v_cndmask_b32_e64 v41, v29, v37, s[16:17]
	v_cndmask_b32_e64 v45, v29, v37, s[10:11]
	v_cndmask_b32_e64 v42, v30, v38, s[16:17]
	v_cndmask_b32_e64 v46, v30, v38, s[10:11]
	v_cndmask_b32_e64 v43, v31, v39, s[16:17]
	v_cndmask_b32_e64 v47, v31, v39, s[10:11]
	v_mov_b32_dpp v40, v40 row_ror:1 row_mask:0xf bank_mask:0xf
	v_mov_b32_dpp v44, v44 row_ror:2 row_mask:0xf bank_mask:0xf
	v_mov_b32_dpp v41, v41 row_ror:1 row_mask:0xf bank_mask:0xf
	v_mov_b32_dpp v45, v45 row_ror:2 row_mask:0xf bank_mask:0xf
	v_mov_b32_dpp v42, v42 row_ror:1 row_mask:0xf bank_mask:0xf
	v_mov_b32_dpp v46, v46 row_ror:2 row_mask:0xf bank_mask:0xf
	v_mov_b32_dpp v43, v43 row_ror:1 row_mask:0xf bank_mask:0xf
	v_mov_b32_dpp v47, v47 row_ror:2 row_mask:0xf bank_mask:0xf

; __device__ __forceinline__ unsigned pk2(float lo, float hi) { const f32x2 v = {lo, hi}; const bf16x2_t b = __builtin_convertvector(v, bf16x2_t); return __builtin_bit_cast(unsigned, b); }
;     __device__ __forceinline__ void operator()(const f32x4 (&acc)[2][2][4][2], const pg8::Unit& u, int wr, int wc, int fr, int fq, PG8_LAS unsigned char* xl) const {
;     ...
;                         const f32x4 cur = acc[ai][bj][m][n]; f32x4 p1, p2;
;                         if (!sample) { const f32x4 prv = (m == 0) ? hb[bj] : acc[ai][bj][m == 0 ? 0 : m - 1][n];
; #pragma unroll
;                             for (int j = 0; j < 4; ++j) { const float s1 = fr == 15 ? prv[j] : cur[j], s2 = fr >= 14 ? prv[j] : cur[j]; p1[j] = dpp_ror<1>(s1); p2[j] = dpp_ror<2>(s2); }
;                         } else { const int t = fr & 3, b = (row - MP) >> 2;
; #pragma unroll
;                             for (int j = 0; j < 4; ++j) { p1[j] = dpp_ror<1>(cur[j]); p2[j] = dpp_ror<2>(cur[j]); }
;                             const f32x4 c1 = *(const f32x4*)(ctx_s + (size_t)(b * 2 + 1) * FF2 + bj * FF + jc0 + 4 * n), c0 = *(const f32x4*)(ctx_s + (size_t)(b * 2) * FF2 + bj * FF + jc0 + 4 * n);
; #pragma unroll
;                             for (int j = 0; j < 4; ++j) { p2[j] = t == 0 ? c0[j] : (t == 1 ? c1[j] : p2[j]); p1[j] = t == 0 ? c1[j] : p1[j]; }
;                         }
;                         cc[bj] = bb[bj] + w0[bj] * p2 + w1[bj] * p1 + w2[bj] * cur;
;                     }
;                     const f32x4 gv = gelu_mul4(cc[0], cc[1]);
;                     u32x2 w; w.x = pk2(gv[0], gv[1]); w.y = pk2(gv[2], gv[3]);
;                     *(u32x2*)(G + (size_t)row * FF + jc0 + 4 * n) = w;
;                     if (!sample && ai == 0 && wr == 0 && m == 0 && fr < 2 && (pm & 7) != 0) {
; #pragma unroll
;                         for (int bj = 0; bj < 2; ++bj) *(f32x4*)(PH + (size_t)(pm * 2 + fr) * FF2 + bj * FF + jc0 + 4 * n) = cc[bj];
;                     }
;                     if (sample && (fr & 3) >= 2) { const int b = (row - MP) >> 2, t = fr & 3;
; #pragma unroll
;                         for (int bj = 0; bj < 2; ++bj) *(f32x4*)(nf_s + (size_t)(b * 2 + t - 2) * FF2 + bj * FF + jc0 + 4 * n) = acc[ai][bj][m][n];
.LBB0_1821:
.LBB0_1822:
	v_cndmask_b32_e64 v36, v24, v32, s[16:17]
	v_cndmask_b32_e64 v48, v24, v32, s[10:11]
	v_cndmask_b32_e64 v37, v25, v33, s[16:17]
	v_cndmask_b32_e64 v49, v25, v33, s[10:11]
	v_cndmask_b32_e64 v38, v26, v34, s[16:17]
	v_cndmask_b32_e64 v50, v26, v34, s[10:11]
	v_cndmask_b32_e64 v39, v27, v35, s[16:17]
	v_cndmask_b32_e64 v51, v27, v35, s[10:11]
	v_mov_b32_dpp v36, v36 row_ror:1 row_mask:0xf bank_mask:0xf
	v_mov_b32_dpp v48, v48 row_ror:2 row_mask:0xf bank_mask:0xf
	v_mov_b32_dpp v37, v37 row_ror:1 row_mask:0xf bank_mask:0xf
	v_mov_b32_dpp v49, v49 row_ror:2 row_mask:0xf bank_mask:0xf
	v_mov_b32_dpp v38, v38 row_ror:1 row_mask:0xf bank_mask:0xf
	v_mov_b32_dpp v50, v50 row_ror:2 row_mask:0xf bank_mask:0xf
	v_mov_b32_dpp v39, v39 row_ror:1 row_mask:0xf bank_mask:0xf
	v_mov_b32_dpp v51, v51 row_ror:2 row_mask:0xf bank_mask:0xf
.LBB0_1823:
	v_pk_fma_f32 v[32:33], v[98:99], v[46:47], v[102:103]
	v_pk_fma_f32 v[34:35], v[96:97], v[44:45], v[100:101]
	v_pk_fma_f32 v[32:33], v[90:91], v[42:43], v[32:33]
	v_pk_fma_f32 v[34:35], v[88:89], v[40:41], v[34:35]
	v_pk_fma_f32 v[32:33], v[30:31], v[82:83], v[32:33]
	v_pk_fma_f32 v[34:35], v[28:29], v[80:81], v[34:35]
	v_pk_fma_f32 v[40:41], v[86:87], v[50:51], v[94:95]
	v_pk_fma_f32 v[42:43], v[84:85], v[48:49], v[92:93]
	v_pk_fma_f32 v[38:39], v[78:79], v[38:39], v[40:41]
	v_pk_fma_f32 v[36:37], v[76:77], v[36:37], v[42:43]
	v_pk_mul_f32 v[40:41], v[32:33], v[32:33]
	v_pk_mul_f32 v[42:43], v[34:35], v[34:35]
	v_pk_fma_f32 v[40:41], v[40:41], s[82:83], v[246:247] op_sel_hi:[1,0,0]
	v_pk_fma_f32 v[42:43], v[42:43], s[82:83], v[246:247] op_sel_hi:[1,0,0]
	v_pk_mul_f32 v[40:41], v[32:33], v[40:41]
	v_pk_mul_f32 v[42:43], v[34:35], v[42:43]
	v_exp_f32_e32 v40, v40
	v_exp_f32_e32 v42, v42
	v_exp_f32_e32 v41, v41
	v_exp_f32_e32 v43, v43
	v_pk_fma_f32 v[38:39], v[26:27], v[74:75], v[38:39]
	v_pk_fma_f32 v[36:37], v[24:25], v[72:73], v[36:37]
	v_pk_add_f32 v[40:41], v[40:41], 1.0 op_sel_hi:[1,0]
	v_pk_add_f32 v[42:43], v[42:43], 1.0 op_sel_hi:[1,0]
	v_rcp_f32_e32 v40, v40
	v_rcp_f32_e32 v42, v42
	v_rcp_f32_e32 v41, v41
	v_rcp_f32_e32 v43, v43
	v_pk_mul_f32 v[32:33], v[32:33], v[38:39]
	v_pk_mul_f32 v[34:35], v[34:35], v[36:37]
	v_pk_mul_f32 v[32:33], v[32:33], v[40:41]
	v_pk_mul_f32 v[34:35], v[34:35], v[42:43]
	s_nop 0
	v_cvt_pk_bf16_f32 v34, v34, v35
	v_cvt_pk_bf16_f32 v35, v32, v33
	ds_bpermute_b32 v236, v244, v136
	ds_bpermute_b32 v237, v244, v137
	ds_bpermute_b32 v238, v244, v34
	ds_bpermute_b32 v239, v244, v35
	s_waitcnt lgkmcnt(0)
	global_store_dwordx2 v[236:237], v[238:239], off offset:8
	s_and_saveexec_b64 s[6:7], s[96:97]
	s_cbranch_execnz .Lnfs_1_27

; template <int N> __device__ __forceinline__ float dpp_ror(float v) { const int i = __builtin_bit_cast(int, v); return __builtin_bit_cast(float, __builtin_amdgcn_update_dpp(i, i, 0x120 + N, 0xF, 0xF, false)); }
;     __device__ __forceinline__ void operator()(const f32x4 (&acc)[2][2][4][2], const pg8::Unit& u, int wr, int wc, int fr, int fq, PG8_LAS unsigned char* xl) const {
;     ...
;                         if (!sample) { const f32x4 prv = (m == 0) ? hb[bj] : acc[ai][bj][m == 0 ? 0 : m - 1][n];
; #pragma unroll
;                             for (int j = 0; j < 4; ++j) { const float s1 = fr == 15 ? prv[j] : cur[j], s2 = fr >= 14 ? prv[j] : cur[j]; p1[j] = dpp_ror<1>(s1); p2[j] = dpp_ror<2>(s2); }
.LBB0_1827:
.LBB0_1828:
	v_cndmask_b32_e64 v32, v20, v28, s[16:17]
	v_cndmask_b32_e64 v36, v20, v28, s[10:11]
	v_cndmask_b32_e64 v33, v21, v29, s[16:17]
	v_cndmask_b32_e64 v37, v21, v29, s[10:11]
	v_cndmask_b32_e64 v34, v22, v30, s[16:17]
	v_cndmask_b32_e64 v38, v22, v30, s[10:11]
	v_cndmask_b32_e64 v35, v23, v31, s[16:17]
	v_cndmask_b32_e64 v39, v23, v31, s[10:11]
	v_mov_b32_dpp v32, v32 row_ror:1 row_mask:0xf bank_mask:0xf
	v_mov_b32_dpp v36, v36 row_ror:2 row_mask:0xf bank_mask:0xf
	v_mov_b32_dpp v33, v33 row_ror:1 row_mask:0xf bank_mask:0xf
	v_mov_b32_dpp v37, v37 row_ror:2 row_mask:0xf bank_mask:0xf
	v_mov_b32_dpp v34, v34 row_ror:1 row_mask:0xf bank_mask:0xf
	v_mov_b32_dpp v38, v38 row_ror:2 row_mask:0xf bank_mask:0xf
	v_mov_b32_dpp v35, v35 row_ror:1 row_mask:0xf bank_mask:0xf
	v_mov_b32_dpp v39, v39 row_ror:2 row_mask:0xf bank_mask:0xf

; __device__ __forceinline__ unsigned pk2(float lo, float hi) { const f32x2 v = {lo, hi}; const bf16x2_t b = __builtin_convertvector(v, bf16x2_t); return __builtin_bit_cast(unsigned, b); }
;     __device__ __forceinline__ void operator()(const f32x4 (&acc)[2][2][4][2], const pg8::Unit& u, int wr, int wc, int fr, int fq, PG8_LAS unsigned char* xl) const {
;     ...
;                         const f32x4 cur = acc[ai][bj][m][n]; f32x4 p1, p2;
;                         if (!sample) { const f32x4 prv = (m == 0) ? hb[bj] : acc[ai][bj][m == 0 ? 0 : m - 1][n];
; #pragma unroll
;                             for (int j = 0; j < 4; ++j) { const float s1 = fr == 15 ? prv[j] : cur[j], s2 = fr >= 14 ? prv[j] : cur[j]; p1[j] = dpp_ror<1>(s1); p2[j] = dpp_ror<2>(s2); }
;                         } else { const int t = fr & 3, b = (row - MP) >> 2;
; #pragma unroll
;                             for (int j = 0; j < 4; ++j) { p1[j] = dpp_ror<1>(cur[j]); p2[j] = dpp_ror<2>(cur[j]); }
;                             const f32x4 c1 = *(const f32x4*)(ctx_s + (size_t)(b * 2 + 1) * FF2 + bj * FF + jc0 + 4 * n), c0 = *(const f32x4*)(ctx_s + (size_t)(b * 2) * FF2 + bj * FF + jc0 + 4 * n);
; #pragma unroll
;                             for (int j = 0; j < 4; ++j) { p2[j] = t == 0 ? c0[j] : (t == 1 ? c1[j] : p2[j]); p1[j] = t == 0 ? c1[j] : p1[j]; }
;                         }
;                         cc[bj] = bb[bj] + w0[bj] * p2 + w1[bj] * p1 + w2[bj] * cur;
;                     }
;                     const f32x4 gv = gelu_mul4(cc[0], cc[1]);
;                     u32x2 w; w.x = pk2(gv[0], gv[1]); w.y = pk2(gv[2], gv[3]);
;                     *(u32x2*)(G + (size_t)row * FF + jc0 + 4 * n) = w;
;                     if (!sample && ai == 0 && wr == 0 && m == 0 && fr < 2 && (pm & 7) != 0) {
; #pragma unroll
;                         for (int bj = 0; bj < 2; ++bj) *(f32x4*)(PH + (size_t)(pm * 2 + fr) * FF2 + bj * FF + jc0 + 4 * n) = cc[bj];
;                     }
;                     if (sample && (fr & 3) >= 2) { const int b = (row - MP) >> 2, t = fr & 3;
; #pragma unroll
;                         for (int bj = 0; bj < 2; ++bj) *(f32x4*)(nf_s + (size_t)(b * 2 + t - 2) * FF2 + bj * FF + jc0 + 4 * n) = acc[ai][bj][m][n];
.LBB0_1831:
.LBB0_1832:
	v_cndmask_b32_e64 v28, v16, v24, s[16:17]
	v_cndmask_b32_e64 v40, v16, v24, s[10:11]
	v_cndmask_b32_e64 v29, v17, v25, s[16:17]
	v_cndmask_b32_e64 v41, v17, v25, s[10:11]
	v_cndmask_b32_e64 v30, v18, v26, s[16:17]
	v_cndmask_b32_e64 v42, v18, v26, s[10:11]
	v_cndmask_b32_e64 v31, v19, v27, s[16:17]
	v_cndmask_b32_e64 v43, v19, v27, s[10:11]
	v_mov_b32_dpp v28, v28 row_ror:1 row_mask:0xf bank_mask:0xf
	v_mov_b32_dpp v40, v40 row_ror:2 row_mask:0xf bank_mask:0xf
	v_mov_b32_dpp v29, v29 row_ror:1 row_mask:0xf bank_mask:0xf
	v_mov_b32_dpp v41, v41 row_ror:2 row_mask:0xf bank_mask:0xf
	v_mov_b32_dpp v30, v30 row_ror:1 row_mask:0xf bank_mask:0xf
	v_mov_b32_dpp v42, v42 row_ror:2 row_mask:0xf bank_mask:0xf
	v_mov_b32_dpp v31, v31 row_ror:1 row_mask:0xf bank_mask:0xf
	v_mov_b32_dpp v43, v43 row_ror:2 row_mask:0xf bank_mask:0xf
.LBB0_1833:
	v_pk_fma_f32 v[24:25], v[98:99], v[38:39], v[102:103]
	v_pk_fma_f32 v[26:27], v[96:97], v[36:37], v[100:101]
	v_pk_fma_f32 v[24:25], v[90:91], v[34:35], v[24:25]
	v_pk_fma_f32 v[26:27], v[88:89], v[32:33], v[26:27]
	v_pk_fma_f32 v[24:25], v[22:23], v[82:83], v[24:25]
	v_pk_fma_f32 v[26:27], v[20:21], v[80:81], v[26:27]
	v_pk_fma_f32 v[32:33], v[86:87], v[42:43], v[94:95]
	v_pk_fma_f32 v[34:35], v[84:85], v[40:41], v[92:93]
	v_pk_fma_f32 v[30:31], v[78:79], v[30:31], v[32:33]
	v_pk_fma_f32 v[28:29], v[76:77], v[28:29], v[34:35]
	v_pk_mul_f32 v[32:33], v[24:25], v[24:25]
	v_pk_mul_f32 v[34:35], v[26:27], v[26:27]
	v_pk_fma_f32 v[32:33], v[32:33], s[82:83], v[246:247] op_sel_hi:[1,0,0]
	v_pk_fma_f32 v[34:35], v[34:35], s[82:83], v[246:247] op_sel_hi:[1,0,0]
	v_pk_mul_f32 v[32:33], v[24:25], v[32:33]
	v_pk_mul_f32 v[34:35], v[26:27], v[34:35]
	v_exp_f32_e32 v32, v32
	v_exp_f32_e32 v34, v34
	v_exp_f32_e32 v33, v33
	v_exp_f32_e32 v35, v35
	v_pk_fma_f32 v[30:31], v[18:19], v[74:75], v[30:31]
	v_pk_fma_f32 v[28:29], v[16:17], v[72:73], v[28:29]
	v_pk_add_f32 v[32:33], v[32:33], 1.0 op_sel_hi:[1,0]
	v_pk_add_f32 v[34:35], v[34:35], 1.0 op_sel_hi:[1,0]
	v_rcp_f32_e32 v32, v32
	v_rcp_f32_e32 v34, v34
	v_rcp_f32_e32 v33, v33
	v_rcp_f32_e32 v35, v35
	v_pk_mul_f32 v[24:25], v[24:25], v[30:31]
	v_pk_mul_f32 v[26:27], v[26:27], v[28:29]
	v_pk_mul_f32 v[24:25], v[24:25], v[32:33]
	v_pk_mul_f32 v[26:27], v[26:27], v[34:35]
	s_nop 0
	v_cvt_pk_bf16_f32 v26, v26, v27
	v_cvt_pk_bf16_f32 v27, v24, v25
	ds_bpermute_b32 v236, v244, v128
	ds_bpermute_b32 v237, v244, v129
	ds_bpermute_b32 v238, v244, v26
	ds_bpermute_b32 v239, v244, v27
	s_waitcnt lgkmcnt(0)
	global_store_dwordx2 v[236:237], v[238:239], off offset:8
	s_and_saveexec_b64 s[6:7], s[96:97]
	s_cbranch_execnz .Lnfs_1_28

; template <int N> __device__ __forceinline__ float dpp_ror(float v) { const int i = __builtin_bit_cast(int, v); return __builtin_bit_cast(float, __builtin_amdgcn_update_dpp(i, i, 0x120 + N, 0xF, 0xF, false)); }
;     __device__ __forceinline__ void operator()(const f32x4 (&acc)[2][2][4][2], const pg8::Unit& u, int wr, int wc, int fr, int fq, PG8_LAS unsigned char* xl) const {
;     ...
;                         if (!sample) { const f32x4 prv = (m == 0) ? hb[bj] : acc[ai][bj][m == 0 ? 0 : m - 1][n];
; #pragma unroll
;                             for (int j = 0; j < 4; ++j) { const float s1 = fr == 15 ? prv[j] : cur[j], s2 = fr >= 14 ? prv[j] : cur[j]; p1[j] = dpp_ror<1>(s1); p2[j] = dpp_ror<2>(s2); }
.LBB0_1837:
.LBB0_1838:
	v_cndmask_b32_e64 v24, v8, v20, s[16:17]
	v_cndmask_b32_e64 v28, v8, v20, s[10:11]
	v_cndmask_b32_e64 v25, v9, v21, s[16:17]
	v_cndmask_b32_e64 v29, v9, v21, s[10:11]
	v_cndmask_b32_e64 v26, v10, v22, s[16:17]
	v_cndmask_b32_e64 v30, v10, v22, s[10:11]
	v_cndmask_b32_e64 v27, v11, v23, s[16:17]
	v_cndmask_b32_e64 v31, v11, v23, s[10:11]
	v_mov_b32_dpp v24, v24 row_ror:1 row_mask:0xf bank_mask:0xf
	v_mov_b32_dpp v28, v28 row_ror:2 row_mask:0xf bank_mask:0xf
	v_mov_b32_dpp v25, v25 row_ror:1 row_mask:0xf bank_mask:0xf
	v_mov_b32_dpp v29, v29 row_ror:2 row_mask:0xf bank_mask:0xf
	v_mov_b32_dpp v26, v26 row_ror:1 row_mask:0xf bank_mask:0xf
	v_mov_b32_dpp v30, v30 row_ror:2 row_mask:0xf bank_mask:0xf
	v_mov_b32_dpp v27, v27 row_ror:1 row_mask:0xf bank_mask:0xf
	v_mov_b32_dpp v31, v31 row_ror:2 row_mask:0xf bank_mask:0xf

; __device__ __forceinline__ unsigned pk2(float lo, float hi) { const f32x2 v = {lo, hi}; const bf16x2_t b = __builtin_convertvector(v, bf16x2_t); return __builtin_bit_cast(unsigned, b); }
;     __device__ __forceinline__ void operator()(const f32x4 (&acc)[2][2][4][2], const pg8::Unit& u, int wr, int wc, int fr, int fq, PG8_LAS unsigned char* xl) const {
;     ...
;                         const f32x4 cur = acc[ai][bj][m][n]; f32x4 p1, p2;
;                         if (!sample) { const f32x4 prv = (m == 0) ? hb[bj] : acc[ai][bj][m == 0 ? 0 : m - 1][n];
; #pragma unroll
;                             for (int j = 0; j < 4; ++j) { const float s1 = fr == 15 ? prv[j] : cur[j], s2 = fr >= 14 ? prv[j] : cur[j]; p1[j] = dpp_ror<1>(s1); p2[j] = dpp_ror<2>(s2); }
;                         } else { const int t = fr & 3, b = (row - MP) >> 2;
; #pragma unroll
;                             for (int j = 0; j < 4; ++j) { p1[j] = dpp_ror<1>(cur[j]); p2[j] = dpp_ror<2>(cur[j]); }
;                             const f32x4 c1 = *(const f32x4*)(ctx_s + (size_t)(b * 2 + 1) * FF2 + bj * FF + jc0 + 4 * n), c0 = *(const f32x4*)(ctx_s + (size_t)(b * 2) * FF2 + bj * FF + jc0 + 4 * n);
; #pragma unroll
;                             for (int j = 0; j < 4; ++j) { p2[j] = t == 0 ? c0[j] : (t == 1 ? c1[j] : p2[j]); p1[j] = t == 0 ? c1[j] : p1[j]; }
;                         }
;                         cc[bj] = bb[bj] + w0[bj] * p2 + w1[bj] * p1 + w2[bj] * cur;
;                     }
;                     const f32x4 gv = gelu_mul4(cc[0], cc[1]);
;                     u32x2 w; w.x = pk2(gv[0], gv[1]); w.y = pk2(gv[2], gv[3]);
;                     *(u32x2*)(G + (size_t)row * FF + jc0 + 4 * n) = w;
;                     if (!sample && ai == 0 && wr == 0 && m == 0 && fr < 2 && (pm & 7) != 0) {
; #pragma unroll
;                         for (int bj = 0; bj < 2; ++bj) *(f32x4*)(PH + (size_t)(pm * 2 + fr) * FF2 + bj * FF + jc0 + 4 * n) = cc[bj];
;                     }
;                     if (sample && (fr & 3) >= 2) { const int b = (row - MP) >> 2, t = fr & 3;
; #pragma unroll
;                         for (int bj = 0; bj < 2; ++bj) *(f32x4*)(nf_s + (size_t)(b * 2 + t - 2) * FF2 + bj * FF + jc0 + 4 * n) = acc[ai][bj][m][n];
;                     }
.LBB0_1841:
.LBB0_1842:
	v_cndmask_b32_e64 v20, v0, v16, s[16:17]
	v_cndmask_b32_e64 v32, v0, v16, s[10:11]
	v_cndmask_b32_e64 v21, v1, v17, s[16:17]
	v_cndmask_b32_e64 v33, v1, v17, s[10:11]
	v_cndmask_b32_e64 v22, v2, v18, s[16:17]
	v_cndmask_b32_e64 v34, v2, v18, s[10:11]
	v_cndmask_b32_e64 v23, v3, v19, s[16:17]
	v_cndmask_b32_e64 v35, v3, v19, s[10:11]
	v_mov_b32_dpp v20, v20 row_ror:1 row_mask:0xf bank_mask:0xf
	v_mov_b32_dpp v32, v32 row_ror:2 row_mask:0xf bank_mask:0xf
	v_mov_b32_dpp v21, v21 row_ror:1 row_mask:0xf bank_mask:0xf
	v_mov_b32_dpp v33, v33 row_ror:2 row_mask:0xf bank_mask:0xf
	v_mov_b32_dpp v22, v22 row_ror:1 row_mask:0xf bank_mask:0xf
	v_mov_b32_dpp v34, v34 row_ror:2 row_mask:0xf bank_mask:0xf
	v_mov_b32_dpp v23, v23 row_ror:1 row_mask:0xf bank_mask:0xf
	v_mov_b32_dpp v35, v35 row_ror:2 row_mask:0xf bank_mask:0xf
.LBB0_1843:
	v_pk_fma_f32 v[16:17], v[98:99], v[30:31], v[102:103]
	v_pk_fma_f32 v[18:19], v[96:97], v[28:29], v[100:101]
	v_pk_fma_f32 v[16:17], v[90:91], v[26:27], v[16:17]
	v_pk_fma_f32 v[18:19], v[88:89], v[24:25], v[18:19]
	v_pk_fma_f32 v[16:17], v[10:11], v[82:83], v[16:17]
	v_pk_fma_f32 v[18:19], v[8:9], v[80:81], v[18:19]
	v_pk_fma_f32 v[24:25], v[86:87], v[34:35], v[94:95]
	v_pk_fma_f32 v[26:27], v[84:85], v[32:33], v[92:93]
	v_pk_fma_f32 v[22:23], v[78:79], v[22:23], v[24:25]
	v_pk_fma_f32 v[20:21], v[76:77], v[20:21], v[26:27]
	v_pk_mul_f32 v[24:25], v[16:17], v[16:17]
	v_pk_mul_f32 v[26:27], v[18:19], v[18:19]
	v_pk_fma_f32 v[24:25], v[24:25], s[82:83], v[246:247] op_sel_hi:[1,0,0]
	v_pk_fma_f32 v[26:27], v[26:27], s[82:83], v[246:247] op_sel_hi:[1,0,0]
	v_pk_mul_f32 v[24:25], v[16:17], v[24:25]
	v_pk_mul_f32 v[26:27], v[18:19], v[26:27]
	v_exp_f32_e32 v24, v24
	v_exp_f32_e32 v26, v26
	v_exp_f32_e32 v25, v25
	v_exp_f32_e32 v27, v27
	v_pk_fma_f32 v[22:23], v[2:3], v[74:75], v[22:23]
	v_pk_fma_f32 v[20:21], v[0:1], v[72:73], v[20:21]
	v_pk_add_f32 v[24:25], v[24:25], 1.0 op_sel_hi:[1,0]
	v_pk_add_f32 v[26:27], v[26:27], 1.0 op_sel_hi:[1,0]
	v_rcp_f32_e32 v24, v24
	v_rcp_f32_e32 v26, v26
	v_rcp_f32_e32 v25, v25
	v_rcp_f32_e32 v27, v27
	v_pk_mul_f32 v[16:17], v[16:17], v[22:23]
	v_pk_mul_f32 v[18:19], v[18:19], v[20:21]
	v_pk_mul_f32 v[16:17], v[16:17], v[24:25]
	v_pk_mul_f32 v[18:19], v[18:19], v[26:27]
	s_nop 0
	v_cvt_pk_bf16_f32 v18, v18, v19
	v_cvt_pk_bf16_f32 v19, v16, v17
	ds_bpermute_b32 v236, v244, v130
	ds_bpermute_b32 v237, v244, v131
	ds_bpermute_b32 v238, v244, v18
	ds_bpermute_b32 v239, v244, v19
	s_waitcnt lgkmcnt(0)
	global_store_dwordx2 v[236:237], v[238:239], off offset:8
	s_branch .Lisl_end_1
.Lnfs_1_15:
	v_mov_b64_e32 v[160:161], s[24:25]
	v_mad_i64_i32 v[160:161], vcc, v220, s76, v[160:161]
	v_lshl_add_u64 v[160:161], v[196:197], 2, v[160:161]
	global_store_dwordx4 v[160:161], v[156:159], off
	v_add_co_u32_e32 v160, vcc, 0x2000, v160
	s_nop 1
	v_addc_co_u32_e32 v161, vcc, 0, v161, vcc
	global_store_dwordx4 v[160:161], v[152:155], off offset:3072
	s_branch .LBB0_1687
.Lsmp_1_30:
	v_or_b32_e32 v162, 1, v160
	v_mov_b64_e32 v[160:161], s[48:49]
	v_mad_i64_i32 v[162:163], vcc, v162, s76, v[160:161]
	v_mad_i64_i32 v[160:161], vcc, v222, s76, v[160:161]
	v_lshl_add_u64 v[174:175], v[162:163], 0, v[198:199]
	v_lshl_add_u64 v[172:173], v[160:161], 0, v[198:199]
	global_load_dwordx4 v[160:163], v[174:175], off
	global_load_dwordx4 v[164:167], v[172:173], off
	v_mov_b32_e32 v168, v148
	v_mov_b32_e32 v169, v148
	v_mov_b32_e32 v170, v149
	v_mov_b32_e32 v171, v149
	v_mov_b32_e32 v224, v150
	v_mov_b32_e32 v226, v151
	v_mov_b32_e32 v223, v150
	v_mov_b32_e32 v225, v151
	v_mov_b32_dpp v168, v168 row_ror:1 row_mask:0xf bank_mask:0xf
	v_mov_b32_dpp v169, v169 row_ror:2 row_mask:0xf bank_mask:0xf
	v_mov_b32_dpp v170, v170 row_ror:1 row_mask:0xf bank_mask:0xf
	v_mov_b32_dpp v171, v171 row_ror:2 row_mask:0xf bank_mask:0xf
	v_mov_b32_dpp v224, v224 row_ror:2 row_mask:0xf bank_mask:0xf
	v_mov_b32_dpp v226, v226 row_ror:2 row_mask:0xf bank_mask:0xf
	v_mov_b32_dpp v223, v223 row_ror:1 row_mask:0xf bank_mask:0xf
	v_mov_b32_dpp v225, v225 row_ror:1 row_mask:0xf bank_mask:0xf
	s_waitcnt vmcnt(1)
	v_cndmask_b32_e64 v169, v169, v160, s[14:15]
	v_cndmask_b32_e64 v160, v168, v160, s[12:13]
	v_cndmask_b32_e64 v168, v171, v161, s[14:15]
	v_cndmask_b32_e64 v161, v170, v161, s[12:13]
	v_cndmask_b32_e64 v170, v224, v162, s[14:15]
	v_cndmask_b32_e64 v171, v226, v163, s[14:15]
	v_cndmask_b32_e64 v162, v223, v162, s[12:13]
	v_cndmask_b32_e64 v163, v225, v163, s[12:13]
	s_waitcnt vmcnt(0)
	v_cndmask_b32_e64 v164, v169, v164, s[12:13]
	v_cndmask_b32_e64 v165, v168, v165, s[12:13]
	v_cndmask_b32_e64 v166, v170, v166, s[12:13]
	v_cndmask_b32_e64 v167, v171, v167, s[12:13]
	s_branch .LBB0_1691
.Lsmp_1_31:
	v_add_co_u32_e32 v156, vcc, 0x2000, v174
	v_mov_b32_e32 v223, v144
	s_nop 0
	v_addc_co_u32_e32 v157, vcc, 0, v175, vcc
	v_add_co_u32_e32 v168, vcc, 0x2000, v172
	global_load_dwordx4 v[156:159], v[156:157], off offset:3072
	s_nop 0
	v_addc_co_u32_e32 v169, vcc, 0, v173, vcc
	global_load_dwordx4 v[168:171], v[168:169], off offset:3072
	v_mov_b32_e32 v224, v144
	v_mov_b32_e32 v225, v145
	v_mov_b32_e32 v226, v145
	v_mov_b32_e32 v228, v146
	v_mov_b32_e32 v230, v147
	v_mov_b32_e32 v227, v146
	v_mov_b32_e32 v229, v147
	v_mov_b32_dpp v223, v223 row_ror:1 row_mask:0xf bank_mask:0xf
	v_mov_b32_dpp v224, v224 row_ror:2 row_mask:0xf bank_mask:0xf
	v_mov_b32_dpp v225, v225 row_ror:1 row_mask:0xf bank_mask:0xf
	v_mov_b32_dpp v226, v226 row_ror:2 row_mask:0xf bank_mask:0xf
	v_mov_b32_dpp v228, v228 row_ror:2 row_mask:0xf bank_mask:0xf
	v_mov_b32_dpp v230, v230 row_ror:2 row_mask:0xf bank_mask:0xf
	v_mov_b32_dpp v227, v227 row_ror:1 row_mask:0xf bank_mask:0xf
	v_mov_b32_dpp v229, v229 row_ror:1 row_mask:0xf bank_mask:0xf
	s_waitcnt vmcnt(1)
	v_cndmask_b32_e64 v224, v224, v156, s[14:15]
	v_cndmask_b32_e64 v156, v223, v156, s[12:13]
	v_cndmask_b32_e64 v223, v226, v157, s[14:15]
	v_cndmask_b32_e64 v157, v225, v157, s[12:13]
	v_cndmask_b32_e64 v225, v228, v158, s[14:15]
	v_cndmask_b32_e64 v226, v230, v159, s[14:15]
	v_cndmask_b32_e64 v158, v227, v158, s[12:13]
	v_cndmask_b32_e64 v159, v229, v159, s[12:13]
	s_waitcnt vmcnt(0)
	v_cndmask_b32_e64 v168, v224, v168, s[12:13]
	v_cndmask_b32_e64 v169, v223, v169, s[12:13]
	v_cndmask_b32_e64 v170, v225, v170, s[12:13]
	v_cndmask_b32_e64 v171, v226, v171, s[12:13]
	s_branch .LBB0_1695
; __device__ __forceinline__ unsigned pk2(float lo, float hi) { const f32x2 v = {lo, hi}; const bf16x2_t b = __builtin_convertvector(v, bf16x2_t); return __builtin_bit_cast(unsigned, b); }
; template <int N> __device__ __forceinline__ float dpp_ror(float v) { const int i = __builtin_bit_cast(int, v); return __builtin_bit_cast(float, __builtin_amdgcn_update_dpp(i, i, 0x120 + N, 0xF, 0xF, false)); }
;     __device__ __forceinline__ void operator()(const f32x4 (&acc)[2][2][4][2], const pg8::Unit& u, int wr, int wc, int fr, int fq, PG8_LAS unsigned char* xl) const {
;     ...
;                         } else { const int t = fr & 3, b = (row - MP) >> 2;
; #pragma unroll
;                             for (int j = 0; j < 4; ++j) { p1[j] = dpp_ror<1>(cur[j]); p2[j] = dpp_ror<2>(cur[j]); }
;                             const f32x4 c1 = *(const f32x4*)(ctx_s + (size_t)(b * 2 + 1) * FF2 + bj * FF + jc0 + 4 * n), c0 = *(const f32x4*)(ctx_s + (size_t)(b * 2) * FF2 + bj * FF + jc0 + 4 * n);
; #pragma unroll
;                             for (int j = 0; j < 4; ++j) { p2[j] = t == 0 ? c0[j] : (t == 1 ? c1[j] : p2[j]); p1[j] = t == 0 ? c1[j] : p1[j]; }
;                         }
;                         cc[bj] = bb[bj] + w0[bj] * p2 + w1[bj] * p1 + w2[bj] * cur;
;                     }
;                     const f32x4 gv = gelu_mul4(cc[0], cc[1]);
;                     u32x2 w; w.x = pk2(gv[0], gv[1]); w.y = pk2(gv[2], gv[3]);
;                     *(u32x2*)(G + (size_t)row * FF + jc0 + 4 * n) = w;
;                     if (!sample && ai == 0 && wr == 0 && m == 0 && fr < 2 && (pm & 7) != 0) {
; #pragma unroll
;                         for (int bj = 0; bj < 2; ++bj) *(f32x4*)(PH + (size_t)(pm * 2 + fr) * FF2 + bj * FF + jc0 + 4 * n) = cc[bj];
;                     }
;                     if (sample && (fr & 3) >= 2) { const int b = (row - MP) >> 2, t = fr & 3;
; #pragma unroll
;                         for (int bj = 0; bj < 2; ++bj) *(f32x4*)(nf_s + (size_t)(b * 2 + t - 2) * FF2 + bj * FF + jc0 + 4 * n) = acc[ai][bj][m][n];
;                     }
.Lnfs_1_16:
	v_mov_b64_e32 v[152:153], s[24:25]
	v_mad_i64_i32 v[152:153], vcc, v170, s76, v[152:153]
	v_lshl_add_u64 v[152:153], v[196:197], 2, v[152:153]
	global_store_dwordx4 v[152:153], v[148:151], off
	v_add_co_u32_e32 v152, vcc, 0x2000, v152
	s_nop 1
	v_addc_co_u32_e32 v153, vcc, 0, v153, vcc
	global_store_dwordx4 v[152:153], v[144:147], off offset:3072
	s_branch .LBB0_1697
.Lsmp_1_32:
	v_or_b32_e32 v154, 1, v152
	v_mov_b64_e32 v[152:153], s[48:49]
	v_mad_i64_i32 v[154:155], vcc, v154, s76, v[152:153]
	v_mad_i64_i32 v[152:153], vcc, v171, s76, v[152:153]
	v_lshl_add_u64 v[166:167], v[154:155], 0, v[198:199]
	v_lshl_add_u64 v[164:165], v[152:153], 0, v[198:199]
	global_load_dwordx4 v[152:155], v[166:167], off
	global_load_dwordx4 v[156:159], v[164:165], off
	v_mov_b32_e32 v160, v140
	v_mov_b32_e32 v161, v140
	v_mov_b32_e32 v162, v141
	v_mov_b32_e32 v163, v141
	v_mov_b32_e32 v223, v142
	v_mov_b32_e32 v225, v143
	v_mov_b32_e32 v222, v142
	v_mov_b32_e32 v224, v143
	v_mov_b32_dpp v160, v160 row_ror:1 row_mask:0xf bank_mask:0xf
	v_mov_b32_dpp v161, v161 row_ror:2 row_mask:0xf bank_mask:0xf
	v_mov_b32_dpp v162, v162 row_ror:1 row_mask:0xf bank_mask:0xf
	v_mov_b32_dpp v163, v163 row_ror:2 row_mask:0xf bank_mask:0xf
	v_mov_b32_dpp v223, v223 row_ror:2 row_mask:0xf bank_mask:0xf
	v_mov_b32_dpp v225, v225 row_ror:2 row_mask:0xf bank_mask:0xf
	v_mov_b32_dpp v222, v222 row_ror:1 row_mask:0xf bank_mask:0xf
	v_mov_b32_dpp v224, v224 row_ror:1 row_mask:0xf bank_mask:0xf
	s_waitcnt vmcnt(1)
	v_cndmask_b32_e64 v161, v161, v152, s[14:15]
	v_cndmask_b32_e64 v152, v160, v152, s[12:13]
	v_cndmask_b32_e64 v160, v163, v153, s[14:15]
	v_cndmask_b32_e64 v153, v162, v153, s[12:13]
	v_cndmask_b32_e64 v162, v223, v154, s[14:15]
	v_cndmask_b32_e64 v163, v225, v155, s[14:15]
	v_cndmask_b32_e64 v154, v222, v154, s[12:13]
	v_cndmask_b32_e64 v155, v224, v155, s[12:13]
	s_waitcnt vmcnt(0)
	v_cndmask_b32_e64 v156, v161, v156, s[12:13]
	v_cndmask_b32_e64 v157, v160, v157, s[12:13]
	v_cndmask_b32_e64 v158, v162, v158, s[12:13]
	v_cndmask_b32_e64 v159, v163, v159, s[12:13]
	s_branch .LBB0_1701
.Lsmp_1_33:
	v_add_co_u32_e32 v148, vcc, 0x2000, v166
	v_mov_b32_e32 v222, v136
	s_nop 0
	v_addc_co_u32_e32 v149, vcc, 0, v167, vcc
	v_add_co_u32_e32 v160, vcc, 0x2000, v164
	global_load_dwordx4 v[148:151], v[148:149], off offset:3072
	s_nop 0
	v_addc_co_u32_e32 v161, vcc, 0, v165, vcc
	global_load_dwordx4 v[160:163], v[160:161], off offset:3072
	v_mov_b32_e32 v223, v136
	v_mov_b32_e32 v224, v137
	v_mov_b32_e32 v225, v137
	v_mov_b32_e32 v227, v138
	v_mov_b32_e32 v229, v139
	v_mov_b32_e32 v226, v138
	v_mov_b32_e32 v228, v139
	v_mov_b32_dpp v222, v222 row_ror:1 row_mask:0xf bank_mask:0xf
	v_mov_b32_dpp v223, v223 row_ror:2 row_mask:0xf bank_mask:0xf
	v_mov_b32_dpp v224, v224 row_ror:1 row_mask:0xf bank_mask:0xf
	v_mov_b32_dpp v225, v225 row_ror:2 row_mask:0xf bank_mask:0xf
	v_mov_b32_dpp v227, v227 row_ror:2 row_mask:0xf bank_mask:0xf
	v_mov_b32_dpp v229, v229 row_ror:2 row_mask:0xf bank_mask:0xf
	v_mov_b32_dpp v226, v226 row_ror:1 row_mask:0xf bank_mask:0xf
	v_mov_b32_dpp v228, v228 row_ror:1 row_mask:0xf bank_mask:0xf
	s_waitcnt vmcnt(1)
	v_cndmask_b32_e64 v223, v223, v148, s[14:15]
	v_cndmask_b32_e64 v148, v222, v148, s[12:13]
	v_cndmask_b32_e64 v222, v225, v149, s[14:15]
	v_cndmask_b32_e64 v149, v224, v149, s[12:13]
	v_cndmask_b32_e64 v224, v227, v150, s[14:15]
	v_cndmask_b32_e64 v225, v229, v151, s[14:15]
	v_cndmask_b32_e64 v150, v226, v150, s[12:13]
	v_cndmask_b32_e64 v151, v228, v151, s[12:13]
	s_waitcnt vmcnt(0)
	v_cndmask_b32_e64 v160, v223, v160, s[12:13]
	v_cndmask_b32_e64 v161, v222, v161, s[12:13]
	v_cndmask_b32_e64 v162, v224, v162, s[12:13]
	v_cndmask_b32_e64 v163, v225, v163, s[12:13]
	s_branch .LBB0_1705
.Lnfs_1_17:
	v_mov_b64_e32 v[144:145], s[24:25]
	v_mad_i64_i32 v[144:145], vcc, v162, s76, v[144:145]
	v_lshl_add_u64 v[144:145], v[196:197], 2, v[144:145]
	global_store_dwordx4 v[144:145], v[140:143], off
	v_add_co_u32_e32 v144, vcc, 0x2000, v144
	s_nop 1
	v_addc_co_u32_e32 v145, vcc, 0, v145, vcc
	global_store_dwordx4 v[144:145], v[136:139], off offset:3072
	s_branch .LBB0_1707
.Lsmp_1_34:
	v_or_b32_e32 v146, 1, v144
	v_mov_b64_e32 v[144:145], s[48:49]
	v_mad_i64_i32 v[146:147], vcc, v146, s76, v[144:145]
	v_mad_i64_i32 v[144:145], vcc, v163, s76, v[144:145]
	v_lshl_add_u64 v[158:159], v[146:147], 0, v[198:199]
	v_lshl_add_u64 v[156:157], v[144:145], 0, v[198:199]
	global_load_dwordx4 v[144:147], v[158:159], off
	global_load_dwordx4 v[148:151], v[156:157], off
	v_mov_b32_e32 v152, v132
	v_mov_b32_e32 v153, v132
	v_mov_b32_e32 v154, v133
	v_mov_b32_e32 v155, v133
	v_mov_b32_e32 v222, v134
	v_mov_b32_e32 v224, v135
	v_mov_b32_e32 v171, v134
	v_mov_b32_e32 v223, v135
	v_mov_b32_dpp v152, v152 row_ror:1 row_mask:0xf bank_mask:0xf
	v_mov_b32_dpp v153, v153 row_ror:2 row_mask:0xf bank_mask:0xf
	v_mov_b32_dpp v154, v154 row_ror:1 row_mask:0xf bank_mask:0xf
	v_mov_b32_dpp v155, v155 row_ror:2 row_mask:0xf bank_mask:0xf
	v_mov_b32_dpp v222, v222 row_ror:2 row_mask:0xf bank_mask:0xf
	v_mov_b32_dpp v224, v224 row_ror:2 row_mask:0xf bank_mask:0xf
	v_mov_b32_dpp v171, v171 row_ror:1 row_mask:0xf bank_mask:0xf
	v_mov_b32_dpp v223, v223 row_ror:1 row_mask:0xf bank_mask:0xf
	s_waitcnt vmcnt(1)
	v_cndmask_b32_e64 v153, v153, v144, s[14:15]
	v_cndmask_b32_e64 v144, v152, v144, s[12:13]
	v_cndmask_b32_e64 v152, v155, v145, s[14:15]
	v_cndmask_b32_e64 v145, v154, v145, s[12:13]
	v_cndmask_b32_e64 v154, v222, v146, s[14:15]
	v_cndmask_b32_e64 v155, v224, v147, s[14:15]
	v_cndmask_b32_e64 v146, v171, v146, s[12:13]
	v_cndmask_b32_e64 v147, v223, v147, s[12:13]
	s_waitcnt vmcnt(0)
	v_cndmask_b32_e64 v148, v153, v148, s[12:13]
	v_cndmask_b32_e64 v149, v152, v149, s[12:13]
	v_cndmask_b32_e64 v150, v154, v150, s[12:13]
	v_cndmask_b32_e64 v151, v155, v151, s[12:13]
	s_branch .LBB0_1711
; __device__ __forceinline__ unsigned pk2(float lo, float hi) { const f32x2 v = {lo, hi}; const bf16x2_t b = __builtin_convertvector(v, bf16x2_t); return __builtin_bit_cast(unsigned, b); }
; template <int N> __device__ __forceinline__ float dpp_ror(float v) { const int i = __builtin_bit_cast(int, v); return __builtin_bit_cast(float, __builtin_amdgcn_update_dpp(i, i, 0x120 + N, 0xF, 0xF, false)); }
;     __device__ __forceinline__ void operator()(const f32x4 (&acc)[2][2][4][2], const pg8::Unit& u, int wr, int wc, int fr, int fq, PG8_LAS unsigned char* xl) const {
;     ...
;                         } else { const int t = fr & 3, b = (row - MP) >> 2;
; #pragma unroll
;                             for (int j = 0; j < 4; ++j) { p1[j] = dpp_ror<1>(cur[j]); p2[j] = dpp_ror<2>(cur[j]); }
;                             const f32x4 c1 = *(const f32x4*)(ctx_s + (size_t)(b * 2 + 1) * FF2 + bj * FF + jc0 + 4 * n), c0 = *(const f32x4*)(ctx_s + (size_t)(b * 2) * FF2 + bj * FF + jc0 + 4 * n);
; #pragma unroll
;                             for (int j = 0; j < 4; ++j) { p2[j] = t == 0 ? c0[j] : (t == 1 ? c1[j] : p2[j]); p1[j] = t == 0 ? c1[j] : p1[j]; }
;                         }
;                         cc[bj] = bb[bj] + w0[bj] * p2 + w1[bj] * p1 + w2[bj] * cur;
;                     }
;                     const f32x4 gv = gelu_mul4(cc[0], cc[1]);
;                     u32x2 w; w.x = pk2(gv[0], gv[1]); w.y = pk2(gv[2], gv[3]);
;                     *(u32x2*)(G + (size_t)row * FF + jc0 + 4 * n) = w;
;                     if (!sample && ai == 0 && wr == 0 && m == 0 && fr < 2 && (pm & 7) != 0) {
; #pragma unroll
;                         for (int bj = 0; bj < 2; ++bj) *(f32x4*)(PH + (size_t)(pm * 2 + fr) * FF2 + bj * FF + jc0 + 4 * n) = cc[bj];
;                     }
;                     if (sample && (fr & 3) >= 2) { const int b = (row - MP) >> 2, t = fr & 3;
; #pragma unroll
;                         for (int bj = 0; bj < 2; ++bj) *(f32x4*)(nf_s + (size_t)(b * 2 + t - 2) * FF2 + bj * FF + jc0 + 4 * n) = acc[ai][bj][m][n];
;                     }
.Lsmp_1_35:
	v_add_co_u32_e32 v140, vcc, 0x2000, v158
	v_mov_b32_e32 v171, v128
	s_nop 0
	v_addc_co_u32_e32 v141, vcc, 0, v159, vcc
	v_add_co_u32_e32 v152, vcc, 0x2000, v156
	global_load_dwordx4 v[140:143], v[140:141], off offset:3072
	s_nop 0
	v_addc_co_u32_e32 v153, vcc, 0, v157, vcc
	global_load_dwordx4 v[152:155], v[152:153], off offset:3072
	v_mov_b32_e32 v222, v128
	v_mov_b32_e32 v223, v129
	v_mov_b32_e32 v224, v129
	v_mov_b32_e32 v226, v130
	v_mov_b32_e32 v228, v131
	v_mov_b32_e32 v225, v130
	v_mov_b32_e32 v227, v131
	v_mov_b32_dpp v171, v171 row_ror:1 row_mask:0xf bank_mask:0xf
	v_mov_b32_dpp v222, v222 row_ror:2 row_mask:0xf bank_mask:0xf
	v_mov_b32_dpp v223, v223 row_ror:1 row_mask:0xf bank_mask:0xf
	v_mov_b32_dpp v224, v224 row_ror:2 row_mask:0xf bank_mask:0xf
	v_mov_b32_dpp v226, v226 row_ror:2 row_mask:0xf bank_mask:0xf
	v_mov_b32_dpp v228, v228 row_ror:2 row_mask:0xf bank_mask:0xf
	v_mov_b32_dpp v225, v225 row_ror:1 row_mask:0xf bank_mask:0xf
	v_mov_b32_dpp v227, v227 row_ror:1 row_mask:0xf bank_mask:0xf
	s_waitcnt vmcnt(1)
	v_cndmask_b32_e64 v222, v222, v140, s[14:15]
	v_cndmask_b32_e64 v140, v171, v140, s[12:13]
	v_cndmask_b32_e64 v171, v224, v141, s[14:15]
	v_cndmask_b32_e64 v141, v223, v141, s[12:13]
	v_cndmask_b32_e64 v223, v226, v142, s[14:15]
	v_cndmask_b32_e64 v224, v228, v143, s[14:15]
	v_cndmask_b32_e64 v142, v225, v142, s[12:13]
	v_cndmask_b32_e64 v143, v227, v143, s[12:13]
	s_waitcnt vmcnt(0)
	v_cndmask_b32_e64 v152, v222, v152, s[12:13]
	v_cndmask_b32_e64 v153, v171, v153, s[12:13]
	v_cndmask_b32_e64 v154, v223, v154, s[12:13]
	v_cndmask_b32_e64 v155, v224, v155, s[12:13]
	s_branch .LBB0_1715
.Lnfs_1_18:
	v_mov_b64_e32 v[136:137], s[24:25]
	v_mad_i64_i32 v[136:137], vcc, v154, s76, v[136:137]
	v_lshl_add_u64 v[136:137], v[196:197], 2, v[136:137]
	global_store_dwordx4 v[136:137], v[132:135], off
	s_nop 1
	v_add_co_u32_e32 v132, vcc, 0x2000, v136
	s_nop 1
	v_addc_co_u32_e32 v133, vcc, 0, v137, vcc
	global_store_dwordx4 v[132:133], v[128:131], off offset:3072
	s_branch .LBB0_1717
.Lsmp_1_36:
	v_or_b32_e32 v134, 1, v132
	v_mov_b64_e32 v[132:133], s[48:49]
	v_mad_i64_i32 v[134:135], vcc, v134, s76, v[132:133]
	v_mad_i64_i32 v[132:133], vcc, v155, s76, v[132:133]
	v_lshl_add_u64 v[150:151], v[134:135], 0, v[198:199]
	v_lshl_add_u64 v[148:149], v[132:133], 0, v[198:199]
	global_load_dwordx4 v[132:135], v[150:151], off
	global_load_dwordx4 v[136:139], v[148:149], off
	v_mov_b32_e32 v144, v124
	v_mov_b32_e32 v145, v124
	v_mov_b32_e32 v146, v125
	v_mov_b32_e32 v147, v125
	v_mov_b32_e32 v171, v126
	v_mov_b32_e32 v223, v127
	v_mov_b32_e32 v163, v126
	v_mov_b32_e32 v222, v127
	v_mov_b32_dpp v144, v144 row_ror:1 row_mask:0xf bank_mask:0xf
	v_mov_b32_dpp v145, v145 row_ror:2 row_mask:0xf bank_mask:0xf
	v_mov_b32_dpp v146, v146 row_ror:1 row_mask:0xf bank_mask:0xf
	v_mov_b32_dpp v147, v147 row_ror:2 row_mask:0xf bank_mask:0xf
	v_mov_b32_dpp v171, v171 row_ror:2 row_mask:0xf bank_mask:0xf
	v_mov_b32_dpp v223, v223 row_ror:2 row_mask:0xf bank_mask:0xf
	v_mov_b32_dpp v163, v163 row_ror:1 row_mask:0xf bank_mask:0xf
	v_mov_b32_dpp v222, v222 row_ror:1 row_mask:0xf bank_mask:0xf
	s_waitcnt vmcnt(1)
	v_cndmask_b32_e64 v145, v145, v132, s[14:15]
	v_cndmask_b32_e64 v132, v144, v132, s[12:13]
	v_cndmask_b32_e64 v144, v147, v133, s[14:15]
	v_cndmask_b32_e64 v133, v146, v133, s[12:13]
	v_cndmask_b32_e64 v146, v171, v134, s[14:15]
	v_cndmask_b32_e64 v147, v223, v135, s[14:15]
	v_cndmask_b32_e64 v134, v163, v134, s[12:13]
	v_cndmask_b32_e64 v135, v222, v135, s[12:13]
	s_waitcnt vmcnt(0)
	v_cndmask_b32_e64 v136, v145, v136, s[12:13]
	v_cndmask_b32_e64 v137, v144, v137, s[12:13]
	v_cndmask_b32_e64 v138, v146, v138, s[12:13]
	v_cndmask_b32_e64 v139, v147, v139, s[12:13]
	s_branch .LBB0_1723
.Lsmp_1_37:
	s_waitcnt lgkmcnt(1)
	v_add_co_u32_e32 v140, vcc, 0x2000, v150
	v_mov_b32_e32 v163, v88
	s_nop 0
	v_addc_co_u32_e32 v141, vcc, 0, v151, vcc
	v_add_co_u32_e32 v144, vcc, 0x2000, v148
	global_load_dwordx4 v[140:143], v[140:141], off offset:3072
	s_nop 0
	v_addc_co_u32_e32 v145, vcc, 0, v149, vcc
	global_load_dwordx4 v[144:147], v[144:145], off offset:3072
	v_mov_b32_e32 v171, v88
	v_mov_b32_e32 v222, v89
	v_mov_b32_e32 v223, v89
	v_mov_b32_e32 v225, v90
	v_mov_b32_e32 v227, v91
	v_mov_b32_e32 v224, v90
	v_mov_b32_e32 v226, v91
	v_mov_b32_dpp v163, v163 row_ror:1 row_mask:0xf bank_mask:0xf
	v_mov_b32_dpp v171, v171 row_ror:2 row_mask:0xf bank_mask:0xf
	v_mov_b32_dpp v222, v222 row_ror:1 row_mask:0xf bank_mask:0xf
	v_mov_b32_dpp v223, v223 row_ror:2 row_mask:0xf bank_mask:0xf
	v_mov_b32_dpp v225, v225 row_ror:2 row_mask:0xf bank_mask:0xf
	v_mov_b32_dpp v227, v227 row_ror:2 row_mask:0xf bank_mask:0xf
	v_mov_b32_dpp v224, v224 row_ror:1 row_mask:0xf bank_mask:0xf
	v_mov_b32_dpp v226, v226 row_ror:1 row_mask:0xf bank_mask:0xf
	s_waitcnt vmcnt(1)
	v_cndmask_b32_e64 v171, v171, v140, s[14:15]
	v_cndmask_b32_e64 v140, v163, v140, s[12:13]
	v_cndmask_b32_e64 v163, v223, v141, s[14:15]
	v_cndmask_b32_e64 v141, v222, v141, s[12:13]
	v_cndmask_b32_e64 v222, v225, v142, s[14:15]
	v_cndmask_b32_e64 v223, v227, v143, s[14:15]
	v_cndmask_b32_e64 v142, v224, v142, s[12:13]
	v_cndmask_b32_e64 v143, v226, v143, s[12:13]
	s_waitcnt vmcnt(0)
	v_cndmask_b32_e64 v144, v171, v144, s[12:13]
	v_cndmask_b32_e64 v145, v163, v145, s[12:13]
	v_cndmask_b32_e64 v146, v222, v146, s[12:13]
	v_cndmask_b32_e64 v147, v223, v147, s[12:13]
	s_branch .LBB0_1727
.Lnfs_1_19:
	v_mov_b64_e32 v[128:129], s[24:25]
	v_mad_i64_i32 v[128:129], vcc, v146, s76, v[128:129]
	v_lshl_add_u64 v[128:129], v[196:197], 2, v[128:129]
	global_store_dwordx4 v[128:129], v[124:127], off
	v_add_co_u32_e32 v128, vcc, 0x2000, v128
	s_nop 1
	v_addc_co_u32_e32 v129, vcc, 0, v129, vcc
	global_store_dwordx4 v[128:129], v[88:91], off offset:3072
	s_branch .LBB0_1729
; template <int N> __device__ __forceinline__ float dpp_ror(float v) { const int i = __builtin_bit_cast(int, v); return __builtin_bit_cast(float, __builtin_amdgcn_update_dpp(i, i, 0x120 + N, 0xF, 0xF, false)); }
;     __device__ __forceinline__ void operator()(const f32x4 (&acc)[2][2][4][2], const pg8::Unit& u, int wr, int wc, int fr, int fq, PG8_LAS unsigned char* xl) const {
;     ...
;                         } else { const int t = fr & 3, b = (row - MP) >> 2;
; #pragma unroll
;                             for (int j = 0; j < 4; ++j) { p1[j] = dpp_ror<1>(cur[j]); p2[j] = dpp_ror<2>(cur[j]); }
;                             const f32x4 c1 = *(const f32x4*)(ctx_s + (size_t)(b * 2 + 1) * FF2 + bj * FF + jc0 + 4 * n), c0 = *(const f32x4*)(ctx_s + (size_t)(b * 2) * FF2 + bj * FF + jc0 + 4 * n);
; #pragma unroll
;                             for (int j = 0; j < 4; ++j) { p2[j] = t == 0 ? c0[j] : (t == 1 ? c1[j] : p2[j]); p1[j] = t == 0 ? c1[j] : p1[j]; }
;                         }
;     ...
;                     if (sample && (fr & 3) >= 2) { const int b = (row - MP) >> 2, t = fr & 3;
; #pragma unroll
;                         for (int bj = 0; bj < 2; ++bj) *(f32x4*)(nf_s + (size_t)(b * 2 + t - 2) * FF2 + bj * FF + jc0 + 4 * n) = acc[ai][bj][m][n];
;                     }
.Lsmp_1_38:
	v_or_b32_e32 v130, 1, v128
	v_mov_b64_e32 v[128:129], s[48:49]
	v_mad_i64_i32 v[130:131], vcc, v130, s76, v[128:129]
	v_mad_i64_i32 v[128:129], vcc, v147, s76, v[128:129]
	v_lshl_add_u64 v[142:143], v[130:131], 0, v[198:199]
	v_lshl_add_u64 v[140:141], v[128:129], 0, v[198:199]
	global_load_dwordx4 v[128:131], v[142:143], off
	global_load_dwordx4 v[132:135], v[140:141], off
	v_mov_b32_e32 v136, v84
	v_mov_b32_e32 v137, v84
	v_mov_b32_e32 v138, v85
	v_mov_b32_e32 v139, v85
	v_mov_b32_e32 v163, v86
	v_mov_b32_e32 v222, v87
	v_mov_b32_e32 v155, v86
	v_mov_b32_e32 v171, v87
	v_mov_b32_dpp v136, v136 row_ror:1 row_mask:0xf bank_mask:0xf
	v_mov_b32_dpp v137, v137 row_ror:2 row_mask:0xf bank_mask:0xf
	v_mov_b32_dpp v138, v138 row_ror:1 row_mask:0xf bank_mask:0xf
	v_mov_b32_dpp v139, v139 row_ror:2 row_mask:0xf bank_mask:0xf
	v_mov_b32_dpp v163, v163 row_ror:2 row_mask:0xf bank_mask:0xf
	v_mov_b32_dpp v222, v222 row_ror:2 row_mask:0xf bank_mask:0xf
	v_mov_b32_dpp v155, v155 row_ror:1 row_mask:0xf bank_mask:0xf
	v_mov_b32_dpp v171, v171 row_ror:1 row_mask:0xf bank_mask:0xf
	s_waitcnt vmcnt(1)
	v_cndmask_b32_e64 v137, v137, v128, s[14:15]
	v_cndmask_b32_e64 v128, v136, v128, s[12:13]
	v_cndmask_b32_e64 v136, v139, v129, s[14:15]
	v_cndmask_b32_e64 v129, v138, v129, s[12:13]
	v_cndmask_b32_e64 v138, v163, v130, s[14:15]
	v_cndmask_b32_e64 v139, v222, v131, s[14:15]
	v_cndmask_b32_e64 v130, v155, v130, s[12:13]
	v_cndmask_b32_e64 v131, v171, v131, s[12:13]
	s_waitcnt vmcnt(0)
	v_cndmask_b32_e64 v132, v137, v132, s[12:13]
	v_cndmask_b32_e64 v133, v136, v133, s[12:13]
	v_cndmask_b32_e64 v134, v138, v134, s[12:13]
	v_cndmask_b32_e64 v135, v139, v135, s[12:13]
	s_branch .LBB0_1733
.Lsmp_1_39:
	v_add_co_u32_e32 v124, vcc, 0x2000, v142
	v_mov_b32_e32 v155, v80
	s_nop 0
	v_addc_co_u32_e32 v125, vcc, 0, v143, vcc
	v_add_co_u32_e32 v136, vcc, 0x2000, v140
	global_load_dwordx4 v[124:127], v[124:125], off offset:3072
	s_nop 0
	v_addc_co_u32_e32 v137, vcc, 0, v141, vcc
	global_load_dwordx4 v[136:139], v[136:137], off offset:3072
	v_mov_b32_e32 v163, v80
	v_mov_b32_e32 v171, v81
	v_mov_b32_e32 v222, v81
	v_mov_b32_e32 v224, v82
	v_mov_b32_e32 v226, v83
	v_mov_b32_e32 v223, v82
	v_mov_b32_e32 v225, v83
	v_mov_b32_dpp v155, v155 row_ror:1 row_mask:0xf bank_mask:0xf
	v_mov_b32_dpp v163, v163 row_ror:2 row_mask:0xf bank_mask:0xf
	v_mov_b32_dpp v171, v171 row_ror:1 row_mask:0xf bank_mask:0xf
	v_mov_b32_dpp v222, v222 row_ror:2 row_mask:0xf bank_mask:0xf
	v_mov_b32_dpp v224, v224 row_ror:2 row_mask:0xf bank_mask:0xf
	v_mov_b32_dpp v226, v226 row_ror:2 row_mask:0xf bank_mask:0xf
	v_mov_b32_dpp v223, v223 row_ror:1 row_mask:0xf bank_mask:0xf
	v_mov_b32_dpp v225, v225 row_ror:1 row_mask:0xf bank_mask:0xf
	s_waitcnt vmcnt(1)
	v_cndmask_b32_e64 v163, v163, v124, s[14:15]
	v_cndmask_b32_e64 v124, v155, v124, s[12:13]
	v_cndmask_b32_e64 v155, v222, v125, s[14:15]
	v_cndmask_b32_e64 v125, v171, v125, s[12:13]
	v_cndmask_b32_e64 v171, v224, v126, s[14:15]
	v_cndmask_b32_e64 v222, v226, v127, s[14:15]
	v_cndmask_b32_e64 v126, v223, v126, s[12:13]
	v_cndmask_b32_e64 v127, v225, v127, s[12:13]
	s_waitcnt vmcnt(0)
	v_cndmask_b32_e64 v136, v163, v136, s[12:13]
	v_cndmask_b32_e64 v137, v155, v137, s[12:13]
	v_cndmask_b32_e64 v138, v171, v138, s[12:13]
	v_cndmask_b32_e64 v139, v222, v139, s[12:13]
	s_branch .LBB0_1737
.Lnfs_1_20:
	v_mov_b64_e32 v[88:89], s[24:25]
	v_mad_i64_i32 v[88:89], vcc, v138, s76, v[88:89]
	v_lshl_add_u64 v[88:89], v[196:197], 2, v[88:89]
	global_store_dwordx4 v[88:89], v[84:87], off
	v_add_co_u32_e32 v88, vcc, 0x2000, v88
	s_nop 1
	v_addc_co_u32_e32 v89, vcc, 0, v89, vcc
	global_store_dwordx4 v[88:89], v[80:83], off offset:3072
	s_branch .LBB0_1739
.Lsmp_1_40:
	v_or_b32_e32 v90, 1, v88
	v_mov_b64_e32 v[88:89], s[48:49]
	v_mad_i64_i32 v[90:91], vcc, v90, s76, v[88:89]
	v_mad_i64_i32 v[88:89], vcc, v139, s76, v[88:89]
	v_lshl_add_u64 v[134:135], v[90:91], 0, v[198:199]
	v_lshl_add_u64 v[132:133], v[88:89], 0, v[198:199]
	global_load_dwordx4 v[88:91], v[134:135], off
	global_load_dwordx4 v[124:127], v[132:133], off
	v_mov_b32_e32 v128, v76
	v_mov_b32_e32 v129, v76
	v_mov_b32_e32 v130, v77
	v_mov_b32_e32 v131, v77
	v_mov_b32_e32 v155, v78
	v_mov_b32_e32 v171, v79
	v_mov_b32_e32 v147, v78
	v_mov_b32_e32 v163, v79
	v_mov_b32_dpp v128, v128 row_ror:1 row_mask:0xf bank_mask:0xf
	v_mov_b32_dpp v129, v129 row_ror:2 row_mask:0xf bank_mask:0xf
	v_mov_b32_dpp v130, v130 row_ror:1 row_mask:0xf bank_mask:0xf
	v_mov_b32_dpp v131, v131 row_ror:2 row_mask:0xf bank_mask:0xf
	v_mov_b32_dpp v155, v155 row_ror:2 row_mask:0xf bank_mask:0xf
	v_mov_b32_dpp v171, v171 row_ror:2 row_mask:0xf bank_mask:0xf
	v_mov_b32_dpp v147, v147 row_ror:1 row_mask:0xf bank_mask:0xf
	v_mov_b32_dpp v163, v163 row_ror:1 row_mask:0xf bank_mask:0xf
	s_waitcnt vmcnt(1)
	v_cndmask_b32_e64 v129, v129, v88, s[14:15]
	v_cndmask_b32_e64 v88, v128, v88, s[12:13]
	v_cndmask_b32_e64 v128, v131, v89, s[14:15]
	v_cndmask_b32_e64 v89, v130, v89, s[12:13]
	v_cndmask_b32_e64 v130, v155, v90, s[14:15]
	v_cndmask_b32_e64 v131, v171, v91, s[14:15]
	v_cndmask_b32_e64 v90, v147, v90, s[12:13]
	v_cndmask_b32_e64 v91, v163, v91, s[12:13]
	s_waitcnt vmcnt(0)
	v_cndmask_b32_e64 v124, v129, v124, s[12:13]
	v_cndmask_b32_e64 v125, v128, v125, s[12:13]
	v_cndmask_b32_e64 v126, v130, v126, s[12:13]
	v_cndmask_b32_e64 v127, v131, v127, s[12:13]
	s_branch .LBB0_1743
; template <int N> __device__ __forceinline__ float dpp_ror(float v) { const int i = __builtin_bit_cast(int, v); return __builtin_bit_cast(float, __builtin_amdgcn_update_dpp(i, i, 0x120 + N, 0xF, 0xF, false)); }
;     __device__ __forceinline__ void operator()(const f32x4 (&acc)[2][2][4][2], const pg8::Unit& u, int wr, int wc, int fr, int fq, PG8_LAS unsigned char* xl) const {
;     ...
;                         } else { const int t = fr & 3, b = (row - MP) >> 2;
; #pragma unroll
;                             for (int j = 0; j < 4; ++j) { p1[j] = dpp_ror<1>(cur[j]); p2[j] = dpp_ror<2>(cur[j]); }
;                             const f32x4 c1 = *(const f32x4*)(ctx_s + (size_t)(b * 2 + 1) * FF2 + bj * FF + jc0 + 4 * n), c0 = *(const f32x4*)(ctx_s + (size_t)(b * 2) * FF2 + bj * FF + jc0 + 4 * n);
; #pragma unroll
;                             for (int j = 0; j < 4; ++j) { p2[j] = t == 0 ? c0[j] : (t == 1 ? c1[j] : p2[j]); p1[j] = t == 0 ? c1[j] : p1[j]; }
;                         }
;     ...
;                     if (sample && (fr & 3) >= 2) { const int b = (row - MP) >> 2, t = fr & 3;
; #pragma unroll
;                         for (int bj = 0; bj < 2; ++bj) *(f32x4*)(nf_s + (size_t)(b * 2 + t - 2) * FF2 + bj * FF + jc0 + 4 * n) = acc[ai][bj][m][n];
;                     }
.Lsmp_1_41:
	v_add_co_u32_e32 v84, vcc, 0x2000, v134
	v_mov_b32_e32 v147, v72
	s_nop 0
	v_addc_co_u32_e32 v85, vcc, 0, v135, vcc
	v_add_co_u32_e32 v128, vcc, 0x2000, v132
	global_load_dwordx4 v[84:87], v[84:85], off offset:3072
	s_nop 0
	v_addc_co_u32_e32 v129, vcc, 0, v133, vcc
	global_load_dwordx4 v[128:131], v[128:129], off offset:3072
	v_mov_b32_e32 v155, v72
	v_mov_b32_e32 v163, v73
	v_mov_b32_e32 v171, v73
	v_mov_b32_e32 v223, v74
	v_mov_b32_e32 v225, v75
	v_mov_b32_e32 v222, v74
	v_mov_b32_e32 v224, v75
	v_mov_b32_dpp v147, v147 row_ror:1 row_mask:0xf bank_mask:0xf
	v_mov_b32_dpp v155, v155 row_ror:2 row_mask:0xf bank_mask:0xf
	v_mov_b32_dpp v163, v163 row_ror:1 row_mask:0xf bank_mask:0xf
	v_mov_b32_dpp v171, v171 row_ror:2 row_mask:0xf bank_mask:0xf
	v_mov_b32_dpp v223, v223 row_ror:2 row_mask:0xf bank_mask:0xf
	v_mov_b32_dpp v225, v225 row_ror:2 row_mask:0xf bank_mask:0xf
	v_mov_b32_dpp v222, v222 row_ror:1 row_mask:0xf bank_mask:0xf
	v_mov_b32_dpp v224, v224 row_ror:1 row_mask:0xf bank_mask:0xf
	s_waitcnt vmcnt(1)
	v_cndmask_b32_e64 v155, v155, v84, s[14:15]
	v_cndmask_b32_e64 v84, v147, v84, s[12:13]
	v_cndmask_b32_e64 v147, v171, v85, s[14:15]
	v_cndmask_b32_e64 v85, v163, v85, s[12:13]
	v_cndmask_b32_e64 v163, v223, v86, s[14:15]
	v_cndmask_b32_e64 v171, v225, v87, s[14:15]
	v_cndmask_b32_e64 v86, v222, v86, s[12:13]
	v_cndmask_b32_e64 v87, v224, v87, s[12:13]
	s_waitcnt vmcnt(0)
	v_cndmask_b32_e64 v128, v155, v128, s[12:13]
	v_cndmask_b32_e64 v129, v147, v129, s[12:13]
	v_cndmask_b32_e64 v130, v163, v130, s[12:13]
	v_cndmask_b32_e64 v131, v171, v131, s[12:13]
	s_branch .LBB0_1747
.Lnfs_1_21:
	v_mov_b64_e32 v[80:81], s[24:25]
	v_mad_i64_i32 v[80:81], vcc, v139, s76, v[80:81]
	v_lshl_add_u64 v[80:81], v[196:197], 2, v[80:81]
	global_store_dwordx4 v[80:81], v[76:79], off
	v_add_co_u32_e32 v80, vcc, 0x2000, v80
	s_nop 1
	v_addc_co_u32_e32 v81, vcc, 0, v81, vcc
	global_store_dwordx4 v[80:81], v[72:75], off offset:3072
	s_branch .LBB0_1749
.Lsmp_1_42:
	v_or_b32_e32 v82, 1, v80
	v_mov_b64_e32 v[80:81], s[48:49]
	v_mad_i64_i32 v[82:83], vcc, v82, s76, v[80:81]
	v_mad_i64_i32 v[80:81], vcc, v147, s76, v[80:81]
	v_lshl_add_u64 v[126:127], v[82:83], 0, v[198:199]
	v_lshl_add_u64 v[124:125], v[80:81], 0, v[198:199]
	global_load_dwordx4 v[80:83], v[126:127], off
	global_load_dwordx4 v[84:87], v[124:125], off
	v_mov_b32_e32 v88, v12
	v_mov_b32_e32 v89, v12
	v_mov_b32_e32 v90, v13
	v_mov_b32_e32 v91, v13
	v_mov_b32_e32 v131, v14
	v_mov_b32_e32 v163, v15
	v_mov_b32_e32 v130, v14
	v_mov_b32_e32 v155, v15
	v_mov_b32_dpp v88, v88 row_ror:1 row_mask:0xf bank_mask:0xf
	v_mov_b32_dpp v89, v89 row_ror:2 row_mask:0xf bank_mask:0xf
	v_mov_b32_dpp v90, v90 row_ror:1 row_mask:0xf bank_mask:0xf
	v_mov_b32_dpp v91, v91 row_ror:2 row_mask:0xf bank_mask:0xf
	v_mov_b32_dpp v131, v131 row_ror:2 row_mask:0xf bank_mask:0xf
	v_mov_b32_dpp v163, v163 row_ror:2 row_mask:0xf bank_mask:0xf
	v_mov_b32_dpp v130, v130 row_ror:1 row_mask:0xf bank_mask:0xf
	v_mov_b32_dpp v155, v155 row_ror:1 row_mask:0xf bank_mask:0xf
	s_waitcnt vmcnt(1)
	v_cndmask_b32_e64 v89, v89, v80, s[14:15]
	v_cndmask_b32_e64 v80, v88, v80, s[12:13]
	v_cndmask_b32_e64 v88, v91, v81, s[14:15]
	v_cndmask_b32_e64 v81, v90, v81, s[12:13]
	v_cndmask_b32_e64 v90, v131, v82, s[14:15]
	v_cndmask_b32_e64 v91, v163, v83, s[14:15]
	v_cndmask_b32_e64 v82, v130, v82, s[12:13]
	v_cndmask_b32_e64 v83, v155, v83, s[12:13]
	s_waitcnt vmcnt(0)
	v_cndmask_b32_e64 v84, v89, v84, s[12:13]
	v_cndmask_b32_e64 v85, v88, v85, s[12:13]
	v_cndmask_b32_e64 v86, v90, v86, s[12:13]
	v_cndmask_b32_e64 v87, v91, v87, s[12:13]
	s_branch .LBB0_1753
; template <int N> __device__ __forceinline__ float dpp_ror(float v) { const int i = __builtin_bit_cast(int, v); return __builtin_bit_cast(float, __builtin_amdgcn_update_dpp(i, i, 0x120 + N, 0xF, 0xF, false)); }
;     __device__ __forceinline__ void operator()(const f32x4 (&acc)[2][2][4][2], const pg8::Unit& u, int wr, int wc, int fr, int fq, PG8_LAS unsigned char* xl) const {
;     ...
;                         } else { const int t = fr & 3, b = (row - MP) >> 2;
; #pragma unroll
;                             for (int j = 0; j < 4; ++j) { p1[j] = dpp_ror<1>(cur[j]); p2[j] = dpp_ror<2>(cur[j]); }
;                             const f32x4 c1 = *(const f32x4*)(ctx_s + (size_t)(b * 2 + 1) * FF2 + bj * FF + jc0 + 4 * n), c0 = *(const f32x4*)(ctx_s + (size_t)(b * 2) * FF2 + bj * FF + jc0 + 4 * n);
; #pragma unroll
;                             for (int j = 0; j < 4; ++j) { p2[j] = t == 0 ? c0[j] : (t == 1 ? c1[j] : p2[j]); p1[j] = t == 0 ? c1[j] : p1[j]; }
;                         }
;     ...
;                     if (sample && (fr & 3) >= 2) { const int b = (row - MP) >> 2, t = fr & 3;
; #pragma unroll
;                         for (int bj = 0; bj < 2; ++bj) *(f32x4*)(nf_s + (size_t)(b * 2 + t - 2) * FF2 + bj * FF + jc0 + 4 * n) = acc[ai][bj][m][n];
;                     }
.Lsmp_1_43:
	v_add_co_u32_e32 v76, vcc, 0x2000, v126
	v_mov_b32_e32 v130, v4
	s_nop 0
	v_addc_co_u32_e32 v77, vcc, 0, v127, vcc
	v_add_co_u32_e32 v88, vcc, 0x2000, v124
	global_load_dwordx4 v[76:79], v[76:77], off offset:3072
	s_nop 0
	v_addc_co_u32_e32 v89, vcc, 0, v125, vcc
	global_load_dwordx4 v[88:91], v[88:89], off offset:3072
	v_mov_b32_e32 v131, v4
	v_mov_b32_e32 v155, v5
	v_mov_b32_e32 v163, v5
	v_mov_b32_e32 v222, v6
	v_mov_b32_e32 v224, v7
	v_mov_b32_e32 v171, v6
	v_mov_b32_e32 v223, v7
	v_mov_b32_dpp v130, v130 row_ror:1 row_mask:0xf bank_mask:0xf
	v_mov_b32_dpp v131, v131 row_ror:2 row_mask:0xf bank_mask:0xf
	v_mov_b32_dpp v155, v155 row_ror:1 row_mask:0xf bank_mask:0xf
	v_mov_b32_dpp v163, v163 row_ror:2 row_mask:0xf bank_mask:0xf
	v_mov_b32_dpp v222, v222 row_ror:2 row_mask:0xf bank_mask:0xf
	v_mov_b32_dpp v224, v224 row_ror:2 row_mask:0xf bank_mask:0xf
	v_mov_b32_dpp v171, v171 row_ror:1 row_mask:0xf bank_mask:0xf
	v_mov_b32_dpp v223, v223 row_ror:1 row_mask:0xf bank_mask:0xf
	s_waitcnt vmcnt(1)
	v_cndmask_b32_e64 v131, v131, v76, s[14:15]
	v_cndmask_b32_e64 v76, v130, v76, s[12:13]
	v_cndmask_b32_e64 v130, v163, v77, s[14:15]
	v_cndmask_b32_e64 v77, v155, v77, s[12:13]
	v_cndmask_b32_e64 v155, v222, v78, s[14:15]
	v_cndmask_b32_e64 v163, v224, v79, s[14:15]
	v_cndmask_b32_e64 v78, v171, v78, s[12:13]
	v_cndmask_b32_e64 v79, v223, v79, s[12:13]
	s_waitcnt vmcnt(0)
	v_cndmask_b32_e64 v88, v131, v88, s[12:13]
	v_cndmask_b32_e64 v89, v130, v89, s[12:13]
	v_cndmask_b32_e64 v90, v155, v90, s[12:13]
	v_cndmask_b32_e64 v91, v163, v91, s[12:13]
	s_branch .LBB0_1757
.Lnfs_1_22:
	v_mov_b64_e32 v[72:73], s[24:25]
	v_mad_i64_i32 v[72:73], vcc, v147, s76, v[72:73]
	v_lshl_add_u64 v[72:73], v[196:197], 2, v[72:73]
	global_store_dwordx4 v[72:73], v[12:15], off
	v_add_co_u32_e32 v72, vcc, 0x2000, v72
	s_nop 1
	v_addc_co_u32_e32 v73, vcc, 0, v73, vcc
	global_store_dwordx4 v[72:73], v[4:7], off offset:3072
	s_branch .LBB0_1759
.Lsmp_1_44:
	global_load_dwordx4 v[108:111], v[202:203], off offset:16
	global_load_dwordx4 v[112:115], v[200:201], off offset:16
	v_mov_b32_e32 v120, v68
	v_mov_b32_e32 v121, v68
	v_mov_b32_e32 v122, v69
	v_mov_b32_e32 v123, v69
	v_mov_b32_e32 v163, v70
	v_mov_b32_e32 v221, v71
	v_mov_b32_e32 v155, v70
	v_mov_b32_e32 v171, v71
	v_mov_b32_dpp v120, v120 row_ror:1 row_mask:0xf bank_mask:0xf
	v_mov_b32_dpp v121, v121 row_ror:2 row_mask:0xf bank_mask:0xf
	v_mov_b32_dpp v122, v122 row_ror:1 row_mask:0xf bank_mask:0xf
	v_mov_b32_dpp v123, v123 row_ror:2 row_mask:0xf bank_mask:0xf
	v_mov_b32_dpp v163, v163 row_ror:2 row_mask:0xf bank_mask:0xf
	v_mov_b32_dpp v221, v221 row_ror:2 row_mask:0xf bank_mask:0xf
	v_mov_b32_dpp v155, v155 row_ror:1 row_mask:0xf bank_mask:0xf
	v_mov_b32_dpp v171, v171 row_ror:1 row_mask:0xf bank_mask:0xf
	s_waitcnt vmcnt(1)
	v_cndmask_b32_e64 v121, v121, v108, s[14:15]
	v_cndmask_b32_e64 v108, v120, v108, s[12:13]
	v_cndmask_b32_e64 v120, v123, v109, s[14:15]
	v_cndmask_b32_e64 v109, v122, v109, s[12:13]
	v_cndmask_b32_e64 v122, v163, v110, s[14:15]
	v_cndmask_b32_e64 v123, v221, v111, s[14:15]
	v_cndmask_b32_e64 v110, v155, v110, s[12:13]
	v_cndmask_b32_e64 v111, v171, v111, s[12:13]
	s_waitcnt vmcnt(0)
	v_cndmask_b32_e64 v112, v121, v112, s[12:13]
	v_cndmask_b32_e64 v113, v120, v113, s[12:13]
	v_cndmask_b32_e64 v114, v122, v114, s[12:13]
	v_cndmask_b32_e64 v115, v123, v115, s[12:13]
	s_branch .LBB0_1765
.Lsmp_1_45:
	s_waitcnt lgkmcnt(1)
	v_add_co_u32_e32 v116, vcc, 0x2000, v202
	v_mov_b32_e32 v155, v64
	s_nop 0
	v_addc_co_u32_e32 v117, vcc, 0, v203, vcc
	v_add_co_u32_e32 v120, vcc, 0x2000, v200
	global_load_dwordx4 v[116:119], v[116:117], off offset:3088
	s_nop 0
	v_addc_co_u32_e32 v121, vcc, 0, v201, vcc
	global_load_dwordx4 v[120:123], v[120:121], off offset:3088
	v_mov_b32_e32 v163, v64
	v_mov_b32_e32 v171, v65
	v_mov_b32_e32 v200, v65
	v_mov_b32_e32 v202, v66
	v_mov_b32_e32 v221, v67
	v_mov_b32_e32 v201, v66
	v_mov_b32_e32 v203, v67
	v_mov_b32_dpp v155, v155 row_ror:1 row_mask:0xf bank_mask:0xf
	v_mov_b32_dpp v163, v163 row_ror:2 row_mask:0xf bank_mask:0xf
	v_mov_b32_dpp v171, v171 row_ror:1 row_mask:0xf bank_mask:0xf
	v_mov_b32_dpp v200, v200 row_ror:2 row_mask:0xf bank_mask:0xf
	v_mov_b32_dpp v202, v202 row_ror:2 row_mask:0xf bank_mask:0xf
	v_mov_b32_dpp v221, v221 row_ror:2 row_mask:0xf bank_mask:0xf
	v_mov_b32_dpp v201, v201 row_ror:1 row_mask:0xf bank_mask:0xf
	v_mov_b32_dpp v203, v203 row_ror:1 row_mask:0xf bank_mask:0xf
	s_waitcnt vmcnt(1)
	v_cndmask_b32_e64 v163, v163, v116, s[14:15]
	v_cndmask_b32_e64 v116, v155, v116, s[12:13]
	v_cndmask_b32_e64 v155, v200, v117, s[14:15]
	v_cndmask_b32_e64 v117, v171, v117, s[12:13]
	v_cndmask_b32_e64 v171, v202, v118, s[14:15]
	v_cndmask_b32_e64 v200, v221, v119, s[14:15]
	v_cndmask_b32_e64 v118, v201, v118, s[12:13]
	v_cndmask_b32_e64 v119, v203, v119, s[12:13]
	s_waitcnt vmcnt(0)
	v_cndmask_b32_e64 v120, v163, v120, s[12:13]
	v_cndmask_b32_e64 v121, v155, v121, s[12:13]
	v_cndmask_b32_e64 v122, v171, v122, s[12:13]
	v_cndmask_b32_e64 v123, v200, v123, s[12:13]
	s_branch .LBB0_1769

;     __device__ __forceinline__ void operator()(const f32x4 (&acc)[2][2][4][2], const pg8::Unit& u, int wr, int wc, int fr, int fq, PG8_LAS unsigned char* xl) const {
;     ...
;                     if (sample && (fr & 3) >= 2) { const int b = (row - MP) >> 2, t = fr & 3;
; #pragma unroll
;                         for (int bj = 0; bj < 2; ++bj) *(f32x4*)(nf_s + (size_t)(b * 2 + t - 2) * FF2 + bj * FF + jc0 + 4 * n) = acc[ai][bj][m][n];
;                     }
.Lnfs_1_23:
	v_mov_b64_e32 v[64:65], s[24:25]
	v_mad_i64_i32 v[64:65], s[58:59], v170, s76, v[64:65]
	v_lshl_add_u64 v[64:65], v[196:197], 2, v[64:65]
	global_store_dwordx4 v[64:65], v[60:63], off offset:16
	v_add_co_u32_e32 v64, vcc, 0x2000, v64
	s_nop 1
	v_addc_co_u32_e32 v65, vcc, 0, v65, vcc
	global_store_dwordx4 v[64:65], v[56:59], off offset:3088
	s_branch .LBB0_1783

;     __device__ __forceinline__ void operator()(const f32x4 (&acc)[2][2][4][2], const pg8::Unit& u, int wr, int wc, int fr, int fq, PG8_LAS unsigned char* xl) const {
;     ...
;                     if (sample && (fr & 3) >= 2) { const int b = (row - MP) >> 2, t = fr & 3;
; #pragma unroll
;                         for (int bj = 0; bj < 2; ++bj) *(f32x4*)(nf_s + (size_t)(b * 2 + t - 2) * FF2 + bj * FF + jc0 + 4 * n) = acc[ai][bj][m][n];
;                     }
.Lnfs_1_24:
	v_mov_b64_e32 v[56:57], s[24:25]
	v_mad_i64_i32 v[56:57], s[58:59], v162, s76, v[56:57]
	v_lshl_add_u64 v[56:57], v[196:197], 2, v[56:57]
	global_store_dwordx4 v[56:57], v[52:55], off offset:16
	v_add_co_u32_e32 v56, vcc, 0x2000, v56
	s_nop 1
	v_addc_co_u32_e32 v57, vcc, 0, v57, vcc
	global_store_dwordx4 v[56:57], v[48:51], off offset:3088
	s_branch .LBB0_1793

;     __device__ __forceinline__ void operator()(const f32x4 (&acc)[2][2][4][2], const pg8::Unit& u, int wr, int wc, int fr, int fq, PG8_LAS unsigned char* xl) const {
;     ...
;                     if (sample && (fr & 3) >= 2) { const int b = (row - MP) >> 2, t = fr & 3;
; #pragma unroll
;                         for (int bj = 0; bj < 2; ++bj) *(f32x4*)(nf_s + (size_t)(b * 2 + t - 2) * FF2 + bj * FF + jc0 + 4 * n) = acc[ai][bj][m][n];
;                     }
.Lnfs_1_25:
	v_mov_b64_e32 v[48:49], s[24:25]
	v_mad_i64_i32 v[48:49], s[58:59], v154, s76, v[48:49]
	v_lshl_add_u64 v[48:49], v[196:197], 2, v[48:49]
	global_store_dwordx4 v[48:49], v[44:47], off offset:16
	s_nop 1
	v_add_co_u32_e32 v44, vcc, 0x2000, v48
	s_nop 1
	v_addc_co_u32_e32 v45, vcc, 0, v49, vcc
	global_store_dwordx4 v[44:45], v[40:43], off offset:3088
	s_branch .LBB0_1803

;     __device__ __forceinline__ void operator()(const f32x4 (&acc)[2][2][4][2], const pg8::Unit& u, int wr, int wc, int fr, int fq, PG8_LAS unsigned char* xl) const {
;     ...
;                     if (sample && (fr & 3) >= 2) { const int b = (row - MP) >> 2, t = fr & 3;
; #pragma unroll
;                         for (int bj = 0; bj < 2; ++bj) *(f32x4*)(nf_s + (size_t)(b * 2 + t - 2) * FF2 + bj * FF + jc0 + 4 * n) = acc[ai][bj][m][n];
;                     }
.Lnfs_1_26:
	v_mov_b64_e32 v[40:41], s[24:25]
	v_mad_i64_i32 v[40:41], s[8:9], v146, s76, v[40:41]
	v_lshl_add_u64 v[40:41], v[196:197], 2, v[40:41]
	global_store_dwordx4 v[40:41], v[36:39], off offset:16
	v_add_co_u32_e32 v40, vcc, 0x2000, v40
	s_nop 1
	v_addc_co_u32_e32 v41, vcc, 0, v41, vcc
	global_store_dwordx4 v[40:41], v[32:35], off offset:3088
	s_branch .LBB0_1815

;     __device__ __forceinline__ void operator()(const f32x4 (&acc)[2][2][4][2], const pg8::Unit& u, int wr, int wc, int fr, int fq, PG8_LAS unsigned char* xl) const {
;     ...
;                     if (sample && (fr & 3) >= 2) { const int b = (row - MP) >> 2, t = fr & 3;
; #pragma unroll
;                         for (int bj = 0; bj < 2; ++bj) *(f32x4*)(nf_s + (size_t)(b * 2 + t - 2) * FF2 + bj * FF + jc0 + 4 * n) = acc[ai][bj][m][n];
;                     }
.Lnfs_1_27:
	v_mov_b64_e32 v[32:33], s[24:25]
	v_mad_i64_i32 v[32:33], s[8:9], v138, s76, v[32:33]
	v_lshl_add_u64 v[32:33], v[196:197], 2, v[32:33]
	global_store_dwordx4 v[32:33], v[28:31], off offset:16
	v_add_co_u32_e32 v32, vcc, 0x2000, v32
	s_nop 1
	v_addc_co_u32_e32 v33, vcc, 0, v33, vcc
	global_store_dwordx4 v[32:33], v[24:27], off offset:3088
	s_branch .LBB0_1825

;     __device__ __forceinline__ void operator()(const f32x4 (&acc)[2][2][4][2], const pg8::Unit& u, int wr, int wc, int fr, int fq, PG8_LAS unsigned char* xl) const {
;     ...
;                     if (sample && (fr & 3) >= 2) { const int b = (row - MP) >> 2, t = fr & 3;
; #pragma unroll
;                         for (int bj = 0; bj < 2; ++bj) *(f32x4*)(nf_s + (size_t)(b * 2 + t - 2) * FF2 + bj * FF + jc0 + 4 * n) = acc[ai][bj][m][n];
;                     }
.Lnfs_1_28:
	v_mov_b64_e32 v[24:25], s[24:25]
	v_mad_i64_i32 v[24:25], s[8:9], v139, s76, v[24:25]
	v_lshl_add_u64 v[24:25], v[196:197], 2, v[24:25]
	global_store_dwordx4 v[24:25], v[20:23], off offset:16
	v_add_co_u32_e32 v24, vcc, 0x2000, v24
	s_nop 1
	v_addc_co_u32_e32 v25, vcc, 0, v25, vcc
	global_store_dwordx4 v[24:25], v[16:19], off offset:3088
	s_branch .LBB0_1835

;     __device__ __forceinline__ void operator()(const f32x4 (&acc)[2][2][4][2], const pg8::Unit& u, int wr, int wc, int fr, int fq, PG8_LAS unsigned char* xl) const {
;     ...
;                     if (sample && (fr & 3) >= 2) { const int b = (row - MP) >> 2, t = fr & 3;
; #pragma unroll
;                         for (int bj = 0; bj < 2; ++bj) *(f32x4*)(nf_s + (size_t)(b * 2 + t - 2) * FF2 + bj * FF + jc0 + 4 * n) = acc[ai][bj][m][n];
;                     }
.Lnfs_1_29:
	v_mov_b64_e32 v[16:17], s[24:25]
	v_mad_i64_i32 v[16:17], s[8:9], v147, s76, v[16:17]
	v_lshl_add_u64 v[16:17], v[196:197], 2, v[16:17]
	global_store_dwordx4 v[16:17], v[8:11], off offset:16
	v_add_co_u32_e32 v16, vcc, 0x2000, v16
	s_nop 1
	v_addc_co_u32_e32 v17, vcc, 0, v17, vcc
	global_store_dwordx4 v[16:17], v[0:3], off offset:3088
	s_branch .LBB0_1845
.Lisl_end_1:
	s_and_saveexec_b64 s[6:7], s[96:97]
	s_cbranch_execnz .Lnfs_1_29
